# K-loop MFMA segment heads: s_setprio 1 raised before parking at the pre-MFMA barrier, duplicate lgkmcnt(0) dropped (2 fewer issue slots after each barrier release)
# speedup vs baseline: 1.0193x; 1.0022x over previous
; #define PG8_STAGE(bufoff, gbase, voff) do { _Pragma("unroll") for (int _i = 0; _i < 2; ++_i) \
;         __builtin_amdgcn_global_load_lds((const unsigned*)((const char*)(gbase) + (voff)[_i]), (LAS unsigned*)(lds + (bufoff) + ldsw + _i * 8192), 16, 0, 0); } while (0)
; #define PG8_LDA(dst, b, h) do { _Pragma("unroll") for (int m = 0; m < 4; ++m) _Pragma("unroll") for (int k = 0; k < 2; ++k) dst[m][k] = *(const LAS bf16x8*)(lds + PG8_SA(b, h) + aoff + m * 2048 + k * 1024); } while (0)
; #define PG8_LDB(dst, b, h) do { _Pragma("unroll") for (int n = 0; n < 2; ++n) _Pragma("unroll") for (int k = 0; k < 2; ++k) dst[n][k] = *(const LAS bf16x8*)(lds + PG8_SB(b, h) + boff + n * 2048 + k * 1024); } while (0)
; #define PG8_WAIT_V(n) asm volatile("s_waitcnt vmcnt(" #n ")" ::: "memory")
; #define PG8_WAIT_L(n) asm volatile("s_waitcnt lgkmcnt(" #n ")" ::: "memory")
; #define PG8_BAR __builtin_amdgcn_s_barrier()
; #define PG8_SCHED __builtin_amdgcn_sched_barrier(0)
; template <class Epi>
; __device__ __forceinline__ void gemm_phase(LAS unsigned char* lds, const bf16_t* A, int lda, const bf16_t* Bt, int ldb, int M, int N, int K, int asel, const Epi& E, const int fixed_round = -1) {
;     ...
;             const char* a1 = cA + (size_t)(t + 1) * kstep;
;             const char* a2 = last ? nA : cA + (size_t)(t + 2) * kstep; const char* b2 = last ? nB : cB + (size_t)(t + 2) * kstep;
;             const char* a3 = a2 + kstep; const char* b3 = b2 + kstep;
;             PG8_LDB(B0, 0, 0); PG8_SCHED; PG8_LDA(At, 0, 0); PG8_STAGE(PG8_SA(1, 1), a1 + hstepA, voffA);
;             PG8_WAIT_L(8); PG8_BAR; PG8_WAIT_L(0); PG8_MMA(0, 0, At, B0); PG8_BAR; PG8_SCHED;
;             PG8_LDB(B1, 0, 1); PG8_STAGE(PG8_SB(0, 0), b2, voffB);
;             PG8_BAR; PG8_WAIT_L(0); PG8_MMA(0, 1, At, B1); PG8_BAR;
;             PG8_LDA(At, 0, 1); PG8_STAGE(PG8_SA(0, 0), a2, voffA);
;             PG8_BAR; PG8_WAIT_L(0); PG8_MMA(1, 0, At, B0); PG8_BAR; PG8_SCHED;
;             PG8_STAGE(PG8_SB(0, 1), b2 + hstepB, voffB);
;             PG8_WAIT_V(6); PG8_BAR; PG8_MMA(1, 1, At, B1); PG8_BAR;
.LBB0_199:
	ds_read_b128 v[148:151], v161
	ds_read_b128 v[152:155], v161 offset:1024
	ds_read_b128 v[156:159], v161 offset:2048
	ds_read_b128 v[166:169], v161 offset:3072
	s_add_i32 m0, s39, 0xc000
	ds_read_b128 v[170:173], v162
	ds_read_b128 v[174:177], v162 offset:1024
	ds_read_b128 v[178:181], v162 offset:2048
	ds_read_b128 v[182:185], v162 offset:3072
	ds_read_b128 v[186:189], v162 offset:4096
	ds_read_b128 v[190:193], v162 offset:5120
	ds_read_b128 v[196:199], v162 offset:6144
	ds_read_b128 v[202:205], v162 offset:7168
	global_load_lds_dwordx4 v140, s[28:29]
	s_add_i32 m0, s39, 0xe000
	s_nop 0
	global_load_lds_dwordx4 v142, s[28:29]
	s_waitcnt lgkmcnt(8)
	s_setprio 1
	s_barrier
	s_waitcnt lgkmcnt(0)
	v_mfma_f32_16x16x32_bf16 v[124:127], v[148:151], v[170:173], v[124:127]
	v_mfma_f32_16x16x32_bf16 v[120:123], v[156:159], v[170:173], v[120:123]
	v_mfma_f32_16x16x32_bf16 v[112:115], v[148:151], v[178:181], v[112:115]
	v_mfma_f32_16x16x32_bf16 v[108:111], v[156:159], v[178:181], v[108:111]
	v_mfma_f32_16x16x32_bf16 v[100:103], v[148:151], v[186:189], v[100:103]
	v_mfma_f32_16x16x32_bf16 v[92:95], v[156:159], v[186:189], v[92:95]
	v_mfma_f32_16x16x32_bf16 v[84:87], v[148:151], v[196:199], v[84:87]
	v_mfma_f32_16x16x32_bf16 v[76:79], v[156:159], v[196:199], v[76:79]
	v_mfma_f32_16x16x32_bf16 v[124:127], v[152:155], v[174:177], v[124:127]
	v_mfma_f32_16x16x32_bf16 v[120:123], v[166:169], v[174:177], v[120:123]
	v_mfma_f32_16x16x32_bf16 v[112:115], v[152:155], v[182:185], v[112:115]
	v_mfma_f32_16x16x32_bf16 v[108:111], v[166:169], v[182:185], v[108:111]
	v_mfma_f32_16x16x32_bf16 v[100:103], v[152:155], v[190:193], v[100:103]
	v_mfma_f32_16x16x32_bf16 v[92:95], v[166:169], v[190:193], v[92:95]
	v_mfma_f32_16x16x32_bf16 v[84:87], v[152:155], v[202:205], v[84:87]
	v_mfma_f32_16x16x32_bf16 v[76:79], v[166:169], v[202:205], v[76:79]
	s_setprio 0
	s_barrier
	s_add_u32 s30, s28, 0xfff80080
	s_addc_u32 s31, s29, -1
	s_cmp_eq_u32 s58, 28
	s_cselect_b32 s35, s4, s31
	s_cselect_b32 s34, s21, s30
	s_cselect_b32 s31, s19, s57
	s_cselect_b32 s30, s55, s56
	s_add_i32 s59, s46, s38
	s_add_u32 s98, s30, s6
	s_addc_u32 s99, s31, s7
	s_mov_b32 m0, s59
	ds_read_b128 v[206:209], v163
	ds_read_b128 v[210:213], v163 offset:1024
	ds_read_b128 v[214:217], v163 offset:2048
	ds_read_b128 v[218:221], v163 offset:3072
	global_load_lds_dwordx4 v130, s[30:31]
	s_add_i32 m0, s59, 0x2000
	s_nop 0
	global_load_lds_dwordx4 v134, s[30:31]
	s_setprio 1
	s_barrier
	s_waitcnt lgkmcnt(0)
	v_mfma_f32_16x16x32_bf16 v[116:119], v[206:209], v[170:173], v[116:119]
	v_mfma_f32_16x16x32_bf16 v[104:107], v[214:217], v[170:173], v[104:107]
	v_mfma_f32_16x16x32_bf16 v[96:99], v[206:209], v[178:181], v[96:99]
	v_mfma_f32_16x16x32_bf16 v[88:91], v[214:217], v[178:181], v[88:91]
	v_mfma_f32_16x16x32_bf16 v[80:83], v[206:209], v[186:189], v[80:83]
	v_mfma_f32_16x16x32_bf16 v[72:75], v[214:217], v[186:189], v[72:75]
	v_mfma_f32_16x16x32_bf16 v[68:71], v[206:209], v[196:199], v[68:71]
	v_mfma_f32_16x16x32_bf16 v[64:67], v[214:217], v[196:199], v[64:67]
	v_mfma_f32_16x16x32_bf16 v[116:119], v[210:213], v[174:177], v[116:119]
	v_mfma_f32_16x16x32_bf16 v[104:107], v[218:221], v[174:177], v[104:107]
	v_mfma_f32_16x16x32_bf16 v[96:99], v[210:213], v[182:185], v[96:99]
	v_mfma_f32_16x16x32_bf16 v[88:91], v[218:221], v[182:185], v[88:91]
	v_mfma_f32_16x16x32_bf16 v[80:83], v[210:213], v[190:193], v[80:83]
	v_mfma_f32_16x16x32_bf16 v[72:75], v[218:221], v[190:193], v[72:75]
	v_mfma_f32_16x16x32_bf16 v[68:71], v[210:213], v[202:205], v[68:71]
	v_mfma_f32_16x16x32_bf16 v[64:67], v[218:221], v[202:205], v[64:67]
	s_setprio 0
	s_mov_b32 m0, s39
	s_add_u32 s100, s34, s6
	s_addc_u32 s101, s35, s7
	s_barrier
	ds_read_b128 v[170:173], v162 offset:16384
	ds_read_b128 v[174:177], v162 offset:17408
	ds_read_b128 v[178:181], v162 offset:18432
	ds_read_b128 v[182:185], v162 offset:19456
	ds_read_b128 v[186:189], v162 offset:20480
	ds_read_b128 v[190:193], v162 offset:21504
	ds_read_b128 v[196:199], v162 offset:22528
	ds_read_b128 v[202:205], v162 offset:23552
	global_load_lds_dwordx4 v128, s[34:35]
	s_mov_b32 m0, s40
	s_nop 0
	global_load_lds_dwordx4 v132, s[34:35]
	s_setprio 1
	s_barrier
	s_waitcnt lgkmcnt(0)
	v_mfma_f32_16x16x32_bf16 v[60:63], v[148:151], v[170:173], v[60:63]
	v_mfma_f32_16x16x32_bf16 v[56:59], v[156:159], v[170:173], v[56:59]
	v_mfma_f32_16x16x32_bf16 v[52:55], v[148:151], v[178:181], v[52:55]
	v_mfma_f32_16x16x32_bf16 v[44:47], v[156:159], v[178:181], v[44:47]
	v_mfma_f32_16x16x32_bf16 v[36:39], v[148:151], v[186:189], v[36:39]
	v_mfma_f32_16x16x32_bf16 v[28:31], v[156:159], v[186:189], v[28:31]
	v_mfma_f32_16x16x32_bf16 v[20:23], v[148:151], v[196:199], v[20:23]
	v_mfma_f32_16x16x32_bf16 v[12:15], v[156:159], v[196:199], v[12:15]
	v_mfma_f32_16x16x32_bf16 v[60:63], v[152:155], v[174:177], v[60:63]
	v_mfma_f32_16x16x32_bf16 v[56:59], v[166:169], v[174:177], v[56:59]
	v_mfma_f32_16x16x32_bf16 v[52:55], v[152:155], v[182:185], v[52:55]
	v_mfma_f32_16x16x32_bf16 v[44:47], v[166:169], v[182:185], v[44:47]
	v_mfma_f32_16x16x32_bf16 v[36:39], v[152:155], v[190:193], v[36:39]
	v_mfma_f32_16x16x32_bf16 v[28:31], v[166:169], v[190:193], v[28:31]
	v_mfma_f32_16x16x32_bf16 v[20:23], v[152:155], v[202:205], v[20:23]
	v_mfma_f32_16x16x32_bf16 v[12:15], v[166:169], v[202:205], v[12:15]
	s_setprio 0
	s_barrier
	s_add_u32 s60, s30, 0x80000
	s_addc_u32 s61, s31, 0
	s_add_i32 s59, s47, s38
	s_mov_b32 m0, s59
	s_nop 0
	global_load_lds_dwordx4 v130, s[60:61]
	s_add_i32 m0, s59, 0x2000
	s_nop 0
	global_load_lds_dwordx4 v134, s[60:61]
	s_waitcnt vmcnt(6)
	s_setprio 1
	s_barrier
; #define PG8_STAGE(bufoff, gbase, voff) do { _Pragma("unroll") for (int _i = 0; _i < 2; ++_i) \
;         __builtin_amdgcn_global_load_lds((const unsigned*)((const char*)(gbase) + (voff)[_i]), (LAS unsigned*)(lds + (bufoff) + ldsw + _i * 8192), 16, 0, 0); } while (0)
; #define PG8_LDA(dst, b, h) do { _Pragma("unroll") for (int m = 0; m < 4; ++m) _Pragma("unroll") for (int k = 0; k < 2; ++k) dst[m][k] = *(const LAS bf16x8*)(lds + PG8_SA(b, h) + aoff + m * 2048 + k * 1024); } while (0)
; #define PG8_LDB(dst, b, h) do { _Pragma("unroll") for (int n = 0; n < 2; ++n) _Pragma("unroll") for (int k = 0; k < 2; ++k) dst[n][k] = *(const LAS bf16x8*)(lds + PG8_SB(b, h) + boff + n * 2048 + k * 1024); } while (0)
; #define PG8_WAIT_V(n) asm volatile("s_waitcnt vmcnt(" #n ")" ::: "memory")
; #define PG8_WAIT_L(n) asm volatile("s_waitcnt lgkmcnt(" #n ")" ::: "memory")
; #define PG8_BAR __builtin_amdgcn_s_barrier()
; #define PG8_SCHED __builtin_amdgcn_sched_barrier(0)
; template <class Epi>
; __device__ __forceinline__ void gemm_phase(LAS unsigned char* lds, const bf16_t* A, int lda, const bf16_t* Bt, int ldb, int M, int N, int K, int asel, const Epi& E, const int fixed_round = -1) {
;     ...
;             PG8_WAIT_V(6); PG8_BAR; PG8_MMA(1, 1, At, B1); PG8_BAR;
;             PG8_LDB(B0, 1, 0); PG8_SCHED; PG8_LDA(At, 1, 0); PG8_STAGE(PG8_SA(0, 1), a2 + hstepA, voffA);
;             PG8_WAIT_L(8); PG8_BAR; PG8_WAIT_L(0); PG8_MMA(0, 0, At, B0); PG8_BAR; PG8_SCHED;
;             PG8_LDB(B1, 1, 1); PG8_STAGE(PG8_SB(1, 0), b3, voffB);
;             PG8_BAR; PG8_WAIT_L(0); PG8_MMA(0, 1, At, B1); PG8_BAR;
;             PG8_LDA(At, 1, 1); PG8_STAGE(PG8_SA(1, 0), a3, voffA);
	v_mfma_f32_16x16x32_bf16 v[48:51], v[206:209], v[170:173], v[48:51]
	v_mfma_f32_16x16x32_bf16 v[40:43], v[214:217], v[170:173], v[40:43]
	v_mfma_f32_16x16x32_bf16 v[32:35], v[206:209], v[178:181], v[32:35]
	v_mfma_f32_16x16x32_bf16 v[24:27], v[214:217], v[178:181], v[24:27]
	v_mfma_f32_16x16x32_bf16 v[16:19], v[206:209], v[186:189], v[16:19]
	v_mfma_f32_16x16x32_bf16 v[8:11], v[214:217], v[186:189], v[8:11]
	v_mfma_f32_16x16x32_bf16 v[4:7], v[206:209], v[196:199], v[4:7]
	v_mfma_f32_16x16x32_bf16 v[0:3], v[214:217], v[196:199], v[0:3]
	v_mfma_f32_16x16x32_bf16 v[48:51], v[210:213], v[174:177], v[48:51]
	v_mfma_f32_16x16x32_bf16 v[40:43], v[218:221], v[174:177], v[40:43]
	v_mfma_f32_16x16x32_bf16 v[32:35], v[210:213], v[182:185], v[32:35]
	v_mfma_f32_16x16x32_bf16 v[24:27], v[218:221], v[182:185], v[24:27]
	v_mfma_f32_16x16x32_bf16 v[16:19], v[210:213], v[190:193], v[16:19]
	v_mfma_f32_16x16x32_bf16 v[8:11], v[218:221], v[190:193], v[8:11]
	v_mfma_f32_16x16x32_bf16 v[4:7], v[210:213], v[202:205], v[4:7]
	v_mfma_f32_16x16x32_bf16 v[0:3], v[218:221], v[202:205], v[0:3]
	s_setprio 0
	s_add_i32 s59, 0, 0x18000
	v_add_u32_e32 v136, s59, v160
	s_barrier
	ds_read_b128 v[148:151], v136
	ds_read_b128 v[152:155], v136 offset:1024
	ds_read_b128 v[156:159], v136 offset:2048
	ds_read_b128 v[166:169], v136 offset:3072
	s_add_u32 s34, s34, 0x80000
	s_addc_u32 s35, s35, 0
	s_mov_b32 m0, s41
	ds_read_b128 v[170:173], v162 offset:32768
	ds_read_b128 v[174:177], v162 offset:33792
	ds_read_b128 v[178:181], v162 offset:34816
	ds_read_b128 v[182:185], v162 offset:35840
	ds_read_b128 v[186:189], v162 offset:36864
	ds_read_b128 v[190:193], v162 offset:37888
	ds_read_b128 v[196:199], v162 offset:38912
	ds_read_b128 v[202:205], v162 offset:39936
	global_load_lds_dwordx4 v128, s[34:35]
	s_mov_b32 m0, s42
	s_nop 0
	global_load_lds_dwordx4 v132, s[34:35]
	s_waitcnt lgkmcnt(8)
	s_setprio 1
	s_barrier
	s_waitcnt lgkmcnt(0)
	v_mfma_f32_16x16x32_bf16 v[124:127], v[148:151], v[170:173], v[124:127]
	v_mfma_f32_16x16x32_bf16 v[120:123], v[156:159], v[170:173], v[120:123]
	v_mfma_f32_16x16x32_bf16 v[112:115], v[148:151], v[178:181], v[112:115]
	v_mfma_f32_16x16x32_bf16 v[108:111], v[156:159], v[178:181], v[108:111]
	v_mfma_f32_16x16x32_bf16 v[100:103], v[148:151], v[186:189], v[100:103]
	v_mfma_f32_16x16x32_bf16 v[92:95], v[156:159], v[186:189], v[92:95]
	v_mfma_f32_16x16x32_bf16 v[84:87], v[148:151], v[196:199], v[84:87]
	v_mfma_f32_16x16x32_bf16 v[76:79], v[156:159], v[196:199], v[76:79]
	v_mfma_f32_16x16x32_bf16 v[124:127], v[152:155], v[174:177], v[124:127]
	v_mfma_f32_16x16x32_bf16 v[120:123], v[166:169], v[174:177], v[120:123]
	v_mfma_f32_16x16x32_bf16 v[112:115], v[152:155], v[182:185], v[112:115]
	v_mfma_f32_16x16x32_bf16 v[108:111], v[166:169], v[182:185], v[108:111]
	v_mfma_f32_16x16x32_bf16 v[100:103], v[152:155], v[190:193], v[100:103]
	v_mfma_f32_16x16x32_bf16 v[92:95], v[166:169], v[190:193], v[92:95]
	v_mfma_f32_16x16x32_bf16 v[84:87], v[152:155], v[202:205], v[84:87]
	v_mfma_f32_16x16x32_bf16 v[76:79], v[166:169], v[202:205], v[76:79]
	s_setprio 0
	s_barrier
	s_add_i32 s34, 0, 0x1c000
	s_add_i32 s35, s59, s38
	v_add_u32_e32 v136, s34, v160
	s_mov_b32 m0, s35
	ds_read_b128 v[206:209], v136
	ds_read_b128 v[210:213], v136 offset:1024
	ds_read_b128 v[214:217], v136 offset:2048
	ds_read_b128 v[218:221], v136 offset:3072
	global_load_lds_dwordx4 v130, s[98:99]
	s_add_i32 m0, s35, 0x2000
	s_nop 0
	global_load_lds_dwordx4 v134, s[98:99]
	s_setprio 1
	s_barrier
	s_waitcnt lgkmcnt(0)
	v_mfma_f32_16x16x32_bf16 v[116:119], v[206:209], v[170:173], v[116:119]
	v_mfma_f32_16x16x32_bf16 v[104:107], v[214:217], v[170:173], v[104:107]
	v_mfma_f32_16x16x32_bf16 v[96:99], v[206:209], v[178:181], v[96:99]
	v_mfma_f32_16x16x32_bf16 v[88:91], v[214:217], v[178:181], v[88:91]
	v_mfma_f32_16x16x32_bf16 v[80:83], v[206:209], v[186:189], v[80:83]
	v_mfma_f32_16x16x32_bf16 v[72:75], v[214:217], v[186:189], v[72:75]
	v_mfma_f32_16x16x32_bf16 v[68:71], v[206:209], v[196:199], v[68:71]
	v_mfma_f32_16x16x32_bf16 v[64:67], v[214:217], v[196:199], v[64:67]
	v_mfma_f32_16x16x32_bf16 v[116:119], v[210:213], v[174:177], v[116:119]
	v_mfma_f32_16x16x32_bf16 v[104:107], v[218:221], v[174:177], v[104:107]
	v_mfma_f32_16x16x32_bf16 v[96:99], v[210:213], v[182:185], v[96:99]
	v_mfma_f32_16x16x32_bf16 v[88:91], v[218:221], v[182:185], v[88:91]
	v_mfma_f32_16x16x32_bf16 v[80:83], v[210:213], v[190:193], v[80:83]
	v_mfma_f32_16x16x32_bf16 v[72:75], v[218:221], v[190:193], v[72:75]
	v_mfma_f32_16x16x32_bf16 v[68:71], v[210:213], v[202:205], v[68:71]
	v_mfma_f32_16x16x32_bf16 v[64:67], v[218:221], v[202:205], v[64:67]
	s_setprio 0
	s_mov_b32 m0, s43
	s_barrier
	ds_read_b128 v[170:173], v162 offset:49152
	ds_read_b128 v[174:177], v162 offset:50176
	ds_read_b128 v[178:181], v162 offset:51200
	ds_read_b128 v[182:185], v162 offset:52224
	ds_read_b128 v[186:189], v162 offset:53248
	ds_read_b128 v[190:193], v162 offset:54272
	ds_read_b128 v[196:199], v162 offset:55296
	ds_read_b128 v[202:205], v162 offset:56320
	global_load_lds_dwordx4 v128, s[100:101]
	s_mov_b32 m0, s44
	s_nop 0
	global_load_lds_dwordx4 v132, s[100:101]
	s_setprio 1
	s_barrier
; __device__ __forceinline__ unsigned cvt_pk_bf16(float lo, float hi) { const bf16x2_t r = __builtin_convertvector((f32x2){lo, hi}, bf16x2_t); return __builtin_bit_cast(unsigned, r); }
; #define PG8_STAGE(bufoff, gbase, voff) do { _Pragma("unroll") for (int _i = 0; _i < 2; ++_i) \
;         __builtin_amdgcn_global_load_lds((const unsigned*)((const char*)(gbase) + (voff)[_i]), (LAS unsigned*)(lds + (bufoff) + ldsw + _i * 8192), 16, 0, 0); } while (0)
; #define PG8_WAIT_V(n) asm volatile("s_waitcnt vmcnt(" #n ")" ::: "memory")
; #define PG8_WAIT_L(n) asm volatile("s_waitcnt lgkmcnt(" #n ")" ::: "memory")
; #define PG8_BAR __builtin_amdgcn_s_barrier()
; #define PG8_SCHED __builtin_amdgcn_sched_barrier(0)
; template <class Epi>
; __device__ __forceinline__ void gemm_phase(LAS unsigned char* lds, const bf16_t* A, int lda, const bf16_t* Bt, int ldb, int M, int N, int K, int asel, const Epi& E, const int fixed_round = -1) {
;     ...
;             PG8_BAR; PG8_WAIT_L(0); PG8_MMA(1, 0, At, B0); PG8_BAR; PG8_SCHED;
;             PG8_STAGE(PG8_SB(1, 1), b3 + hstepB, voffB);
;             PG8_WAIT_V(6); PG8_BAR; PG8_MMA(1, 1, At, B1); PG8_BAR;
;     __device__ __forceinline__ void operator()(const AccT& acc, const Unit& u, int wr, int wc, int fr, int fq) const {
;     ...
;         if (pn < 8) {
;             bf16_t* base = pn < 4 ? Q : Kn; const int colt = (pn & 3) * BM; const float sc = pn < 4 ? 0.08838834764831845f : 1.0f;
; #pragma unroll
;             for (int ai = 0; ai < 2; ++ai)
; #pragma unroll
;                 for (int m = 0; m < 4; ++m) { bf16_t* rowp = base + (size_t)(row0 + ai * HALF + m * 16) * 1024 + colt + cl;
; #pragma unroll
;                     for (int bj = 0; bj < 2; ++bj) { const f32x4 v0 = acc[ai][bj][m][0] * sc, v1 = acc[ai][bj][m][1] * sc;
;                         u32x4 w; w.x = cvt_pk_bf16(v0[0], v0[1]); w.y = cvt_pk_bf16(v0[2], v0[3]); w.z = cvt_pk_bf16(v1[0], v1[1]); w.w = cvt_pk_bf16(v1[2], v1[3]);
;                         *(u32x4*)(rowp + bj * HALF) = w; } }
	s_waitcnt lgkmcnt(0)
	v_mfma_f32_16x16x32_bf16 v[60:63], v[148:151], v[170:173], v[60:63]
	v_mfma_f32_16x16x32_bf16 v[56:59], v[156:159], v[170:173], v[56:59]
	v_mfma_f32_16x16x32_bf16 v[52:55], v[148:151], v[178:181], v[52:55]
	v_mfma_f32_16x16x32_bf16 v[44:47], v[156:159], v[178:181], v[44:47]
	v_mfma_f32_16x16x32_bf16 v[36:39], v[148:151], v[186:189], v[36:39]
	v_mfma_f32_16x16x32_bf16 v[28:31], v[156:159], v[186:189], v[28:31]
	v_mfma_f32_16x16x32_bf16 v[20:23], v[148:151], v[196:199], v[20:23]
	v_mfma_f32_16x16x32_bf16 v[12:15], v[156:159], v[196:199], v[12:15]
	v_mfma_f32_16x16x32_bf16 v[60:63], v[152:155], v[174:177], v[60:63]
	v_mfma_f32_16x16x32_bf16 v[56:59], v[166:169], v[174:177], v[56:59]
	v_mfma_f32_16x16x32_bf16 v[52:55], v[152:155], v[182:185], v[52:55]
	v_mfma_f32_16x16x32_bf16 v[44:47], v[166:169], v[182:185], v[44:47]
	v_mfma_f32_16x16x32_bf16 v[36:39], v[152:155], v[190:193], v[36:39]
	v_mfma_f32_16x16x32_bf16 v[28:31], v[166:169], v[190:193], v[28:31]
	v_mfma_f32_16x16x32_bf16 v[20:23], v[152:155], v[202:205], v[20:23]
	v_mfma_f32_16x16x32_bf16 v[12:15], v[166:169], v[202:205], v[12:15]
	s_setprio 0
	s_barrier
	s_add_u32 s30, s30, 0x80080
	s_addc_u32 s31, s31, 0
	s_add_i32 s34, s34, s38
	s_mov_b32 m0, s34
	s_nop 0
	global_load_lds_dwordx4 v130, s[30:31]
	s_add_i32 m0, s34, 0x2000
	s_nop 0
	global_load_lds_dwordx4 v134, s[30:31]
	s_waitcnt vmcnt(6)
	s_setprio 1
	s_barrier
	v_mfma_f32_16x16x32_bf16 v[48:51], v[206:209], v[170:173], v[48:51]
	v_mfma_f32_16x16x32_bf16 v[40:43], v[214:217], v[170:173], v[40:43]
	v_mfma_f32_16x16x32_bf16 v[32:35], v[206:209], v[178:181], v[32:35]
	v_mfma_f32_16x16x32_bf16 v[24:27], v[214:217], v[178:181], v[24:27]
	v_mfma_f32_16x16x32_bf16 v[16:19], v[206:209], v[186:189], v[16:19]
	v_mfma_f32_16x16x32_bf16 v[8:11], v[214:217], v[186:189], v[8:11]
	v_mfma_f32_16x16x32_bf16 v[4:7], v[206:209], v[196:199], v[4:7]
	v_mfma_f32_16x16x32_bf16 v[0:3], v[214:217], v[196:199], v[0:3]
	v_mfma_f32_16x16x32_bf16 v[48:51], v[210:213], v[174:177], v[48:51]
	v_mfma_f32_16x16x32_bf16 v[40:43], v[218:221], v[174:177], v[40:43]
	v_mfma_f32_16x16x32_bf16 v[32:35], v[210:213], v[182:185], v[32:35]
	v_mfma_f32_16x16x32_bf16 v[24:27], v[218:221], v[182:185], v[24:27]
	v_mfma_f32_16x16x32_bf16 v[16:19], v[210:213], v[190:193], v[16:19]
	v_mfma_f32_16x16x32_bf16 v[8:11], v[218:221], v[190:193], v[8:11]
	v_mfma_f32_16x16x32_bf16 v[4:7], v[210:213], v[202:205], v[4:7]
	v_mfma_f32_16x16x32_bf16 v[0:3], v[218:221], v[202:205], v[0:3]
	s_setprio 0
	s_add_i32 s58, s58, 2
	s_add_u32 s28, s28, 0x100
	s_addc_u32 s29, s29, 0
	s_add_u32 s56, s56, 0x100
	s_addc_u32 s57, s57, 0
	s_cmp_gt_u32 s58, 29
	s_cbranch_scc0 .Lrot_1
	s_barrier
	s_lshl_b32 s19, s26, 8
	v_add_u32_e32 v154, s19, v139
	s_cmp_lt_i32 s27, 8
	v_or_b32_e32 v152, 16, v154
	v_or_b32_e32 v150, 32, v154
	v_or_b32_e32 v148, 48, v154
	s_cselect_b64 s[28:29], -1, 0
	s_cmp_gt_i32 s27, 7
	v_ashrrev_i32_e32 v155, 31, v154
	v_lshlrev_b32_e32 v136, 1, v138
	v_ashrrev_i32_e32 v153, 31, v152
	v_ashrrev_i32_e32 v151, 31, v150
	v_ashrrev_i32_e32 v149, 31, v148
	s_cbranch_scc1 .LBB0_203
	s_cmp_lt_i32 s27, 4
	s_cselect_b64 vcc, -1, 0
	s_and_b64 s[30:31], vcc, exec
	s_cselect_b32 s4, s89, s81
	s_cselect_b32 s21, s88, s91
	s_lshl_b32 s30, s27, 9
	s_and_b32 s30, s30, 0x600
	s_add_u32 s30, s21, s30
	v_cndmask_b32_e32 v156, 1.0, v164, vcc
	s_addc_u32 s31, s4, 0
	v_lshl_add_u64 v[170:171], s[30:31], 0, v[136:137]
	v_lshlrev_b64 v[158:159], 11, v[154:155]
	v_pk_mul_f32 v[168:169], v[156:157], v[126:127] op_sel_hi:[0,1]
	v_pk_mul_f32 v[166:167], v[156:157], v[124:125] op_sel_hi:[0,1]
	v_pk_mul_f32 v[172:173], v[156:157], v[122:123] op_sel_hi:[0,1]
	v_pk_mul_f32 v[174:175], v[156:157], v[120:121] op_sel_hi:[0,1]
	v_lshl_add_u64 v[158:159], v[170:171], 0, v[158:159]
	v_cvt_pk_bf16_f32 v166, v166, v167
	v_cvt_pk_bf16_f32 v167, v168, v169
	v_cvt_pk_bf16_f32 v168, v174, v175
	v_cvt_pk_bf16_f32 v169, v172, v173
	global_store_dwordx4 v[158:159], v[166:169], off
	v_pk_mul_f32 v[172:173], v[156:157], v[106:107] op_sel_hi:[0,1]
	v_pk_mul_f32 v[174:175], v[156:157], v[104:105] op_sel_hi:[0,1]
	v_pk_mul_f32 v[168:169], v[156:157], v[118:119] op_sel_hi:[0,1]
	v_pk_mul_f32 v[166:167], v[156:157], v[116:117] op_sel_hi:[0,1]
	v_cvt_pk_bf16_f32 v166, v166, v167
	v_cvt_pk_bf16_f32 v167, v168, v169
	v_cvt_pk_bf16_f32 v168, v174, v175
	v_cvt_pk_bf16_f32 v169, v172, v173
	global_store_dwordx4 v[158:159], v[166:169], off offset:256
	v_pk_mul_f32 v[174:175], v[156:157], v[110:111] op_sel_hi:[0,1]
	v_pk_mul_f32 v[176:177], v[156:157], v[108:109] op_sel_hi:[0,1]
	v_lshlrev_b64 v[166:167], 11, v[152:153]
	v_lshl_add_u64 v[172:173], v[170:171], 0, v[166:167]
	v_pk_mul_f32 v[168:169], v[156:157], v[114:115] op_sel_hi:[0,1]
	v_pk_mul_f32 v[166:167], v[156:157], v[112:113] op_sel_hi:[0,1]
	v_cvt_pk_bf16_f32 v166, v166, v167
	v_cvt_pk_bf16_f32 v167, v168, v169
	v_cvt_pk_bf16_f32 v168, v176, v177
	v_cvt_pk_bf16_f32 v169, v174, v175
	global_store_dwordx4 v[172:173], v[166:169], off
	v_pk_mul_f32 v[174:175], v[156:157], v[90:91] op_sel_hi:[0,1]
	v_pk_mul_f32 v[176:177], v[156:157], v[88:89] op_sel_hi:[0,1]
	v_pk_mul_f32 v[168:169], v[156:157], v[98:99] op_sel_hi:[0,1]
	v_pk_mul_f32 v[166:167], v[156:157], v[96:97] op_sel_hi:[0,1]
	v_cvt_pk_bf16_f32 v166, v166, v167
	v_cvt_pk_bf16_f32 v167, v168, v169
	v_cvt_pk_bf16_f32 v168, v176, v177
	v_cvt_pk_bf16_f32 v169, v174, v175
	global_store_dwordx4 v[172:173], v[166:169], off offset:256
	v_pk_mul_f32 v[174:175], v[156:157], v[94:95] op_sel_hi:[0,1]
	v_pk_mul_f32 v[176:177], v[156:157], v[92:93] op_sel_hi:[0,1]
	v_lshlrev_b64 v[166:167], 11, v[150:151]
; __device__ __forceinline__ unsigned cvt_pk_bf16(float lo, float hi) { const bf16x2_t r = __builtin_convertvector((f32x2){lo, hi}, bf16x2_t); return __builtin_bit_cast(unsigned, r); }
;     __device__ __forceinline__ void operator()(const AccT& acc, const Unit& u, int wr, int wc, int fr, int fq) const {
;     ...
;         if (pn < 8) {
;             bf16_t* base = pn < 4 ? Q : Kn; const int colt = (pn & 3) * BM; const float sc = pn < 4 ? 0.08838834764831845f : 1.0f;
; #pragma unroll
;             for (int ai = 0; ai < 2; ++ai)
; #pragma unroll
;                 for (int m = 0; m < 4; ++m) { bf16_t* rowp = base + (size_t)(row0 + ai * HALF + m * 16) * 1024 + colt + cl;
; #pragma unroll
;                     for (int bj = 0; bj < 2; ++bj) { const f32x4 v0 = acc[ai][bj][m][0] * sc, v1 = acc[ai][bj][m][1] * sc;
;                         u32x4 w; w.x = cvt_pk_bf16(v0[0], v0[1]); w.y = cvt_pk_bf16(v0[2], v0[3]); w.z = cvt_pk_bf16(v1[0], v1[1]); w.w = cvt_pk_bf16(v1[2], v1[3]);
;                         *(u32x4*)(rowp + bj * HALF) = w; } }
;         }
;         if (pn >= 16) {
	v_lshl_add_u64 v[172:173], v[170:171], 0, v[166:167]
	v_pk_mul_f32 v[168:169], v[156:157], v[102:103] op_sel_hi:[0,1]
	v_pk_mul_f32 v[166:167], v[156:157], v[100:101] op_sel_hi:[0,1]
	v_cvt_pk_bf16_f32 v166, v166, v167
	v_cvt_pk_bf16_f32 v167, v168, v169
	v_cvt_pk_bf16_f32 v168, v176, v177
	v_cvt_pk_bf16_f32 v169, v174, v175
	global_store_dwordx4 v[172:173], v[166:169], off
	v_pk_mul_f32 v[174:175], v[156:157], v[74:75] op_sel_hi:[0,1]
	v_pk_mul_f32 v[176:177], v[156:157], v[72:73] op_sel_hi:[0,1]
	v_pk_mul_f32 v[168:169], v[156:157], v[82:83] op_sel_hi:[0,1]
	v_pk_mul_f32 v[166:167], v[156:157], v[80:81] op_sel_hi:[0,1]
	v_cvt_pk_bf16_f32 v166, v166, v167
	v_cvt_pk_bf16_f32 v167, v168, v169
	v_cvt_pk_bf16_f32 v168, v176, v177
	v_cvt_pk_bf16_f32 v169, v174, v175
	global_store_dwordx4 v[172:173], v[166:169], off offset:256
	v_pk_mul_f32 v[172:173], v[156:157], v[78:79] op_sel_hi:[0,1]
	v_pk_mul_f32 v[174:175], v[156:157], v[76:77] op_sel_hi:[0,1]
	v_lshlrev_b64 v[166:167], 11, v[148:149]
	v_lshl_add_u64 v[170:171], v[170:171], 0, v[166:167]
	v_pk_mul_f32 v[168:169], v[156:157], v[86:87] op_sel_hi:[0,1]
	v_pk_mul_f32 v[166:167], v[156:157], v[84:85] op_sel_hi:[0,1]
	v_cvt_pk_bf16_f32 v166, v166, v167
	v_cvt_pk_bf16_f32 v167, v168, v169
	v_cvt_pk_bf16_f32 v168, v174, v175
	v_cvt_pk_bf16_f32 v169, v172, v173
	global_store_dwordx4 v[170:171], v[166:169], off
	v_pk_mul_f32 v[172:173], v[156:157], v[66:67] op_sel_hi:[0,1]
	v_pk_mul_f32 v[174:175], v[156:157], v[64:65] op_sel_hi:[0,1]
	v_pk_mul_f32 v[168:169], v[156:157], v[70:71] op_sel_hi:[0,1]
	v_pk_mul_f32 v[166:167], v[156:157], v[68:69] op_sel_hi:[0,1]
	v_cvt_pk_bf16_f32 v166, v166, v167
	v_cvt_pk_bf16_f32 v167, v168, v169
	v_cvt_pk_bf16_f32 v168, v174, v175
	v_cvt_pk_bf16_f32 v169, v172, v173
	global_store_dwordx4 v[170:171], v[166:169], off offset:256
	v_pk_mul_f32 v[172:173], v[156:157], v[58:59] op_sel_hi:[0,1]
	s_mov_b32 s4, 0x40000
	v_pk_mul_f32 v[168:169], v[156:157], v[62:63] op_sel_hi:[0,1]
	v_pk_mul_f32 v[166:167], v[156:157], v[60:61] op_sel_hi:[0,1]
	v_pk_mul_f32 v[174:175], v[156:157], v[56:57] op_sel_hi:[0,1]
	v_cvt_pk_bf16_f32 v166, v166, v167
	v_cvt_pk_bf16_f32 v167, v168, v169
	v_cvt_pk_bf16_f32 v169, v172, v173
	v_add_co_u32_e32 v172, vcc, s4, v158
	v_cvt_pk_bf16_f32 v168, v174, v175
	s_nop 0
	v_addc_co_u32_e32 v173, vcc, 0, v159, vcc
	s_mov_b64 s[30:31], 0x40000
	global_store_dwordx4 v[172:173], v[166:169], off
	v_pk_mul_f32 v[172:173], v[156:157], v[42:43] op_sel_hi:[0,1]
	v_pk_mul_f32 v[174:175], v[156:157], v[40:41] op_sel_hi:[0,1]
	v_pk_mul_f32 v[168:169], v[156:157], v[50:51] op_sel_hi:[0,1]
	v_pk_mul_f32 v[166:167], v[156:157], v[48:49] op_sel_hi:[0,1]
	v_lshl_add_u64 v[170:171], v[158:159], 0, s[30:31]
	v_cvt_pk_bf16_f32 v166, v166, v167
	v_cvt_pk_bf16_f32 v167, v168, v169
	v_cvt_pk_bf16_f32 v168, v174, v175
	v_cvt_pk_bf16_f32 v169, v172, v173
	global_store_dwordx4 v[170:171], v[166:169], off offset:256
	v_pk_mul_f32 v[172:173], v[156:157], v[46:47] op_sel_hi:[0,1]
	s_mov_b32 s4, 0x48000
	v_pk_mul_f32 v[168:169], v[156:157], v[54:55] op_sel_hi:[0,1]
	v_pk_mul_f32 v[166:167], v[156:157], v[52:53] op_sel_hi:[0,1]
	v_pk_mul_f32 v[174:175], v[156:157], v[44:45] op_sel_hi:[0,1]
	v_cvt_pk_bf16_f32 v166, v166, v167
	v_cvt_pk_bf16_f32 v167, v168, v169
	v_cvt_pk_bf16_f32 v169, v172, v173
	v_add_co_u32_e32 v172, vcc, s4, v158
	v_cvt_pk_bf16_f32 v168, v174, v175
	s_nop 0
	v_addc_co_u32_e32 v173, vcc, 0, v159, vcc
	s_mov_b64 s[30:31], 0x48000
	global_store_dwordx4 v[172:173], v[166:169], off
	v_pk_mul_f32 v[172:173], v[156:157], v[26:27] op_sel_hi:[0,1]
	v_pk_mul_f32 v[174:175], v[156:157], v[24:25] op_sel_hi:[0,1]
	v_pk_mul_f32 v[168:169], v[156:157], v[34:35] op_sel_hi:[0,1]
	v_pk_mul_f32 v[166:167], v[156:157], v[32:33] op_sel_hi:[0,1]
	v_lshl_add_u64 v[170:171], v[158:159], 0, s[30:31]
	v_cvt_pk_bf16_f32 v166, v166, v167
	v_cvt_pk_bf16_f32 v167, v168, v169
	v_cvt_pk_bf16_f32 v168, v174, v175
	v_cvt_pk_bf16_f32 v169, v172, v173
	global_store_dwordx4 v[170:171], v[166:169], off offset:256
	v_pk_mul_f32 v[172:173], v[156:157], v[30:31] op_sel_hi:[0,1]
	v_pk_mul_f32 v[174:175], v[156:157], v[28:29] op_sel_hi:[0,1]
	v_pk_mul_f32 v[168:169], v[156:157], v[38:39] op_sel_hi:[0,1]
	v_pk_mul_f32 v[166:167], v[156:157], v[36:37] op_sel_hi:[0,1]
	v_cvt_pk_bf16_f32 v166, v166, v167
	v_cvt_pk_bf16_f32 v167, v168, v169
	v_cvt_pk_bf16_f32 v169, v172, v173
	v_add_co_u32_e32 v172, vcc, s48, v158
	v_cvt_pk_bf16_f32 v168, v174, v175
	s_nop 0
	v_addc_co_u32_e32 v173, vcc, 0, v159, vcc
	global_store_dwordx4 v[172:173], v[166:169], off
	v_pk_mul_f32 v[172:173], v[156:157], v[10:11] op_sel_hi:[0,1]
	v_pk_mul_f32 v[174:175], v[156:157], v[8:9] op_sel_hi:[0,1]
	v_pk_mul_f32 v[168:169], v[156:157], v[18:19] op_sel_hi:[0,1]
	v_pk_mul_f32 v[166:167], v[156:157], v[16:17] op_sel_hi:[0,1]
	v_lshl_add_u64 v[170:171], v[158:159], 0, s[8:9]
	v_cvt_pk_bf16_f32 v166, v166, v167
	v_cvt_pk_bf16_f32 v167, v168, v169
	v_cvt_pk_bf16_f32 v168, v174, v175
	v_cvt_pk_bf16_f32 v169, v172, v173
	global_store_dwordx4 v[170:171], v[166:169], off offset:256
	v_lshl_add_u64 v[170:171], v[158:159], 0, s[10:11]
	v_pk_mul_f32 v[172:173], v[156:157], v[14:15] op_sel_hi:[0,1]
	v_pk_mul_f32 v[168:169], v[156:157], v[22:23] op_sel_hi:[0,1]
	v_pk_mul_f32 v[166:167], v[156:157], v[20:21] op_sel_hi:[0,1]
	v_pk_mul_f32 v[174:175], v[156:157], v[12:13] op_sel_hi:[0,1]
	v_add_co_u32_e32 v158, vcc, s49, v158
	v_cvt_pk_bf16_f32 v166, v166, v167
	v_cvt_pk_bf16_f32 v167, v168, v169
	v_cvt_pk_bf16_f32 v168, v174, v175
	v_cvt_pk_bf16_f32 v169, v172, v173
	v_addc_co_u32_e32 v159, vcc, 0, v159, vcc
	global_store_dwordx4 v[158:159], v[166:169], off
	v_pk_mul_f32 v[158:159], v[156:157], v[6:7] op_sel_hi:[0,1]
	v_pk_mul_f32 v[172:173], v[156:157], v[0:1] op_sel_hi:[0,1]
	v_pk_mul_f32 v[166:167], v[156:157], v[4:5] op_sel_hi:[0,1]
	v_pk_mul_f32 v[168:169], v[156:157], v[2:3] op_sel_hi:[0,1]
	v_cvt_pk_bf16_f32 v156, v166, v167
	v_cvt_pk_bf16_f32 v157, v158, v159
	v_cvt_pk_bf16_f32 v158, v172, v173
	v_cvt_pk_bf16_f32 v159, v168, v169
	global_store_dwordx4 v[170:171], v[156:159], off offset:256
	s_cmp_lt_i32 s27, 16
	s_cbranch_scc0 .LBB0_204

; #define PG8_STAGE(bufoff, gbase, voff) do { _Pragma("unroll") for (int _i = 0; _i < 2; ++_i) \
;         __builtin_amdgcn_global_load_lds((const unsigned*)((const char*)(gbase) + (voff)[_i]), (LAS unsigned*)(lds + (bufoff) + ldsw + _i * 8192), 16, 0, 0); } while (0)
; #define PG8_LDA(dst, b, h) do { _Pragma("unroll") for (int m = 0; m < 4; ++m) _Pragma("unroll") for (int k = 0; k < 2; ++k) dst[m][k] = *(const LAS bf16x8*)(lds + PG8_SA(b, h) + aoff + m * 2048 + k * 1024); } while (0)
; #define PG8_LDB(dst, b, h) do { _Pragma("unroll") for (int n = 0; n < 2; ++n) _Pragma("unroll") for (int k = 0; k < 2; ++k) dst[n][k] = *(const LAS bf16x8*)(lds + PG8_SB(b, h) + boff + n * 2048 + k * 1024); } while (0)
; #define PG8_WAIT_V(n) asm volatile("s_waitcnt vmcnt(" #n ")" ::: "memory")
; #define PG8_WAIT_L(n) asm volatile("s_waitcnt lgkmcnt(" #n ")" ::: "memory")
; #define PG8_BAR __builtin_amdgcn_s_barrier()
; #define PG8_SCHED __builtin_amdgcn_sched_barrier(0)
; template <class Epi>
; __device__ __forceinline__ void gemm_phase(LAS unsigned char* lds, const bf16_t* A, int lda, const bf16_t* Bt, int ldb, int M, int N, int K, int asel, const Epi& E, const int fixed_round = -1) {
;     ...
;             const char* a1 = cA + (size_t)(t + 1) * kstep;
;             const char* a2 = last ? nA : cA + (size_t)(t + 2) * kstep; const char* b2 = last ? nB : cB + (size_t)(t + 2) * kstep;
;             const char* a3 = a2 + kstep; const char* b3 = b2 + kstep;
;             PG8_LDB(B0, 0, 0); PG8_SCHED; PG8_LDA(At, 0, 0); PG8_STAGE(PG8_SA(1, 1), a1 + hstepA, voffA);
;             PG8_WAIT_L(8); PG8_BAR; PG8_WAIT_L(0); PG8_MMA(0, 0, At, B0); PG8_BAR; PG8_SCHED;
;             PG8_LDB(B1, 0, 1); PG8_STAGE(PG8_SB(0, 0), b2, voffB);
;             PG8_BAR; PG8_WAIT_L(0); PG8_MMA(0, 1, At, B1); PG8_BAR;
;             PG8_LDA(At, 0, 1); PG8_STAGE(PG8_SA(0, 0), a2, voffA);
;             PG8_BAR; PG8_WAIT_L(0); PG8_MMA(1, 0, At, B0); PG8_BAR; PG8_SCHED;
;             PG8_STAGE(PG8_SB(0, 1), b2 + hstepB, voffB);
;             PG8_WAIT_V(6); PG8_BAR; PG8_MMA(1, 1, At, B1); PG8_BAR;
.LBB0_224:
	ds_read_b128 v[146:149], v143
	ds_read_b128 v[150:153], v143 offset:1024
	ds_read_b128 v[154:157], v143 offset:2048
	ds_read_b128 v[158:161], v143 offset:3072
	s_add_i32 m0, s7, 0xc000
	ds_read_b128 v[162:165], v144
	ds_read_b128 v[166:169], v144 offset:1024
	ds_read_b128 v[170:173], v144 offset:2048
	ds_read_b128 v[174:177], v144 offset:3072
	ds_read_b128 v[178:181], v144 offset:4096
	ds_read_b128 v[182:185], v144 offset:5120
	ds_read_b128 v[186:189], v144 offset:6144
	ds_read_b128 v[190:193], v144 offset:7168
	global_load_lds_dwordx4 v132, s[16:17]
	s_add_i32 m0, s7, 0xe000
	s_nop 0
	global_load_lds_dwordx4 v134, s[16:17]
	s_waitcnt lgkmcnt(8)
	s_setprio 1
	s_barrier
	s_waitcnt lgkmcnt(0)
	v_mfma_f32_16x16x32_bf16 v[124:127], v[162:165], v[146:149], v[124:127]
	v_mfma_f32_16x16x32_bf16 v[108:111], v[162:165], v[154:157], v[108:111]
	v_mfma_f32_16x16x32_bf16 v[120:123], v[170:173], v[146:149], v[120:123]
	v_mfma_f32_16x16x32_bf16 v[104:107], v[170:173], v[154:157], v[104:107]
	v_mfma_f32_16x16x32_bf16 v[116:119], v[178:181], v[146:149], v[116:119]
	v_mfma_f32_16x16x32_bf16 v[100:103], v[178:181], v[154:157], v[100:103]
	v_mfma_f32_16x16x32_bf16 v[112:115], v[186:189], v[146:149], v[112:115]
	v_mfma_f32_16x16x32_bf16 v[92:95], v[186:189], v[154:157], v[92:95]
	v_mfma_f32_16x16x32_bf16 v[124:127], v[166:169], v[150:153], v[124:127]
	v_mfma_f32_16x16x32_bf16 v[108:111], v[166:169], v[158:161], v[108:111]
	v_mfma_f32_16x16x32_bf16 v[120:123], v[174:177], v[150:153], v[120:123]
	v_mfma_f32_16x16x32_bf16 v[104:107], v[174:177], v[158:161], v[104:107]
	v_mfma_f32_16x16x32_bf16 v[116:119], v[182:185], v[150:153], v[116:119]
	v_mfma_f32_16x16x32_bf16 v[100:103], v[182:185], v[158:161], v[100:103]
	v_mfma_f32_16x16x32_bf16 v[112:115], v[190:193], v[150:153], v[112:115]
	v_mfma_f32_16x16x32_bf16 v[92:95], v[190:193], v[158:161], v[92:95]
	s_setprio 0
	s_barrier
	s_add_u32 s18, s16, 0xfff80080
	s_addc_u32 s19, s17, -1
	s_cmp_eq_u32 s41, 28
	s_cselect_b32 s21, s11, s19
	s_cselect_b32 s20, s37, s18
	s_cselect_b32 s19, s9, s40
	s_cselect_b32 s18, s38, s39
	s_add_i32 s42, s34, s25
	s_add_u32 s98, s18, s2
	s_addc_u32 s99, s19, s3
	s_mov_b32 m0, s42
	ds_read_b128 v[196:199], v145
	ds_read_b128 v[202:205], v145 offset:1024
	ds_read_b128 v[206:209], v145 offset:2048
	ds_read_b128 v[210:213], v145 offset:3072
	global_load_lds_dwordx4 v128, s[18:19]
	s_add_i32 m0, s42, 0x2000
	s_nop 0
	global_load_lds_dwordx4 v130, s[18:19]
	s_setprio 1
	s_barrier
	s_waitcnt lgkmcnt(0)
	v_mfma_f32_16x16x32_bf16 v[80:83], v[162:165], v[196:199], v[80:83]
	v_mfma_f32_16x16x32_bf16 v[48:51], v[162:165], v[206:209], v[48:51]
	v_mfma_f32_16x16x32_bf16 v[68:71], v[170:173], v[196:199], v[68:71]
	v_mfma_f32_16x16x32_bf16 v[40:43], v[170:173], v[206:209], v[40:43]
	v_mfma_f32_16x16x32_bf16 v[60:63], v[178:181], v[196:199], v[60:63]
	v_mfma_f32_16x16x32_bf16 v[36:39], v[178:181], v[206:209], v[36:39]
	v_mfma_f32_16x16x32_bf16 v[52:55], v[186:189], v[196:199], v[52:55]
	v_mfma_f32_16x16x32_bf16 v[28:31], v[186:189], v[206:209], v[28:31]
	v_mfma_f32_16x16x32_bf16 v[80:83], v[166:169], v[202:205], v[80:83]
	v_mfma_f32_16x16x32_bf16 v[48:51], v[166:169], v[210:213], v[48:51]
	v_mfma_f32_16x16x32_bf16 v[68:71], v[174:177], v[202:205], v[68:71]
	v_mfma_f32_16x16x32_bf16 v[40:43], v[174:177], v[210:213], v[40:43]
	v_mfma_f32_16x16x32_bf16 v[60:63], v[182:185], v[202:205], v[60:63]
	v_mfma_f32_16x16x32_bf16 v[36:39], v[182:185], v[210:213], v[36:39]
	v_mfma_f32_16x16x32_bf16 v[52:55], v[190:193], v[202:205], v[52:55]
	v_mfma_f32_16x16x32_bf16 v[28:31], v[190:193], v[210:213], v[28:31]
	s_setprio 0
	s_mov_b32 m0, s7
	s_add_u32 s100, s20, s2
	s_addc_u32 s101, s21, s3
	s_barrier
	ds_read_b128 v[162:165], v144 offset:16384
	ds_read_b128 v[166:169], v144 offset:17408
	ds_read_b128 v[170:173], v144 offset:18432
	ds_read_b128 v[174:177], v144 offset:19456
	ds_read_b128 v[178:181], v144 offset:20480
	ds_read_b128 v[182:185], v144 offset:21504
	ds_read_b128 v[186:189], v144 offset:22528
	ds_read_b128 v[190:193], v144 offset:23552
	global_load_lds_dwordx4 v128, s[20:21]
	s_mov_b32 m0, s26
	s_nop 0
	global_load_lds_dwordx4 v130, s[20:21]
	s_setprio 1
	s_barrier
	s_waitcnt lgkmcnt(0)
	v_mfma_f32_16x16x32_bf16 v[96:99], v[162:165], v[146:149], v[96:99]
	v_mfma_f32_16x16x32_bf16 v[72:75], v[162:165], v[154:157], v[72:75]
	v_mfma_f32_16x16x32_bf16 v[88:91], v[170:173], v[146:149], v[88:91]
	v_mfma_f32_16x16x32_bf16 v[64:67], v[170:173], v[154:157], v[64:67]
	v_mfma_f32_16x16x32_bf16 v[84:87], v[178:181], v[146:149], v[84:87]
	v_mfma_f32_16x16x32_bf16 v[56:59], v[178:181], v[154:157], v[56:59]
	v_mfma_f32_16x16x32_bf16 v[76:79], v[186:189], v[146:149], v[76:79]
	v_mfma_f32_16x16x32_bf16 v[44:47], v[186:189], v[154:157], v[44:47]
	v_mfma_f32_16x16x32_bf16 v[96:99], v[166:169], v[150:153], v[96:99]
	v_mfma_f32_16x16x32_bf16 v[72:75], v[166:169], v[158:161], v[72:75]
	v_mfma_f32_16x16x32_bf16 v[88:91], v[174:177], v[150:153], v[88:91]
	v_mfma_f32_16x16x32_bf16 v[64:67], v[174:177], v[158:161], v[64:67]
	v_mfma_f32_16x16x32_bf16 v[84:87], v[182:185], v[150:153], v[84:87]
	v_mfma_f32_16x16x32_bf16 v[56:59], v[182:185], v[158:161], v[56:59]
	v_mfma_f32_16x16x32_bf16 v[76:79], v[190:193], v[150:153], v[76:79]
	v_mfma_f32_16x16x32_bf16 v[44:47], v[190:193], v[158:161], v[44:47]
	s_setprio 0
	s_barrier
	s_add_u32 s42, s18, 0x80000
	s_addc_u32 s43, s19, 0
	s_add_i32 s44, s35, s25
	s_mov_b32 m0, s44
	s_nop 0
	global_load_lds_dwordx4 v128, s[42:43]
	s_add_i32 m0, s44, 0x2000
	s_nop 0
	global_load_lds_dwordx4 v130, s[42:43]
	s_waitcnt vmcnt(6)
	s_setprio 1
	s_barrier
; #define PG8_STAGE(bufoff, gbase, voff) do { _Pragma("unroll") for (int _i = 0; _i < 2; ++_i) \
;         __builtin_amdgcn_global_load_lds((const unsigned*)((const char*)(gbase) + (voff)[_i]), (LAS unsigned*)(lds + (bufoff) + ldsw + _i * 8192), 16, 0, 0); } while (0)
; #define PG8_LDA(dst, b, h) do { _Pragma("unroll") for (int m = 0; m < 4; ++m) _Pragma("unroll") for (int k = 0; k < 2; ++k) dst[m][k] = *(const LAS bf16x8*)(lds + PG8_SA(b, h) + aoff + m * 2048 + k * 1024); } while (0)
; #define PG8_LDB(dst, b, h) do { _Pragma("unroll") for (int n = 0; n < 2; ++n) _Pragma("unroll") for (int k = 0; k < 2; ++k) dst[n][k] = *(const LAS bf16x8*)(lds + PG8_SB(b, h) + boff + n * 2048 + k * 1024); } while (0)
; #define PG8_WAIT_V(n) asm volatile("s_waitcnt vmcnt(" #n ")" ::: "memory")
; #define PG8_WAIT_L(n) asm volatile("s_waitcnt lgkmcnt(" #n ")" ::: "memory")
; #define PG8_BAR __builtin_amdgcn_s_barrier()
; #define PG8_SCHED __builtin_amdgcn_sched_barrier(0)
; template <class Epi>
; __device__ __forceinline__ void gemm_phase(LAS unsigned char* lds, const bf16_t* A, int lda, const bf16_t* Bt, int ldb, int M, int N, int K, int asel, const Epi& E, const int fixed_round = -1) {
;     ...
;             PG8_WAIT_V(6); PG8_BAR; PG8_MMA(1, 1, At, B1); PG8_BAR;
;             PG8_LDB(B0, 1, 0); PG8_SCHED; PG8_LDA(At, 1, 0); PG8_STAGE(PG8_SA(0, 1), a2 + hstepA, voffA);
;             PG8_WAIT_L(8); PG8_BAR; PG8_WAIT_L(0); PG8_MMA(0, 0, At, B0); PG8_BAR; PG8_SCHED;
;             PG8_LDB(B1, 1, 1); PG8_STAGE(PG8_SB(1, 0), b3, voffB);
;             PG8_BAR; PG8_WAIT_L(0); PG8_MMA(0, 1, At, B1); PG8_BAR;
;             PG8_LDA(At, 1, 1); PG8_STAGE(PG8_SA(1, 0), a3, voffA);
	v_mfma_f32_16x16x32_bf16 v[32:35], v[162:165], v[196:199], v[32:35]
	v_mfma_f32_16x16x32_bf16 v[12:15], v[162:165], v[206:209], v[12:15]
	v_mfma_f32_16x16x32_bf16 v[24:27], v[170:173], v[196:199], v[24:27]
	v_mfma_f32_16x16x32_bf16 v[8:11], v[170:173], v[206:209], v[8:11]
	v_mfma_f32_16x16x32_bf16 v[20:23], v[178:181], v[196:199], v[20:23]
	v_mfma_f32_16x16x32_bf16 v[4:7], v[178:181], v[206:209], v[4:7]
	v_mfma_f32_16x16x32_bf16 v[16:19], v[186:189], v[196:199], v[16:19]
	v_mfma_f32_16x16x32_bf16 v[0:3], v[186:189], v[206:209], v[0:3]
	v_mfma_f32_16x16x32_bf16 v[32:35], v[166:169], v[202:205], v[32:35]
	v_mfma_f32_16x16x32_bf16 v[12:15], v[166:169], v[210:213], v[12:15]
	v_mfma_f32_16x16x32_bf16 v[24:27], v[174:177], v[202:205], v[24:27]
	v_mfma_f32_16x16x32_bf16 v[8:11], v[174:177], v[210:213], v[8:11]
	v_mfma_f32_16x16x32_bf16 v[20:23], v[182:185], v[202:205], v[20:23]
	v_mfma_f32_16x16x32_bf16 v[4:7], v[182:185], v[210:213], v[4:7]
	v_mfma_f32_16x16x32_bf16 v[16:19], v[190:193], v[202:205], v[16:19]
	v_mfma_f32_16x16x32_bf16 v[0:3], v[190:193], v[210:213], v[0:3]
	s_setprio 0
	s_add_i32 s42, 0, 0x18000
	v_add_u32_e32 v158, s42, v140
	s_barrier
	ds_read_b128 v[146:149], v158
	ds_read_b128 v[150:153], v158 offset:1024
	ds_read_b128 v[154:157], v158 offset:2048
	ds_read_b128 v[158:161], v158 offset:3072
	s_add_u32 s20, s20, 0x80000
	s_addc_u32 s21, s21, 0
	s_mov_b32 m0, s27
	ds_read_b128 v[162:165], v144 offset:32768
	ds_read_b128 v[166:169], v144 offset:33792
	ds_read_b128 v[170:173], v144 offset:34816
	ds_read_b128 v[174:177], v144 offset:35840
	ds_read_b128 v[178:181], v144 offset:36864
	ds_read_b128 v[182:185], v144 offset:37888
	ds_read_b128 v[186:189], v144 offset:38912
	ds_read_b128 v[190:193], v144 offset:39936
	global_load_lds_dwordx4 v128, s[20:21]
	s_mov_b32 m0, s28
	s_nop 0
	global_load_lds_dwordx4 v130, s[20:21]
	s_waitcnt lgkmcnt(8)
	s_setprio 1
	s_barrier
	s_waitcnt lgkmcnt(0)
	v_mfma_f32_16x16x32_bf16 v[124:127], v[162:165], v[146:149], v[124:127]
	v_mfma_f32_16x16x32_bf16 v[108:111], v[162:165], v[154:157], v[108:111]
	v_mfma_f32_16x16x32_bf16 v[120:123], v[170:173], v[146:149], v[120:123]
	v_mfma_f32_16x16x32_bf16 v[104:107], v[170:173], v[154:157], v[104:107]
	v_mfma_f32_16x16x32_bf16 v[116:119], v[178:181], v[146:149], v[116:119]
	v_mfma_f32_16x16x32_bf16 v[100:103], v[178:181], v[154:157], v[100:103]
	v_mfma_f32_16x16x32_bf16 v[112:115], v[186:189], v[146:149], v[112:115]
	v_mfma_f32_16x16x32_bf16 v[92:95], v[186:189], v[154:157], v[92:95]
	v_mfma_f32_16x16x32_bf16 v[124:127], v[166:169], v[150:153], v[124:127]
	v_mfma_f32_16x16x32_bf16 v[108:111], v[166:169], v[158:161], v[108:111]
	v_mfma_f32_16x16x32_bf16 v[120:123], v[174:177], v[150:153], v[120:123]
	v_mfma_f32_16x16x32_bf16 v[104:107], v[174:177], v[158:161], v[104:107]
	v_mfma_f32_16x16x32_bf16 v[116:119], v[182:185], v[150:153], v[116:119]
	v_mfma_f32_16x16x32_bf16 v[100:103], v[182:185], v[158:161], v[100:103]
	v_mfma_f32_16x16x32_bf16 v[112:115], v[190:193], v[150:153], v[112:115]
	v_mfma_f32_16x16x32_bf16 v[92:95], v[190:193], v[158:161], v[92:95]
	s_setprio 0
	s_barrier
	s_add_i32 s20, 0, 0x1c000
	s_add_i32 s21, s42, s25
	v_add_u32_e32 v195, s20, v140
	s_mov_b32 m0, s21
	ds_read_b128 v[196:199], v195
	ds_read_b128 v[202:205], v195 offset:1024
	ds_read_b128 v[206:209], v195 offset:2048
	ds_read_b128 v[210:213], v195 offset:3072
	global_load_lds_dwordx4 v128, s[98:99]
	s_add_i32 m0, s21, 0x2000
	s_nop 0
	global_load_lds_dwordx4 v130, s[98:99]
	s_setprio 1
	s_barrier
	s_waitcnt lgkmcnt(0)
	v_mfma_f32_16x16x32_bf16 v[80:83], v[162:165], v[196:199], v[80:83]
	v_mfma_f32_16x16x32_bf16 v[48:51], v[162:165], v[206:209], v[48:51]
	v_mfma_f32_16x16x32_bf16 v[68:71], v[170:173], v[196:199], v[68:71]
	v_mfma_f32_16x16x32_bf16 v[40:43], v[170:173], v[206:209], v[40:43]
	v_mfma_f32_16x16x32_bf16 v[60:63], v[178:181], v[196:199], v[60:63]
	v_mfma_f32_16x16x32_bf16 v[36:39], v[178:181], v[206:209], v[36:39]
	v_mfma_f32_16x16x32_bf16 v[52:55], v[186:189], v[196:199], v[52:55]
	v_mfma_f32_16x16x32_bf16 v[28:31], v[186:189], v[206:209], v[28:31]
	v_mfma_f32_16x16x32_bf16 v[80:83], v[166:169], v[202:205], v[80:83]
	v_mfma_f32_16x16x32_bf16 v[48:51], v[166:169], v[210:213], v[48:51]
	v_mfma_f32_16x16x32_bf16 v[68:71], v[174:177], v[202:205], v[68:71]
	v_mfma_f32_16x16x32_bf16 v[40:43], v[174:177], v[210:213], v[40:43]
	v_mfma_f32_16x16x32_bf16 v[60:63], v[182:185], v[202:205], v[60:63]
	v_mfma_f32_16x16x32_bf16 v[36:39], v[182:185], v[210:213], v[36:39]
	v_mfma_f32_16x16x32_bf16 v[52:55], v[190:193], v[202:205], v[52:55]
	v_mfma_f32_16x16x32_bf16 v[28:31], v[190:193], v[210:213], v[28:31]
	s_setprio 0
	s_mov_b32 m0, s30
	s_barrier
	ds_read_b128 v[162:165], v144 offset:49152
	ds_read_b128 v[166:169], v144 offset:50176
	ds_read_b128 v[170:173], v144 offset:51200
	ds_read_b128 v[174:177], v144 offset:52224
	ds_read_b128 v[178:181], v144 offset:53248
	ds_read_b128 v[182:185], v144 offset:54272
	ds_read_b128 v[186:189], v144 offset:55296
	ds_read_b128 v[190:193], v144 offset:56320
	global_load_lds_dwordx4 v128, s[100:101]
	s_mov_b32 m0, s31
	s_nop 0
	global_load_lds_dwordx4 v130, s[100:101]
	s_setprio 1
	s_barrier
; #define PG8_STAGE(bufoff, gbase, voff) do { _Pragma("unroll") for (int _i = 0; _i < 2; ++_i) \
;         __builtin_amdgcn_global_load_lds((const unsigned*)((const char*)(gbase) + (voff)[_i]), (LAS unsigned*)(lds + (bufoff) + ldsw + _i * 8192), 16, 0, 0); } while (0)
; #define PG8_WAIT_V(n) asm volatile("s_waitcnt vmcnt(" #n ")" ::: "memory")
; #define PG8_WAIT_L(n) asm volatile("s_waitcnt lgkmcnt(" #n ")" ::: "memory")
; #define PG8_BAR __builtin_amdgcn_s_barrier()
; #define PG8_SCHED __builtin_amdgcn_sched_barrier(0)
; template <class Epi>
; __device__ __forceinline__ void gemm_phase(LAS unsigned char* lds, const bf16_t* A, int lda, const bf16_t* Bt, int ldb, int M, int N, int K, int asel, const Epi& E, const int fixed_round = -1) {
;     ...
;             PG8_BAR; PG8_WAIT_L(0); PG8_MMA(1, 0, At, B0); PG8_BAR; PG8_SCHED;
;             PG8_STAGE(PG8_SB(1, 1), b3 + hstepB, voffB);
;             PG8_WAIT_V(6); PG8_BAR; PG8_MMA(1, 1, At, B1); PG8_BAR;
	s_waitcnt lgkmcnt(0)
	v_mfma_f32_16x16x32_bf16 v[96:99], v[162:165], v[146:149], v[96:99]
	v_mfma_f32_16x16x32_bf16 v[72:75], v[162:165], v[154:157], v[72:75]
	v_mfma_f32_16x16x32_bf16 v[88:91], v[170:173], v[146:149], v[88:91]
	v_mfma_f32_16x16x32_bf16 v[64:67], v[170:173], v[154:157], v[64:67]
	v_mfma_f32_16x16x32_bf16 v[84:87], v[178:181], v[146:149], v[84:87]
	v_mfma_f32_16x16x32_bf16 v[56:59], v[178:181], v[154:157], v[56:59]
	v_mfma_f32_16x16x32_bf16 v[76:79], v[186:189], v[146:149], v[76:79]
	v_mfma_f32_16x16x32_bf16 v[44:47], v[186:189], v[154:157], v[44:47]
	v_mfma_f32_16x16x32_bf16 v[96:99], v[166:169], v[150:153], v[96:99]
	v_mfma_f32_16x16x32_bf16 v[72:75], v[166:169], v[158:161], v[72:75]
	v_mfma_f32_16x16x32_bf16 v[88:91], v[174:177], v[150:153], v[88:91]
	v_mfma_f32_16x16x32_bf16 v[64:67], v[174:177], v[158:161], v[64:67]
	v_mfma_f32_16x16x32_bf16 v[84:87], v[182:185], v[150:153], v[84:87]
	v_mfma_f32_16x16x32_bf16 v[56:59], v[182:185], v[158:161], v[56:59]
	v_mfma_f32_16x16x32_bf16 v[76:79], v[190:193], v[150:153], v[76:79]
	v_mfma_f32_16x16x32_bf16 v[44:47], v[190:193], v[158:161], v[44:47]
	s_setprio 0
	s_barrier
	s_add_u32 s18, s18, 0x80080
	s_addc_u32 s19, s19, 0
	s_add_i32 s20, s20, s25
	s_mov_b32 m0, s20
	s_nop 0
	global_load_lds_dwordx4 v128, s[18:19]
	s_add_i32 m0, s20, 0x2000
	s_nop 0
	global_load_lds_dwordx4 v130, s[18:19]
	s_waitcnt vmcnt(6)
	s_setprio 1
	s_barrier
	v_mfma_f32_16x16x32_bf16 v[32:35], v[162:165], v[196:199], v[32:35]
	v_mfma_f32_16x16x32_bf16 v[12:15], v[162:165], v[206:209], v[12:15]
	v_mfma_f32_16x16x32_bf16 v[24:27], v[170:173], v[196:199], v[24:27]
	v_mfma_f32_16x16x32_bf16 v[8:11], v[170:173], v[206:209], v[8:11]
	v_mfma_f32_16x16x32_bf16 v[20:23], v[178:181], v[196:199], v[20:23]
	v_mfma_f32_16x16x32_bf16 v[4:7], v[178:181], v[206:209], v[4:7]
	v_mfma_f32_16x16x32_bf16 v[16:19], v[186:189], v[196:199], v[16:19]
	v_mfma_f32_16x16x32_bf16 v[0:3], v[186:189], v[206:209], v[0:3]
	v_mfma_f32_16x16x32_bf16 v[32:35], v[166:169], v[202:205], v[32:35]
	v_mfma_f32_16x16x32_bf16 v[12:15], v[166:169], v[210:213], v[12:15]
	v_mfma_f32_16x16x32_bf16 v[24:27], v[174:177], v[202:205], v[24:27]
	v_mfma_f32_16x16x32_bf16 v[8:11], v[174:177], v[210:213], v[8:11]
	v_mfma_f32_16x16x32_bf16 v[20:23], v[182:185], v[202:205], v[20:23]
	v_mfma_f32_16x16x32_bf16 v[4:7], v[182:185], v[210:213], v[4:7]
	v_mfma_f32_16x16x32_bf16 v[16:19], v[190:193], v[202:205], v[16:19]
	v_mfma_f32_16x16x32_bf16 v[0:3], v[190:193], v[210:213], v[0:3]
	s_setprio 0
	s_add_i32 s41, s41, 2
	s_add_u32 s16, s16, 0x100
	s_addc_u32 s17, s17, 0
	s_add_u32 s39, s39, 0x100
	s_addc_u32 s40, s40, 0
	s_cmp_gt_u32 s41, 29
	s_cbranch_scc0 .Lrot_2
	s_barrier
; __device__ __forceinline__ unsigned cvt_pk_bf16(float lo, float hi) { const bf16x2_t r = __builtin_convertvector((f32x2){lo, hi}, bf16x2_t); return __builtin_bit_cast(unsigned, r); }
; #define PG8_WAIT_V(n) asm volatile("s_waitcnt vmcnt(" #n ")" ::: "memory")
; #define PG8_BAR __builtin_amdgcn_s_barrier()
; template <class Epi>
; __device__ __forceinline__ void gemm_phase(LAS unsigned char* lds, const bf16_t* A, int lda, const bf16_t* Bt, int ldb, int M, int N, int K, int asel, const Epi& E, const int fixed_round = -1) {
;     ...
;         cur = nxt; cA = nA; cB = nB; ++ui;
;     }
;     PG8_WAIT_V(0);
;     if (wr == 0) PG8_BAR;
;     PG8_BAR;
;     __device__ __forceinline__ void operator()(const AccT& acc, const Unit& u, int wr, int wc, int fr, int fq) const {
;         const int bb = u.pm >> 4, s0 = (u.pm & 15) * BM + wr * 64 + 4 * fq, feat0 = u.pn * BM + wc * 32 + fr;
; #pragma unroll
;         for (int bj = 0; bj < 2; ++bj)
; #pragma unroll
;             for (int n = 0; n < 2; ++n) { bf16_t* fp = VT + ((size_t)bb * 2048 + feat0 + bj * HALF + n * 16) * SEQ + s0;
; #pragma unroll
;                 for (int ai = 0; ai < 2; ++ai)
; #pragma unroll
;                     for (int m = 0; m < 4; ++m) { const f32x4 v = acc[ai][bj][m][n]; u32x2 w; w.x = cvt_pk_bf16(v[0], v[1]); w.y = cvt_pk_bf16(v[2], v[3]);
;                         *(u32x2*)(fp + ai * HALF + m * 16) = w; } }
;     }
	s_ashr_i32 s16, s6, 4
	v_lshl_or_b32 v148, s36, 8, v142
	s_lshl_b32 s6, s6, 8
	s_ashr_i32 s17, s16, 31
	v_ashrrev_i32_e32 v149, 31, v148
	s_and_b32 s6, s6, 0xf00
	s_lshl_b64 s[16:17], s[16:17], 24
	v_lshlrev_b64 v[148:149], 13, v[148:149]
	v_add_u32_e32 v146, s6, v141
	v_lshl_add_u64 v[148:149], v[148:149], 0, s[16:17]
	v_readlane_b32 s16, v254, 47
	v_ashrrev_i32_e32 v147, 31, v146
	v_readlane_b32 s17, v254, 48
	v_lshlrev_b64 v[146:147], 1, v[146:147]
	v_cvt_pk_bf16_f32 v76, v76, v77
	v_lshl_add_u64 v[150:151], s[16:17], 0, v[148:149]
	v_lshl_add_u64 v[150:151], v[150:151], 0, v[146:147]
	v_cvt_pk_bf16_f32 v77, v78, v79
	global_store_dwordx2 v[150:151], v[76:77], off offset:352
	v_or_b32_e32 v76, 0x20000, v148
	v_mov_b32_e32 v77, v149
	v_lshl_add_u64 v[76:77], s[16:17], 0, v[76:77]
	v_cvt_pk_bf16_f32 v124, v124, v125
	v_cvt_pk_bf16_f32 v125, v126, v127
	v_cvt_pk_bf16_f32 v120, v120, v121
	v_cvt_pk_bf16_f32 v121, v122, v123
	v_cvt_pk_bf16_f32 v116, v116, v117
	v_cvt_pk_bf16_f32 v117, v118, v119
	v_cvt_pk_bf16_f32 v112, v112, v113
	v_cvt_pk_bf16_f32 v113, v114, v115
	v_cvt_pk_bf16_f32 v96, v96, v97
	v_cvt_pk_bf16_f32 v97, v98, v99
	v_cvt_pk_bf16_f32 v88, v88, v89
	v_cvt_pk_bf16_f32 v89, v90, v91
	v_cvt_pk_bf16_f32 v84, v84, v85
	v_cvt_pk_bf16_f32 v85, v86, v87
	v_lshl_add_u64 v[76:77], v[76:77], 0, v[146:147]
	v_cvt_pk_bf16_f32 v78, v108, v109
	v_cvt_pk_bf16_f32 v79, v110, v111
	v_cvt_pk_bf16_f32 v44, v44, v45
	v_cvt_pk_bf16_f32 v45, v46, v47
	global_store_dwordx2 v[150:151], v[124:125], off
	global_store_dwordx2 v[150:151], v[120:121], off offset:32
	global_store_dwordx2 v[150:151], v[116:117], off offset:64
	global_store_dwordx2 v[150:151], v[112:113], off offset:96
	global_store_dwordx2 v[150:151], v[96:97], off offset:256
	global_store_dwordx2 v[150:151], v[88:89], off offset:288
	global_store_dwordx2 v[150:151], v[84:85], off offset:320
	global_store_dwordx2 v[76:77], v[78:79], off
	v_cvt_pk_bf16_f32 v78, v104, v105
	v_cvt_pk_bf16_f32 v79, v106, v107
	global_store_dwordx2 v[76:77], v[44:45], off offset:352
	v_or_b32_e32 v44, 0x100000, v148
	v_mov_b32_e32 v45, v149
	global_store_dwordx2 v[76:77], v[78:79], off offset:32
	v_cvt_pk_bf16_f32 v78, v100, v101
	v_cvt_pk_bf16_f32 v79, v102, v103
	v_lshl_add_u64 v[44:45], s[16:17], 0, v[44:45]
	global_store_dwordx2 v[76:77], v[78:79], off offset:64
	v_cvt_pk_bf16_f32 v78, v92, v93
	v_cvt_pk_bf16_f32 v79, v94, v95
	v_cvt_pk_bf16_f32 v72, v72, v73
	v_cvt_pk_bf16_f32 v73, v74, v75
	v_cvt_pk_bf16_f32 v64, v64, v65
	v_cvt_pk_bf16_f32 v65, v66, v67
	v_cvt_pk_bf16_f32 v56, v56, v57
	v_cvt_pk_bf16_f32 v57, v58, v59
	v_lshl_add_u64 v[44:45], v[44:45], 0, v[146:147]
	v_cvt_pk_bf16_f32 v46, v80, v81
	v_cvt_pk_bf16_f32 v47, v82, v83
	global_store_dwordx2 v[76:77], v[78:79], off offset:96
	global_store_dwordx2 v[76:77], v[72:73], off offset:256
	global_store_dwordx2 v[76:77], v[64:65], off offset:288
	global_store_dwordx2 v[76:77], v[56:57], off offset:320
	global_store_dwordx2 v[44:45], v[46:47], off
	v_cvt_pk_bf16_f32 v46, v68, v69
	v_cvt_pk_bf16_f32 v47, v70, v71
	v_cvt_pk_bf16_f32 v16, v16, v17
	v_cvt_pk_bf16_f32 v17, v18, v19
	v_or_b32_e32 v148, 0x120000, v148
	global_store_dwordx2 v[44:45], v[46:47], off offset:32
	v_cvt_pk_bf16_f32 v46, v60, v61
	v_cvt_pk_bf16_f32 v47, v62, v63
	global_store_dwordx2 v[44:45], v[16:17], off offset:352
	v_lshl_add_u64 v[16:17], s[16:17], 0, v[148:149]
	global_store_dwordx2 v[44:45], v[46:47], off offset:64
	v_cvt_pk_bf16_f32 v46, v52, v53
	v_cvt_pk_bf16_f32 v47, v54, v55
	v_cvt_pk_bf16_f32 v32, v32, v33
	v_cvt_pk_bf16_f32 v33, v34, v35
	v_cvt_pk_bf16_f32 v24, v24, v25
	v_cvt_pk_bf16_f32 v25, v26, v27
	v_cvt_pk_bf16_f32 v20, v20, v21
	v_cvt_pk_bf16_f32 v21, v22, v23
	v_lshl_add_u64 v[16:17], v[16:17], 0, v[146:147]
	v_cvt_pk_bf16_f32 v18, v48, v49
	v_cvt_pk_bf16_f32 v19, v50, v51
	global_store_dwordx2 v[44:45], v[46:47], off offset:96
	global_store_dwordx2 v[44:45], v[32:33], off offset:256
	global_store_dwordx2 v[44:45], v[24:25], off offset:288
	global_store_dwordx2 v[44:45], v[20:21], off offset:320
	global_store_dwordx2 v[16:17], v[18:19], off
	v_cvt_pk_bf16_f32 v18, v40, v41
	v_cvt_pk_bf16_f32 v19, v42, v43
	global_store_dwordx2 v[16:17], v[18:19], off offset:32
	v_cvt_pk_bf16_f32 v18, v36, v37
	v_cvt_pk_bf16_f32 v19, v38, v39
	global_store_dwordx2 v[16:17], v[18:19], off offset:64
	v_cvt_pk_bf16_f32 v18, v28, v29
	v_cvt_pk_bf16_f32 v19, v30, v31
	v_cvt_pk_bf16_f32 v12, v12, v13
	v_cvt_pk_bf16_f32 v13, v14, v15
	v_cvt_pk_bf16_f32 v8, v8, v9
	v_cvt_pk_bf16_f32 v9, v10, v11
	v_cvt_pk_bf16_f32 v4, v4, v5
	v_cvt_pk_bf16_f32 v5, v6, v7
	v_cvt_pk_bf16_f32 v0, v0, v1
	v_cvt_pk_bf16_f32 v1, v2, v3
	s_and_b64 vcc, exec, s[4:5]
	s_mov_b32 s36, s8
	s_mov_b32 s6, s10
	s_mov_b64 s[18:19], s[14:15]
	s_mov_b64 s[16:17], s[12:13]
	global_store_dwordx2 v[16:17], v[18:19], off offset:96
	global_store_dwordx2 v[16:17], v[12:13], off offset:256
	global_store_dwordx2 v[16:17], v[8:9], off offset:288
	global_store_dwordx2 v[16:17], v[4:5], off offset:320
	global_store_dwordx2 v[16:17], v[0:1], off offset:352
	s_cbranch_vccz .LBB0_217
	s_waitcnt vmcnt(0)
	s_cmpk_gt_u32 s22, 0xff
	s_cbranch_scc1 .LBB0_228
	s_barrier

; #define PG8_STAGE(bufoff, gbase, voff) do { _Pragma("unroll") for (int _i = 0; _i < 2; ++_i) \
;         __builtin_amdgcn_global_load_lds((const unsigned*)((const char*)(gbase) + (voff)[_i]), (LAS unsigned*)(lds + (bufoff) + ldsw + _i * 8192), 16, 0, 0); } while (0)
; #define PG8_LDA(dst, b, h) do { _Pragma("unroll") for (int m = 0; m < 4; ++m) _Pragma("unroll") for (int k = 0; k < 2; ++k) dst[m][k] = *(const LAS bf16x8*)(lds + PG8_SA(b, h) + aoff + m * 2048 + k * 1024); } while (0)
; #define PG8_LDB(dst, b, h) do { _Pragma("unroll") for (int n = 0; n < 2; ++n) _Pragma("unroll") for (int k = 0; k < 2; ++k) dst[n][k] = *(const LAS bf16x8*)(lds + PG8_SB(b, h) + boff + n * 2048 + k * 1024); } while (0)
; #define PG8_WAIT_V(n) asm volatile("s_waitcnt vmcnt(" #n ")" ::: "memory")
; #define PG8_WAIT_L(n) asm volatile("s_waitcnt lgkmcnt(" #n ")" ::: "memory")
; #define PG8_BAR __builtin_amdgcn_s_barrier()
; #define PG8_SCHED __builtin_amdgcn_sched_barrier(0)
; template <class Epi>
; __device__ __forceinline__ void gemm_phase(LAS unsigned char* lds, const bf16_t* A, int lda, const bf16_t* Bt, int ldb, int M, int N, int K, int asel, const Epi& E, const int fixed_round = -1) {
;     ...
;             const char* a1 = cA + (size_t)(t + 1) * kstep;
;             const char* a2 = last ? nA : cA + (size_t)(t + 2) * kstep; const char* b2 = last ? nB : cB + (size_t)(t + 2) * kstep;
;             const char* a3 = a2 + kstep; const char* b3 = b2 + kstep;
;             PG8_LDB(B0, 0, 0); PG8_SCHED; PG8_LDA(At, 0, 0); PG8_STAGE(PG8_SA(1, 1), a1 + hstepA, voffA);
;             PG8_WAIT_L(8); PG8_BAR; PG8_WAIT_L(0); PG8_MMA(0, 0, At, B0); PG8_BAR; PG8_SCHED;
;             PG8_LDB(B1, 0, 1); PG8_STAGE(PG8_SB(0, 0), b2, voffB);
;             PG8_BAR; PG8_WAIT_L(0); PG8_MMA(0, 1, At, B1); PG8_BAR;
;             PG8_LDA(At, 0, 1); PG8_STAGE(PG8_SA(0, 0), a2, voffA);
;             PG8_BAR; PG8_WAIT_L(0); PG8_MMA(1, 0, At, B0); PG8_BAR; PG8_SCHED;
;             PG8_STAGE(PG8_SB(0, 1), b2 + hstepB, voffB);
;             PG8_WAIT_V(6); PG8_BAR; PG8_MMA(1, 1, At, B1); PG8_BAR;
.LBB0_245:
	ds_read_b128 v[148:151], v161
	ds_read_b128 v[152:155], v161 offset:1024
	ds_read_b128 v[156:159], v161 offset:2048
	ds_read_b128 v[166:169], v161 offset:3072
	s_add_i32 m0, s37, 0xc000
	ds_read_b128 v[170:173], v162
	ds_read_b128 v[174:177], v162 offset:1024
	ds_read_b128 v[178:181], v162 offset:2048
	ds_read_b128 v[182:185], v162 offset:3072
	ds_read_b128 v[186:189], v162 offset:4096
	ds_read_b128 v[190:193], v162 offset:5120
	ds_read_b128 v[196:199], v162 offset:6144
	ds_read_b128 v[202:205], v162 offset:7168
	global_load_lds_dwordx4 v140, s[26:27]
	s_add_i32 m0, s37, 0xe000
	s_nop 0
	global_load_lds_dwordx4 v142, s[26:27]
	s_waitcnt lgkmcnt(8)
	s_setprio 1
	s_barrier
	s_waitcnt lgkmcnt(0)
	v_mfma_f32_16x16x32_bf16 v[124:127], v[148:151], v[170:173], v[124:127]
	v_mfma_f32_16x16x32_bf16 v[120:123], v[156:159], v[170:173], v[120:123]
	v_mfma_f32_16x16x32_bf16 v[112:115], v[148:151], v[178:181], v[112:115]
	v_mfma_f32_16x16x32_bf16 v[108:111], v[156:159], v[178:181], v[108:111]
	v_mfma_f32_16x16x32_bf16 v[100:103], v[148:151], v[186:189], v[100:103]
	v_mfma_f32_16x16x32_bf16 v[92:95], v[156:159], v[186:189], v[92:95]
	v_mfma_f32_16x16x32_bf16 v[84:87], v[148:151], v[196:199], v[84:87]
	v_mfma_f32_16x16x32_bf16 v[76:79], v[156:159], v[196:199], v[76:79]
	v_mfma_f32_16x16x32_bf16 v[124:127], v[152:155], v[174:177], v[124:127]
	v_mfma_f32_16x16x32_bf16 v[120:123], v[166:169], v[174:177], v[120:123]
	v_mfma_f32_16x16x32_bf16 v[112:115], v[152:155], v[182:185], v[112:115]
	v_mfma_f32_16x16x32_bf16 v[108:111], v[166:169], v[182:185], v[108:111]
	v_mfma_f32_16x16x32_bf16 v[100:103], v[152:155], v[190:193], v[100:103]
	v_mfma_f32_16x16x32_bf16 v[92:95], v[166:169], v[190:193], v[92:95]
	v_mfma_f32_16x16x32_bf16 v[84:87], v[152:155], v[202:205], v[84:87]
	v_mfma_f32_16x16x32_bf16 v[76:79], v[166:169], v[202:205], v[76:79]
	s_setprio 0
	s_barrier
	s_add_u32 s28, s26, 0xfff80080
	s_addc_u32 s29, s27, -1
	s_cmp_eq_u32 s57, 28
	s_cselect_b32 s31, s2, s29
	s_cselect_b32 s30, s19, s28
	s_cselect_b32 s29, s17, s56
	s_cselect_b32 s28, s54, s55
	s_add_i32 s58, s44, s36
	s_add_u32 s98, s28, s4
	s_addc_u32 s99, s29, s5
	s_mov_b32 m0, s58
	ds_read_b128 v[206:209], v163
	ds_read_b128 v[210:213], v163 offset:1024
	ds_read_b128 v[214:217], v163 offset:2048
	ds_read_b128 v[218:221], v163 offset:3072
	global_load_lds_dwordx4 v130, s[28:29]
	s_add_i32 m0, s58, 0x2000
	s_nop 0
	global_load_lds_dwordx4 v134, s[28:29]
	s_setprio 1
	s_barrier
	s_waitcnt lgkmcnt(0)
	v_mfma_f32_16x16x32_bf16 v[116:119], v[206:209], v[170:173], v[116:119]
	v_mfma_f32_16x16x32_bf16 v[104:107], v[214:217], v[170:173], v[104:107]
	v_mfma_f32_16x16x32_bf16 v[96:99], v[206:209], v[178:181], v[96:99]
	v_mfma_f32_16x16x32_bf16 v[88:91], v[214:217], v[178:181], v[88:91]
	v_mfma_f32_16x16x32_bf16 v[80:83], v[206:209], v[186:189], v[80:83]
	v_mfma_f32_16x16x32_bf16 v[72:75], v[214:217], v[186:189], v[72:75]
	v_mfma_f32_16x16x32_bf16 v[68:71], v[206:209], v[196:199], v[68:71]
	v_mfma_f32_16x16x32_bf16 v[64:67], v[214:217], v[196:199], v[64:67]
	v_mfma_f32_16x16x32_bf16 v[116:119], v[210:213], v[174:177], v[116:119]
	v_mfma_f32_16x16x32_bf16 v[104:107], v[218:221], v[174:177], v[104:107]
	v_mfma_f32_16x16x32_bf16 v[96:99], v[210:213], v[182:185], v[96:99]
	v_mfma_f32_16x16x32_bf16 v[88:91], v[218:221], v[182:185], v[88:91]
	v_mfma_f32_16x16x32_bf16 v[80:83], v[210:213], v[190:193], v[80:83]
	v_mfma_f32_16x16x32_bf16 v[72:75], v[218:221], v[190:193], v[72:75]
	v_mfma_f32_16x16x32_bf16 v[68:71], v[210:213], v[202:205], v[68:71]
	v_mfma_f32_16x16x32_bf16 v[64:67], v[218:221], v[202:205], v[64:67]
	s_setprio 0
	s_mov_b32 m0, s37
	s_add_u32 s100, s30, s4
	s_addc_u32 s101, s31, s5
	s_barrier
	ds_read_b128 v[170:173], v162 offset:16384
	ds_read_b128 v[174:177], v162 offset:17408
	ds_read_b128 v[178:181], v162 offset:18432
	ds_read_b128 v[182:185], v162 offset:19456
	ds_read_b128 v[186:189], v162 offset:20480
	ds_read_b128 v[190:193], v162 offset:21504
	ds_read_b128 v[196:199], v162 offset:22528
	ds_read_b128 v[202:205], v162 offset:23552
	global_load_lds_dwordx4 v128, s[30:31]
	s_mov_b32 m0, s38
	s_nop 0
	global_load_lds_dwordx4 v132, s[30:31]
	s_setprio 1
	s_barrier
	s_waitcnt lgkmcnt(0)
	v_mfma_f32_16x16x32_bf16 v[60:63], v[148:151], v[170:173], v[60:63]
	v_mfma_f32_16x16x32_bf16 v[56:59], v[156:159], v[170:173], v[56:59]
	v_mfma_f32_16x16x32_bf16 v[52:55], v[148:151], v[178:181], v[52:55]
	v_mfma_f32_16x16x32_bf16 v[44:47], v[156:159], v[178:181], v[44:47]
	v_mfma_f32_16x16x32_bf16 v[36:39], v[148:151], v[186:189], v[36:39]
	v_mfma_f32_16x16x32_bf16 v[28:31], v[156:159], v[186:189], v[28:31]
	v_mfma_f32_16x16x32_bf16 v[20:23], v[148:151], v[196:199], v[20:23]
	v_mfma_f32_16x16x32_bf16 v[12:15], v[156:159], v[196:199], v[12:15]
	v_mfma_f32_16x16x32_bf16 v[60:63], v[152:155], v[174:177], v[60:63]
	v_mfma_f32_16x16x32_bf16 v[56:59], v[166:169], v[174:177], v[56:59]
	v_mfma_f32_16x16x32_bf16 v[52:55], v[152:155], v[182:185], v[52:55]
	v_mfma_f32_16x16x32_bf16 v[44:47], v[166:169], v[182:185], v[44:47]
	v_mfma_f32_16x16x32_bf16 v[36:39], v[152:155], v[190:193], v[36:39]
	v_mfma_f32_16x16x32_bf16 v[28:31], v[166:169], v[190:193], v[28:31]
	v_mfma_f32_16x16x32_bf16 v[20:23], v[152:155], v[202:205], v[20:23]
	v_mfma_f32_16x16x32_bf16 v[12:15], v[166:169], v[202:205], v[12:15]
	s_setprio 0
	s_barrier
	s_add_u32 s58, s28, 0x80000
	s_addc_u32 s59, s29, 0
	s_add_i32 s60, s45, s36
	s_mov_b32 m0, s60
	s_nop 0
	global_load_lds_dwordx4 v130, s[58:59]
	s_add_i32 m0, s60, 0x2000
	s_nop 0
	global_load_lds_dwordx4 v134, s[58:59]
	s_waitcnt vmcnt(6)
	s_setprio 1
	s_barrier
; #define PG8_STAGE(bufoff, gbase, voff) do { _Pragma("unroll") for (int _i = 0; _i < 2; ++_i) \
;         __builtin_amdgcn_global_load_lds((const unsigned*)((const char*)(gbase) + (voff)[_i]), (LAS unsigned*)(lds + (bufoff) + ldsw + _i * 8192), 16, 0, 0); } while (0)
; #define PG8_LDA(dst, b, h) do { _Pragma("unroll") for (int m = 0; m < 4; ++m) _Pragma("unroll") for (int k = 0; k < 2; ++k) dst[m][k] = *(const LAS bf16x8*)(lds + PG8_SA(b, h) + aoff + m * 2048 + k * 1024); } while (0)
; #define PG8_LDB(dst, b, h) do { _Pragma("unroll") for (int n = 0; n < 2; ++n) _Pragma("unroll") for (int k = 0; k < 2; ++k) dst[n][k] = *(const LAS bf16x8*)(lds + PG8_SB(b, h) + boff + n * 2048 + k * 1024); } while (0)
; #define PG8_WAIT_V(n) asm volatile("s_waitcnt vmcnt(" #n ")" ::: "memory")
; #define PG8_WAIT_L(n) asm volatile("s_waitcnt lgkmcnt(" #n ")" ::: "memory")
; #define PG8_BAR __builtin_amdgcn_s_barrier()
; #define PG8_SCHED __builtin_amdgcn_sched_barrier(0)
; template <class Epi>
; __device__ __forceinline__ void gemm_phase(LAS unsigned char* lds, const bf16_t* A, int lda, const bf16_t* Bt, int ldb, int M, int N, int K, int asel, const Epi& E, const int fixed_round = -1) {
;     ...
;             PG8_WAIT_V(6); PG8_BAR; PG8_MMA(1, 1, At, B1); PG8_BAR;
;             PG8_LDB(B0, 1, 0); PG8_SCHED; PG8_LDA(At, 1, 0); PG8_STAGE(PG8_SA(0, 1), a2 + hstepA, voffA);
;             PG8_WAIT_L(8); PG8_BAR; PG8_WAIT_L(0); PG8_MMA(0, 0, At, B0); PG8_BAR; PG8_SCHED;
;             PG8_LDB(B1, 1, 1); PG8_STAGE(PG8_SB(1, 0), b3, voffB);
;             PG8_BAR; PG8_WAIT_L(0); PG8_MMA(0, 1, At, B1); PG8_BAR;
;             PG8_LDA(At, 1, 1); PG8_STAGE(PG8_SA(1, 0), a3, voffA);
	v_mfma_f32_16x16x32_bf16 v[48:51], v[206:209], v[170:173], v[48:51]
	v_mfma_f32_16x16x32_bf16 v[40:43], v[214:217], v[170:173], v[40:43]
	v_mfma_f32_16x16x32_bf16 v[32:35], v[206:209], v[178:181], v[32:35]
	v_mfma_f32_16x16x32_bf16 v[24:27], v[214:217], v[178:181], v[24:27]
	v_mfma_f32_16x16x32_bf16 v[16:19], v[206:209], v[186:189], v[16:19]
	v_mfma_f32_16x16x32_bf16 v[8:11], v[214:217], v[186:189], v[8:11]
	v_mfma_f32_16x16x32_bf16 v[4:7], v[206:209], v[196:199], v[4:7]
	v_mfma_f32_16x16x32_bf16 v[0:3], v[214:217], v[196:199], v[0:3]
	v_mfma_f32_16x16x32_bf16 v[48:51], v[210:213], v[174:177], v[48:51]
	v_mfma_f32_16x16x32_bf16 v[40:43], v[218:221], v[174:177], v[40:43]
	v_mfma_f32_16x16x32_bf16 v[32:35], v[210:213], v[182:185], v[32:35]
	v_mfma_f32_16x16x32_bf16 v[24:27], v[218:221], v[182:185], v[24:27]
	v_mfma_f32_16x16x32_bf16 v[16:19], v[210:213], v[190:193], v[16:19]
	v_mfma_f32_16x16x32_bf16 v[8:11], v[218:221], v[190:193], v[8:11]
	v_mfma_f32_16x16x32_bf16 v[4:7], v[210:213], v[202:205], v[4:7]
	v_mfma_f32_16x16x32_bf16 v[0:3], v[218:221], v[202:205], v[0:3]
	s_setprio 0
	s_add_i32 s58, 0, 0x18000
	v_add_u32_e32 v136, s58, v160
	s_barrier
	ds_read_b128 v[148:151], v136
	ds_read_b128 v[152:155], v136 offset:1024
	ds_read_b128 v[156:159], v136 offset:2048
	ds_read_b128 v[166:169], v136 offset:3072
	s_add_u32 s30, s30, 0x80000
	s_addc_u32 s31, s31, 0
	s_mov_b32 m0, s39
	ds_read_b128 v[170:173], v162 offset:32768
	ds_read_b128 v[174:177], v162 offset:33792
	ds_read_b128 v[178:181], v162 offset:34816
	ds_read_b128 v[182:185], v162 offset:35840
	ds_read_b128 v[186:189], v162 offset:36864
	ds_read_b128 v[190:193], v162 offset:37888
	ds_read_b128 v[196:199], v162 offset:38912
	ds_read_b128 v[202:205], v162 offset:39936
	global_load_lds_dwordx4 v128, s[30:31]
	s_mov_b32 m0, s40
	s_nop 0
	global_load_lds_dwordx4 v132, s[30:31]
	s_waitcnt lgkmcnt(8)
	s_setprio 1
	s_barrier
	s_waitcnt lgkmcnt(0)
	v_mfma_f32_16x16x32_bf16 v[124:127], v[148:151], v[170:173], v[124:127]
	v_mfma_f32_16x16x32_bf16 v[120:123], v[156:159], v[170:173], v[120:123]
	v_mfma_f32_16x16x32_bf16 v[112:115], v[148:151], v[178:181], v[112:115]
	v_mfma_f32_16x16x32_bf16 v[108:111], v[156:159], v[178:181], v[108:111]
	v_mfma_f32_16x16x32_bf16 v[100:103], v[148:151], v[186:189], v[100:103]
	v_mfma_f32_16x16x32_bf16 v[92:95], v[156:159], v[186:189], v[92:95]
	v_mfma_f32_16x16x32_bf16 v[84:87], v[148:151], v[196:199], v[84:87]
	v_mfma_f32_16x16x32_bf16 v[76:79], v[156:159], v[196:199], v[76:79]
	v_mfma_f32_16x16x32_bf16 v[124:127], v[152:155], v[174:177], v[124:127]
	v_mfma_f32_16x16x32_bf16 v[120:123], v[166:169], v[174:177], v[120:123]
	v_mfma_f32_16x16x32_bf16 v[112:115], v[152:155], v[182:185], v[112:115]
	v_mfma_f32_16x16x32_bf16 v[108:111], v[166:169], v[182:185], v[108:111]
	v_mfma_f32_16x16x32_bf16 v[100:103], v[152:155], v[190:193], v[100:103]
	v_mfma_f32_16x16x32_bf16 v[92:95], v[166:169], v[190:193], v[92:95]
	v_mfma_f32_16x16x32_bf16 v[84:87], v[152:155], v[202:205], v[84:87]
	v_mfma_f32_16x16x32_bf16 v[76:79], v[166:169], v[202:205], v[76:79]
	s_setprio 0
	s_barrier
	s_add_i32 s30, 0, 0x1c000
	s_add_i32 s31, s58, s36
	v_add_u32_e32 v136, s30, v160
	s_mov_b32 m0, s31
	ds_read_b128 v[206:209], v136
	ds_read_b128 v[210:213], v136 offset:1024
	ds_read_b128 v[214:217], v136 offset:2048
	ds_read_b128 v[218:221], v136 offset:3072
	global_load_lds_dwordx4 v130, s[98:99]
	s_add_i32 m0, s31, 0x2000
	s_nop 0
	global_load_lds_dwordx4 v134, s[98:99]
	s_setprio 1
	s_barrier
	s_waitcnt lgkmcnt(0)
	v_mfma_f32_16x16x32_bf16 v[116:119], v[206:209], v[170:173], v[116:119]
	v_mfma_f32_16x16x32_bf16 v[104:107], v[214:217], v[170:173], v[104:107]
	v_mfma_f32_16x16x32_bf16 v[96:99], v[206:209], v[178:181], v[96:99]
	v_mfma_f32_16x16x32_bf16 v[88:91], v[214:217], v[178:181], v[88:91]
	v_mfma_f32_16x16x32_bf16 v[80:83], v[206:209], v[186:189], v[80:83]
	v_mfma_f32_16x16x32_bf16 v[72:75], v[214:217], v[186:189], v[72:75]
	v_mfma_f32_16x16x32_bf16 v[68:71], v[206:209], v[196:199], v[68:71]
	v_mfma_f32_16x16x32_bf16 v[64:67], v[214:217], v[196:199], v[64:67]
	v_mfma_f32_16x16x32_bf16 v[116:119], v[210:213], v[174:177], v[116:119]
	v_mfma_f32_16x16x32_bf16 v[104:107], v[218:221], v[174:177], v[104:107]
	v_mfma_f32_16x16x32_bf16 v[96:99], v[210:213], v[182:185], v[96:99]
	v_mfma_f32_16x16x32_bf16 v[88:91], v[218:221], v[182:185], v[88:91]
	v_mfma_f32_16x16x32_bf16 v[80:83], v[210:213], v[190:193], v[80:83]
	v_mfma_f32_16x16x32_bf16 v[72:75], v[218:221], v[190:193], v[72:75]
	v_mfma_f32_16x16x32_bf16 v[68:71], v[210:213], v[202:205], v[68:71]
	v_mfma_f32_16x16x32_bf16 v[64:67], v[218:221], v[202:205], v[64:67]
	s_setprio 0
	s_mov_b32 m0, s41
	s_barrier
	ds_read_b128 v[170:173], v162 offset:49152
	ds_read_b128 v[174:177], v162 offset:50176
	ds_read_b128 v[178:181], v162 offset:51200
	ds_read_b128 v[182:185], v162 offset:52224
	ds_read_b128 v[186:189], v162 offset:53248
	ds_read_b128 v[190:193], v162 offset:54272
	ds_read_b128 v[196:199], v162 offset:55296
	ds_read_b128 v[202:205], v162 offset:56320
	global_load_lds_dwordx4 v128, s[100:101]
	s_mov_b32 m0, s42
	s_nop 0
	global_load_lds_dwordx4 v132, s[100:101]
	s_setprio 1
	s_barrier
; __device__ __forceinline__ unsigned cvt_pk_bf16(float lo, float hi) { const bf16x2_t r = __builtin_convertvector((f32x2){lo, hi}, bf16x2_t); return __builtin_bit_cast(unsigned, r); }
; #define PG8_STAGE(bufoff, gbase, voff) do { _Pragma("unroll") for (int _i = 0; _i < 2; ++_i) \
;         __builtin_amdgcn_global_load_lds((const unsigned*)((const char*)(gbase) + (voff)[_i]), (LAS unsigned*)(lds + (bufoff) + ldsw + _i * 8192), 16, 0, 0); } while (0)
; #define PG8_WAIT_V(n) asm volatile("s_waitcnt vmcnt(" #n ")" ::: "memory")
; #define PG8_WAIT_L(n) asm volatile("s_waitcnt lgkmcnt(" #n ")" ::: "memory")
; #define PG8_BAR __builtin_amdgcn_s_barrier()
; #define PG8_SCHED __builtin_amdgcn_sched_barrier(0)
; template <class Epi>
; __device__ __forceinline__ void gemm_phase(LAS unsigned char* lds, const bf16_t* A, int lda, const bf16_t* Bt, int ldb, int M, int N, int K, int asel, const Epi& E, const int fixed_round = -1) {
;     ...
;             PG8_BAR; PG8_WAIT_L(0); PG8_MMA(1, 0, At, B0); PG8_BAR; PG8_SCHED;
;             PG8_STAGE(PG8_SB(1, 1), b3 + hstepB, voffB);
;             PG8_WAIT_V(6); PG8_BAR; PG8_MMA(1, 1, At, B1); PG8_BAR;
;     __device__ __forceinline__ void operator()(const AccT& acc, const Unit& u, int wr, int wc, int fr, int fq) const {
;     ...
;         if (pn < 8) {
;             bf16_t* base = pn < 4 ? Q : Kn; const int colt = (pn & 3) * BM; const float sc = pn < 4 ? 0.08838834764831845f : 1.0f;
; #pragma unroll
;             for (int ai = 0; ai < 2; ++ai)
; #pragma unroll
;                 for (int m = 0; m < 4; ++m) { bf16_t* rowp = base + (size_t)(row0 + ai * HALF + m * 16) * 1024 + colt + cl;
; #pragma unroll
;                     for (int bj = 0; bj < 2; ++bj) { const f32x4 v0 = acc[ai][bj][m][0] * sc, v1 = acc[ai][bj][m][1] * sc;
;                         u32x4 w; w.x = cvt_pk_bf16(v0[0], v0[1]); w.y = cvt_pk_bf16(v0[2], v0[3]); w.z = cvt_pk_bf16(v1[0], v1[1]); w.w = cvt_pk_bf16(v1[2], v1[3]);
;                         *(u32x4*)(rowp + bj * HALF) = w; } }
	s_waitcnt lgkmcnt(0)
	v_mfma_f32_16x16x32_bf16 v[60:63], v[148:151], v[170:173], v[60:63]
	v_mfma_f32_16x16x32_bf16 v[56:59], v[156:159], v[170:173], v[56:59]
	v_mfma_f32_16x16x32_bf16 v[52:55], v[148:151], v[178:181], v[52:55]
	v_mfma_f32_16x16x32_bf16 v[44:47], v[156:159], v[178:181], v[44:47]
	v_mfma_f32_16x16x32_bf16 v[36:39], v[148:151], v[186:189], v[36:39]
	v_mfma_f32_16x16x32_bf16 v[28:31], v[156:159], v[186:189], v[28:31]
	v_mfma_f32_16x16x32_bf16 v[20:23], v[148:151], v[196:199], v[20:23]
	v_mfma_f32_16x16x32_bf16 v[12:15], v[156:159], v[196:199], v[12:15]
	v_mfma_f32_16x16x32_bf16 v[60:63], v[152:155], v[174:177], v[60:63]
	v_mfma_f32_16x16x32_bf16 v[56:59], v[166:169], v[174:177], v[56:59]
	v_mfma_f32_16x16x32_bf16 v[52:55], v[152:155], v[182:185], v[52:55]
	v_mfma_f32_16x16x32_bf16 v[44:47], v[166:169], v[182:185], v[44:47]
	v_mfma_f32_16x16x32_bf16 v[36:39], v[152:155], v[190:193], v[36:39]
	v_mfma_f32_16x16x32_bf16 v[28:31], v[166:169], v[190:193], v[28:31]
	v_mfma_f32_16x16x32_bf16 v[20:23], v[152:155], v[202:205], v[20:23]
	v_mfma_f32_16x16x32_bf16 v[12:15], v[166:169], v[202:205], v[12:15]
	s_setprio 0
	s_barrier
	s_add_u32 s28, s28, 0x80080
	s_addc_u32 s29, s29, 0
	s_add_i32 s30, s30, s36
	s_mov_b32 m0, s30
	s_nop 0
	global_load_lds_dwordx4 v130, s[28:29]
	s_add_i32 m0, s30, 0x2000
	s_nop 0
	global_load_lds_dwordx4 v134, s[28:29]
	s_waitcnt vmcnt(6)
	s_setprio 1
	s_barrier
	v_mfma_f32_16x16x32_bf16 v[48:51], v[206:209], v[170:173], v[48:51]
	v_mfma_f32_16x16x32_bf16 v[40:43], v[214:217], v[170:173], v[40:43]
	v_mfma_f32_16x16x32_bf16 v[32:35], v[206:209], v[178:181], v[32:35]
	v_mfma_f32_16x16x32_bf16 v[24:27], v[214:217], v[178:181], v[24:27]
	v_mfma_f32_16x16x32_bf16 v[16:19], v[206:209], v[186:189], v[16:19]
	v_mfma_f32_16x16x32_bf16 v[8:11], v[214:217], v[186:189], v[8:11]
	v_mfma_f32_16x16x32_bf16 v[4:7], v[206:209], v[196:199], v[4:7]
	v_mfma_f32_16x16x32_bf16 v[0:3], v[214:217], v[196:199], v[0:3]
	v_mfma_f32_16x16x32_bf16 v[48:51], v[210:213], v[174:177], v[48:51]
	v_mfma_f32_16x16x32_bf16 v[40:43], v[218:221], v[174:177], v[40:43]
	v_mfma_f32_16x16x32_bf16 v[32:35], v[210:213], v[182:185], v[32:35]
	v_mfma_f32_16x16x32_bf16 v[24:27], v[218:221], v[182:185], v[24:27]
	v_mfma_f32_16x16x32_bf16 v[16:19], v[210:213], v[190:193], v[16:19]
	v_mfma_f32_16x16x32_bf16 v[8:11], v[218:221], v[190:193], v[8:11]
	v_mfma_f32_16x16x32_bf16 v[4:7], v[210:213], v[202:205], v[4:7]
	v_mfma_f32_16x16x32_bf16 v[0:3], v[218:221], v[202:205], v[0:3]
	s_setprio 0
	s_add_i32 s57, s57, 2
	s_add_u32 s26, s26, 0x100
	s_addc_u32 s27, s27, 0
	s_add_u32 s55, s55, 0x100
	s_addc_u32 s56, s56, 0
	s_cmp_gt_u32 s57, 29
	s_cbranch_scc0 .Lrot_3
	s_barrier
	s_lshl_b32 s17, s24, 8
	v_add_u32_e32 v154, s17, v139
	s_cmp_lt_i32 s25, -8
	v_or_b32_e32 v152, 16, v154
	v_or_b32_e32 v150, 32, v154
	v_or_b32_e32 v148, 48, v154
	s_cselect_b64 s[26:27], -1, 0
	s_cmp_gt_i32 s25, -9
	v_ashrrev_i32_e32 v155, 31, v154
	v_lshlrev_b32_e32 v136, 1, v138
	v_ashrrev_i32_e32 v153, 31, v152
	v_ashrrev_i32_e32 v151, 31, v150
	v_ashrrev_i32_e32 v149, 31, v148
	s_cbranch_scc1 .LBB0_248
	s_cmp_lt_u32 s25, -12
	s_cselect_b64 vcc, -1, 0
	s_and_b64 s[28:29], vcc, exec
	s_cselect_b32 s2, s89, s81
	s_cselect_b32 s19, s88, s91
	s_lshl_b32 s28, s25, 9
	s_and_b32 s28, s28, 0x600
	s_add_u32 s28, s19, s28
	v_cndmask_b32_e32 v156, 1.0, v164, vcc
	s_addc_u32 s29, s2, 0
	v_lshl_add_u64 v[170:171], s[28:29], 0, v[136:137]
	v_lshlrev_b64 v[158:159], 11, v[154:155]
	v_pk_mul_f32 v[168:169], v[156:157], v[126:127] op_sel_hi:[0,1]
	v_pk_mul_f32 v[166:167], v[156:157], v[124:125] op_sel_hi:[0,1]
	v_pk_mul_f32 v[172:173], v[156:157], v[122:123] op_sel_hi:[0,1]
	v_pk_mul_f32 v[174:175], v[156:157], v[120:121] op_sel_hi:[0,1]
	v_lshl_add_u64 v[158:159], v[170:171], 0, v[158:159]
	v_cvt_pk_bf16_f32 v166, v166, v167
	v_cvt_pk_bf16_f32 v167, v168, v169
	v_cvt_pk_bf16_f32 v168, v174, v175
	v_cvt_pk_bf16_f32 v169, v172, v173
	global_store_dwordx4 v[158:159], v[166:169], off
	v_pk_mul_f32 v[172:173], v[156:157], v[106:107] op_sel_hi:[0,1]
	v_pk_mul_f32 v[174:175], v[156:157], v[104:105] op_sel_hi:[0,1]
	v_pk_mul_f32 v[168:169], v[156:157], v[118:119] op_sel_hi:[0,1]
	v_pk_mul_f32 v[166:167], v[156:157], v[116:117] op_sel_hi:[0,1]
	v_cvt_pk_bf16_f32 v166, v166, v167
	v_cvt_pk_bf16_f32 v167, v168, v169
	v_cvt_pk_bf16_f32 v168, v174, v175
	v_cvt_pk_bf16_f32 v169, v172, v173
	global_store_dwordx4 v[158:159], v[166:169], off offset:256
	v_pk_mul_f32 v[174:175], v[156:157], v[110:111] op_sel_hi:[0,1]
	v_pk_mul_f32 v[176:177], v[156:157], v[108:109] op_sel_hi:[0,1]
	v_lshlrev_b64 v[166:167], 11, v[152:153]
	v_lshl_add_u64 v[172:173], v[170:171], 0, v[166:167]
	v_pk_mul_f32 v[168:169], v[156:157], v[114:115] op_sel_hi:[0,1]
	v_pk_mul_f32 v[166:167], v[156:157], v[112:113] op_sel_hi:[0,1]
	v_cvt_pk_bf16_f32 v166, v166, v167
	v_cvt_pk_bf16_f32 v167, v168, v169
	v_cvt_pk_bf16_f32 v168, v176, v177
	v_cvt_pk_bf16_f32 v169, v174, v175
	global_store_dwordx4 v[172:173], v[166:169], off
	v_pk_mul_f32 v[174:175], v[156:157], v[90:91] op_sel_hi:[0,1]
	v_pk_mul_f32 v[176:177], v[156:157], v[88:89] op_sel_hi:[0,1]
	v_pk_mul_f32 v[168:169], v[156:157], v[98:99] op_sel_hi:[0,1]
	v_pk_mul_f32 v[166:167], v[156:157], v[96:97] op_sel_hi:[0,1]
	v_cvt_pk_bf16_f32 v166, v166, v167
	v_cvt_pk_bf16_f32 v167, v168, v169
	v_cvt_pk_bf16_f32 v168, v176, v177
	v_cvt_pk_bf16_f32 v169, v174, v175
	global_store_dwordx4 v[172:173], v[166:169], off offset:256
	v_pk_mul_f32 v[174:175], v[156:157], v[94:95] op_sel_hi:[0,1]
	v_pk_mul_f32 v[176:177], v[156:157], v[92:93] op_sel_hi:[0,1]
	v_lshlrev_b64 v[166:167], 11, v[150:151]
; __device__ __forceinline__ unsigned cvt_pk_bf16(float lo, float hi) { const bf16x2_t r = __builtin_convertvector((f32x2){lo, hi}, bf16x2_t); return __builtin_bit_cast(unsigned, r); }
;     __device__ __forceinline__ void operator()(const AccT& acc, const Unit& u, int wr, int wc, int fr, int fq) const {
;     ...
;         if (pn < 8) {
;             bf16_t* base = pn < 4 ? Q : Kn; const int colt = (pn & 3) * BM; const float sc = pn < 4 ? 0.08838834764831845f : 1.0f;
; #pragma unroll
;             for (int ai = 0; ai < 2; ++ai)
; #pragma unroll
;                 for (int m = 0; m < 4; ++m) { bf16_t* rowp = base + (size_t)(row0 + ai * HALF + m * 16) * 1024 + colt + cl;
; #pragma unroll
;                     for (int bj = 0; bj < 2; ++bj) { const f32x4 v0 = acc[ai][bj][m][0] * sc, v1 = acc[ai][bj][m][1] * sc;
;                         u32x4 w; w.x = cvt_pk_bf16(v0[0], v0[1]); w.y = cvt_pk_bf16(v0[2], v0[3]); w.z = cvt_pk_bf16(v1[0], v1[1]); w.w = cvt_pk_bf16(v1[2], v1[3]);
;                         *(u32x4*)(rowp + bj * HALF) = w; } }
;         }
;         if (pn >= 16) {
	v_lshl_add_u64 v[172:173], v[170:171], 0, v[166:167]
	v_pk_mul_f32 v[168:169], v[156:157], v[102:103] op_sel_hi:[0,1]
	v_pk_mul_f32 v[166:167], v[156:157], v[100:101] op_sel_hi:[0,1]
	v_cvt_pk_bf16_f32 v166, v166, v167
	v_cvt_pk_bf16_f32 v167, v168, v169
	v_cvt_pk_bf16_f32 v168, v176, v177
	v_cvt_pk_bf16_f32 v169, v174, v175
	global_store_dwordx4 v[172:173], v[166:169], off
	v_pk_mul_f32 v[174:175], v[156:157], v[74:75] op_sel_hi:[0,1]
	v_pk_mul_f32 v[176:177], v[156:157], v[72:73] op_sel_hi:[0,1]
	v_pk_mul_f32 v[168:169], v[156:157], v[82:83] op_sel_hi:[0,1]
	v_pk_mul_f32 v[166:167], v[156:157], v[80:81] op_sel_hi:[0,1]
	v_cvt_pk_bf16_f32 v166, v166, v167
	v_cvt_pk_bf16_f32 v167, v168, v169
	v_cvt_pk_bf16_f32 v168, v176, v177
	v_cvt_pk_bf16_f32 v169, v174, v175
	global_store_dwordx4 v[172:173], v[166:169], off offset:256
	v_pk_mul_f32 v[172:173], v[156:157], v[78:79] op_sel_hi:[0,1]
	v_pk_mul_f32 v[174:175], v[156:157], v[76:77] op_sel_hi:[0,1]
	v_lshlrev_b64 v[166:167], 11, v[148:149]
	v_lshl_add_u64 v[170:171], v[170:171], 0, v[166:167]
	v_pk_mul_f32 v[168:169], v[156:157], v[86:87] op_sel_hi:[0,1]
	v_pk_mul_f32 v[166:167], v[156:157], v[84:85] op_sel_hi:[0,1]
	v_cvt_pk_bf16_f32 v166, v166, v167
	v_cvt_pk_bf16_f32 v167, v168, v169
	v_cvt_pk_bf16_f32 v168, v174, v175
	v_cvt_pk_bf16_f32 v169, v172, v173
	global_store_dwordx4 v[170:171], v[166:169], off
	v_pk_mul_f32 v[172:173], v[156:157], v[66:67] op_sel_hi:[0,1]
	v_pk_mul_f32 v[174:175], v[156:157], v[64:65] op_sel_hi:[0,1]
	v_pk_mul_f32 v[168:169], v[156:157], v[70:71] op_sel_hi:[0,1]
	v_pk_mul_f32 v[166:167], v[156:157], v[68:69] op_sel_hi:[0,1]
	v_cvt_pk_bf16_f32 v166, v166, v167
	v_cvt_pk_bf16_f32 v167, v168, v169
	v_cvt_pk_bf16_f32 v168, v174, v175
	v_cvt_pk_bf16_f32 v169, v172, v173
	global_store_dwordx4 v[170:171], v[166:169], off offset:256
	v_pk_mul_f32 v[172:173], v[156:157], v[58:59] op_sel_hi:[0,1]
	s_mov_b32 s2, 0x40000
	v_pk_mul_f32 v[168:169], v[156:157], v[62:63] op_sel_hi:[0,1]
	v_pk_mul_f32 v[166:167], v[156:157], v[60:61] op_sel_hi:[0,1]
	v_pk_mul_f32 v[174:175], v[156:157], v[56:57] op_sel_hi:[0,1]
	v_cvt_pk_bf16_f32 v166, v166, v167
	v_cvt_pk_bf16_f32 v167, v168, v169
	v_cvt_pk_bf16_f32 v169, v172, v173
	v_add_co_u32_e32 v172, vcc, s2, v158
	v_cvt_pk_bf16_f32 v168, v174, v175
	s_nop 0
	v_addc_co_u32_e32 v173, vcc, 0, v159, vcc
	s_mov_b64 s[28:29], 0x40000
	global_store_dwordx4 v[172:173], v[166:169], off
	v_pk_mul_f32 v[172:173], v[156:157], v[42:43] op_sel_hi:[0,1]
	v_pk_mul_f32 v[174:175], v[156:157], v[40:41] op_sel_hi:[0,1]
	v_pk_mul_f32 v[168:169], v[156:157], v[50:51] op_sel_hi:[0,1]
	v_pk_mul_f32 v[166:167], v[156:157], v[48:49] op_sel_hi:[0,1]
	v_lshl_add_u64 v[170:171], v[158:159], 0, s[28:29]
	v_cvt_pk_bf16_f32 v166, v166, v167
	v_cvt_pk_bf16_f32 v167, v168, v169
	v_cvt_pk_bf16_f32 v168, v174, v175
	v_cvt_pk_bf16_f32 v169, v172, v173
	global_store_dwordx4 v[170:171], v[166:169], off offset:256
	v_pk_mul_f32 v[172:173], v[156:157], v[46:47] op_sel_hi:[0,1]
	v_pk_mul_f32 v[174:175], v[156:157], v[44:45] op_sel_hi:[0,1]
	v_pk_mul_f32 v[168:169], v[156:157], v[54:55] op_sel_hi:[0,1]
	v_pk_mul_f32 v[166:167], v[156:157], v[52:53] op_sel_hi:[0,1]
	v_cvt_pk_bf16_f32 v166, v166, v167
	v_cvt_pk_bf16_f32 v167, v168, v169
	v_cvt_pk_bf16_f32 v169, v172, v173
	v_add_co_u32_e32 v172, vcc, s46, v158
	v_cvt_pk_bf16_f32 v168, v174, v175
	s_nop 0
	v_addc_co_u32_e32 v173, vcc, 0, v159, vcc
	s_mov_b64 s[28:29], 0x48000
	global_store_dwordx4 v[172:173], v[166:169], off
	v_pk_mul_f32 v[172:173], v[156:157], v[26:27] op_sel_hi:[0,1]
	v_pk_mul_f32 v[174:175], v[156:157], v[24:25] op_sel_hi:[0,1]
	v_pk_mul_f32 v[168:169], v[156:157], v[34:35] op_sel_hi:[0,1]
	v_pk_mul_f32 v[166:167], v[156:157], v[32:33] op_sel_hi:[0,1]
	v_lshl_add_u64 v[170:171], v[158:159], 0, s[28:29]
	v_cvt_pk_bf16_f32 v166, v166, v167
	v_cvt_pk_bf16_f32 v167, v168, v169
	v_cvt_pk_bf16_f32 v168, v174, v175
	v_cvt_pk_bf16_f32 v169, v172, v173
	global_store_dwordx4 v[170:171], v[166:169], off offset:256
	v_pk_mul_f32 v[172:173], v[156:157], v[30:31] op_sel_hi:[0,1]
	v_pk_mul_f32 v[174:175], v[156:157], v[28:29] op_sel_hi:[0,1]
	v_pk_mul_f32 v[168:169], v[156:157], v[38:39] op_sel_hi:[0,1]
	v_pk_mul_f32 v[166:167], v[156:157], v[36:37] op_sel_hi:[0,1]
	v_cvt_pk_bf16_f32 v166, v166, v167
	v_cvt_pk_bf16_f32 v167, v168, v169
	v_cvt_pk_bf16_f32 v169, v172, v173
	v_add_co_u32_e32 v172, vcc, s47, v158
	v_cvt_pk_bf16_f32 v168, v174, v175
	s_nop 0
	v_addc_co_u32_e32 v173, vcc, 0, v159, vcc
	global_store_dwordx4 v[172:173], v[166:169], off
	v_pk_mul_f32 v[172:173], v[156:157], v[10:11] op_sel_hi:[0,1]
	v_pk_mul_f32 v[174:175], v[156:157], v[8:9] op_sel_hi:[0,1]
	v_pk_mul_f32 v[168:169], v[156:157], v[18:19] op_sel_hi:[0,1]
	v_pk_mul_f32 v[166:167], v[156:157], v[16:17] op_sel_hi:[0,1]
	v_lshl_add_u64 v[170:171], v[158:159], 0, s[6:7]
	v_cvt_pk_bf16_f32 v166, v166, v167
	v_cvt_pk_bf16_f32 v167, v168, v169
	v_cvt_pk_bf16_f32 v168, v174, v175
	v_cvt_pk_bf16_f32 v169, v172, v173
	global_store_dwordx4 v[170:171], v[166:169], off offset:256
	v_lshl_add_u64 v[170:171], v[158:159], 0, s[8:9]
	v_pk_mul_f32 v[172:173], v[156:157], v[14:15] op_sel_hi:[0,1]
	v_pk_mul_f32 v[168:169], v[156:157], v[22:23] op_sel_hi:[0,1]
	v_pk_mul_f32 v[166:167], v[156:157], v[20:21] op_sel_hi:[0,1]
	v_pk_mul_f32 v[174:175], v[156:157], v[12:13] op_sel_hi:[0,1]
	v_add_co_u32_e32 v158, vcc, s48, v158
	v_cvt_pk_bf16_f32 v166, v166, v167
	v_cvt_pk_bf16_f32 v167, v168, v169
	v_cvt_pk_bf16_f32 v168, v174, v175
	v_cvt_pk_bf16_f32 v169, v172, v173
	v_addc_co_u32_e32 v159, vcc, 0, v159, vcc
	global_store_dwordx4 v[158:159], v[166:169], off
	v_pk_mul_f32 v[158:159], v[156:157], v[6:7] op_sel_hi:[0,1]
	v_pk_mul_f32 v[172:173], v[156:157], v[0:1] op_sel_hi:[0,1]
	v_pk_mul_f32 v[166:167], v[156:157], v[4:5] op_sel_hi:[0,1]
	v_pk_mul_f32 v[168:169], v[156:157], v[2:3] op_sel_hi:[0,1]
	v_cvt_pk_bf16_f32 v156, v166, v167
	v_cvt_pk_bf16_f32 v157, v158, v159
	v_cvt_pk_bf16_f32 v158, v172, v173
	v_cvt_pk_bf16_f32 v159, v168, v169
	global_store_dwordx4 v[170:171], v[156:159], off offset:256

; #define PG8_STAGE(bufoff, gbase, voff) do { _Pragma("unroll") for (int _i = 0; _i < 2; ++_i) \
;         __builtin_amdgcn_global_load_lds((const unsigned*)((const char*)(gbase) + (voff)[_i]), (LAS unsigned*)(lds + (bufoff) + ldsw + _i * 8192), 16, 0, 0); } while (0)
; #define PG8_LDA(dst, b, h) do { _Pragma("unroll") for (int m = 0; m < 4; ++m) _Pragma("unroll") for (int k = 0; k < 2; ++k) dst[m][k] = *(const LAS bf16x8*)(lds + PG8_SA(b, h) + aoff + m * 2048 + k * 1024); } while (0)
; #define PG8_LDB(dst, b, h) do { _Pragma("unroll") for (int n = 0; n < 2; ++n) _Pragma("unroll") for (int k = 0; k < 2; ++k) dst[n][k] = *(const LAS bf16x8*)(lds + PG8_SB(b, h) + boff + n * 2048 + k * 1024); } while (0)
; #define PG8_WAIT_V(n) asm volatile("s_waitcnt vmcnt(" #n ")" ::: "memory")
; #define PG8_WAIT_L(n) asm volatile("s_waitcnt lgkmcnt(" #n ")" ::: "memory")
; #define PG8_BAR __builtin_amdgcn_s_barrier()
; #define PG8_SCHED __builtin_amdgcn_sched_barrier(0)
; template <class Epi>
; __device__ __forceinline__ void gemm_phase(LAS unsigned char* lds, const bf16_t* A, int lda, const bf16_t* Bt, int ldb, int M, int N, int K, int asel, const Epi& E, const int fixed_round = -1) {
;     ...
;             const char* a1 = cA + (size_t)(t + 1) * kstep;
;             const char* a2 = last ? nA : cA + (size_t)(t + 2) * kstep; const char* b2 = last ? nB : cB + (size_t)(t + 2) * kstep;
;             const char* a3 = a2 + kstep; const char* b3 = b2 + kstep;
;             PG8_LDB(B0, 0, 0); PG8_SCHED; PG8_LDA(At, 0, 0); PG8_STAGE(PG8_SA(1, 1), a1 + hstepA, voffA);
;             PG8_WAIT_L(8); PG8_BAR; PG8_WAIT_L(0); PG8_MMA(0, 0, At, B0); PG8_BAR; PG8_SCHED;
;             PG8_LDB(B1, 0, 1); PG8_STAGE(PG8_SB(0, 0), b2, voffB);
;             PG8_BAR; PG8_WAIT_L(0); PG8_MMA(0, 1, At, B1); PG8_BAR;
;             PG8_LDA(At, 0, 1); PG8_STAGE(PG8_SA(0, 0), a2, voffA);
;             PG8_BAR; PG8_WAIT_L(0); PG8_MMA(1, 0, At, B0); PG8_BAR; PG8_SCHED;
;             PG8_STAGE(PG8_SB(0, 1), b2 + hstepB, voffB);
;             PG8_WAIT_V(6); PG8_BAR; PG8_MMA(1, 1, At, B1); PG8_BAR;
.LBB0_440:
	s_add_i32 s34, s34, 2
	s_add_u32 s16, s12, s14
	ds_read_b128 v[150:153], v141
	ds_read_b128 v[154:157], v141 offset:1024
	ds_read_b128 v[160:163], v141 offset:2048
	ds_read_b128 v[168:171], v141 offset:3072
	s_addc_u32 s17, s13, s15
	s_add_u32 s16, s16, 0x14500100
	s_addc_u32 s17, s17, 0
	s_add_u32 s46, s26, s14
	s_addc_u32 s47, s27, s15
	s_cmpk_eq_i32 s14, 0xf00
	s_cselect_b32 s19, s1, s17
	s_cselect_b32 s18, s0, s16
	s_cselect_b32 s17, s3, s47
	s_cselect_b32 s16, s2, s46
	s_mov_b32 m0, s36
	v_lshl_add_u64 v[146:147], v[136:137], 0, s[14:15]
	ds_read_b128 v[172:175], v142
	ds_read_b128 v[176:179], v142 offset:1024
	ds_read_b128 v[180:183], v142 offset:2048
	ds_read_b128 v[184:187], v142 offset:3072
	ds_read_b128 v[188:191], v142 offset:4096
	ds_read_b128 v[196:199], v142 offset:5120
	ds_read_b128 v[202:205], v142 offset:6144
	ds_read_b128 v[206:209], v142 offset:7168
	global_load_lds_dwordx4 v[146:147], off
	v_lshl_add_u64 v[146:147], v[138:139], 0, s[14:15]
	s_mov_b32 m0, s37
	s_nop 0
	global_load_lds_dwordx4 v[146:147], off
	s_waitcnt lgkmcnt(8)
	s_setprio 1
	s_barrier
	s_waitcnt lgkmcnt(0)
	v_mfma_f32_16x16x32_bf16 v[124:127], v[150:153], v[172:175], v[124:127]
	v_mfma_f32_16x16x32_bf16 v[120:123], v[160:163], v[172:175], v[120:123]
	v_mfma_f32_16x16x32_bf16 v[116:119], v[150:153], v[180:183], v[116:119]
	v_mfma_f32_16x16x32_bf16 v[112:115], v[160:163], v[180:183], v[112:115]
	v_mfma_f32_16x16x32_bf16 v[100:103], v[150:153], v[188:191], v[100:103]
	v_mfma_f32_16x16x32_bf16 v[92:95], v[160:163], v[188:191], v[92:95]
	v_mfma_f32_16x16x32_bf16 v[84:87], v[150:153], v[202:205], v[84:87]
	v_mfma_f32_16x16x32_bf16 v[76:79], v[160:163], v[202:205], v[76:79]
	v_mfma_f32_16x16x32_bf16 v[124:127], v[154:157], v[176:179], v[124:127]
	v_mfma_f32_16x16x32_bf16 v[120:123], v[168:171], v[176:179], v[120:123]
	v_mfma_f32_16x16x32_bf16 v[116:119], v[154:157], v[184:187], v[116:119]
	v_mfma_f32_16x16x32_bf16 v[112:115], v[168:171], v[184:187], v[112:115]
	v_mfma_f32_16x16x32_bf16 v[100:103], v[154:157], v[196:199], v[100:103]
	v_mfma_f32_16x16x32_bf16 v[92:95], v[168:171], v[196:199], v[92:95]
	v_mfma_f32_16x16x32_bf16 v[84:87], v[154:157], v[206:209], v[84:87]
	v_mfma_f32_16x16x32_bf16 v[76:79], v[168:171], v[206:209], v[76:79]
	s_setprio 0
	s_barrier
	s_mov_b32 m0, s38
	s_add_u32 s98, s16, s10
	s_addc_u32 s99, s17, s11
	ds_read_b128 v[210:213], v143
	ds_read_b128 v[214:217], v143 offset:1024
	ds_read_b128 v[218:221], v143 offset:2048
	ds_read_b128 v[222:225], v143 offset:3072
	global_load_lds_dwordx4 v130, s[16:17]
	s_mov_b32 m0, s39
	s_nop 0
	global_load_lds_dwordx4 v134, s[16:17]
	s_setprio 1
	s_barrier
	s_waitcnt lgkmcnt(0)
	v_mfma_f32_16x16x32_bf16 v[108:111], v[210:213], v[172:175], v[108:111]
	v_mfma_f32_16x16x32_bf16 v[104:107], v[218:221], v[172:175], v[104:107]
	v_mfma_f32_16x16x32_bf16 v[96:99], v[210:213], v[180:183], v[96:99]
	v_mfma_f32_16x16x32_bf16 v[88:91], v[218:221], v[180:183], v[88:91]
	v_mfma_f32_16x16x32_bf16 v[80:83], v[210:213], v[188:191], v[80:83]
	v_mfma_f32_16x16x32_bf16 v[72:75], v[218:221], v[188:191], v[72:75]
	v_mfma_f32_16x16x32_bf16 v[68:71], v[210:213], v[202:205], v[68:71]
	v_mfma_f32_16x16x32_bf16 v[64:67], v[218:221], v[202:205], v[64:67]
	v_mfma_f32_16x16x32_bf16 v[108:111], v[214:217], v[176:179], v[108:111]
	v_mfma_f32_16x16x32_bf16 v[104:107], v[222:225], v[176:179], v[104:107]
	v_mfma_f32_16x16x32_bf16 v[96:99], v[214:217], v[184:187], v[96:99]
	v_mfma_f32_16x16x32_bf16 v[88:91], v[222:225], v[184:187], v[88:91]
	v_mfma_f32_16x16x32_bf16 v[80:83], v[214:217], v[196:199], v[80:83]
	v_mfma_f32_16x16x32_bf16 v[72:75], v[222:225], v[196:199], v[72:75]
	v_mfma_f32_16x16x32_bf16 v[68:71], v[214:217], v[206:209], v[68:71]
	v_mfma_f32_16x16x32_bf16 v[64:67], v[222:225], v[206:209], v[64:67]
	s_setprio 0
	s_mov_b32 m0, s25
	s_add_u32 s100, s18, s10
	s_addc_u32 s101, s19, s11
	s_barrier
	ds_read_b128 v[172:175], v142 offset:16384
	ds_read_b128 v[176:179], v142 offset:17408
	ds_read_b128 v[180:183], v142 offset:18432
	ds_read_b128 v[184:187], v142 offset:19456
	ds_read_b128 v[188:191], v142 offset:20480
	ds_read_b128 v[196:199], v142 offset:21504
	ds_read_b128 v[202:205], v142 offset:22528
	ds_read_b128 v[206:209], v142 offset:23552
	global_load_lds_dwordx4 v128, s[18:19]
	s_mov_b32 m0, s28
	s_nop 0
	global_load_lds_dwordx4 v132, s[18:19]
	s_setprio 1
	s_barrier
	s_waitcnt lgkmcnt(0)
	v_mfma_f32_16x16x32_bf16 v[60:63], v[150:153], v[172:175], v[60:63]
	v_mfma_f32_16x16x32_bf16 v[56:59], v[160:163], v[172:175], v[56:59]
	v_mfma_f32_16x16x32_bf16 v[52:55], v[150:153], v[180:183], v[52:55]
	v_mfma_f32_16x16x32_bf16 v[44:47], v[160:163], v[180:183], v[44:47]
	v_mfma_f32_16x16x32_bf16 v[36:39], v[150:153], v[188:191], v[36:39]
	v_mfma_f32_16x16x32_bf16 v[28:31], v[160:163], v[188:191], v[28:31]
	v_mfma_f32_16x16x32_bf16 v[20:23], v[150:153], v[202:205], v[20:23]
	v_mfma_f32_16x16x32_bf16 v[12:15], v[160:163], v[202:205], v[12:15]
	v_mfma_f32_16x16x32_bf16 v[60:63], v[154:157], v[176:179], v[60:63]
	v_mfma_f32_16x16x32_bf16 v[56:59], v[168:171], v[176:179], v[56:59]
	v_mfma_f32_16x16x32_bf16 v[52:55], v[154:157], v[184:187], v[52:55]
	v_mfma_f32_16x16x32_bf16 v[44:47], v[168:171], v[184:187], v[44:47]
	v_mfma_f32_16x16x32_bf16 v[36:39], v[154:157], v[196:199], v[36:39]
	v_mfma_f32_16x16x32_bf16 v[28:31], v[168:171], v[196:199], v[28:31]
	v_mfma_f32_16x16x32_bf16 v[20:23], v[154:157], v[206:209], v[20:23]
	v_mfma_f32_16x16x32_bf16 v[12:15], v[168:171], v[206:209], v[12:15]
	s_setprio 0
	s_barrier
; #define PG8_STAGE(bufoff, gbase, voff) do { _Pragma("unroll") for (int _i = 0; _i < 2; ++_i) \
;         __builtin_amdgcn_global_load_lds((const unsigned*)((const char*)(gbase) + (voff)[_i]), (LAS unsigned*)(lds + (bufoff) + ldsw + _i * 8192), 16, 0, 0); } while (0)
; #define PG8_LDA(dst, b, h) do { _Pragma("unroll") for (int m = 0; m < 4; ++m) _Pragma("unroll") for (int k = 0; k < 2; ++k) dst[m][k] = *(const LAS bf16x8*)(lds + PG8_SA(b, h) + aoff + m * 2048 + k * 1024); } while (0)
; #define PG8_LDB(dst, b, h) do { _Pragma("unroll") for (int n = 0; n < 2; ++n) _Pragma("unroll") for (int k = 0; k < 2; ++k) dst[n][k] = *(const LAS bf16x8*)(lds + PG8_SB(b, h) + boff + n * 2048 + k * 1024); } while (0)
; #define PG8_WAIT_V(n) asm volatile("s_waitcnt vmcnt(" #n ")" ::: "memory")
; #define PG8_WAIT_L(n) asm volatile("s_waitcnt lgkmcnt(" #n ")" ::: "memory")
; #define PG8_BAR __builtin_amdgcn_s_barrier()
; #define PG8_SCHED __builtin_amdgcn_sched_barrier(0)
; template <class Epi>
; __device__ __forceinline__ void gemm_phase(LAS unsigned char* lds, const bf16_t* A, int lda, const bf16_t* Bt, int ldb, int M, int N, int K, int asel, const Epi& E, const int fixed_round = -1) {
;     ...
;             PG8_STAGE(PG8_SB(0, 1), b2 + hstepB, voffB);
;             PG8_WAIT_V(6); PG8_BAR; PG8_MMA(1, 1, At, B1); PG8_BAR;
;             PG8_LDB(B0, 1, 0); PG8_SCHED; PG8_LDA(At, 1, 0); PG8_STAGE(PG8_SA(0, 1), a2 + hstepA, voffA);
;             PG8_WAIT_L(8); PG8_BAR; PG8_WAIT_L(0); PG8_MMA(0, 0, At, B0); PG8_BAR; PG8_SCHED;
;             PG8_LDB(B1, 1, 1); PG8_STAGE(PG8_SB(1, 0), b3, voffB);
;             PG8_BAR; PG8_WAIT_L(0); PG8_MMA(0, 1, At, B1); PG8_BAR;
;             PG8_LDA(At, 1, 1); PG8_STAGE(PG8_SA(1, 0), a3, voffA);
	s_add_u32 s46, s16, 0x80000
	s_addc_u32 s47, s17, 0
	s_mov_b32 m0, s40
	s_nop 0
	global_load_lds_dwordx4 v130, s[46:47]
	s_mov_b32 m0, s41
	s_nop 0
	global_load_lds_dwordx4 v134, s[46:47]
	s_waitcnt vmcnt(6)
	s_setprio 1
	s_barrier
	v_mfma_f32_16x16x32_bf16 v[48:51], v[210:213], v[172:175], v[48:51]
	v_mfma_f32_16x16x32_bf16 v[40:43], v[218:221], v[172:175], v[40:43]
	v_mfma_f32_16x16x32_bf16 v[32:35], v[210:213], v[180:183], v[32:35]
	v_mfma_f32_16x16x32_bf16 v[24:27], v[218:221], v[180:183], v[24:27]
	v_mfma_f32_16x16x32_bf16 v[16:19], v[210:213], v[188:191], v[16:19]
	v_mfma_f32_16x16x32_bf16 v[8:11], v[218:221], v[188:191], v[8:11]
	v_mfma_f32_16x16x32_bf16 v[4:7], v[210:213], v[202:205], v[4:7]
	v_mfma_f32_16x16x32_bf16 v[0:3], v[218:221], v[202:205], v[0:3]
	v_mfma_f32_16x16x32_bf16 v[48:51], v[214:217], v[176:179], v[48:51]
	v_mfma_f32_16x16x32_bf16 v[40:43], v[222:225], v[176:179], v[40:43]
	v_mfma_f32_16x16x32_bf16 v[32:35], v[214:217], v[184:187], v[32:35]
	v_mfma_f32_16x16x32_bf16 v[24:27], v[222:225], v[184:187], v[24:27]
	v_mfma_f32_16x16x32_bf16 v[16:19], v[214:217], v[196:199], v[16:19]
	v_mfma_f32_16x16x32_bf16 v[8:11], v[222:225], v[196:199], v[8:11]
	v_mfma_f32_16x16x32_bf16 v[4:7], v[214:217], v[206:209], v[4:7]
	v_mfma_f32_16x16x32_bf16 v[0:3], v[222:225], v[206:209], v[0:3]
	s_setprio 0
	s_barrier
	ds_read_b128 v[150:153], v144
	ds_read_b128 v[154:157], v144 offset:1024
	ds_read_b128 v[160:163], v144 offset:2048
	ds_read_b128 v[168:171], v144 offset:3072
	s_add_u32 s18, s18, 0x80000
	s_addc_u32 s19, s19, 0
	s_mov_b32 m0, s29
	ds_read_b128 v[172:175], v142 offset:32768
	ds_read_b128 v[176:179], v142 offset:33792
	ds_read_b128 v[180:183], v142 offset:34816
	ds_read_b128 v[184:187], v142 offset:35840
	ds_read_b128 v[188:191], v142 offset:36864
	ds_read_b128 v[196:199], v142 offset:37888
	ds_read_b128 v[202:205], v142 offset:38912
	ds_read_b128 v[206:209], v142 offset:39936
	global_load_lds_dwordx4 v128, s[18:19]
	s_mov_b32 m0, s30
	s_nop 0
	global_load_lds_dwordx4 v132, s[18:19]
	s_waitcnt lgkmcnt(8)
	s_setprio 1
	s_barrier
	s_waitcnt lgkmcnt(0)
	v_mfma_f32_16x16x32_bf16 v[124:127], v[150:153], v[172:175], v[124:127]
	v_mfma_f32_16x16x32_bf16 v[120:123], v[160:163], v[172:175], v[120:123]
	v_mfma_f32_16x16x32_bf16 v[116:119], v[150:153], v[180:183], v[116:119]
	v_mfma_f32_16x16x32_bf16 v[112:115], v[160:163], v[180:183], v[112:115]
	v_mfma_f32_16x16x32_bf16 v[100:103], v[150:153], v[188:191], v[100:103]
	v_mfma_f32_16x16x32_bf16 v[92:95], v[160:163], v[188:191], v[92:95]
	v_mfma_f32_16x16x32_bf16 v[84:87], v[150:153], v[202:205], v[84:87]
	v_mfma_f32_16x16x32_bf16 v[76:79], v[160:163], v[202:205], v[76:79]
	v_mfma_f32_16x16x32_bf16 v[124:127], v[154:157], v[176:179], v[124:127]
	v_mfma_f32_16x16x32_bf16 v[120:123], v[168:171], v[176:179], v[120:123]
	v_mfma_f32_16x16x32_bf16 v[116:119], v[154:157], v[184:187], v[116:119]
	v_mfma_f32_16x16x32_bf16 v[112:115], v[168:171], v[184:187], v[112:115]
	v_mfma_f32_16x16x32_bf16 v[100:103], v[154:157], v[196:199], v[100:103]
	v_mfma_f32_16x16x32_bf16 v[92:95], v[168:171], v[196:199], v[92:95]
	v_mfma_f32_16x16x32_bf16 v[84:87], v[154:157], v[206:209], v[84:87]
	v_mfma_f32_16x16x32_bf16 v[76:79], v[168:171], v[206:209], v[76:79]
	s_setprio 0
	s_barrier
	s_mov_b32 m0, s42
	ds_read_b128 v[210:213], v145
	ds_read_b128 v[214:217], v145 offset:1024
	ds_read_b128 v[218:221], v145 offset:2048
	ds_read_b128 v[222:225], v145 offset:3072
	global_load_lds_dwordx4 v130, s[98:99]
	s_mov_b32 m0, s43
	s_nop 0
	global_load_lds_dwordx4 v134, s[98:99]
	s_setprio 1
	s_barrier
	s_waitcnt lgkmcnt(0)
	v_mfma_f32_16x16x32_bf16 v[108:111], v[210:213], v[172:175], v[108:111]
	v_mfma_f32_16x16x32_bf16 v[104:107], v[218:221], v[172:175], v[104:107]
	v_mfma_f32_16x16x32_bf16 v[96:99], v[210:213], v[180:183], v[96:99]
	v_mfma_f32_16x16x32_bf16 v[88:91], v[218:221], v[180:183], v[88:91]
	v_mfma_f32_16x16x32_bf16 v[80:83], v[210:213], v[188:191], v[80:83]
	v_mfma_f32_16x16x32_bf16 v[72:75], v[218:221], v[188:191], v[72:75]
	v_mfma_f32_16x16x32_bf16 v[68:71], v[210:213], v[202:205], v[68:71]
	v_mfma_f32_16x16x32_bf16 v[64:67], v[218:221], v[202:205], v[64:67]
	v_mfma_f32_16x16x32_bf16 v[108:111], v[214:217], v[176:179], v[108:111]
	v_mfma_f32_16x16x32_bf16 v[104:107], v[222:225], v[176:179], v[104:107]
	v_mfma_f32_16x16x32_bf16 v[96:99], v[214:217], v[184:187], v[96:99]
	v_mfma_f32_16x16x32_bf16 v[88:91], v[222:225], v[184:187], v[88:91]
	v_mfma_f32_16x16x32_bf16 v[80:83], v[214:217], v[196:199], v[80:83]
	v_mfma_f32_16x16x32_bf16 v[72:75], v[222:225], v[196:199], v[72:75]
	v_mfma_f32_16x16x32_bf16 v[68:71], v[214:217], v[206:209], v[68:71]
	v_mfma_f32_16x16x32_bf16 v[64:67], v[222:225], v[206:209], v[64:67]
	s_setprio 0
	s_mov_b32 m0, s31
	s_barrier
	ds_read_b128 v[172:175], v142 offset:49152
	ds_read_b128 v[176:179], v142 offset:50176
	ds_read_b128 v[180:183], v142 offset:51200
	ds_read_b128 v[184:187], v142 offset:52224
	ds_read_b128 v[188:191], v142 offset:53248
	ds_read_b128 v[196:199], v142 offset:54272
	ds_read_b128 v[202:205], v142 offset:55296
	ds_read_b128 v[206:209], v142 offset:56320
	global_load_lds_dwordx4 v128, s[100:101]
	s_mov_b32 m0, s33
	s_nop 0
	global_load_lds_dwordx4 v132, s[100:101]
	s_setprio 1
	s_barrier
; #define LAS __attribute__((address_space(3)))
; #define PG8_STAGE(bufoff, gbase, voff) do { _Pragma("unroll") for (int _i = 0; _i < 2; ++_i) \
;         __builtin_amdgcn_global_load_lds((const unsigned*)((const char*)(gbase) + (voff)[_i]), (LAS unsigned*)(lds + (bufoff) + ldsw + _i * 8192), 16, 0, 0); } while (0)
; #define PG8_WAIT_V(n) asm volatile("s_waitcnt vmcnt(" #n ")" ::: "memory")
; #define PG8_WAIT_L(n) asm volatile("s_waitcnt lgkmcnt(" #n ")" ::: "memory")
; #define PG8_BAR __builtin_amdgcn_s_barrier()
; #define PG8_SCHED __builtin_amdgcn_sched_barrier(0)
; template <class Epi>
; __device__ __forceinline__ void gemm_phase(LAS unsigned char* lds, const bf16_t* A, int lda, const bf16_t* Bt, int ldb, int M, int N, int K, int asel, const Epi& E, const int fixed_round = -1) {
;     ...
;             PG8_BAR; PG8_WAIT_L(0); PG8_MMA(1, 0, At, B0); PG8_BAR; PG8_SCHED;
;             PG8_STAGE(PG8_SB(1, 1), b3 + hstepB, voffB);
;             PG8_WAIT_V(6); PG8_BAR; PG8_MMA(1, 1, At, B1); PG8_BAR;
;             if constexpr (Epi::HEADSCALE) {
;                 if (t & 2) {
;                     const LAS float* rt = (const LAS float*)(lds + L_RT) + (t >> 2);
; #pragma unroll
;                     for (int ai = 0; ai < 2; ++ai)
; #pragma unroll
;                         for (int m = 0; m < 4; ++m) { const float f = rt[(ai * HALF + wr * 64 + m * 16 + fr) * 8];
; #pragma unroll
;                             for (int bj = 0; bj < 2; ++bj)
; #pragma unroll
;                                 for (int n = 0; n < 2; ++n) acc[ai][bj][m][n] *= f; }
;                 }
;             }
	s_waitcnt lgkmcnt(0)
	v_mfma_f32_16x16x32_bf16 v[60:63], v[150:153], v[172:175], v[60:63]
	v_mfma_f32_16x16x32_bf16 v[56:59], v[160:163], v[172:175], v[56:59]
	v_mfma_f32_16x16x32_bf16 v[52:55], v[150:153], v[180:183], v[52:55]
	v_mfma_f32_16x16x32_bf16 v[44:47], v[160:163], v[180:183], v[44:47]
	v_mfma_f32_16x16x32_bf16 v[36:39], v[150:153], v[188:191], v[36:39]
	v_mfma_f32_16x16x32_bf16 v[28:31], v[160:163], v[188:191], v[28:31]
	v_mfma_f32_16x16x32_bf16 v[20:23], v[150:153], v[202:205], v[20:23]
	v_mfma_f32_16x16x32_bf16 v[12:15], v[160:163], v[202:205], v[12:15]
	v_mfma_f32_16x16x32_bf16 v[60:63], v[154:157], v[176:179], v[60:63]
	v_mfma_f32_16x16x32_bf16 v[56:59], v[168:171], v[176:179], v[56:59]
	v_mfma_f32_16x16x32_bf16 v[52:55], v[154:157], v[184:187], v[52:55]
	v_mfma_f32_16x16x32_bf16 v[44:47], v[168:171], v[184:187], v[44:47]
	v_mfma_f32_16x16x32_bf16 v[36:39], v[154:157], v[196:199], v[36:39]
	v_mfma_f32_16x16x32_bf16 v[28:31], v[168:171], v[196:199], v[28:31]
	v_mfma_f32_16x16x32_bf16 v[20:23], v[154:157], v[206:209], v[20:23]
	v_mfma_f32_16x16x32_bf16 v[12:15], v[168:171], v[206:209], v[12:15]
	s_setprio 0
	s_barrier
	s_add_u32 s16, s16, 0x80080
	s_addc_u32 s17, s17, 0
	s_mov_b32 m0, s44
	s_nop 0
	global_load_lds_dwordx4 v130, s[16:17]
	s_mov_b32 m0, s45
	s_nop 0
	global_load_lds_dwordx4 v134, s[16:17]
	s_waitcnt vmcnt(6)
	s_setprio 1
	s_barrier
	v_mfma_f32_16x16x32_bf16 v[48:51], v[210:213], v[172:175], v[48:51]
	v_mfma_f32_16x16x32_bf16 v[40:43], v[218:221], v[172:175], v[40:43]
	v_mfma_f32_16x16x32_bf16 v[32:35], v[210:213], v[180:183], v[32:35]
	v_mfma_f32_16x16x32_bf16 v[24:27], v[218:221], v[180:183], v[24:27]
	v_mfma_f32_16x16x32_bf16 v[16:19], v[210:213], v[188:191], v[16:19]
	v_mfma_f32_16x16x32_bf16 v[8:11], v[218:221], v[188:191], v[8:11]
	v_mfma_f32_16x16x32_bf16 v[4:7], v[210:213], v[202:205], v[4:7]
	v_mfma_f32_16x16x32_bf16 v[0:3], v[218:221], v[202:205], v[0:3]
	v_mfma_f32_16x16x32_bf16 v[48:51], v[214:217], v[176:179], v[48:51]
	v_mfma_f32_16x16x32_bf16 v[40:43], v[222:225], v[176:179], v[40:43]
	v_mfma_f32_16x16x32_bf16 v[32:35], v[214:217], v[184:187], v[32:35]
	v_mfma_f32_16x16x32_bf16 v[24:27], v[222:225], v[184:187], v[24:27]
	v_mfma_f32_16x16x32_bf16 v[16:19], v[214:217], v[196:199], v[16:19]
	v_mfma_f32_16x16x32_bf16 v[8:11], v[222:225], v[196:199], v[8:11]
	v_mfma_f32_16x16x32_bf16 v[4:7], v[214:217], v[206:209], v[4:7]
	v_mfma_f32_16x16x32_bf16 v[0:3], v[222:225], v[206:209], v[0:3]
	s_setprio 0
	s_bitcmp0_b32 s34, 1
	s_barrier
	s_cbranch_scc1 .LBB0_439
	s_and_b32 s16, s34, -4
	v_add_u32_e32 v148, s16, v140
	ds_read2st64_b32 v[146:147], v148 offset1:2
	ds_read2st64_b32 v[150:151], v148 offset0:4 offset1:6
	s_waitcnt lgkmcnt(0)
	v_pk_mul_f32 v[126:127], v[126:127], v[146:147] op_sel_hi:[1,0]
	v_pk_mul_f32 v[124:125], v[124:125], v[146:147] op_sel_hi:[1,0]
	v_pk_mul_f32 v[122:123], v[122:123], v[146:147] op_sel_hi:[1,0]
	v_pk_mul_f32 v[120:121], v[120:121], v[146:147] op_sel_hi:[1,0]
	v_pk_mul_f32 v[110:111], v[110:111], v[146:147] op_sel_hi:[1,0]
	v_pk_mul_f32 v[108:109], v[108:109], v[146:147] op_sel_hi:[1,0]
	v_pk_mul_f32 v[106:107], v[106:107], v[146:147] op_sel_hi:[1,0]
	v_pk_mul_f32 v[104:105], v[104:105], v[146:147] op_sel_hi:[1,0]
	v_mov_b32_e32 v146, v147
	v_pk_mul_f32 v[118:119], v[118:119], v[146:147] op_sel_hi:[1,0]
	v_pk_mul_f32 v[116:117], v[116:117], v[146:147] op_sel_hi:[1,0]
	v_pk_mul_f32 v[114:115], v[114:115], v[146:147] op_sel_hi:[1,0]
	v_pk_mul_f32 v[112:113], v[112:113], v[146:147] op_sel_hi:[1,0]
	v_pk_mul_f32 v[98:99], v[98:99], v[146:147] op_sel_hi:[1,0]
	v_pk_mul_f32 v[96:97], v[96:97], v[146:147] op_sel_hi:[1,0]
	v_pk_mul_f32 v[90:91], v[90:91], v[146:147] op_sel_hi:[1,0]
	v_pk_mul_f32 v[88:89], v[88:89], v[146:147] op_sel_hi:[1,0]
	v_pk_mul_f32 v[102:103], v[102:103], v[150:151] op_sel_hi:[1,0]
	v_pk_mul_f32 v[100:101], v[100:101], v[150:151] op_sel_hi:[1,0]
	v_pk_mul_f32 v[94:95], v[94:95], v[150:151] op_sel_hi:[1,0]
	v_pk_mul_f32 v[92:93], v[92:93], v[150:151] op_sel_hi:[1,0]
	v_pk_mul_f32 v[82:83], v[82:83], v[150:151] op_sel_hi:[1,0]
	v_pk_mul_f32 v[80:81], v[80:81], v[150:151] op_sel_hi:[1,0]
	v_pk_mul_f32 v[74:75], v[74:75], v[150:151] op_sel_hi:[1,0]
	v_pk_mul_f32 v[72:73], v[72:73], v[150:151] op_sel_hi:[1,0]
	v_mov_b32_e32 v146, v151
	ds_read2st64_b32 v[150:151], v148 offset0:16 offset1:18
	v_pk_mul_f32 v[86:87], v[86:87], v[146:147] op_sel_hi:[1,0]
	v_pk_mul_f32 v[84:85], v[84:85], v[146:147] op_sel_hi:[1,0]
	v_pk_mul_f32 v[78:79], v[78:79], v[146:147] op_sel_hi:[1,0]
	v_pk_mul_f32 v[76:77], v[76:77], v[146:147] op_sel_hi:[1,0]
	v_pk_mul_f32 v[70:71], v[70:71], v[146:147] op_sel_hi:[1,0]
	v_pk_mul_f32 v[68:69], v[68:69], v[146:147] op_sel_hi:[1,0]
	v_pk_mul_f32 v[66:67], v[66:67], v[146:147] op_sel_hi:[1,0]
	v_pk_mul_f32 v[64:65], v[64:65], v[146:147] op_sel_hi:[1,0]
	s_waitcnt lgkmcnt(0)
	v_pk_mul_f32 v[62:63], v[62:63], v[150:151] op_sel_hi:[1,0]
	v_pk_mul_f32 v[60:61], v[60:61], v[150:151] op_sel_hi:[1,0]
	v_pk_mul_f32 v[58:59], v[58:59], v[150:151] op_sel_hi:[1,0]
	v_pk_mul_f32 v[56:57], v[56:57], v[150:151] op_sel_hi:[1,0]
	v_pk_mul_f32 v[50:51], v[50:51], v[150:151] op_sel_hi:[1,0]
	v_pk_mul_f32 v[48:49], v[48:49], v[150:151] op_sel_hi:[1,0]
	v_pk_mul_f32 v[42:43], v[42:43], v[150:151] op_sel_hi:[1,0]
	v_pk_mul_f32 v[40:41], v[40:41], v[150:151] op_sel_hi:[1,0]
	v_mov_b32_e32 v146, v151
	ds_read2st64_b32 v[150:151], v148 offset0:20 offset1:22
	v_pk_mul_f32 v[54:55], v[54:55], v[146:147] op_sel_hi:[1,0]
	v_pk_mul_f32 v[52:53], v[52:53], v[146:147] op_sel_hi:[1,0]
	v_pk_mul_f32 v[46:47], v[46:47], v[146:147] op_sel_hi:[1,0]
	v_pk_mul_f32 v[44:45], v[44:45], v[146:147] op_sel_hi:[1,0]
	v_pk_mul_f32 v[34:35], v[34:35], v[146:147] op_sel_hi:[1,0]
	v_pk_mul_f32 v[32:33], v[32:33], v[146:147] op_sel_hi:[1,0]
	v_pk_mul_f32 v[26:27], v[26:27], v[146:147] op_sel_hi:[1,0]
	v_pk_mul_f32 v[24:25], v[24:25], v[146:147] op_sel_hi:[1,0]
	s_waitcnt lgkmcnt(0)
	v_mov_b32_e32 v146, v151
	v_pk_mul_f32 v[38:39], v[38:39], v[150:151] op_sel_hi:[1,0]
	v_pk_mul_f32 v[36:37], v[36:37], v[150:151] op_sel_hi:[1,0]
	v_pk_mul_f32 v[30:31], v[30:31], v[150:151] op_sel_hi:[1,0]
	v_pk_mul_f32 v[28:29], v[28:29], v[150:151] op_sel_hi:[1,0]
	v_pk_mul_f32 v[18:19], v[18:19], v[150:151] op_sel_hi:[1,0]
	v_pk_mul_f32 v[16:17], v[16:17], v[150:151] op_sel_hi:[1,0]
	v_pk_mul_f32 v[10:11], v[10:11], v[150:151] op_sel_hi:[1,0]
	v_pk_mul_f32 v[8:9], v[8:9], v[150:151] op_sel_hi:[1,0]
	v_pk_mul_f32 v[22:23], v[22:23], v[146:147] op_sel_hi:[1,0]
	v_pk_mul_f32 v[20:21], v[20:21], v[146:147] op_sel_hi:[1,0]
	v_pk_mul_f32 v[14:15], v[14:15], v[146:147] op_sel_hi:[1,0]
	v_pk_mul_f32 v[12:13], v[12:13], v[146:147] op_sel_hi:[1,0]
	v_pk_mul_f32 v[6:7], v[6:7], v[146:147] op_sel_hi:[1,0]
	v_pk_mul_f32 v[4:5], v[4:5], v[146:147] op_sel_hi:[1,0]
	v_pk_mul_f32 v[2:3], v[2:3], v[146:147] op_sel_hi:[1,0]
	v_pk_mul_f32 v[0:1], v[0:1], v[146:147] op_sel_hi:[1,0]
	s_branch .LBB0_439

; #define PG8_STAGE(bufoff, gbase, voff) do { _Pragma("unroll") for (int _i = 0; _i < 2; ++_i) \
;         __builtin_amdgcn_global_load_lds((const unsigned*)((const char*)(gbase) + (voff)[_i]), (LAS unsigned*)(lds + (bufoff) + ldsw + _i * 8192), 16, 0, 0); } while (0)
; #define PG8_LDA(dst, b, h) do { _Pragma("unroll") for (int m = 0; m < 4; ++m) _Pragma("unroll") for (int k = 0; k < 2; ++k) dst[m][k] = *(const LAS bf16x8*)(lds + PG8_SA(b, h) + aoff + m * 2048 + k * 1024); } while (0)
; #define PG8_LDB(dst, b, h) do { _Pragma("unroll") for (int n = 0; n < 2; ++n) _Pragma("unroll") for (int k = 0; k < 2; ++k) dst[n][k] = *(const LAS bf16x8*)(lds + PG8_SB(b, h) + boff + n * 2048 + k * 1024); } while (0)
; #define PG8_WAIT_V(n) asm volatile("s_waitcnt vmcnt(" #n ")" ::: "memory")
; #define PG8_WAIT_L(n) asm volatile("s_waitcnt lgkmcnt(" #n ")" ::: "memory")
; #define PG8_BAR __builtin_amdgcn_s_barrier()
; #define PG8_SCHED __builtin_amdgcn_sched_barrier(0)
; template <class Epi>
; __device__ __forceinline__ void gemm_phase(LAS unsigned char* lds, const bf16_t* A, int lda, const bf16_t* Bt, int ldb, int M, int N, int K, int asel, const Epi& E, const int fixed_round = -1) {
;     ...
;             const char* a1 = cA + (size_t)(t + 1) * kstep;
;             const char* a2 = last ? nA : cA + (size_t)(t + 2) * kstep; const char* b2 = last ? nB : cB + (size_t)(t + 2) * kstep;
;             const char* a3 = a2 + kstep; const char* b3 = b2 + kstep;
;             PG8_LDB(B0, 0, 0); PG8_SCHED; PG8_LDA(At, 0, 0); PG8_STAGE(PG8_SA(1, 1), a1 + hstepA, voffA);
;             PG8_WAIT_L(8); PG8_BAR; PG8_WAIT_L(0); PG8_MMA(0, 0, At, B0); PG8_BAR; PG8_SCHED;
;             PG8_LDB(B1, 0, 1); PG8_STAGE(PG8_SB(0, 0), b2, voffB);
;             PG8_BAR; PG8_WAIT_L(0); PG8_MMA(0, 1, At, B1); PG8_BAR;
;             PG8_LDA(At, 0, 1); PG8_STAGE(PG8_SA(0, 0), a2, voffA);
;             PG8_BAR; PG8_WAIT_L(0); PG8_MMA(1, 0, At, B0); PG8_BAR; PG8_SCHED;
;             PG8_STAGE(PG8_SB(0, 1), b2 + hstepB, voffB);
;             PG8_WAIT_V(6); PG8_BAR; PG8_MMA(1, 1, At, B1); PG8_BAR;
.LBB0_487:
	s_add_i32 s35, s35, 2
	s_add_u32 s18, s6, s14
	ds_read_b128 v[150:153], v141
	ds_read_b128 v[154:157], v141 offset:1024
	ds_read_b128 v[160:163], v141 offset:2048
	ds_read_b128 v[168:171], v141 offset:3072
	s_addc_u32 s19, s7, s15
	s_add_u32 s18, s18, 0x14500100
	s_addc_u32 s19, s19, 0
	s_add_u32 s59, s26, s14
	s_addc_u32 s60, s27, s15
	s_cmpk_eq_i32 s14, 0xf00
	s_cselect_b32 s21, s1, s19
	s_cselect_b32 s20, s0, s18
	s_cselect_b32 s19, s3, s60
	s_cselect_b32 s18, s2, s59
	s_mov_b32 m0, s49
	v_lshl_add_u64 v[146:147], v[136:137], 0, s[14:15]
	ds_read_b128 v[172:175], v142
	ds_read_b128 v[176:179], v142 offset:1024
	ds_read_b128 v[180:183], v142 offset:2048
	ds_read_b128 v[184:187], v142 offset:3072
	ds_read_b128 v[188:191], v142 offset:4096
	ds_read_b128 v[192:195], v142 offset:5120
	ds_read_b128 v[196:199], v142 offset:6144
	ds_read_b128 v[202:205], v142 offset:7168
	global_load_lds_dwordx4 v[146:147], off
	v_lshl_add_u64 v[146:147], v[138:139], 0, s[14:15]
	s_mov_b32 m0, s50
	s_nop 0
	global_load_lds_dwordx4 v[146:147], off
	s_waitcnt lgkmcnt(8)
	s_setprio 1
	s_barrier
	s_waitcnt lgkmcnt(0)
	v_mfma_f32_16x16x32_bf16 v[124:127], v[150:153], v[172:175], v[124:127]
	v_mfma_f32_16x16x32_bf16 v[120:123], v[160:163], v[172:175], v[120:123]
	v_mfma_f32_16x16x32_bf16 v[116:119], v[150:153], v[180:183], v[116:119]
	v_mfma_f32_16x16x32_bf16 v[112:115], v[160:163], v[180:183], v[112:115]
	v_mfma_f32_16x16x32_bf16 v[100:103], v[150:153], v[188:191], v[100:103]
	v_mfma_f32_16x16x32_bf16 v[92:95], v[160:163], v[188:191], v[92:95]
	v_mfma_f32_16x16x32_bf16 v[84:87], v[150:153], v[196:199], v[84:87]
	v_mfma_f32_16x16x32_bf16 v[76:79], v[160:163], v[196:199], v[76:79]
	v_mfma_f32_16x16x32_bf16 v[124:127], v[154:157], v[176:179], v[124:127]
	v_mfma_f32_16x16x32_bf16 v[120:123], v[168:171], v[176:179], v[120:123]
	v_mfma_f32_16x16x32_bf16 v[116:119], v[154:157], v[184:187], v[116:119]
	v_mfma_f32_16x16x32_bf16 v[112:115], v[168:171], v[184:187], v[112:115]
	v_mfma_f32_16x16x32_bf16 v[100:103], v[154:157], v[192:195], v[100:103]
	v_mfma_f32_16x16x32_bf16 v[92:95], v[168:171], v[192:195], v[92:95]
	v_mfma_f32_16x16x32_bf16 v[84:87], v[154:157], v[202:205], v[84:87]
	v_mfma_f32_16x16x32_bf16 v[76:79], v[168:171], v[202:205], v[76:79]
	s_setprio 0
	s_barrier
	s_mov_b32 m0, s51
	s_add_u32 s98, s18, s4
	s_addc_u32 s99, s19, s5
	ds_read_b128 v[206:209], v143
	ds_read_b128 v[210:213], v143 offset:1024
	ds_read_b128 v[214:217], v143 offset:2048
	ds_read_b128 v[218:221], v143 offset:3072
	global_load_lds_dwordx4 v130, s[18:19]
	s_mov_b32 m0, s52
	s_nop 0
	global_load_lds_dwordx4 v134, s[18:19]
	s_setprio 1
	s_barrier
	s_waitcnt lgkmcnt(0)
	v_mfma_f32_16x16x32_bf16 v[108:111], v[206:209], v[172:175], v[108:111]
	v_mfma_f32_16x16x32_bf16 v[104:107], v[214:217], v[172:175], v[104:107]
	v_mfma_f32_16x16x32_bf16 v[96:99], v[206:209], v[180:183], v[96:99]
	v_mfma_f32_16x16x32_bf16 v[88:91], v[214:217], v[180:183], v[88:91]
	v_mfma_f32_16x16x32_bf16 v[80:83], v[206:209], v[188:191], v[80:83]
	v_mfma_f32_16x16x32_bf16 v[72:75], v[214:217], v[188:191], v[72:75]
	v_mfma_f32_16x16x32_bf16 v[68:71], v[206:209], v[196:199], v[68:71]
	v_mfma_f32_16x16x32_bf16 v[64:67], v[214:217], v[196:199], v[64:67]
	v_mfma_f32_16x16x32_bf16 v[108:111], v[210:213], v[176:179], v[108:111]
	v_mfma_f32_16x16x32_bf16 v[104:107], v[218:221], v[176:179], v[104:107]
	v_mfma_f32_16x16x32_bf16 v[96:99], v[210:213], v[184:187], v[96:99]
	v_mfma_f32_16x16x32_bf16 v[88:91], v[218:221], v[184:187], v[88:91]
	v_mfma_f32_16x16x32_bf16 v[80:83], v[210:213], v[192:195], v[80:83]
	v_mfma_f32_16x16x32_bf16 v[72:75], v[218:221], v[192:195], v[72:75]
	v_mfma_f32_16x16x32_bf16 v[68:71], v[210:213], v[202:205], v[68:71]
	v_mfma_f32_16x16x32_bf16 v[64:67], v[218:221], v[202:205], v[64:67]
	s_setprio 0
	s_mov_b32 m0, s43
	s_add_u32 s100, s20, s4
	s_addc_u32 s101, s21, s5
	s_barrier
	ds_read_b128 v[172:175], v142 offset:16384
	ds_read_b128 v[176:179], v142 offset:17408
	ds_read_b128 v[180:183], v142 offset:18432
	ds_read_b128 v[184:187], v142 offset:19456
	ds_read_b128 v[188:191], v142 offset:20480
	ds_read_b128 v[192:195], v142 offset:21504
	ds_read_b128 v[196:199], v142 offset:22528
	ds_read_b128 v[202:205], v142 offset:23552
	global_load_lds_dwordx4 v128, s[20:21]
	s_mov_b32 m0, s44
	s_nop 0
	global_load_lds_dwordx4 v132, s[20:21]
	s_setprio 1
	s_barrier
	s_waitcnt lgkmcnt(0)
	v_mfma_f32_16x16x32_bf16 v[60:63], v[150:153], v[172:175], v[60:63]
	v_mfma_f32_16x16x32_bf16 v[56:59], v[160:163], v[172:175], v[56:59]
	v_mfma_f32_16x16x32_bf16 v[52:55], v[150:153], v[180:183], v[52:55]
	v_mfma_f32_16x16x32_bf16 v[44:47], v[160:163], v[180:183], v[44:47]
	v_mfma_f32_16x16x32_bf16 v[36:39], v[150:153], v[188:191], v[36:39]
	v_mfma_f32_16x16x32_bf16 v[28:31], v[160:163], v[188:191], v[28:31]
	v_mfma_f32_16x16x32_bf16 v[20:23], v[150:153], v[196:199], v[20:23]
	v_mfma_f32_16x16x32_bf16 v[12:15], v[160:163], v[196:199], v[12:15]
	v_mfma_f32_16x16x32_bf16 v[60:63], v[154:157], v[176:179], v[60:63]
	v_mfma_f32_16x16x32_bf16 v[56:59], v[168:171], v[176:179], v[56:59]
	v_mfma_f32_16x16x32_bf16 v[52:55], v[154:157], v[184:187], v[52:55]
	v_mfma_f32_16x16x32_bf16 v[44:47], v[168:171], v[184:187], v[44:47]
	v_mfma_f32_16x16x32_bf16 v[36:39], v[154:157], v[192:195], v[36:39]
	v_mfma_f32_16x16x32_bf16 v[28:31], v[168:171], v[192:195], v[28:31]
	v_mfma_f32_16x16x32_bf16 v[20:23], v[154:157], v[202:205], v[20:23]
	v_mfma_f32_16x16x32_bf16 v[12:15], v[168:171], v[202:205], v[12:15]
	s_setprio 0
	s_barrier
	s_add_u32 s60, s18, 0x80000
	s_addc_u32 s61, s19, 0
	s_mov_b32 m0, s53
	s_nop 0
	global_load_lds_dwordx4 v130, s[60:61]
	s_mov_b32 m0, s54
	s_nop 0
	global_load_lds_dwordx4 v134, s[60:61]
	s_waitcnt vmcnt(6)
	s_setprio 1
	s_barrier
; #define PG8_STAGE(bufoff, gbase, voff) do { _Pragma("unroll") for (int _i = 0; _i < 2; ++_i) \
;         __builtin_amdgcn_global_load_lds((const unsigned*)((const char*)(gbase) + (voff)[_i]), (LAS unsigned*)(lds + (bufoff) + ldsw + _i * 8192), 16, 0, 0); } while (0)
; #define PG8_LDA(dst, b, h) do { _Pragma("unroll") for (int m = 0; m < 4; ++m) _Pragma("unroll") for (int k = 0; k < 2; ++k) dst[m][k] = *(const LAS bf16x8*)(lds + PG8_SA(b, h) + aoff + m * 2048 + k * 1024); } while (0)
; #define PG8_LDB(dst, b, h) do { _Pragma("unroll") for (int n = 0; n < 2; ++n) _Pragma("unroll") for (int k = 0; k < 2; ++k) dst[n][k] = *(const LAS bf16x8*)(lds + PG8_SB(b, h) + boff + n * 2048 + k * 1024); } while (0)
; #define PG8_WAIT_V(n) asm volatile("s_waitcnt vmcnt(" #n ")" ::: "memory")
; #define PG8_WAIT_L(n) asm volatile("s_waitcnt lgkmcnt(" #n ")" ::: "memory")
; #define PG8_BAR __builtin_amdgcn_s_barrier()
; #define PG8_SCHED __builtin_amdgcn_sched_barrier(0)
; template <class Epi>
; __device__ __forceinline__ void gemm_phase(LAS unsigned char* lds, const bf16_t* A, int lda, const bf16_t* Bt, int ldb, int M, int N, int K, int asel, const Epi& E, const int fixed_round = -1) {
;     ...
;             PG8_LDB(B0, 0, 0); PG8_SCHED; PG8_LDA(At, 0, 0); PG8_STAGE(PG8_SA(1, 1), a1 + hstepA, voffA);
;             PG8_WAIT_L(8); PG8_BAR; PG8_WAIT_L(0); PG8_MMA(0, 0, At, B0); PG8_BAR; PG8_SCHED;
;             PG8_LDB(B1, 0, 1); PG8_STAGE(PG8_SB(0, 0), b2, voffB);
;             PG8_BAR; PG8_WAIT_L(0); PG8_MMA(0, 1, At, B1); PG8_BAR;
;             PG8_LDA(At, 0, 1); PG8_STAGE(PG8_SA(0, 0), a2, voffA);
;             PG8_BAR; PG8_WAIT_L(0); PG8_MMA(1, 0, At, B0); PG8_BAR; PG8_SCHED;
;             PG8_STAGE(PG8_SB(0, 1), b2 + hstepB, voffB);
;             PG8_WAIT_V(6); PG8_BAR; PG8_MMA(1, 1, At, B1); PG8_BAR;
	v_mfma_f32_16x16x32_bf16 v[48:51], v[206:209], v[172:175], v[48:51]
	v_mfma_f32_16x16x32_bf16 v[40:43], v[214:217], v[172:175], v[40:43]
	v_mfma_f32_16x16x32_bf16 v[32:35], v[206:209], v[180:183], v[32:35]
	v_mfma_f32_16x16x32_bf16 v[24:27], v[214:217], v[180:183], v[24:27]
	v_mfma_f32_16x16x32_bf16 v[16:19], v[206:209], v[188:191], v[16:19]
	v_mfma_f32_16x16x32_bf16 v[8:11], v[214:217], v[188:191], v[8:11]
	v_mfma_f32_16x16x32_bf16 v[4:7], v[206:209], v[196:199], v[4:7]
	v_mfma_f32_16x16x32_bf16 v[0:3], v[214:217], v[196:199], v[0:3]
	v_mfma_f32_16x16x32_bf16 v[48:51], v[210:213], v[176:179], v[48:51]
	v_mfma_f32_16x16x32_bf16 v[40:43], v[218:221], v[176:179], v[40:43]
	v_mfma_f32_16x16x32_bf16 v[32:35], v[210:213], v[184:187], v[32:35]
	v_mfma_f32_16x16x32_bf16 v[24:27], v[218:221], v[184:187], v[24:27]
	v_mfma_f32_16x16x32_bf16 v[16:19], v[210:213], v[192:195], v[16:19]
	v_mfma_f32_16x16x32_bf16 v[8:11], v[218:221], v[192:195], v[8:11]
	v_mfma_f32_16x16x32_bf16 v[4:7], v[210:213], v[202:205], v[4:7]
	v_mfma_f32_16x16x32_bf16 v[0:3], v[218:221], v[202:205], v[0:3]
	s_setprio 0
	s_barrier
	ds_read_b128 v[150:153], v144
	ds_read_b128 v[154:157], v144 offset:1024
	ds_read_b128 v[160:163], v144 offset:2048
	ds_read_b128 v[168:171], v144 offset:3072
	s_add_u32 s20, s20, 0x80000
	s_addc_u32 s21, s21, 0
	s_mov_b32 m0, s45
	ds_read_b128 v[172:175], v142 offset:32768
	ds_read_b128 v[176:179], v142 offset:33792
	ds_read_b128 v[180:183], v142 offset:34816
	ds_read_b128 v[184:187], v142 offset:35840
	ds_read_b128 v[188:191], v142 offset:36864
	ds_read_b128 v[192:195], v142 offset:37888
	ds_read_b128 v[196:199], v142 offset:38912
	ds_read_b128 v[202:205], v142 offset:39936
	global_load_lds_dwordx4 v128, s[20:21]
	s_mov_b32 m0, s46
	s_nop 0
	global_load_lds_dwordx4 v132, s[20:21]
	s_waitcnt lgkmcnt(8)
	s_setprio 1
	s_barrier
	s_waitcnt lgkmcnt(0)
	v_mfma_f32_16x16x32_bf16 v[124:127], v[150:153], v[172:175], v[124:127]
	v_mfma_f32_16x16x32_bf16 v[120:123], v[160:163], v[172:175], v[120:123]
	v_mfma_f32_16x16x32_bf16 v[116:119], v[150:153], v[180:183], v[116:119]
	v_mfma_f32_16x16x32_bf16 v[112:115], v[160:163], v[180:183], v[112:115]
	v_mfma_f32_16x16x32_bf16 v[100:103], v[150:153], v[188:191], v[100:103]
	v_mfma_f32_16x16x32_bf16 v[92:95], v[160:163], v[188:191], v[92:95]
	v_mfma_f32_16x16x32_bf16 v[84:87], v[150:153], v[196:199], v[84:87]
	v_mfma_f32_16x16x32_bf16 v[76:79], v[160:163], v[196:199], v[76:79]
	v_mfma_f32_16x16x32_bf16 v[124:127], v[154:157], v[176:179], v[124:127]
	v_mfma_f32_16x16x32_bf16 v[120:123], v[168:171], v[176:179], v[120:123]
	v_mfma_f32_16x16x32_bf16 v[116:119], v[154:157], v[184:187], v[116:119]
	v_mfma_f32_16x16x32_bf16 v[112:115], v[168:171], v[184:187], v[112:115]
	v_mfma_f32_16x16x32_bf16 v[100:103], v[154:157], v[192:195], v[100:103]
	v_mfma_f32_16x16x32_bf16 v[92:95], v[168:171], v[192:195], v[92:95]
	v_mfma_f32_16x16x32_bf16 v[84:87], v[154:157], v[202:205], v[84:87]
	v_mfma_f32_16x16x32_bf16 v[76:79], v[168:171], v[202:205], v[76:79]
	s_setprio 0
	s_barrier
	s_mov_b32 m0, s55
	ds_read_b128 v[206:209], v145
	ds_read_b128 v[210:213], v145 offset:1024
	ds_read_b128 v[214:217], v145 offset:2048
	ds_read_b128 v[218:221], v145 offset:3072
	global_load_lds_dwordx4 v130, s[98:99]
	s_mov_b32 m0, s56
	s_nop 0
	global_load_lds_dwordx4 v134, s[98:99]
	s_setprio 1
	s_barrier
	s_waitcnt lgkmcnt(0)
	v_mfma_f32_16x16x32_bf16 v[108:111], v[206:209], v[172:175], v[108:111]
	v_mfma_f32_16x16x32_bf16 v[104:107], v[214:217], v[172:175], v[104:107]
	v_mfma_f32_16x16x32_bf16 v[96:99], v[206:209], v[180:183], v[96:99]
	v_mfma_f32_16x16x32_bf16 v[88:91], v[214:217], v[180:183], v[88:91]
	v_mfma_f32_16x16x32_bf16 v[80:83], v[206:209], v[188:191], v[80:83]
	v_mfma_f32_16x16x32_bf16 v[72:75], v[214:217], v[188:191], v[72:75]
	v_mfma_f32_16x16x32_bf16 v[68:71], v[206:209], v[196:199], v[68:71]
	v_mfma_f32_16x16x32_bf16 v[64:67], v[214:217], v[196:199], v[64:67]
	v_mfma_f32_16x16x32_bf16 v[108:111], v[210:213], v[176:179], v[108:111]
	v_mfma_f32_16x16x32_bf16 v[104:107], v[218:221], v[176:179], v[104:107]
	v_mfma_f32_16x16x32_bf16 v[96:99], v[210:213], v[184:187], v[96:99]
	v_mfma_f32_16x16x32_bf16 v[88:91], v[218:221], v[184:187], v[88:91]
	v_mfma_f32_16x16x32_bf16 v[80:83], v[210:213], v[192:195], v[80:83]
	v_mfma_f32_16x16x32_bf16 v[72:75], v[218:221], v[192:195], v[72:75]
	v_mfma_f32_16x16x32_bf16 v[68:71], v[210:213], v[202:205], v[68:71]
	v_mfma_f32_16x16x32_bf16 v[64:67], v[218:221], v[202:205], v[64:67]
	s_setprio 0
	s_mov_b32 m0, s47
	s_barrier
	ds_read_b128 v[172:175], v142 offset:49152
	ds_read_b128 v[176:179], v142 offset:50176
	ds_read_b128 v[180:183], v142 offset:51200
	ds_read_b128 v[184:187], v142 offset:52224
	ds_read_b128 v[188:191], v142 offset:53248
	ds_read_b128 v[192:195], v142 offset:54272
	ds_read_b128 v[196:199], v142 offset:55296
	ds_read_b128 v[202:205], v142 offset:56320
	global_load_lds_dwordx4 v128, s[100:101]
	s_mov_b32 m0, s48
	s_nop 0
	global_load_lds_dwordx4 v132, s[100:101]
	s_setprio 1
	s_barrier
	s_waitcnt lgkmcnt(0)
	v_mfma_f32_16x16x32_bf16 v[60:63], v[150:153], v[172:175], v[60:63]
	v_mfma_f32_16x16x32_bf16 v[56:59], v[160:163], v[172:175], v[56:59]
	v_mfma_f32_16x16x32_bf16 v[52:55], v[150:153], v[180:183], v[52:55]
	v_mfma_f32_16x16x32_bf16 v[44:47], v[160:163], v[180:183], v[44:47]
	v_mfma_f32_16x16x32_bf16 v[36:39], v[150:153], v[188:191], v[36:39]
	v_mfma_f32_16x16x32_bf16 v[28:31], v[160:163], v[188:191], v[28:31]
	v_mfma_f32_16x16x32_bf16 v[20:23], v[150:153], v[196:199], v[20:23]
	v_mfma_f32_16x16x32_bf16 v[12:15], v[160:163], v[196:199], v[12:15]
	v_mfma_f32_16x16x32_bf16 v[60:63], v[154:157], v[176:179], v[60:63]
	v_mfma_f32_16x16x32_bf16 v[56:59], v[168:171], v[176:179], v[56:59]
	v_mfma_f32_16x16x32_bf16 v[52:55], v[154:157], v[184:187], v[52:55]
	v_mfma_f32_16x16x32_bf16 v[44:47], v[168:171], v[184:187], v[44:47]
	v_mfma_f32_16x16x32_bf16 v[36:39], v[154:157], v[192:195], v[36:39]
	v_mfma_f32_16x16x32_bf16 v[28:31], v[168:171], v[192:195], v[28:31]
	v_mfma_f32_16x16x32_bf16 v[20:23], v[154:157], v[202:205], v[20:23]
	v_mfma_f32_16x16x32_bf16 v[12:15], v[168:171], v[202:205], v[12:15]
	s_setprio 0
	s_barrier
; #define LAS __attribute__((address_space(3)))
; #define PG8_STAGE(bufoff, gbase, voff) do { _Pragma("unroll") for (int _i = 0; _i < 2; ++_i) \
;         __builtin_amdgcn_global_load_lds((const unsigned*)((const char*)(gbase) + (voff)[_i]), (LAS unsigned*)(lds + (bufoff) + ldsw + _i * 8192), 16, 0, 0); } while (0)
; #define PG8_WAIT_V(n) asm volatile("s_waitcnt vmcnt(" #n ")" ::: "memory")
; #define PG8_BAR __builtin_amdgcn_s_barrier()
; template <class Epi>
; __device__ __forceinline__ void gemm_phase(LAS unsigned char* lds, const bf16_t* A, int lda, const bf16_t* Bt, int ldb, int M, int N, int K, int asel, const Epi& E, const int fixed_round = -1) {
;     ...
;             PG8_STAGE(PG8_SB(1, 1), b3 + hstepB, voffB);
;             PG8_WAIT_V(6); PG8_BAR; PG8_MMA(1, 1, At, B1); PG8_BAR;
;             if constexpr (Epi::HEADSCALE) {
;                 if (t & 2) {
;                     const LAS float* rt = (const LAS float*)(lds + L_RT) + (t >> 2);
; #pragma unroll
;                     for (int ai = 0; ai < 2; ++ai)
; #pragma unroll
;                         for (int m = 0; m < 4; ++m) { const float f = rt[(ai * HALF + wr * 64 + m * 16 + fr) * 8];
; #pragma unroll
;                             for (int bj = 0; bj < 2; ++bj)
; #pragma unroll
;                                 for (int n = 0; n < 2; ++n) acc[ai][bj][m][n] *= f; }
;                 }
	s_add_u32 s18, s18, 0x80080
	s_addc_u32 s19, s19, 0
	s_mov_b32 m0, s57
	s_nop 0
	global_load_lds_dwordx4 v130, s[18:19]
	s_mov_b32 m0, s58
	s_nop 0
	global_load_lds_dwordx4 v134, s[18:19]
	s_waitcnt vmcnt(6)
	s_setprio 1
	s_barrier
	v_mfma_f32_16x16x32_bf16 v[48:51], v[206:209], v[172:175], v[48:51]
	v_mfma_f32_16x16x32_bf16 v[40:43], v[214:217], v[172:175], v[40:43]
	v_mfma_f32_16x16x32_bf16 v[32:35], v[206:209], v[180:183], v[32:35]
	v_mfma_f32_16x16x32_bf16 v[24:27], v[214:217], v[180:183], v[24:27]
	v_mfma_f32_16x16x32_bf16 v[16:19], v[206:209], v[188:191], v[16:19]
	v_mfma_f32_16x16x32_bf16 v[8:11], v[214:217], v[188:191], v[8:11]
	v_mfma_f32_16x16x32_bf16 v[4:7], v[206:209], v[196:199], v[4:7]
	v_mfma_f32_16x16x32_bf16 v[0:3], v[214:217], v[196:199], v[0:3]
	v_mfma_f32_16x16x32_bf16 v[48:51], v[210:213], v[176:179], v[48:51]
	v_mfma_f32_16x16x32_bf16 v[40:43], v[218:221], v[176:179], v[40:43]
	v_mfma_f32_16x16x32_bf16 v[32:35], v[210:213], v[184:187], v[32:35]
	v_mfma_f32_16x16x32_bf16 v[24:27], v[218:221], v[184:187], v[24:27]
	v_mfma_f32_16x16x32_bf16 v[16:19], v[210:213], v[192:195], v[16:19]
	v_mfma_f32_16x16x32_bf16 v[8:11], v[218:221], v[192:195], v[8:11]
	v_mfma_f32_16x16x32_bf16 v[4:7], v[210:213], v[202:205], v[4:7]
	v_mfma_f32_16x16x32_bf16 v[0:3], v[218:221], v[202:205], v[0:3]
	s_setprio 0
	s_bitcmp0_b32 s35, 1
	s_barrier
	s_cbranch_scc1 .LBB0_486
	s_and_b32 s18, s35, -4
	v_add_u32_e32 v148, s18, v140
	ds_read2st64_b32 v[146:147], v148 offset1:2
	ds_read2st64_b32 v[150:151], v148 offset0:4 offset1:6
	s_waitcnt lgkmcnt(0)
	v_pk_mul_f32 v[126:127], v[126:127], v[146:147] op_sel_hi:[1,0]
	v_pk_mul_f32 v[124:125], v[124:125], v[146:147] op_sel_hi:[1,0]
	v_pk_mul_f32 v[122:123], v[122:123], v[146:147] op_sel_hi:[1,0]
	v_pk_mul_f32 v[120:121], v[120:121], v[146:147] op_sel_hi:[1,0]
	v_pk_mul_f32 v[110:111], v[110:111], v[146:147] op_sel_hi:[1,0]
	v_pk_mul_f32 v[108:109], v[108:109], v[146:147] op_sel_hi:[1,0]
	v_pk_mul_f32 v[106:107], v[106:107], v[146:147] op_sel_hi:[1,0]
	v_pk_mul_f32 v[104:105], v[104:105], v[146:147] op_sel_hi:[1,0]
	v_mov_b32_e32 v146, v147
	v_pk_mul_f32 v[118:119], v[118:119], v[146:147] op_sel_hi:[1,0]
	v_pk_mul_f32 v[116:117], v[116:117], v[146:147] op_sel_hi:[1,0]
	v_pk_mul_f32 v[114:115], v[114:115], v[146:147] op_sel_hi:[1,0]
	v_pk_mul_f32 v[112:113], v[112:113], v[146:147] op_sel_hi:[1,0]
	v_pk_mul_f32 v[98:99], v[98:99], v[146:147] op_sel_hi:[1,0]
	v_pk_mul_f32 v[96:97], v[96:97], v[146:147] op_sel_hi:[1,0]
	v_pk_mul_f32 v[90:91], v[90:91], v[146:147] op_sel_hi:[1,0]
	v_pk_mul_f32 v[88:89], v[88:89], v[146:147] op_sel_hi:[1,0]
	v_pk_mul_f32 v[102:103], v[102:103], v[150:151] op_sel_hi:[1,0]
	v_pk_mul_f32 v[100:101], v[100:101], v[150:151] op_sel_hi:[1,0]
	v_pk_mul_f32 v[94:95], v[94:95], v[150:151] op_sel_hi:[1,0]
	v_pk_mul_f32 v[92:93], v[92:93], v[150:151] op_sel_hi:[1,0]
	v_pk_mul_f32 v[82:83], v[82:83], v[150:151] op_sel_hi:[1,0]
	v_pk_mul_f32 v[80:81], v[80:81], v[150:151] op_sel_hi:[1,0]
	v_pk_mul_f32 v[74:75], v[74:75], v[150:151] op_sel_hi:[1,0]
	v_pk_mul_f32 v[72:73], v[72:73], v[150:151] op_sel_hi:[1,0]
	v_mov_b32_e32 v146, v151
	ds_read2st64_b32 v[150:151], v148 offset0:16 offset1:18
	v_pk_mul_f32 v[86:87], v[86:87], v[146:147] op_sel_hi:[1,0]
	v_pk_mul_f32 v[84:85], v[84:85], v[146:147] op_sel_hi:[1,0]
	v_pk_mul_f32 v[78:79], v[78:79], v[146:147] op_sel_hi:[1,0]
	v_pk_mul_f32 v[76:77], v[76:77], v[146:147] op_sel_hi:[1,0]
	v_pk_mul_f32 v[70:71], v[70:71], v[146:147] op_sel_hi:[1,0]
	v_pk_mul_f32 v[68:69], v[68:69], v[146:147] op_sel_hi:[1,0]
	v_pk_mul_f32 v[66:67], v[66:67], v[146:147] op_sel_hi:[1,0]
	v_pk_mul_f32 v[64:65], v[64:65], v[146:147] op_sel_hi:[1,0]
	s_waitcnt lgkmcnt(0)
	v_pk_mul_f32 v[62:63], v[62:63], v[150:151] op_sel_hi:[1,0]
	v_pk_mul_f32 v[60:61], v[60:61], v[150:151] op_sel_hi:[1,0]
	v_pk_mul_f32 v[58:59], v[58:59], v[150:151] op_sel_hi:[1,0]
	v_pk_mul_f32 v[56:57], v[56:57], v[150:151] op_sel_hi:[1,0]
	v_pk_mul_f32 v[50:51], v[50:51], v[150:151] op_sel_hi:[1,0]
	v_pk_mul_f32 v[48:49], v[48:49], v[150:151] op_sel_hi:[1,0]
	v_pk_mul_f32 v[42:43], v[42:43], v[150:151] op_sel_hi:[1,0]
	v_pk_mul_f32 v[40:41], v[40:41], v[150:151] op_sel_hi:[1,0]
	v_mov_b32_e32 v146, v151
	ds_read2st64_b32 v[150:151], v148 offset0:20 offset1:22
	v_pk_mul_f32 v[54:55], v[54:55], v[146:147] op_sel_hi:[1,0]
	v_pk_mul_f32 v[52:53], v[52:53], v[146:147] op_sel_hi:[1,0]
	v_pk_mul_f32 v[46:47], v[46:47], v[146:147] op_sel_hi:[1,0]
	v_pk_mul_f32 v[44:45], v[44:45], v[146:147] op_sel_hi:[1,0]
	v_pk_mul_f32 v[34:35], v[34:35], v[146:147] op_sel_hi:[1,0]
	v_pk_mul_f32 v[32:33], v[32:33], v[146:147] op_sel_hi:[1,0]
	v_pk_mul_f32 v[26:27], v[26:27], v[146:147] op_sel_hi:[1,0]
	v_pk_mul_f32 v[24:25], v[24:25], v[146:147] op_sel_hi:[1,0]
	s_waitcnt lgkmcnt(0)
	v_mov_b32_e32 v146, v151
	v_pk_mul_f32 v[38:39], v[38:39], v[150:151] op_sel_hi:[1,0]
	v_pk_mul_f32 v[36:37], v[36:37], v[150:151] op_sel_hi:[1,0]
	v_pk_mul_f32 v[30:31], v[30:31], v[150:151] op_sel_hi:[1,0]
	v_pk_mul_f32 v[28:29], v[28:29], v[150:151] op_sel_hi:[1,0]
	v_pk_mul_f32 v[18:19], v[18:19], v[150:151] op_sel_hi:[1,0]
	v_pk_mul_f32 v[16:17], v[16:17], v[150:151] op_sel_hi:[1,0]
	v_pk_mul_f32 v[10:11], v[10:11], v[150:151] op_sel_hi:[1,0]
	v_pk_mul_f32 v[8:9], v[8:9], v[150:151] op_sel_hi:[1,0]
	v_pk_mul_f32 v[22:23], v[22:23], v[146:147] op_sel_hi:[1,0]
	v_pk_mul_f32 v[20:21], v[20:21], v[146:147] op_sel_hi:[1,0]
	v_pk_mul_f32 v[14:15], v[14:15], v[146:147] op_sel_hi:[1,0]
	v_pk_mul_f32 v[12:13], v[12:13], v[146:147] op_sel_hi:[1,0]
	v_pk_mul_f32 v[6:7], v[6:7], v[146:147] op_sel_hi:[1,0]
	v_pk_mul_f32 v[4:5], v[4:5], v[146:147] op_sel_hi:[1,0]
	v_pk_mul_f32 v[2:3], v[2:3], v[146:147] op_sel_hi:[1,0]
	v_pk_mul_f32 v[0:1], v[0:1], v[146:147] op_sel_hi:[1,0]
	s_branch .LBB0_486

; #define PG8_STAGE(bufoff, gbase, voff) do { _Pragma("unroll") for (int _i = 0; _i < 2; ++_i) \
;         __builtin_amdgcn_global_load_lds((const unsigned*)((const char*)(gbase) + (voff)[_i]), (LAS unsigned*)(lds + (bufoff) + ldsw + _i * 8192), 16, 0, 0); } while (0)
; #define PG8_LDA(dst, b, h) do { _Pragma("unroll") for (int m = 0; m < 4; ++m) _Pragma("unroll") for (int k = 0; k < 2; ++k) dst[m][k] = *(const LAS bf16x8*)(lds + PG8_SA(b, h) + aoff + m * 2048 + k * 1024); } while (0)
; #define PG8_LDB(dst, b, h) do { _Pragma("unroll") for (int n = 0; n < 2; ++n) _Pragma("unroll") for (int k = 0; k < 2; ++k) dst[n][k] = *(const LAS bf16x8*)(lds + PG8_SB(b, h) + boff + n * 2048 + k * 1024); } while (0)
; #define PG8_WAIT_V(n) asm volatile("s_waitcnt vmcnt(" #n ")" ::: "memory")
; #define PG8_WAIT_L(n) asm volatile("s_waitcnt lgkmcnt(" #n ")" ::: "memory")
; #define PG8_BAR __builtin_amdgcn_s_barrier()
; #define PG8_SCHED __builtin_amdgcn_sched_barrier(0)
; template <class Epi>
; __device__ __forceinline__ void gemm_phase(LAS unsigned char* lds, const bf16_t* A, int lda, const bf16_t* Bt, int ldb, int M, int N, int K, int asel, const Epi& E, const int fixed_round = -1) {
;     ...
;         const bool has_next = (fixed_round < 0) && S.next(ui + 1, nxt);
;         const char* nA = has_next ? PG8_ABASE(nxt) : cA; const char* nB = has_next ? (const char*)Bt + (size_t)nxt.pn * tstepB : cB;
;         for (int t = 0; t < nt; t += 2) {
;             const bool last = (t == nt - 2);
;             const char* a1 = cA + (size_t)(t + 1) * kstep;
;             const char* a2 = last ? nA : cA + (size_t)(t + 2) * kstep; const char* b2 = last ? nB : cB + (size_t)(t + 2) * kstep;
;             const char* a3 = a2 + kstep; const char* b3 = b2 + kstep;
;             PG8_LDB(B0, 0, 0); PG8_SCHED; PG8_LDA(At, 0, 0); PG8_STAGE(PG8_SA(1, 1), a1 + hstepA, voffA);
;             PG8_WAIT_L(8); PG8_BAR; PG8_WAIT_L(0); PG8_MMA(0, 0, At, B0); PG8_BAR; PG8_SCHED;
;             PG8_LDB(B1, 0, 1); PG8_STAGE(PG8_SB(0, 0), b2, voffB);
;             PG8_BAR; PG8_WAIT_L(0); PG8_MMA(0, 1, At, B1); PG8_BAR;
;             PG8_LDA(At, 0, 1); PG8_STAGE(PG8_SA(0, 0), a2, voffA);
;             PG8_BAR; PG8_WAIT_L(0); PG8_MMA(1, 0, At, B0); PG8_BAR; PG8_SCHED;
;             PG8_STAGE(PG8_SB(0, 1), b2 + hstepB, voffB);
;             PG8_WAIT_V(6); PG8_BAR; PG8_MMA(1, 1, At, B1); PG8_BAR;
.LBB0_591:
	ds_read_b128 v[152:155], v149
	ds_read_b128 v[156:159], v149 offset:1024
	ds_read_b128 v[160:163], v149 offset:2048
	ds_read_b128 v[164:167], v149 offset:3072
	s_add_i32 m0, s27, 0xc000
	ds_read_b128 v[168:171], v150
	ds_read_b128 v[172:175], v150 offset:1024
	ds_read_b128 v[176:179], v150 offset:2048
	ds_read_b128 v[180:183], v150 offset:3072
	ds_read_b128 v[184:187], v150 offset:4096
	ds_read_b128 v[188:191], v150 offset:5120
	ds_read_b128 v[192:195], v150 offset:6144
	ds_read_b128 v[196:199], v150 offset:7168
	global_load_lds_dwordx4 v136, s[30:31]
	s_add_i32 m0, s27, 0xe000
	s_nop 0
	global_load_lds_dwordx4 v138, s[30:31]
	s_waitcnt lgkmcnt(8)
	s_setprio 1
	s_barrier
	s_waitcnt lgkmcnt(0)
	v_mfma_f32_16x16x32_bf16 v[124:127], v[152:155], v[168:171], v[124:127]
	v_mfma_f32_16x16x32_bf16 v[120:123], v[160:163], v[168:171], v[120:123]
	v_mfma_f32_16x16x32_bf16 v[108:111], v[152:155], v[176:179], v[108:111]
	v_mfma_f32_16x16x32_bf16 v[104:107], v[160:163], v[176:179], v[104:107]
	v_mfma_f32_16x16x32_bf16 v[92:95], v[152:155], v[184:187], v[92:95]
	v_mfma_f32_16x16x32_bf16 v[88:91], v[160:163], v[184:187], v[88:91]
	v_mfma_f32_16x16x32_bf16 v[76:79], v[152:155], v[192:195], v[76:79]
	v_mfma_f32_16x16x32_bf16 v[72:75], v[160:163], v[192:195], v[72:75]
	v_mfma_f32_16x16x32_bf16 v[124:127], v[156:159], v[172:175], v[124:127]
	v_mfma_f32_16x16x32_bf16 v[120:123], v[164:167], v[172:175], v[120:123]
	v_mfma_f32_16x16x32_bf16 v[108:111], v[156:159], v[180:183], v[108:111]
	v_mfma_f32_16x16x32_bf16 v[104:107], v[164:167], v[180:183], v[104:107]
	v_mfma_f32_16x16x32_bf16 v[92:95], v[156:159], v[188:191], v[92:95]
	v_mfma_f32_16x16x32_bf16 v[88:91], v[164:167], v[188:191], v[88:91]
	v_mfma_f32_16x16x32_bf16 v[76:79], v[156:159], v[196:199], v[76:79]
	v_mfma_f32_16x16x32_bf16 v[72:75], v[164:167], v[196:199], v[72:75]
	s_setprio 0
	s_barrier
	s_add_u32 s28, s30, 0xfff80080
	s_addc_u32 s29, s31, -1
	s_cmp_eq_u32 s56, 28
	s_cselect_b32 s37, s7, s29
	s_cselect_b32 s36, s52, s28
	s_cselect_b32 s35, s5, s55
	s_cselect_b32 s34, s53, s54
	s_add_i32 s28, s81, s42
	s_add_u32 s98, s34, s2
	s_addc_u32 s99, s35, s3
	s_mov_b32 m0, s28
	ds_read_b128 v[202:205], v151
	ds_read_b128 v[206:209], v151 offset:1024
	ds_read_b128 v[210:213], v151 offset:2048
	ds_read_b128 v[214:217], v151 offset:3072
	global_load_lds_dwordx4 v130, s[34:35]
	s_add_i32 m0, s28, 0x2000
	s_nop 0
	global_load_lds_dwordx4 v134, s[34:35]
	s_setprio 1
	s_barrier
	s_waitcnt lgkmcnt(0)
	v_mfma_f32_16x16x32_bf16 v[116:119], v[202:205], v[168:171], v[116:119]
	v_mfma_f32_16x16x32_bf16 v[112:115], v[210:213], v[168:171], v[112:115]
	v_mfma_f32_16x16x32_bf16 v[100:103], v[202:205], v[176:179], v[100:103]
	v_mfma_f32_16x16x32_bf16 v[96:99], v[210:213], v[176:179], v[96:99]
	v_mfma_f32_16x16x32_bf16 v[84:87], v[202:205], v[184:187], v[84:87]
	v_mfma_f32_16x16x32_bf16 v[80:83], v[210:213], v[184:187], v[80:83]
	v_mfma_f32_16x16x32_bf16 v[68:71], v[202:205], v[192:195], v[68:71]
	v_mfma_f32_16x16x32_bf16 v[64:67], v[210:213], v[192:195], v[64:67]
	v_mfma_f32_16x16x32_bf16 v[116:119], v[206:209], v[172:175], v[116:119]
	v_mfma_f32_16x16x32_bf16 v[112:115], v[214:217], v[172:175], v[112:115]
	v_mfma_f32_16x16x32_bf16 v[100:103], v[206:209], v[180:183], v[100:103]
	v_mfma_f32_16x16x32_bf16 v[96:99], v[214:217], v[180:183], v[96:99]
	v_mfma_f32_16x16x32_bf16 v[84:87], v[206:209], v[188:191], v[84:87]
	v_mfma_f32_16x16x32_bf16 v[80:83], v[214:217], v[188:191], v[80:83]
	v_mfma_f32_16x16x32_bf16 v[68:71], v[206:209], v[196:199], v[68:71]
	v_mfma_f32_16x16x32_bf16 v[64:67], v[214:217], v[196:199], v[64:67]
	s_setprio 0
	s_mov_b32 m0, s27
	s_add_u32 s100, s36, s2
	s_addc_u32 s101, s37, s3
	s_barrier
	ds_read_b128 v[168:171], v150 offset:16384
	ds_read_b128 v[172:175], v150 offset:17408
	ds_read_b128 v[176:179], v150 offset:18432
	ds_read_b128 v[180:183], v150 offset:19456
	ds_read_b128 v[184:187], v150 offset:20480
	ds_read_b128 v[188:191], v150 offset:21504
	ds_read_b128 v[192:195], v150 offset:22528
	ds_read_b128 v[196:199], v150 offset:23552
	global_load_lds_dwordx4 v128, s[36:37]
	s_mov_b32 m0, s43
	s_nop 0
	global_load_lds_dwordx4 v132, s[36:37]
	s_setprio 1
	s_barrier
	s_waitcnt lgkmcnt(0)
	v_mfma_f32_16x16x32_bf16 v[60:63], v[152:155], v[168:171], v[60:63]
	v_mfma_f32_16x16x32_bf16 v[56:59], v[160:163], v[168:171], v[56:59]
	v_mfma_f32_16x16x32_bf16 v[44:47], v[152:155], v[176:179], v[44:47]
	v_mfma_f32_16x16x32_bf16 v[40:43], v[160:163], v[176:179], v[40:43]
	v_mfma_f32_16x16x32_bf16 v[28:31], v[152:155], v[184:187], v[28:31]
	v_mfma_f32_16x16x32_bf16 v[24:27], v[160:163], v[184:187], v[24:27]
	v_mfma_f32_16x16x32_bf16 v[12:15], v[152:155], v[192:195], v[12:15]
	v_mfma_f32_16x16x32_bf16 v[8:11], v[160:163], v[192:195], v[8:11]
	v_mfma_f32_16x16x32_bf16 v[60:63], v[156:159], v[172:175], v[60:63]
	v_mfma_f32_16x16x32_bf16 v[56:59], v[164:167], v[172:175], v[56:59]
	v_mfma_f32_16x16x32_bf16 v[44:47], v[156:159], v[180:183], v[44:47]
	v_mfma_f32_16x16x32_bf16 v[40:43], v[164:167], v[180:183], v[40:43]
	v_mfma_f32_16x16x32_bf16 v[28:31], v[156:159], v[188:191], v[28:31]
	v_mfma_f32_16x16x32_bf16 v[24:27], v[164:167], v[188:191], v[24:27]
	v_mfma_f32_16x16x32_bf16 v[12:15], v[156:159], v[196:199], v[12:15]
	v_mfma_f32_16x16x32_bf16 v[8:11], v[164:167], v[196:199], v[8:11]
	s_setprio 0
	s_barrier
	s_add_u32 s28, s34, 0x80000
	s_addc_u32 s29, s35, 0
	s_add_i32 s57, s82, s42
	s_mov_b32 m0, s57
	s_nop 0
	global_load_lds_dwordx4 v130, s[28:29]
	s_add_i32 m0, s57, 0x2000
	s_nop 0
	global_load_lds_dwordx4 v134, s[28:29]
	s_waitcnt vmcnt(6)
	s_setprio 1
	s_barrier
; #define PG8_STAGE(bufoff, gbase, voff) do { _Pragma("unroll") for (int _i = 0; _i < 2; ++_i) \
;         __builtin_amdgcn_global_load_lds((const unsigned*)((const char*)(gbase) + (voff)[_i]), (LAS unsigned*)(lds + (bufoff) + ldsw + _i * 8192), 16, 0, 0); } while (0)
; #define PG8_LDA(dst, b, h) do { _Pragma("unroll") for (int m = 0; m < 4; ++m) _Pragma("unroll") for (int k = 0; k < 2; ++k) dst[m][k] = *(const LAS bf16x8*)(lds + PG8_SA(b, h) + aoff + m * 2048 + k * 1024); } while (0)
; #define PG8_LDB(dst, b, h) do { _Pragma("unroll") for (int n = 0; n < 2; ++n) _Pragma("unroll") for (int k = 0; k < 2; ++k) dst[n][k] = *(const LAS bf16x8*)(lds + PG8_SB(b, h) + boff + n * 2048 + k * 1024); } while (0)
; #define PG8_WAIT_V(n) asm volatile("s_waitcnt vmcnt(" #n ")" ::: "memory")
; #define PG8_WAIT_L(n) asm volatile("s_waitcnt lgkmcnt(" #n ")" ::: "memory")
; #define PG8_BAR __builtin_amdgcn_s_barrier()
; #define PG8_SCHED __builtin_amdgcn_sched_barrier(0)
; template <class Epi>
; __device__ __forceinline__ void gemm_phase(LAS unsigned char* lds, const bf16_t* A, int lda, const bf16_t* Bt, int ldb, int M, int N, int K, int asel, const Epi& E, const int fixed_round = -1) {
;     ...
;             PG8_WAIT_V(6); PG8_BAR; PG8_MMA(1, 1, At, B1); PG8_BAR;
;             PG8_LDB(B0, 1, 0); PG8_SCHED; PG8_LDA(At, 1, 0); PG8_STAGE(PG8_SA(0, 1), a2 + hstepA, voffA);
;             PG8_WAIT_L(8); PG8_BAR; PG8_WAIT_L(0); PG8_MMA(0, 0, At, B0); PG8_BAR; PG8_SCHED;
;             PG8_LDB(B1, 1, 1); PG8_STAGE(PG8_SB(1, 0), b3, voffB);
;             PG8_BAR; PG8_WAIT_L(0); PG8_MMA(0, 1, At, B1); PG8_BAR;
;             PG8_LDA(At, 1, 1); PG8_STAGE(PG8_SA(1, 0), a3, voffA);
;             PG8_BAR; PG8_WAIT_L(0); PG8_MMA(1, 0, At, B0); PG8_BAR; PG8_SCHED;
	v_mfma_f32_16x16x32_bf16 v[52:55], v[202:205], v[168:171], v[52:55]
	v_mfma_f32_16x16x32_bf16 v[48:51], v[210:213], v[168:171], v[48:51]
	v_mfma_f32_16x16x32_bf16 v[36:39], v[202:205], v[176:179], v[36:39]
	v_mfma_f32_16x16x32_bf16 v[32:35], v[210:213], v[176:179], v[32:35]
	v_mfma_f32_16x16x32_bf16 v[20:23], v[202:205], v[184:187], v[20:23]
	v_mfma_f32_16x16x32_bf16 v[16:19], v[210:213], v[184:187], v[16:19]
	v_mfma_f32_16x16x32_bf16 v[4:7], v[202:205], v[192:195], v[4:7]
	v_mfma_f32_16x16x32_bf16 v[0:3], v[210:213], v[192:195], v[0:3]
	v_mfma_f32_16x16x32_bf16 v[52:55], v[206:209], v[172:175], v[52:55]
	v_mfma_f32_16x16x32_bf16 v[48:51], v[214:217], v[172:175], v[48:51]
	v_mfma_f32_16x16x32_bf16 v[36:39], v[206:209], v[180:183], v[36:39]
	v_mfma_f32_16x16x32_bf16 v[32:35], v[214:217], v[180:183], v[32:35]
	v_mfma_f32_16x16x32_bf16 v[20:23], v[206:209], v[188:191], v[20:23]
	v_mfma_f32_16x16x32_bf16 v[16:19], v[214:217], v[188:191], v[16:19]
	v_mfma_f32_16x16x32_bf16 v[4:7], v[206:209], v[196:199], v[4:7]
	v_mfma_f32_16x16x32_bf16 v[0:3], v[214:217], v[196:199], v[0:3]
	s_setprio 0
	v_add_u32_e32 v164, s83, v147
	s_barrier
	ds_read_b128 v[152:155], v164
	ds_read_b128 v[156:159], v164 offset:1024
	ds_read_b128 v[160:163], v164 offset:2048
	ds_read_b128 v[164:167], v164 offset:3072
	s_add_u32 s28, s36, 0x80000
	s_addc_u32 s29, s37, 0
	s_mov_b32 m0, s44
	ds_read_b128 v[168:171], v150 offset:32768
	ds_read_b128 v[172:175], v150 offset:33792
	ds_read_b128 v[176:179], v150 offset:34816
	ds_read_b128 v[180:183], v150 offset:35840
	ds_read_b128 v[184:187], v150 offset:36864
	ds_read_b128 v[188:191], v150 offset:37888
	ds_read_b128 v[192:195], v150 offset:38912
	ds_read_b128 v[196:199], v150 offset:39936
	global_load_lds_dwordx4 v128, s[28:29]
	s_mov_b32 m0, s45
	s_nop 0
	global_load_lds_dwordx4 v132, s[28:29]
	s_waitcnt lgkmcnt(8)
	s_setprio 1
	s_barrier
	s_waitcnt lgkmcnt(0)
	v_mfma_f32_16x16x32_bf16 v[124:127], v[152:155], v[168:171], v[124:127]
	v_mfma_f32_16x16x32_bf16 v[120:123], v[160:163], v[168:171], v[120:123]
	v_mfma_f32_16x16x32_bf16 v[108:111], v[152:155], v[176:179], v[108:111]
	v_mfma_f32_16x16x32_bf16 v[104:107], v[160:163], v[176:179], v[104:107]
	v_mfma_f32_16x16x32_bf16 v[92:95], v[152:155], v[184:187], v[92:95]
	v_mfma_f32_16x16x32_bf16 v[88:91], v[160:163], v[184:187], v[88:91]
	v_mfma_f32_16x16x32_bf16 v[76:79], v[152:155], v[192:195], v[76:79]
	v_mfma_f32_16x16x32_bf16 v[72:75], v[160:163], v[192:195], v[72:75]
	v_mfma_f32_16x16x32_bf16 v[124:127], v[156:159], v[172:175], v[124:127]
	v_mfma_f32_16x16x32_bf16 v[120:123], v[164:167], v[172:175], v[120:123]
	v_mfma_f32_16x16x32_bf16 v[108:111], v[156:159], v[180:183], v[108:111]
	v_mfma_f32_16x16x32_bf16 v[104:107], v[164:167], v[180:183], v[104:107]
	v_mfma_f32_16x16x32_bf16 v[92:95], v[156:159], v[188:191], v[92:95]
	v_mfma_f32_16x16x32_bf16 v[88:91], v[164:167], v[188:191], v[88:91]
	v_mfma_f32_16x16x32_bf16 v[76:79], v[156:159], v[196:199], v[76:79]
	v_mfma_f32_16x16x32_bf16 v[72:75], v[164:167], v[196:199], v[72:75]
	s_setprio 0
	s_barrier
	s_add_i32 s28, s83, s42
	v_add_u32_e32 v214, s84, v147
	s_mov_b32 m0, s28
	ds_read_b128 v[202:205], v214
	ds_read_b128 v[206:209], v214 offset:1024
	ds_read_b128 v[210:213], v214 offset:2048
	ds_read_b128 v[214:217], v214 offset:3072
	global_load_lds_dwordx4 v130, s[98:99]
	s_add_i32 m0, s28, 0x2000
	s_nop 0
	global_load_lds_dwordx4 v134, s[98:99]
	s_setprio 1
	s_barrier
	s_waitcnt lgkmcnt(0)
	v_mfma_f32_16x16x32_bf16 v[116:119], v[202:205], v[168:171], v[116:119]
	v_mfma_f32_16x16x32_bf16 v[112:115], v[210:213], v[168:171], v[112:115]
	v_mfma_f32_16x16x32_bf16 v[100:103], v[202:205], v[176:179], v[100:103]
	v_mfma_f32_16x16x32_bf16 v[96:99], v[210:213], v[176:179], v[96:99]
	v_mfma_f32_16x16x32_bf16 v[84:87], v[202:205], v[184:187], v[84:87]
	v_mfma_f32_16x16x32_bf16 v[80:83], v[210:213], v[184:187], v[80:83]
	v_mfma_f32_16x16x32_bf16 v[68:71], v[202:205], v[192:195], v[68:71]
	v_mfma_f32_16x16x32_bf16 v[64:67], v[210:213], v[192:195], v[64:67]
	v_mfma_f32_16x16x32_bf16 v[116:119], v[206:209], v[172:175], v[116:119]
	v_mfma_f32_16x16x32_bf16 v[112:115], v[214:217], v[172:175], v[112:115]
	v_mfma_f32_16x16x32_bf16 v[100:103], v[206:209], v[180:183], v[100:103]
	v_mfma_f32_16x16x32_bf16 v[96:99], v[214:217], v[180:183], v[96:99]
	v_mfma_f32_16x16x32_bf16 v[84:87], v[206:209], v[188:191], v[84:87]
	v_mfma_f32_16x16x32_bf16 v[80:83], v[214:217], v[188:191], v[80:83]
	v_mfma_f32_16x16x32_bf16 v[68:71], v[206:209], v[196:199], v[68:71]
	v_mfma_f32_16x16x32_bf16 v[64:67], v[214:217], v[196:199], v[64:67]
	s_setprio 0
	s_mov_b32 m0, s47
	s_barrier
	ds_read_b128 v[168:171], v150 offset:49152
	ds_read_b128 v[172:175], v150 offset:50176
	ds_read_b128 v[176:179], v150 offset:51200
	ds_read_b128 v[180:183], v150 offset:52224
	ds_read_b128 v[184:187], v150 offset:53248
	ds_read_b128 v[188:191], v150 offset:54272
	ds_read_b128 v[192:195], v150 offset:55296
	ds_read_b128 v[196:199], v150 offset:56320
	global_load_lds_dwordx4 v128, s[100:101]
	s_mov_b32 m0, s48
	s_nop 0
	global_load_lds_dwordx4 v132, s[100:101]
	s_setprio 1
	s_barrier
; __device__ __forceinline__ unsigned cvt_pk_bf16(float lo, float hi) { const bf16x2_t r = __builtin_convertvector((f32x2){lo, hi}, bf16x2_t); return __builtin_bit_cast(unsigned, r); }
; #define PG8_STAGE(bufoff, gbase, voff) do { _Pragma("unroll") for (int _i = 0; _i < 2; ++_i) \
;         __builtin_amdgcn_global_load_lds((const unsigned*)((const char*)(gbase) + (voff)[_i]), (LAS unsigned*)(lds + (bufoff) + ldsw + _i * 8192), 16, 0, 0); } while (0)
; #define PG8_WAIT_V(n) asm volatile("s_waitcnt vmcnt(" #n ")" ::: "memory")
; #define PG8_WAIT_L(n) asm volatile("s_waitcnt lgkmcnt(" #n ")" ::: "memory")
; #define PG8_BAR __builtin_amdgcn_s_barrier()
; #define PG8_SCHED __builtin_amdgcn_sched_barrier(0)
; template <class Epi>
; __device__ __forceinline__ void gemm_phase(LAS unsigned char* lds, const bf16_t* A, int lda, const bf16_t* Bt, int ldb, int M, int N, int K, int asel, const Epi& E, const int fixed_round = -1) {
;     ...
;             PG8_BAR; PG8_WAIT_L(0); PG8_MMA(1, 0, At, B0); PG8_BAR; PG8_SCHED;
;             PG8_STAGE(PG8_SB(1, 1), b3 + hstepB, voffB);
;             PG8_WAIT_V(6); PG8_BAR; PG8_MMA(1, 1, At, B1); PG8_BAR;
;     __device__ __forceinline__ void operator()(const AccT& acc, const Unit& u, int wr, int wc, int fr, int fq) const {
;     ...
;         for (int ai = 0; ai < 2; ++ai)
; #pragma unroll
;             for (int m = 0; m < 4; ++m) { bf16_t* rowp = O + (size_t)(row0 + ai * HALF + m * 16) * DFF + col0;
; #pragma unroll
;                 for (int bj = 0; bj < 2; ++bj) { f32x4 v0 = acc[ai][bj][m][0], v1 = acc[ai][bj][m][1];
; #pragma unroll
;                     for (int j = 0; j < 4; ++j) { float a = fmaxf(v0[j], 0.f), b = fmaxf(v1[j], 0.f); v0[j] = a * a; v1[j] = b * b; }
;                     u32x4 w; w.x = cvt_pk_bf16(v0[0], v0[1]); w.y = cvt_pk_bf16(v0[2], v0[3]); w.z = cvt_pk_bf16(v1[0], v1[1]); w.w = cvt_pk_bf16(v1[2], v1[3]);
;                     *(u32x4*)(rowp + bj * HALF) = w; } }
	s_waitcnt lgkmcnt(0)
	v_mfma_f32_16x16x32_bf16 v[60:63], v[152:155], v[168:171], v[60:63]
	v_mfma_f32_16x16x32_bf16 v[56:59], v[160:163], v[168:171], v[56:59]
	v_mfma_f32_16x16x32_bf16 v[44:47], v[152:155], v[176:179], v[44:47]
	v_mfma_f32_16x16x32_bf16 v[40:43], v[160:163], v[176:179], v[40:43]
	v_mfma_f32_16x16x32_bf16 v[28:31], v[152:155], v[184:187], v[28:31]
	v_mfma_f32_16x16x32_bf16 v[24:27], v[160:163], v[184:187], v[24:27]
	v_mfma_f32_16x16x32_bf16 v[12:15], v[152:155], v[192:195], v[12:15]
	v_mfma_f32_16x16x32_bf16 v[8:11], v[160:163], v[192:195], v[8:11]
	v_mfma_f32_16x16x32_bf16 v[60:63], v[156:159], v[172:175], v[60:63]
	v_mfma_f32_16x16x32_bf16 v[56:59], v[164:167], v[172:175], v[56:59]
	v_mfma_f32_16x16x32_bf16 v[44:47], v[156:159], v[180:183], v[44:47]
	v_mfma_f32_16x16x32_bf16 v[40:43], v[164:167], v[180:183], v[40:43]
	v_mfma_f32_16x16x32_bf16 v[28:31], v[156:159], v[188:191], v[28:31]
	v_mfma_f32_16x16x32_bf16 v[24:27], v[164:167], v[188:191], v[24:27]
	v_mfma_f32_16x16x32_bf16 v[12:15], v[156:159], v[196:199], v[12:15]
	v_mfma_f32_16x16x32_bf16 v[8:11], v[164:167], v[196:199], v[8:11]
	s_setprio 0
	s_barrier
	s_add_u32 s28, s34, 0x80080
	s_addc_u32 s29, s35, 0
	s_add_i32 s34, s84, s42
	s_mov_b32 m0, s34
	s_nop 0
	global_load_lds_dwordx4 v130, s[28:29]
	s_add_i32 m0, s34, 0x2000
	s_nop 0
	global_load_lds_dwordx4 v134, s[28:29]
	s_waitcnt vmcnt(6)
	s_setprio 1
	s_barrier
	v_mfma_f32_16x16x32_bf16 v[52:55], v[202:205], v[168:171], v[52:55]
	v_mfma_f32_16x16x32_bf16 v[48:51], v[210:213], v[168:171], v[48:51]
	v_mfma_f32_16x16x32_bf16 v[36:39], v[202:205], v[176:179], v[36:39]
	v_mfma_f32_16x16x32_bf16 v[32:35], v[210:213], v[176:179], v[32:35]
	v_mfma_f32_16x16x32_bf16 v[20:23], v[202:205], v[184:187], v[20:23]
	v_mfma_f32_16x16x32_bf16 v[16:19], v[210:213], v[184:187], v[16:19]
	v_mfma_f32_16x16x32_bf16 v[4:7], v[202:205], v[192:195], v[4:7]
	v_mfma_f32_16x16x32_bf16 v[0:3], v[210:213], v[192:195], v[0:3]
	v_mfma_f32_16x16x32_bf16 v[52:55], v[206:209], v[172:175], v[52:55]
	v_mfma_f32_16x16x32_bf16 v[48:51], v[214:217], v[172:175], v[48:51]
	v_mfma_f32_16x16x32_bf16 v[36:39], v[206:209], v[180:183], v[36:39]
	v_mfma_f32_16x16x32_bf16 v[32:35], v[214:217], v[180:183], v[32:35]
	v_mfma_f32_16x16x32_bf16 v[20:23], v[206:209], v[188:191], v[20:23]
	v_mfma_f32_16x16x32_bf16 v[16:19], v[214:217], v[188:191], v[16:19]
	v_mfma_f32_16x16x32_bf16 v[4:7], v[206:209], v[196:199], v[4:7]
	v_mfma_f32_16x16x32_bf16 v[0:3], v[214:217], v[196:199], v[0:3]
	s_setprio 0
	s_add_i32 s56, s56, 2
	s_add_u32 s30, s30, 0x100
	s_addc_u32 s31, s31, 0
	s_add_u32 s54, s54, 0x100
	s_addc_u32 s55, s55, 0
	s_cmp_gt_u32 s56, 29
	s_cbranch_scc0 .Lrot_4
	s_barrier
	v_lshl_add_u32 v152, s26, 8, v146
	v_lshl_or_b32 v144, s51, 8, v148
	v_ashrrev_i32_e32 v153, 31, v152
	v_ashrrev_i32_e32 v145, 31, v144
	v_lshlrev_b64 v[154:155], 14, v[152:153]
	v_lshl_add_u64 v[154:155], s[88:89], 0, v[154:155]
	v_lshlrev_b64 v[156:157], 1, v[144:145]
	v_max_f32_e32 v120, 0, v120
	v_max_f32_e32 v121, 0, v121
	v_lshl_add_u64 v[144:145], v[154:155], 0, v[156:157]
	v_pk_mul_f32 v[154:155], v[120:121], v[120:121]
	v_max_f32_e32 v121, v122, v122
	v_max_f32_e32 v120, v126, v126
	v_max_f32_e32 v122, 0, v121
	v_max_f32_e32 v121, v127, v127
	v_max_f32_e32 v124, 0, v124
	v_max_f32_e32 v125, 0, v125
	v_max_f32_e32 v120, 0, v120
	v_max_f32_e32 v121, 0, v121
	v_max_f32_e32 v123, 0, v123
	v_pk_mul_f32 v[124:125], v[124:125], v[124:125]
	v_pk_mul_f32 v[126:127], v[120:121], v[120:121]
	v_pk_mul_f32 v[158:159], v[122:123], v[122:123]
	v_cvt_pk_bf16_f32 v120, v124, v125
	v_cvt_pk_bf16_f32 v121, v126, v127
	v_cvt_pk_bf16_f32 v122, v154, v155
	v_cvt_pk_bf16_f32 v123, v158, v159
	v_max_f32_e32 v112, 0, v112
	v_max_f32_e32 v113, 0, v113
	global_store_dwordx4 v[144:145], v[120:123], off
	s_nop 1
	v_pk_mul_f32 v[120:121], v[112:113], v[112:113]
	v_max_f32_e32 v113, v114, v114
	v_max_f32_e32 v112, v118, v118
	v_max_f32_e32 v114, 0, v113
	v_max_f32_e32 v113, v119, v119
	v_max_f32_e32 v116, 0, v116
	v_max_f32_e32 v117, 0, v117
	v_max_f32_e32 v112, 0, v112
	v_max_f32_e32 v113, 0, v113
	v_max_f32_e32 v115, 0, v115
	v_pk_mul_f32 v[116:117], v[116:117], v[116:117]
	v_pk_mul_f32 v[118:119], v[112:113], v[112:113]
	v_pk_mul_f32 v[122:123], v[114:115], v[114:115]
	v_cvt_pk_bf16_f32 v112, v116, v117
	v_cvt_pk_bf16_f32 v113, v118, v119
	v_cvt_pk_bf16_f32 v114, v120, v121
	v_cvt_pk_bf16_f32 v115, v122, v123
	v_max_f32_e32 v104, 0, v104
	v_max_f32_e32 v105, 0, v105
	global_store_dwordx4 v[144:145], v[112:115], off offset:256
	s_nop 1
	v_or_b32_e32 v112, 16, v152
	v_pk_mul_f32 v[114:115], v[104:105], v[104:105]
	v_max_f32_e32 v105, v106, v106
	v_ashrrev_i32_e32 v113, 31, v112
	v_max_f32_e32 v104, v110, v110
	v_max_f32_e32 v106, 0, v105
	v_max_f32_e32 v105, v111, v111
	v_lshlrev_b64 v[112:113], 14, v[112:113]
	v_max_f32_e32 v108, 0, v108
	v_max_f32_e32 v109, 0, v109
	v_max_f32_e32 v104, 0, v104
	v_max_f32_e32 v105, 0, v105
	v_max_f32_e32 v107, 0, v107
	v_lshl_add_u64 v[112:113], s[88:89], 0, v[112:113]
	v_pk_mul_f32 v[108:109], v[108:109], v[108:109]
	v_pk_mul_f32 v[110:111], v[104:105], v[104:105]
	v_pk_mul_f32 v[116:117], v[106:107], v[106:107]
	v_lshl_add_u64 v[112:113], v[112:113], 0, v[156:157]
	v_cvt_pk_bf16_f32 v104, v108, v109
	v_cvt_pk_bf16_f32 v105, v110, v111
	v_cvt_pk_bf16_f32 v106, v114, v115
	v_cvt_pk_bf16_f32 v107, v116, v117
	v_max_f32_e32 v96, 0, v96
	v_max_f32_e32 v97, 0, v97
	global_store_dwordx4 v[112:113], v[104:107], off
	s_nop 1
	v_pk_mul_f32 v[104:105], v[96:97], v[96:97]
	v_max_f32_e32 v97, v98, v98
	v_max_f32_e32 v96, v102, v102
	v_max_f32_e32 v98, 0, v97
	v_max_f32_e32 v97, v103, v103
; __device__ __forceinline__ unsigned cvt_pk_bf16(float lo, float hi) { const bf16x2_t r = __builtin_convertvector((f32x2){lo, hi}, bf16x2_t); return __builtin_bit_cast(unsigned, r); }
;     __device__ __forceinline__ void operator()(const AccT& acc, const Unit& u, int wr, int wc, int fr, int fq) const {
;     ...
;         for (int ai = 0; ai < 2; ++ai)
; #pragma unroll
;             for (int m = 0; m < 4; ++m) { bf16_t* rowp = O + (size_t)(row0 + ai * HALF + m * 16) * DFF + col0;
; #pragma unroll
;                 for (int bj = 0; bj < 2; ++bj) { f32x4 v0 = acc[ai][bj][m][0], v1 = acc[ai][bj][m][1];
; #pragma unroll
;                     for (int j = 0; j < 4; ++j) { float a = fmaxf(v0[j], 0.f), b = fmaxf(v1[j], 0.f); v0[j] = a * a; v1[j] = b * b; }
;                     u32x4 w; w.x = cvt_pk_bf16(v0[0], v0[1]); w.y = cvt_pk_bf16(v0[2], v0[3]); w.z = cvt_pk_bf16(v1[0], v1[1]); w.w = cvt_pk_bf16(v1[2], v1[3]);
;                     *(u32x4*)(rowp + bj * HALF) = w; } }
	v_max_f32_e32 v100, 0, v100
	v_max_f32_e32 v101, 0, v101
	v_max_f32_e32 v96, 0, v96
	v_max_f32_e32 v97, 0, v97
	v_max_f32_e32 v99, 0, v99
	v_pk_mul_f32 v[100:101], v[100:101], v[100:101]
	v_pk_mul_f32 v[102:103], v[96:97], v[96:97]
	v_pk_mul_f32 v[106:107], v[98:99], v[98:99]
	v_cvt_pk_bf16_f32 v96, v100, v101
	v_cvt_pk_bf16_f32 v97, v102, v103
	v_cvt_pk_bf16_f32 v98, v104, v105
	v_cvt_pk_bf16_f32 v99, v106, v107
	v_max_f32_e32 v88, 0, v88
	v_max_f32_e32 v89, 0, v89
	global_store_dwordx4 v[112:113], v[96:99], off offset:256
	s_nop 1
	v_or_b32_e32 v96, 32, v152
	v_pk_mul_f32 v[98:99], v[88:89], v[88:89]
	v_max_f32_e32 v89, v90, v90
	v_ashrrev_i32_e32 v97, 31, v96
	v_max_f32_e32 v88, v94, v94
	v_max_f32_e32 v90, 0, v89
	v_max_f32_e32 v89, v95, v95
	v_lshlrev_b64 v[96:97], 14, v[96:97]
	v_max_f32_e32 v92, 0, v92
	v_max_f32_e32 v93, 0, v93
	v_max_f32_e32 v88, 0, v88
	v_max_f32_e32 v89, 0, v89
	v_max_f32_e32 v91, 0, v91
	v_lshl_add_u64 v[96:97], s[88:89], 0, v[96:97]
	v_pk_mul_f32 v[92:93], v[92:93], v[92:93]
	v_pk_mul_f32 v[94:95], v[88:89], v[88:89]
	v_pk_mul_f32 v[100:101], v[90:91], v[90:91]
	v_lshl_add_u64 v[96:97], v[96:97], 0, v[156:157]
	v_cvt_pk_bf16_f32 v88, v92, v93
	v_cvt_pk_bf16_f32 v89, v94, v95
	v_cvt_pk_bf16_f32 v90, v98, v99
	v_cvt_pk_bf16_f32 v91, v100, v101
	v_max_f32_e32 v80, 0, v80
	v_max_f32_e32 v81, 0, v81
	global_store_dwordx4 v[96:97], v[88:91], off
	s_nop 1
	v_pk_mul_f32 v[88:89], v[80:81], v[80:81]
	v_max_f32_e32 v81, v82, v82
	v_max_f32_e32 v80, v86, v86
	v_max_f32_e32 v82, 0, v81
	v_max_f32_e32 v81, v87, v87
	v_max_f32_e32 v84, 0, v84
	v_max_f32_e32 v85, 0, v85
	v_max_f32_e32 v80, 0, v80
	v_max_f32_e32 v81, 0, v81
	v_max_f32_e32 v83, 0, v83
	v_pk_mul_f32 v[84:85], v[84:85], v[84:85]
	v_pk_mul_f32 v[86:87], v[80:81], v[80:81]
	v_pk_mul_f32 v[90:91], v[82:83], v[82:83]
	v_cvt_pk_bf16_f32 v80, v84, v85
	v_cvt_pk_bf16_f32 v81, v86, v87
	v_cvt_pk_bf16_f32 v82, v88, v89
	v_cvt_pk_bf16_f32 v83, v90, v91
	v_max_f32_e32 v72, 0, v72
	v_max_f32_e32 v73, 0, v73
	global_store_dwordx4 v[96:97], v[80:83], off offset:256
	s_nop 1
	v_or_b32_e32 v80, 48, v152
	v_pk_mul_f32 v[82:83], v[72:73], v[72:73]
	v_max_f32_e32 v73, v74, v74
	v_ashrrev_i32_e32 v81, 31, v80
	v_max_f32_e32 v72, v78, v78
	v_max_f32_e32 v74, 0, v73
	v_max_f32_e32 v73, v79, v79
	v_lshlrev_b64 v[80:81], 14, v[80:81]
	v_max_f32_e32 v76, 0, v76
	v_max_f32_e32 v77, 0, v77
	v_max_f32_e32 v72, 0, v72
	v_max_f32_e32 v73, 0, v73
	v_max_f32_e32 v75, 0, v75
	v_lshl_add_u64 v[80:81], s[88:89], 0, v[80:81]
	v_pk_mul_f32 v[76:77], v[76:77], v[76:77]
	v_pk_mul_f32 v[78:79], v[72:73], v[72:73]
	v_pk_mul_f32 v[84:85], v[74:75], v[74:75]
	v_lshl_add_u64 v[80:81], v[80:81], 0, v[156:157]
	v_cvt_pk_bf16_f32 v72, v76, v77
	v_cvt_pk_bf16_f32 v73, v78, v79
	v_cvt_pk_bf16_f32 v74, v82, v83
	v_cvt_pk_bf16_f32 v75, v84, v85
	v_max_f32_e32 v64, 0, v64
	v_max_f32_e32 v65, 0, v65
	global_store_dwordx4 v[80:81], v[72:75], off
	s_nop 1
	v_pk_mul_f32 v[72:73], v[64:65], v[64:65]
	v_max_f32_e32 v65, v66, v66
	v_max_f32_e32 v64, v70, v70
	v_max_f32_e32 v66, 0, v65
	v_max_f32_e32 v65, v71, v71
	v_max_f32_e32 v68, 0, v68
	v_max_f32_e32 v69, 0, v69
	v_max_f32_e32 v64, 0, v64
	v_max_f32_e32 v65, 0, v65
	v_max_f32_e32 v67, 0, v67
	v_pk_mul_f32 v[68:69], v[68:69], v[68:69]
	v_pk_mul_f32 v[70:71], v[64:65], v[64:65]
	v_pk_mul_f32 v[74:75], v[66:67], v[66:67]
	v_cvt_pk_bf16_f32 v64, v68, v69
	v_cvt_pk_bf16_f32 v65, v70, v71
	v_cvt_pk_bf16_f32 v66, v72, v73
	v_cvt_pk_bf16_f32 v67, v74, v75
	v_max_f32_e32 v56, 0, v56
	v_max_f32_e32 v57, 0, v57
	global_store_dwordx4 v[80:81], v[64:67], off offset:256
	s_nop 1
	v_pk_mul_f32 v[66:67], v[56:57], v[56:57]
	v_max_f32_e32 v57, v58, v58
	v_max_f32_e32 v60, 0, v60
	v_max_f32_e32 v61, 0, v61
	v_max_f32_e32 v56, v62, v62
	v_max_f32_e32 v58, 0, v57
	v_max_f32_e32 v57, v63, v63
	v_pk_mul_f32 v[60:61], v[60:61], v[60:61]
	v_max_f32_e32 v56, 0, v56
	v_max_f32_e32 v57, 0, v57
	v_max_f32_e32 v59, 0, v59
	s_mov_b32 s5, 0x200000
	v_pk_mul_f32 v[62:63], v[56:57], v[56:57]
	v_pk_mul_f32 v[68:69], v[58:59], v[58:59]
	v_cvt_pk_bf16_f32 v56, v60, v61
	v_add_co_u32_e32 v60, vcc, s5, v144
	v_cvt_pk_bf16_f32 v57, v62, v63
	v_cvt_pk_bf16_f32 v58, v66, v67
	v_cvt_pk_bf16_f32 v59, v68, v69
	v_addc_co_u32_e32 v61, vcc, 0, v145, vcc
	v_max_f32_e32 v48, 0, v48
	v_max_f32_e32 v49, 0, v49
	global_store_dwordx4 v[60:61], v[56:59], off
	s_nop 1
	v_pk_mul_f32 v[56:57], v[48:49], v[48:49]
	v_max_f32_e32 v49, v50, v50
	v_max_f32_e32 v48, v54, v54
	v_max_f32_e32 v50, 0, v49
	v_max_f32_e32 v49, v55, v55
	v_max_f32_e32 v52, 0, v52
	v_max_f32_e32 v53, 0, v53
	v_max_f32_e32 v48, 0, v48
	v_max_f32_e32 v49, 0, v49
	v_max_f32_e32 v51, 0, v51
	s_mov_b64 s[28:29], 0x200000
	v_pk_mul_f32 v[52:53], v[52:53], v[52:53]
	v_pk_mul_f32 v[54:55], v[48:49], v[48:49]
	v_pk_mul_f32 v[58:59], v[50:51], v[50:51]
	v_lshl_add_u64 v[64:65], v[144:145], 0, s[28:29]
; __device__ __forceinline__ unsigned cvt_pk_bf16(float lo, float hi) { const bf16x2_t r = __builtin_convertvector((f32x2){lo, hi}, bf16x2_t); return __builtin_bit_cast(unsigned, r); }
; #define PG8_WAIT_V(n) asm volatile("s_waitcnt vmcnt(" #n ")" ::: "memory")
; #define PG8_BAR __builtin_amdgcn_s_barrier()
; template <class Epi>
; __device__ __forceinline__ void gemm_phase(LAS unsigned char* lds, const bf16_t* A, int lda, const bf16_t* Bt, int ldb, int M, int N, int K, int asel, const Epi& E, const int fixed_round = -1) {
;     ...
;         if (!has_next) break;
; #pragma unroll
;         for (int a = 0; a < 2; ++a)
; #pragma unroll
;             for (int b = 0; b < 2; ++b)
; #pragma unroll
;                 for (int m = 0; m < 4; ++m)
; #pragma unroll
;                     for (int n = 0; n < 2; ++n) acc[a][b][m][n] = (f32x4){0.f, 0.f, 0.f, 0.f};
;         cur = nxt; cA = nA; cB = nB; ++ui;
;     }
;     PG8_WAIT_V(0);
;     if (wr == 0) PG8_BAR;
;     PG8_BAR;
;     __device__ __forceinline__ void operator()(const AccT& acc, const Unit& u, int wr, int wc, int fr, int fq) const {
;     ...
;         for (int ai = 0; ai < 2; ++ai)
; #pragma unroll
;             for (int m = 0; m < 4; ++m) { bf16_t* rowp = O + (size_t)(row0 + ai * HALF + m * 16) * DFF + col0;
; #pragma unroll
;                 for (int bj = 0; bj < 2; ++bj) { f32x4 v0 = acc[ai][bj][m][0], v1 = acc[ai][bj][m][1];
; #pragma unroll
;                     for (int j = 0; j < 4; ++j) { float a = fmaxf(v0[j], 0.f), b = fmaxf(v1[j], 0.f); v0[j] = a * a; v1[j] = b * b; }
;                     u32x4 w; w.x = cvt_pk_bf16(v0[0], v0[1]); w.y = cvt_pk_bf16(v0[2], v0[3]); w.z = cvt_pk_bf16(v1[0], v1[1]); w.w = cvt_pk_bf16(v1[2], v1[3]);
;                     *(u32x4*)(rowp + bj * HALF) = w; } }
	v_cvt_pk_bf16_f32 v48, v52, v53
	v_cvt_pk_bf16_f32 v49, v54, v55
	v_cvt_pk_bf16_f32 v50, v56, v57
	v_cvt_pk_bf16_f32 v51, v58, v59
	v_max_f32_e32 v40, 0, v40
	v_max_f32_e32 v41, 0, v41
	global_store_dwordx4 v[64:65], v[48:51], off offset:256
	s_nop 1
	v_pk_mul_f32 v[50:51], v[40:41], v[40:41]
	v_max_f32_e32 v41, v42, v42
	v_max_f32_e32 v44, 0, v44
	v_max_f32_e32 v45, 0, v45
	v_max_f32_e32 v40, v46, v46
	v_max_f32_e32 v42, 0, v41
	v_max_f32_e32 v41, v47, v47
	v_pk_mul_f32 v[44:45], v[44:45], v[44:45]
	v_max_f32_e32 v40, 0, v40
	v_max_f32_e32 v41, 0, v41
	v_max_f32_e32 v43, 0, v43
	s_mov_b32 s5, 0x240000
	v_pk_mul_f32 v[46:47], v[40:41], v[40:41]
	v_pk_mul_f32 v[52:53], v[42:43], v[42:43]
	v_cvt_pk_bf16_f32 v40, v44, v45
	v_add_co_u32_e32 v44, vcc, s5, v144
	v_cvt_pk_bf16_f32 v41, v46, v47
	v_cvt_pk_bf16_f32 v42, v50, v51
	v_cvt_pk_bf16_f32 v43, v52, v53
	v_addc_co_u32_e32 v45, vcc, 0, v145, vcc
	v_max_f32_e32 v32, 0, v32
	v_max_f32_e32 v33, 0, v33
	global_store_dwordx4 v[44:45], v[40:43], off
	s_nop 1
	v_pk_mul_f32 v[40:41], v[32:33], v[32:33]
	v_max_f32_e32 v33, v34, v34
	v_max_f32_e32 v32, v38, v38
	v_max_f32_e32 v34, 0, v33
	v_max_f32_e32 v33, v39, v39
	v_max_f32_e32 v36, 0, v36
	v_max_f32_e32 v37, 0, v37
	v_max_f32_e32 v32, 0, v32
	v_max_f32_e32 v33, 0, v33
	v_max_f32_e32 v35, 0, v35
	s_mov_b64 s[28:29], 0x240000
	v_pk_mul_f32 v[36:37], v[36:37], v[36:37]
	v_pk_mul_f32 v[38:39], v[32:33], v[32:33]
	v_pk_mul_f32 v[42:43], v[34:35], v[34:35]
	v_lshl_add_u64 v[48:49], v[144:145], 0, s[28:29]
	v_cvt_pk_bf16_f32 v32, v36, v37
	v_cvt_pk_bf16_f32 v33, v38, v39
	v_cvt_pk_bf16_f32 v34, v40, v41
	v_cvt_pk_bf16_f32 v35, v42, v43
	v_max_f32_e32 v24, 0, v24
	v_max_f32_e32 v25, 0, v25
	global_store_dwordx4 v[48:49], v[32:35], off offset:256
	s_nop 1
	v_pk_mul_f32 v[34:35], v[24:25], v[24:25]
	v_max_f32_e32 v25, v26, v26
	v_max_f32_e32 v28, 0, v28
	v_max_f32_e32 v29, 0, v29
	v_max_f32_e32 v24, v30, v30
	v_max_f32_e32 v26, 0, v25
	v_max_f32_e32 v25, v31, v31
	v_pk_mul_f32 v[28:29], v[28:29], v[28:29]
	v_max_f32_e32 v24, 0, v24
	v_max_f32_e32 v25, 0, v25
	v_max_f32_e32 v27, 0, v27
	s_mov_b32 s5, 0x280000
	v_pk_mul_f32 v[30:31], v[24:25], v[24:25]
	v_pk_mul_f32 v[36:37], v[26:27], v[26:27]
	v_cvt_pk_bf16_f32 v24, v28, v29
	v_add_co_u32_e32 v28, vcc, s5, v144
	v_cvt_pk_bf16_f32 v25, v30, v31
	v_cvt_pk_bf16_f32 v26, v34, v35
	v_cvt_pk_bf16_f32 v27, v36, v37
	v_addc_co_u32_e32 v29, vcc, 0, v145, vcc
	v_max_f32_e32 v16, 0, v16
	v_max_f32_e32 v17, 0, v17
	global_store_dwordx4 v[28:29], v[24:27], off
	s_nop 1
	v_pk_mul_f32 v[24:25], v[16:17], v[16:17]
	v_max_f32_e32 v17, v18, v18
	v_max_f32_e32 v16, v22, v22
	v_max_f32_e32 v18, 0, v17
	v_max_f32_e32 v17, v23, v23
	v_max_f32_e32 v20, 0, v20
	v_max_f32_e32 v21, 0, v21
	v_max_f32_e32 v16, 0, v16
	v_max_f32_e32 v17, 0, v17
	v_max_f32_e32 v19, 0, v19
	s_mov_b64 s[28:29], 0x280000
	v_pk_mul_f32 v[20:21], v[20:21], v[20:21]
	v_pk_mul_f32 v[22:23], v[16:17], v[16:17]
	v_pk_mul_f32 v[26:27], v[18:19], v[18:19]
	v_lshl_add_u64 v[32:33], v[144:145], 0, s[28:29]
	v_cvt_pk_bf16_f32 v16, v20, v21
	v_cvt_pk_bf16_f32 v17, v22, v23
	v_cvt_pk_bf16_f32 v18, v24, v25
	v_cvt_pk_bf16_f32 v19, v26, v27
	v_max_f32_e32 v8, 0, v8
	v_max_f32_e32 v9, 0, v9
	global_store_dwordx4 v[32:33], v[16:19], off offset:256
	s_nop 1
	v_pk_mul_f32 v[18:19], v[8:9], v[8:9]
	v_max_f32_e32 v9, v10, v10
	v_max_f32_e32 v12, 0, v12
	v_max_f32_e32 v13, 0, v13
	v_max_f32_e32 v8, v14, v14
	v_max_f32_e32 v10, 0, v9
	v_max_f32_e32 v9, v15, v15
	v_pk_mul_f32 v[12:13], v[12:13], v[12:13]
	v_max_f32_e32 v8, 0, v8
	v_max_f32_e32 v9, 0, v9
	v_max_f32_e32 v11, 0, v11
	v_pk_mul_f32 v[14:15], v[8:9], v[8:9]
	v_pk_mul_f32 v[20:21], v[10:11], v[10:11]
	v_cvt_pk_bf16_f32 v8, v12, v13
	v_add_co_u32_e32 v12, vcc, s50, v144
	v_cvt_pk_bf16_f32 v9, v14, v15
	v_cvt_pk_bf16_f32 v10, v18, v19
	v_cvt_pk_bf16_f32 v11, v20, v21
	v_addc_co_u32_e32 v13, vcc, 0, v145, vcc
	v_max_f32_e32 v0, 0, v0
	v_max_f32_e32 v1, 0, v1
	global_store_dwordx4 v[12:13], v[8:11], off
	s_nop 1
	v_pk_mul_f32 v[8:9], v[0:1], v[0:1]
	v_max_f32_e32 v1, v2, v2
	v_max_f32_e32 v0, v6, v6
	v_max_f32_e32 v2, 0, v1
	v_max_f32_e32 v1, v7, v7
	v_max_f32_e32 v4, 0, v4
	v_max_f32_e32 v5, 0, v5
	v_max_f32_e32 v0, 0, v0
	v_max_f32_e32 v1, 0, v1
	v_max_f32_e32 v3, 0, v3
	s_mov_b64 s[28:29], 0x2c0000
	v_pk_mul_f32 v[4:5], v[4:5], v[4:5]
	v_pk_mul_f32 v[6:7], v[0:1], v[0:1]
	v_pk_mul_f32 v[10:11], v[2:3], v[2:3]
	v_lshl_add_u64 v[16:17], v[144:145], 0, s[28:29]
	v_cvt_pk_bf16_f32 v0, v4, v5
	v_cvt_pk_bf16_f32 v1, v6, v7
	v_cvt_pk_bf16_f32 v2, v8, v9
	v_cvt_pk_bf16_f32 v3, v10, v11
	s_and_b64 vcc, exec, s[0:1]
	s_mov_b32 s51, s4
	s_mov_b32 s26, s6
	s_mov_b64 s[34:35], s[20:21]
	s_mov_b64 s[30:31], s[18:19]
	global_store_dwordx4 v[16:17], v[0:3], off offset:256
	s_cbranch_vccz .LBB0_584
	s_waitcnt vmcnt(0)
	s_cmpk_gt_u32 s33, 0xff
	s_cbranch_scc1 .LBB0_595
	s_barrier

; #define PG8_STAGE(bufoff, gbase, voff) do { _Pragma("unroll") for (int _i = 0; _i < 2; ++_i) \
;         __builtin_amdgcn_global_load_lds((const unsigned*)((const char*)(gbase) + (voff)[_i]), (LAS unsigned*)(lds + (bufoff) + ldsw + _i * 8192), 16, 0, 0); } while (0)
; #define PG8_LDA(dst, b, h) do { _Pragma("unroll") for (int m = 0; m < 4; ++m) _Pragma("unroll") for (int k = 0; k < 2; ++k) dst[m][k] = *(const LAS bf16x8*)(lds + PG8_SA(b, h) + aoff + m * 2048 + k * 1024); } while (0)
; #define PG8_LDB(dst, b, h) do { _Pragma("unroll") for (int n = 0; n < 2; ++n) _Pragma("unroll") for (int k = 0; k < 2; ++k) dst[n][k] = *(const LAS bf16x8*)(lds + PG8_SB(b, h) + boff + n * 2048 + k * 1024); } while (0)
; #define PG8_WAIT_V(n) asm volatile("s_waitcnt vmcnt(" #n ")" ::: "memory")
; #define PG8_WAIT_L(n) asm volatile("s_waitcnt lgkmcnt(" #n ")" ::: "memory")
; #define PG8_BAR __builtin_amdgcn_s_barrier()
; #define PG8_SCHED __builtin_amdgcn_sched_barrier(0)
; template <class Epi>
; __device__ __forceinline__ void gemm_phase(LAS unsigned char* lds, const bf16_t* A, int lda, const bf16_t* Bt, int ldb, int M, int N, int K, int asel, const Epi& E, const int fixed_round = -1) {
;     ...
;         const bool has_next = (fixed_round < 0) && S.next(ui + 1, nxt);
;         const char* nA = has_next ? PG8_ABASE(nxt) : cA; const char* nB = has_next ? (const char*)Bt + (size_t)nxt.pn * tstepB : cB;
;         for (int t = 0; t < nt; t += 2) {
;             const bool last = (t == nt - 2);
;             const char* a1 = cA + (size_t)(t + 1) * kstep;
;             const char* a2 = last ? nA : cA + (size_t)(t + 2) * kstep; const char* b2 = last ? nB : cB + (size_t)(t + 2) * kstep;
;             const char* a3 = a2 + kstep; const char* b3 = b2 + kstep;
;             PG8_LDB(B0, 0, 0); PG8_SCHED; PG8_LDA(At, 0, 0); PG8_STAGE(PG8_SA(1, 1), a1 + hstepA, voffA);
;             PG8_WAIT_L(8); PG8_BAR; PG8_WAIT_L(0); PG8_MMA(0, 0, At, B0); PG8_BAR; PG8_SCHED;
;             PG8_LDB(B1, 0, 1); PG8_STAGE(PG8_SB(0, 0), b2, voffB);
;             PG8_BAR; PG8_WAIT_L(0); PG8_MMA(0, 1, At, B1); PG8_BAR;
;             PG8_LDA(At, 0, 1); PG8_STAGE(PG8_SA(0, 0), a2, voffA);
;             PG8_BAR; PG8_WAIT_L(0); PG8_MMA(1, 0, At, B0); PG8_BAR; PG8_SCHED;
;             PG8_STAGE(PG8_SB(0, 1), b2 + hstepB, voffB);
;             PG8_WAIT_V(6); PG8_BAR; PG8_MMA(1, 1, At, B1); PG8_BAR;
.LBB0_651:
	ds_read_b128 v[146:149], v140
	ds_read_b128 v[150:153], v140 offset:1024
	ds_read_b128 v[160:163], v140 offset:2048
	ds_read_b128 v[166:169], v140 offset:3072
	s_mov_b32 m0, s49
	v_lshl_add_u64 v[156:157], v[136:137], 0, s[20:21]
	ds_read_b128 v[170:173], v141
	ds_read_b128 v[174:177], v141 offset:1024
	ds_read_b128 v[178:181], v141 offset:2048
	ds_read_b128 v[182:185], v141 offset:3072
	ds_read_b128 v[186:189], v141 offset:4096
	ds_read_b128 v[190:193], v141 offset:5120
	ds_read_b128 v[194:197], v141 offset:6144
	ds_read_b128 v[202:205], v141 offset:7168
	global_load_lds_dwordx4 v[156:157], off
	v_lshl_add_u64 v[156:157], v[138:139], 0, s[20:21]
	s_mov_b32 m0, s50
	s_nop 0
	global_load_lds_dwordx4 v[156:157], off
	s_waitcnt lgkmcnt(8)
	s_setprio 1
	s_barrier
	s_waitcnt lgkmcnt(0)
	v_mfma_f32_16x16x32_bf16 v[124:127], v[146:149], v[170:173], v[124:127]
	v_mfma_f32_16x16x32_bf16 v[120:123], v[160:163], v[170:173], v[120:123]
	v_mfma_f32_16x16x32_bf16 v[112:115], v[146:149], v[178:181], v[112:115]
	v_mfma_f32_16x16x32_bf16 v[104:107], v[160:163], v[178:181], v[104:107]
	v_mfma_f32_16x16x32_bf16 v[96:99], v[146:149], v[186:189], v[96:99]
	v_mfma_f32_16x16x32_bf16 v[88:91], v[160:163], v[186:189], v[88:91]
	v_mfma_f32_16x16x32_bf16 v[80:83], v[146:149], v[194:197], v[80:83]
	v_mfma_f32_16x16x32_bf16 v[72:75], v[160:163], v[194:197], v[72:75]
	v_mfma_f32_16x16x32_bf16 v[124:127], v[150:153], v[174:177], v[124:127]
	v_mfma_f32_16x16x32_bf16 v[120:123], v[166:169], v[174:177], v[120:123]
	v_mfma_f32_16x16x32_bf16 v[112:115], v[150:153], v[182:185], v[112:115]
	v_mfma_f32_16x16x32_bf16 v[104:107], v[166:169], v[182:185], v[104:107]
	v_mfma_f32_16x16x32_bf16 v[96:99], v[150:153], v[190:193], v[96:99]
	v_mfma_f32_16x16x32_bf16 v[88:91], v[166:169], v[190:193], v[88:91]
	v_mfma_f32_16x16x32_bf16 v[80:83], v[150:153], v[202:205], v[80:83]
	v_mfma_f32_16x16x32_bf16 v[72:75], v[166:169], v[202:205], v[72:75]
	s_setprio 0
	s_barrier
	s_add_u32 s28, s20, 0xe7900080
	s_addc_u32 s29, s21, -1
	s_cmpk_lg_i32 s48, 0x7c
	s_cselect_b32 s28, s28, 0
	s_cselect_b32 s29, s29, 0
	s_add_u32 s36, s86, s28
	s_addc_u32 s37, s87, s29
	s_add_u32 s34, s2, s28
	s_addc_u32 s35, s3, s29
	s_mov_b32 m0, s51
	s_add_u32 s98, s34, s0
	s_addc_u32 s99, s35, s1
	ds_read_b128 v[206:209], v142
	ds_read_b128 v[210:213], v142 offset:1024
	ds_read_b128 v[214:217], v142 offset:2048
	ds_read_b128 v[218:221], v142 offset:3072
	global_load_lds_dwordx4 v130, s[34:35]
	s_mov_b32 m0, s52
	s_nop 0
	global_load_lds_dwordx4 v134, s[34:35]
	s_setprio 1
	s_barrier
	s_waitcnt lgkmcnt(0)
	v_mfma_f32_16x16x32_bf16 v[116:119], v[206:209], v[170:173], v[116:119]
	v_mfma_f32_16x16x32_bf16 v[108:111], v[214:217], v[170:173], v[108:111]
	v_mfma_f32_16x16x32_bf16 v[100:103], v[206:209], v[178:181], v[100:103]
	v_mfma_f32_16x16x32_bf16 v[92:95], v[214:217], v[178:181], v[92:95]
	v_mfma_f32_16x16x32_bf16 v[84:87], v[206:209], v[186:189], v[84:87]
	v_mfma_f32_16x16x32_bf16 v[76:79], v[214:217], v[186:189], v[76:79]
	v_mfma_f32_16x16x32_bf16 v[68:71], v[206:209], v[194:197], v[68:71]
	v_mfma_f32_16x16x32_bf16 v[64:67], v[214:217], v[194:197], v[64:67]
	v_mfma_f32_16x16x32_bf16 v[116:119], v[210:213], v[174:177], v[116:119]
	v_mfma_f32_16x16x32_bf16 v[108:111], v[218:221], v[174:177], v[108:111]
	v_mfma_f32_16x16x32_bf16 v[100:103], v[210:213], v[182:185], v[100:103]
	v_mfma_f32_16x16x32_bf16 v[92:95], v[218:221], v[182:185], v[92:95]
	v_mfma_f32_16x16x32_bf16 v[84:87], v[210:213], v[190:193], v[84:87]
	v_mfma_f32_16x16x32_bf16 v[76:79], v[218:221], v[190:193], v[76:79]
	v_mfma_f32_16x16x32_bf16 v[68:71], v[210:213], v[202:205], v[68:71]
	v_mfma_f32_16x16x32_bf16 v[64:67], v[218:221], v[202:205], v[64:67]
	s_setprio 0
	s_mov_b32 m0, s42
	s_add_u32 s100, s36, s0
	s_addc_u32 s101, s37, s1
	s_barrier
	ds_read_b128 v[170:173], v141 offset:16384
	ds_read_b128 v[174:177], v141 offset:17408
	ds_read_b128 v[178:181], v141 offset:18432
	ds_read_b128 v[182:185], v141 offset:19456
	ds_read_b128 v[186:189], v141 offset:20480
	ds_read_b128 v[190:193], v141 offset:21504
	ds_read_b128 v[194:197], v141 offset:22528
	ds_read_b128 v[202:205], v141 offset:23552
	global_load_lds_dwordx4 v128, s[36:37]
	s_mov_b32 m0, s43
	s_nop 0
	global_load_lds_dwordx4 v132, s[36:37]
	s_setprio 1
	s_barrier
	s_waitcnt lgkmcnt(0)
	v_mfma_f32_16x16x32_bf16 v[60:63], v[146:149], v[170:173], v[60:63]
	v_mfma_f32_16x16x32_bf16 v[56:59], v[160:163], v[170:173], v[56:59]
	v_mfma_f32_16x16x32_bf16 v[48:51], v[146:149], v[178:181], v[48:51]
	v_mfma_f32_16x16x32_bf16 v[40:43], v[160:163], v[178:181], v[40:43]
	v_mfma_f32_16x16x32_bf16 v[32:35], v[146:149], v[186:189], v[32:35]
	v_mfma_f32_16x16x32_bf16 v[24:27], v[160:163], v[186:189], v[24:27]
	v_mfma_f32_16x16x32_bf16 v[16:19], v[146:149], v[194:197], v[16:19]
	v_mfma_f32_16x16x32_bf16 v[8:11], v[160:163], v[194:197], v[8:11]
	v_mfma_f32_16x16x32_bf16 v[60:63], v[150:153], v[174:177], v[60:63]
	v_mfma_f32_16x16x32_bf16 v[56:59], v[166:169], v[174:177], v[56:59]
	v_mfma_f32_16x16x32_bf16 v[48:51], v[150:153], v[182:185], v[48:51]
	v_mfma_f32_16x16x32_bf16 v[40:43], v[166:169], v[182:185], v[40:43]
	v_mfma_f32_16x16x32_bf16 v[32:35], v[150:153], v[190:193], v[32:35]
	v_mfma_f32_16x16x32_bf16 v[24:27], v[166:169], v[190:193], v[24:27]
	v_mfma_f32_16x16x32_bf16 v[16:19], v[150:153], v[202:205], v[16:19]
	v_mfma_f32_16x16x32_bf16 v[8:11], v[166:169], v[202:205], v[8:11]
	s_setprio 0
	s_barrier
	s_add_u32 s28, s34, 0x200000
	s_addc_u32 s29, s35, 0
	s_mov_b32 m0, s53
	s_nop 0
	global_load_lds_dwordx4 v130, s[28:29]
	s_mov_b32 m0, s54
	s_nop 0
	global_load_lds_dwordx4 v134, s[28:29]
	s_waitcnt vmcnt(6)
	s_setprio 1
	s_barrier
; #define PG8_STAGE(bufoff, gbase, voff) do { _Pragma("unroll") for (int _i = 0; _i < 2; ++_i) \
;         __builtin_amdgcn_global_load_lds((const unsigned*)((const char*)(gbase) + (voff)[_i]), (LAS unsigned*)(lds + (bufoff) + ldsw + _i * 8192), 16, 0, 0); } while (0)
; #define PG8_LDA(dst, b, h) do { _Pragma("unroll") for (int m = 0; m < 4; ++m) _Pragma("unroll") for (int k = 0; k < 2; ++k) dst[m][k] = *(const LAS bf16x8*)(lds + PG8_SA(b, h) + aoff + m * 2048 + k * 1024); } while (0)
; #define PG8_LDB(dst, b, h) do { _Pragma("unroll") for (int n = 0; n < 2; ++n) _Pragma("unroll") for (int k = 0; k < 2; ++k) dst[n][k] = *(const LAS bf16x8*)(lds + PG8_SB(b, h) + boff + n * 2048 + k * 1024); } while (0)
; #define PG8_WAIT_V(n) asm volatile("s_waitcnt vmcnt(" #n ")" ::: "memory")
; #define PG8_WAIT_L(n) asm volatile("s_waitcnt lgkmcnt(" #n ")" ::: "memory")
; #define PG8_BAR __builtin_amdgcn_s_barrier()
; #define PG8_SCHED __builtin_amdgcn_sched_barrier(0)
; template <class Epi>
; __device__ __forceinline__ void gemm_phase(LAS unsigned char* lds, const bf16_t* A, int lda, const bf16_t* Bt, int ldb, int M, int N, int K, int asel, const Epi& E, const int fixed_round = -1) {
;     ...
;             PG8_WAIT_V(6); PG8_BAR; PG8_MMA(1, 1, At, B1); PG8_BAR;
;             PG8_LDB(B0, 1, 0); PG8_SCHED; PG8_LDA(At, 1, 0); PG8_STAGE(PG8_SA(0, 1), a2 + hstepA, voffA);
;             PG8_WAIT_L(8); PG8_BAR; PG8_WAIT_L(0); PG8_MMA(0, 0, At, B0); PG8_BAR; PG8_SCHED;
;             PG8_LDB(B1, 1, 1); PG8_STAGE(PG8_SB(1, 0), b3, voffB);
;             PG8_BAR; PG8_WAIT_L(0); PG8_MMA(0, 1, At, B1); PG8_BAR;
;             PG8_LDA(At, 1, 1); PG8_STAGE(PG8_SA(1, 0), a3, voffA);
;             PG8_BAR; PG8_WAIT_L(0); PG8_MMA(1, 0, At, B0); PG8_BAR; PG8_SCHED;
	v_mfma_f32_16x16x32_bf16 v[52:55], v[206:209], v[170:173], v[52:55]
	v_mfma_f32_16x16x32_bf16 v[44:47], v[214:217], v[170:173], v[44:47]
	v_mfma_f32_16x16x32_bf16 v[36:39], v[206:209], v[178:181], v[36:39]
	v_mfma_f32_16x16x32_bf16 v[28:31], v[214:217], v[178:181], v[28:31]
	v_mfma_f32_16x16x32_bf16 v[20:23], v[206:209], v[186:189], v[20:23]
	v_mfma_f32_16x16x32_bf16 v[12:15], v[214:217], v[186:189], v[12:15]
	v_mfma_f32_16x16x32_bf16 v[4:7], v[206:209], v[194:197], v[4:7]
	v_mfma_f32_16x16x32_bf16 v[0:3], v[214:217], v[194:197], v[0:3]
	v_mfma_f32_16x16x32_bf16 v[52:55], v[210:213], v[174:177], v[52:55]
	v_mfma_f32_16x16x32_bf16 v[44:47], v[218:221], v[174:177], v[44:47]
	v_mfma_f32_16x16x32_bf16 v[36:39], v[210:213], v[182:185], v[36:39]
	v_mfma_f32_16x16x32_bf16 v[28:31], v[218:221], v[182:185], v[28:31]
	v_mfma_f32_16x16x32_bf16 v[20:23], v[210:213], v[190:193], v[20:23]
	v_mfma_f32_16x16x32_bf16 v[12:15], v[218:221], v[190:193], v[12:15]
	v_mfma_f32_16x16x32_bf16 v[4:7], v[210:213], v[202:205], v[4:7]
	v_mfma_f32_16x16x32_bf16 v[0:3], v[218:221], v[202:205], v[0:3]
	s_setprio 0
	s_barrier
	ds_read_b128 v[146:149], v143
	ds_read_b128 v[150:153], v143 offset:1024
	ds_read_b128 v[160:163], v143 offset:2048
	ds_read_b128 v[166:169], v143 offset:3072
	s_add_u32 s28, s36, 0x200000
	s_addc_u32 s29, s37, 0
	s_mov_b32 m0, s44
	ds_read_b128 v[170:173], v141 offset:32768
	ds_read_b128 v[174:177], v141 offset:33792
	ds_read_b128 v[178:181], v141 offset:34816
	ds_read_b128 v[182:185], v141 offset:35840
	ds_read_b128 v[186:189], v141 offset:36864
	ds_read_b128 v[190:193], v141 offset:37888
	ds_read_b128 v[194:197], v141 offset:38912
	ds_read_b128 v[202:205], v141 offset:39936
	global_load_lds_dwordx4 v128, s[28:29]
	s_mov_b32 m0, s45
	s_nop 0
	global_load_lds_dwordx4 v132, s[28:29]
	s_waitcnt lgkmcnt(8)
	s_setprio 1
	s_barrier
	s_waitcnt lgkmcnt(0)
	v_mfma_f32_16x16x32_bf16 v[124:127], v[146:149], v[170:173], v[124:127]
	v_mfma_f32_16x16x32_bf16 v[120:123], v[160:163], v[170:173], v[120:123]
	v_mfma_f32_16x16x32_bf16 v[112:115], v[146:149], v[178:181], v[112:115]
	v_mfma_f32_16x16x32_bf16 v[104:107], v[160:163], v[178:181], v[104:107]
	v_mfma_f32_16x16x32_bf16 v[96:99], v[146:149], v[186:189], v[96:99]
	v_mfma_f32_16x16x32_bf16 v[88:91], v[160:163], v[186:189], v[88:91]
	v_mfma_f32_16x16x32_bf16 v[80:83], v[146:149], v[194:197], v[80:83]
	v_mfma_f32_16x16x32_bf16 v[72:75], v[160:163], v[194:197], v[72:75]
	v_mfma_f32_16x16x32_bf16 v[124:127], v[150:153], v[174:177], v[124:127]
	v_mfma_f32_16x16x32_bf16 v[120:123], v[166:169], v[174:177], v[120:123]
	v_mfma_f32_16x16x32_bf16 v[112:115], v[150:153], v[182:185], v[112:115]
	v_mfma_f32_16x16x32_bf16 v[104:107], v[166:169], v[182:185], v[104:107]
	v_mfma_f32_16x16x32_bf16 v[96:99], v[150:153], v[190:193], v[96:99]
	v_mfma_f32_16x16x32_bf16 v[88:91], v[166:169], v[190:193], v[88:91]
	v_mfma_f32_16x16x32_bf16 v[80:83], v[150:153], v[202:205], v[80:83]
	v_mfma_f32_16x16x32_bf16 v[72:75], v[166:169], v[202:205], v[72:75]
	s_setprio 0
	s_barrier
	s_mov_b32 m0, s55
	ds_read_b128 v[206:209], v144
	ds_read_b128 v[210:213], v144 offset:1024
	ds_read_b128 v[214:217], v144 offset:2048
	ds_read_b128 v[218:221], v144 offset:3072
	global_load_lds_dwordx4 v130, s[98:99]
	s_mov_b32 m0, s56
	s_nop 0
	global_load_lds_dwordx4 v134, s[98:99]
	s_setprio 1
	s_barrier
; #define PG8_STAGE(bufoff, gbase, voff) do { _Pragma("unroll") for (int _i = 0; _i < 2; ++_i) \
;         __builtin_amdgcn_global_load_lds((const unsigned*)((const char*)(gbase) + (voff)[_i]), (LAS unsigned*)(lds + (bufoff) + ldsw + _i * 8192), 16, 0, 0); } while (0)
; #define PG8_LDA(dst, b, h) do { _Pragma("unroll") for (int m = 0; m < 4; ++m) _Pragma("unroll") for (int k = 0; k < 2; ++k) dst[m][k] = *(const LAS bf16x8*)(lds + PG8_SA(b, h) + aoff + m * 2048 + k * 1024); } while (0)
; #define PG8_WAIT_V(n) asm volatile("s_waitcnt vmcnt(" #n ")" ::: "memory")
; #define PG8_WAIT_L(n) asm volatile("s_waitcnt lgkmcnt(" #n ")" ::: "memory")
; #define PG8_BAR __builtin_amdgcn_s_barrier()
; #define PG8_SCHED __builtin_amdgcn_sched_barrier(0)
; template <class Epi>
; __device__ __forceinline__ void gemm_phase(LAS unsigned char* lds, const bf16_t* A, int lda, const bf16_t* Bt, int ldb, int M, int N, int K, int asel, const Epi& E, const int fixed_round = -1) {
;     ...
;             PG8_BAR; PG8_WAIT_L(0); PG8_MMA(0, 1, At, B1); PG8_BAR;
;             PG8_LDA(At, 1, 1); PG8_STAGE(PG8_SA(1, 0), a3, voffA);
;             PG8_BAR; PG8_WAIT_L(0); PG8_MMA(1, 0, At, B0); PG8_BAR; PG8_SCHED;
;             PG8_STAGE(PG8_SB(1, 1), b3 + hstepB, voffB);
;             PG8_WAIT_V(6); PG8_BAR; PG8_MMA(1, 1, At, B1); PG8_BAR;
;     ...
;     PG8_WAIT_V(0);
;     if (wr == 0) PG8_BAR;
;     PG8_BAR;
	s_waitcnt lgkmcnt(0)
	v_mfma_f32_16x16x32_bf16 v[116:119], v[206:209], v[170:173], v[116:119]
	v_mfma_f32_16x16x32_bf16 v[108:111], v[214:217], v[170:173], v[108:111]
	v_mfma_f32_16x16x32_bf16 v[100:103], v[206:209], v[178:181], v[100:103]
	v_mfma_f32_16x16x32_bf16 v[92:95], v[214:217], v[178:181], v[92:95]
	v_mfma_f32_16x16x32_bf16 v[84:87], v[206:209], v[186:189], v[84:87]
	v_mfma_f32_16x16x32_bf16 v[76:79], v[214:217], v[186:189], v[76:79]
	v_mfma_f32_16x16x32_bf16 v[68:71], v[206:209], v[194:197], v[68:71]
	v_mfma_f32_16x16x32_bf16 v[64:67], v[214:217], v[194:197], v[64:67]
	v_mfma_f32_16x16x32_bf16 v[116:119], v[210:213], v[174:177], v[116:119]
	v_mfma_f32_16x16x32_bf16 v[108:111], v[218:221], v[174:177], v[108:111]
	v_mfma_f32_16x16x32_bf16 v[100:103], v[210:213], v[182:185], v[100:103]
	v_mfma_f32_16x16x32_bf16 v[92:95], v[218:221], v[182:185], v[92:95]
	v_mfma_f32_16x16x32_bf16 v[84:87], v[210:213], v[190:193], v[84:87]
	v_mfma_f32_16x16x32_bf16 v[76:79], v[218:221], v[190:193], v[76:79]
	v_mfma_f32_16x16x32_bf16 v[68:71], v[210:213], v[202:205], v[68:71]
	v_mfma_f32_16x16x32_bf16 v[64:67], v[218:221], v[202:205], v[64:67]
	s_setprio 0
	s_mov_b32 m0, s46
	s_barrier
	ds_read_b128 v[170:173], v141 offset:49152
	ds_read_b128 v[174:177], v141 offset:50176
	ds_read_b128 v[178:181], v141 offset:51200
	ds_read_b128 v[182:185], v141 offset:52224
	ds_read_b128 v[186:189], v141 offset:53248
	ds_read_b128 v[190:193], v141 offset:54272
	ds_read_b128 v[194:197], v141 offset:55296
	ds_read_b128 v[202:205], v141 offset:56320
	global_load_lds_dwordx4 v128, s[100:101]
	s_mov_b32 m0, s47
	s_nop 0
	global_load_lds_dwordx4 v132, s[100:101]
	s_setprio 1
	s_barrier
	s_waitcnt lgkmcnt(0)
	v_mfma_f32_16x16x32_bf16 v[60:63], v[146:149], v[170:173], v[60:63]
	v_mfma_f32_16x16x32_bf16 v[56:59], v[160:163], v[170:173], v[56:59]
	v_mfma_f32_16x16x32_bf16 v[48:51], v[146:149], v[178:181], v[48:51]
	v_mfma_f32_16x16x32_bf16 v[40:43], v[160:163], v[178:181], v[40:43]
	v_mfma_f32_16x16x32_bf16 v[32:35], v[146:149], v[186:189], v[32:35]
	v_mfma_f32_16x16x32_bf16 v[24:27], v[160:163], v[186:189], v[24:27]
	v_mfma_f32_16x16x32_bf16 v[16:19], v[146:149], v[194:197], v[16:19]
	v_mfma_f32_16x16x32_bf16 v[8:11], v[160:163], v[194:197], v[8:11]
	v_mfma_f32_16x16x32_bf16 v[60:63], v[150:153], v[174:177], v[60:63]
	v_mfma_f32_16x16x32_bf16 v[56:59], v[166:169], v[174:177], v[56:59]
	v_mfma_f32_16x16x32_bf16 v[48:51], v[150:153], v[182:185], v[48:51]
	v_mfma_f32_16x16x32_bf16 v[40:43], v[166:169], v[182:185], v[40:43]
	v_mfma_f32_16x16x32_bf16 v[32:35], v[150:153], v[190:193], v[32:35]
	v_mfma_f32_16x16x32_bf16 v[24:27], v[166:169], v[190:193], v[24:27]
	v_mfma_f32_16x16x32_bf16 v[16:19], v[150:153], v[202:205], v[16:19]
	v_mfma_f32_16x16x32_bf16 v[8:11], v[166:169], v[202:205], v[8:11]
	s_setprio 0
	s_barrier
	s_add_u32 s28, s34, 0x200080
	s_addc_u32 s29, s35, 0
	s_mov_b32 m0, s57
	s_nop 0
	global_load_lds_dwordx4 v130, s[28:29]
	s_mov_b32 m0, s58
	s_nop 0
	global_load_lds_dwordx4 v134, s[28:29]
	s_waitcnt vmcnt(6)
	s_setprio 1
	s_barrier
	v_mfma_f32_16x16x32_bf16 v[52:55], v[206:209], v[170:173], v[52:55]
	v_mfma_f32_16x16x32_bf16 v[44:47], v[214:217], v[170:173], v[44:47]
	v_mfma_f32_16x16x32_bf16 v[36:39], v[206:209], v[178:181], v[36:39]
	v_mfma_f32_16x16x32_bf16 v[28:31], v[214:217], v[178:181], v[28:31]
	v_mfma_f32_16x16x32_bf16 v[20:23], v[206:209], v[186:189], v[20:23]
	v_mfma_f32_16x16x32_bf16 v[12:15], v[214:217], v[186:189], v[12:15]
	v_mfma_f32_16x16x32_bf16 v[4:7], v[206:209], v[194:197], v[4:7]
	v_mfma_f32_16x16x32_bf16 v[0:3], v[214:217], v[194:197], v[0:3]
	v_mfma_f32_16x16x32_bf16 v[52:55], v[210:213], v[174:177], v[52:55]
	v_mfma_f32_16x16x32_bf16 v[44:47], v[218:221], v[174:177], v[44:47]
	v_mfma_f32_16x16x32_bf16 v[36:39], v[210:213], v[182:185], v[36:39]
	v_mfma_f32_16x16x32_bf16 v[28:31], v[218:221], v[182:185], v[28:31]
	v_mfma_f32_16x16x32_bf16 v[20:23], v[210:213], v[190:193], v[20:23]
	v_mfma_f32_16x16x32_bf16 v[12:15], v[218:221], v[190:193], v[12:15]
	v_mfma_f32_16x16x32_bf16 v[4:7], v[210:213], v[202:205], v[4:7]
	v_mfma_f32_16x16x32_bf16 v[0:3], v[218:221], v[202:205], v[0:3]
	s_setprio 0
	s_add_i32 s48, s48, 2
	s_add_u32 s20, s20, 0x100
	s_addc_u32 s21, s21, 0
	s_cmpk_lt_u32 s48, 0x7e
	s_cbranch_scc1 .Lrot_5
	s_barrier
	s_waitcnt vmcnt(0)
	v_writelane_b32 v255, s8, 26
	s_cmpk_gt_u32 s41, 0xff
	s_nop 0
	v_writelane_b32 v255, s9, 27
	s_cbranch_scc1 .LBB0_654
	s_barrier

; #define PG8_STAGE(bufoff, gbase, voff) do { _Pragma("unroll") for (int _i = 0; _i < 2; ++_i) \
;         __builtin_amdgcn_global_load_lds((const unsigned*)((const char*)(gbase) + (voff)[_i]), (LAS unsigned*)(lds + (bufoff) + ldsw + _i * 8192), 16, 0, 0); } while (0)
; #define PG8_LDA(dst, b, h) do { _Pragma("unroll") for (int m = 0; m < 4; ++m) _Pragma("unroll") for (int k = 0; k < 2; ++k) dst[m][k] = *(const LAS bf16x8*)(lds + PG8_SA(b, h) + aoff + m * 2048 + k * 1024); } while (0)
; #define PG8_LDB(dst, b, h) do { _Pragma("unroll") for (int n = 0; n < 2; ++n) _Pragma("unroll") for (int k = 0; k < 2; ++k) dst[n][k] = *(const LAS bf16x8*)(lds + PG8_SB(b, h) + boff + n * 2048 + k * 1024); } while (0)
; #define PG8_WAIT_V(n) asm volatile("s_waitcnt vmcnt(" #n ")" ::: "memory")
; #define PG8_WAIT_L(n) asm volatile("s_waitcnt lgkmcnt(" #n ")" ::: "memory")
; #define PG8_BAR __builtin_amdgcn_s_barrier()
; #define PG8_SCHED __builtin_amdgcn_sched_barrier(0)
; template <class Epi>
; __device__ __forceinline__ void gemm_phase(LAS unsigned char* lds, const bf16_t* A, int lda, const bf16_t* Bt, int ldb, int M, int N, int K, int asel, const Epi& E, const int fixed_round = -1) {
;     ...
;         const bool has_next = (fixed_round < 0) && S.next(ui + 1, nxt);
;         const char* nA = has_next ? PG8_ABASE(nxt) : cA; const char* nB = has_next ? (const char*)Bt + (size_t)nxt.pn * tstepB : cB;
;         for (int t = 0; t < nt; t += 2) {
;             const bool last = (t == nt - 2);
;             const char* a1 = cA + (size_t)(t + 1) * kstep;
;             const char* a2 = last ? nA : cA + (size_t)(t + 2) * kstep; const char* b2 = last ? nB : cB + (size_t)(t + 2) * kstep;
;             const char* a3 = a2 + kstep; const char* b3 = b2 + kstep;
;             PG8_LDB(B0, 0, 0); PG8_SCHED; PG8_LDA(At, 0, 0); PG8_STAGE(PG8_SA(1, 1), a1 + hstepA, voffA);
;             PG8_WAIT_L(8); PG8_BAR; PG8_WAIT_L(0); PG8_MMA(0, 0, At, B0); PG8_BAR; PG8_SCHED;
;             PG8_LDB(B1, 0, 1); PG8_STAGE(PG8_SB(0, 0), b2, voffB);
;             PG8_BAR; PG8_WAIT_L(0); PG8_MMA(0, 1, At, B1); PG8_BAR;
;             PG8_LDA(At, 0, 1); PG8_STAGE(PG8_SA(0, 0), a2, voffA);
;             PG8_BAR; PG8_WAIT_L(0); PG8_MMA(1, 0, At, B0); PG8_BAR; PG8_SCHED;
;             PG8_STAGE(PG8_SB(0, 1), b2 + hstepB, voffB);
;             PG8_WAIT_V(6); PG8_BAR; PG8_MMA(1, 1, At, B1); PG8_BAR;
.LBB0_690:
	ds_read_b128 v[146:149], v138
	ds_read_b128 v[150:153], v138 offset:1024
	ds_read_b128 v[160:163], v138 offset:2048
	ds_read_b128 v[166:169], v138 offset:3072
	s_mov_b32 m0, s59
	v_lshl_add_u64 v[156:157], v[134:135], 0, s[4:5]
	ds_read_b128 v[170:173], v139
	ds_read_b128 v[174:177], v139 offset:1024
	ds_read_b128 v[178:181], v139 offset:2048
	ds_read_b128 v[182:185], v139 offset:3072
	ds_read_b128 v[186:189], v139 offset:4096
	ds_read_b128 v[190:193], v139 offset:5120
	ds_read_b128 v[194:197], v139 offset:6144
	ds_read_b128 v[202:205], v139 offset:7168
	global_load_lds_dwordx4 v[156:157], off
	v_lshl_add_u64 v[156:157], v[136:137], 0, s[4:5]
	s_mov_b32 m0, s60
	s_nop 0
	global_load_lds_dwordx4 v[156:157], off
	s_waitcnt lgkmcnt(8)
	s_setprio 1
	s_barrier
	s_waitcnt lgkmcnt(0)
	v_mfma_f32_16x16x32_bf16 v[124:127], v[146:149], v[170:173], v[124:127]
	v_mfma_f32_16x16x32_bf16 v[120:123], v[160:163], v[170:173], v[120:123]
	v_mfma_f32_16x16x32_bf16 v[112:115], v[146:149], v[178:181], v[112:115]
	v_mfma_f32_16x16x32_bf16 v[104:107], v[160:163], v[178:181], v[104:107]
	v_mfma_f32_16x16x32_bf16 v[96:99], v[146:149], v[186:189], v[96:99]
	v_mfma_f32_16x16x32_bf16 v[88:91], v[160:163], v[186:189], v[88:91]
	v_mfma_f32_16x16x32_bf16 v[80:83], v[146:149], v[194:197], v[80:83]
	v_mfma_f32_16x16x32_bf16 v[72:75], v[160:163], v[194:197], v[72:75]
	v_mfma_f32_16x16x32_bf16 v[124:127], v[150:153], v[174:177], v[124:127]
	v_mfma_f32_16x16x32_bf16 v[120:123], v[166:169], v[174:177], v[120:123]
	v_mfma_f32_16x16x32_bf16 v[112:115], v[150:153], v[182:185], v[112:115]
	v_mfma_f32_16x16x32_bf16 v[104:107], v[166:169], v[182:185], v[104:107]
	v_mfma_f32_16x16x32_bf16 v[96:99], v[150:153], v[190:193], v[96:99]
	v_mfma_f32_16x16x32_bf16 v[88:91], v[166:169], v[190:193], v[88:91]
	v_mfma_f32_16x16x32_bf16 v[80:83], v[150:153], v[202:205], v[80:83]
	v_mfma_f32_16x16x32_bf16 v[72:75], v[166:169], v[202:205], v[72:75]
	s_setprio 0
	s_barrier
	s_add_u32 s6, s4, 0xe7900080
	s_addc_u32 s7, s5, -1
	s_cmpk_lg_i32 s58, 0x7c
	s_cselect_b32 s6, s6, 0
	s_cselect_b32 s7, s7, 0
	s_add_u32 s40, s8, s6
	s_addc_u32 s41, s9, s7
	s_add_u32 s6, s2, s6
	s_addc_u32 s7, s3, s7
	s_mov_b32 m0, s61
	s_add_u32 s98, s6, s0
	s_addc_u32 s99, s7, s1
	ds_read_b128 v[206:209], v140
	ds_read_b128 v[210:213], v140 offset:1024
	ds_read_b128 v[214:217], v140 offset:2048
	ds_read_b128 v[218:221], v140 offset:3072
	global_load_lds_dwordx4 v144, s[6:7]
	s_mov_b32 m0, s62
	s_nop 0
	global_load_lds_dwordx4 v132, s[6:7]
	s_setprio 1
	s_barrier
	s_waitcnt lgkmcnt(0)
	v_mfma_f32_16x16x32_bf16 v[116:119], v[206:209], v[170:173], v[116:119]
	v_mfma_f32_16x16x32_bf16 v[108:111], v[214:217], v[170:173], v[108:111]
	v_mfma_f32_16x16x32_bf16 v[100:103], v[206:209], v[178:181], v[100:103]
	v_mfma_f32_16x16x32_bf16 v[92:95], v[214:217], v[178:181], v[92:95]
	v_mfma_f32_16x16x32_bf16 v[84:87], v[206:209], v[186:189], v[84:87]
	v_mfma_f32_16x16x32_bf16 v[76:79], v[214:217], v[186:189], v[76:79]
	v_mfma_f32_16x16x32_bf16 v[68:71], v[206:209], v[194:197], v[68:71]
	v_mfma_f32_16x16x32_bf16 v[64:67], v[214:217], v[194:197], v[64:67]
	v_mfma_f32_16x16x32_bf16 v[116:119], v[210:213], v[174:177], v[116:119]
	v_mfma_f32_16x16x32_bf16 v[108:111], v[218:221], v[174:177], v[108:111]
	v_mfma_f32_16x16x32_bf16 v[100:103], v[210:213], v[182:185], v[100:103]
	v_mfma_f32_16x16x32_bf16 v[92:95], v[218:221], v[182:185], v[92:95]
	v_mfma_f32_16x16x32_bf16 v[84:87], v[210:213], v[190:193], v[84:87]
	v_mfma_f32_16x16x32_bf16 v[76:79], v[218:221], v[190:193], v[76:79]
	v_mfma_f32_16x16x32_bf16 v[68:71], v[210:213], v[202:205], v[68:71]
	v_mfma_f32_16x16x32_bf16 v[64:67], v[218:221], v[202:205], v[64:67]
	s_setprio 0
	s_mov_b32 m0, s52
	s_add_u32 s100, s40, s0
	s_addc_u32 s101, s41, s1
	s_barrier
	ds_read_b128 v[170:173], v139 offset:16384
	ds_read_b128 v[174:177], v139 offset:17408
	ds_read_b128 v[178:181], v139 offset:18432
	ds_read_b128 v[182:185], v139 offset:19456
	ds_read_b128 v[186:189], v139 offset:20480
	ds_read_b128 v[190:193], v139 offset:21504
	ds_read_b128 v[194:197], v139 offset:22528
	ds_read_b128 v[202:205], v139 offset:23552
	global_load_lds_dwordx4 v128, s[40:41]
	s_mov_b32 m0, s53
	s_nop 0
	global_load_lds_dwordx4 v130, s[40:41]
	s_setprio 1
	s_barrier
	s_waitcnt lgkmcnt(0)
	v_mfma_f32_16x16x32_bf16 v[60:63], v[146:149], v[170:173], v[60:63]
	v_mfma_f32_16x16x32_bf16 v[56:59], v[160:163], v[170:173], v[56:59]
	v_mfma_f32_16x16x32_bf16 v[48:51], v[146:149], v[178:181], v[48:51]
	v_mfma_f32_16x16x32_bf16 v[40:43], v[160:163], v[178:181], v[40:43]
	v_mfma_f32_16x16x32_bf16 v[32:35], v[146:149], v[186:189], v[32:35]
	v_mfma_f32_16x16x32_bf16 v[24:27], v[160:163], v[186:189], v[24:27]
	v_mfma_f32_16x16x32_bf16 v[16:19], v[146:149], v[194:197], v[16:19]
	v_mfma_f32_16x16x32_bf16 v[8:11], v[160:163], v[194:197], v[8:11]
	v_mfma_f32_16x16x32_bf16 v[60:63], v[150:153], v[174:177], v[60:63]
	v_mfma_f32_16x16x32_bf16 v[56:59], v[166:169], v[174:177], v[56:59]
	v_mfma_f32_16x16x32_bf16 v[48:51], v[150:153], v[182:185], v[48:51]
	v_mfma_f32_16x16x32_bf16 v[40:43], v[166:169], v[182:185], v[40:43]
	v_mfma_f32_16x16x32_bf16 v[32:35], v[150:153], v[190:193], v[32:35]
	v_mfma_f32_16x16x32_bf16 v[24:27], v[166:169], v[190:193], v[24:27]
	v_mfma_f32_16x16x32_bf16 v[16:19], v[150:153], v[202:205], v[16:19]
	v_mfma_f32_16x16x32_bf16 v[8:11], v[166:169], v[202:205], v[8:11]
	s_setprio 0
	s_barrier
	s_add_u32 s28, s6, 0x200000
	s_addc_u32 s29, s7, 0
	s_mov_b32 m0, s63
	s_nop 0
	global_load_lds_dwordx4 v144, s[28:29]
	s_mov_b32 m0, s64
	s_nop 0
	global_load_lds_dwordx4 v132, s[28:29]
	s_waitcnt vmcnt(6)
	s_setprio 1
	s_barrier
; #define PG8_STAGE(bufoff, gbase, voff) do { _Pragma("unroll") for (int _i = 0; _i < 2; ++_i) \
;         __builtin_amdgcn_global_load_lds((const unsigned*)((const char*)(gbase) + (voff)[_i]), (LAS unsigned*)(lds + (bufoff) + ldsw + _i * 8192), 16, 0, 0); } while (0)
; #define PG8_LDA(dst, b, h) do { _Pragma("unroll") for (int m = 0; m < 4; ++m) _Pragma("unroll") for (int k = 0; k < 2; ++k) dst[m][k] = *(const LAS bf16x8*)(lds + PG8_SA(b, h) + aoff + m * 2048 + k * 1024); } while (0)
; #define PG8_LDB(dst, b, h) do { _Pragma("unroll") for (int n = 0; n < 2; ++n) _Pragma("unroll") for (int k = 0; k < 2; ++k) dst[n][k] = *(const LAS bf16x8*)(lds + PG8_SB(b, h) + boff + n * 2048 + k * 1024); } while (0)
; #define PG8_WAIT_V(n) asm volatile("s_waitcnt vmcnt(" #n ")" ::: "memory")
; #define PG8_WAIT_L(n) asm volatile("s_waitcnt lgkmcnt(" #n ")" ::: "memory")
; #define PG8_BAR __builtin_amdgcn_s_barrier()
; #define PG8_SCHED __builtin_amdgcn_sched_barrier(0)
; template <class Epi>
; __device__ __forceinline__ void gemm_phase(LAS unsigned char* lds, const bf16_t* A, int lda, const bf16_t* Bt, int ldb, int M, int N, int K, int asel, const Epi& E, const int fixed_round = -1) {
;     ...
;             PG8_WAIT_V(6); PG8_BAR; PG8_MMA(1, 1, At, B1); PG8_BAR;
;             PG8_LDB(B0, 1, 0); PG8_SCHED; PG8_LDA(At, 1, 0); PG8_STAGE(PG8_SA(0, 1), a2 + hstepA, voffA);
;             PG8_WAIT_L(8); PG8_BAR; PG8_WAIT_L(0); PG8_MMA(0, 0, At, B0); PG8_BAR; PG8_SCHED;
;             PG8_LDB(B1, 1, 1); PG8_STAGE(PG8_SB(1, 0), b3, voffB);
;             PG8_BAR; PG8_WAIT_L(0); PG8_MMA(0, 1, At, B1); PG8_BAR;
;             PG8_LDA(At, 1, 1); PG8_STAGE(PG8_SA(1, 0), a3, voffA);
;             PG8_BAR; PG8_WAIT_L(0); PG8_MMA(1, 0, At, B0); PG8_BAR; PG8_SCHED;
	v_mfma_f32_16x16x32_bf16 v[52:55], v[206:209], v[170:173], v[52:55]
	v_mfma_f32_16x16x32_bf16 v[44:47], v[214:217], v[170:173], v[44:47]
	v_mfma_f32_16x16x32_bf16 v[36:39], v[206:209], v[178:181], v[36:39]
	v_mfma_f32_16x16x32_bf16 v[28:31], v[214:217], v[178:181], v[28:31]
	v_mfma_f32_16x16x32_bf16 v[20:23], v[206:209], v[186:189], v[20:23]
	v_mfma_f32_16x16x32_bf16 v[12:15], v[214:217], v[186:189], v[12:15]
	v_mfma_f32_16x16x32_bf16 v[4:7], v[206:209], v[194:197], v[4:7]
	v_mfma_f32_16x16x32_bf16 v[0:3], v[214:217], v[194:197], v[0:3]
	v_mfma_f32_16x16x32_bf16 v[52:55], v[210:213], v[174:177], v[52:55]
	v_mfma_f32_16x16x32_bf16 v[44:47], v[218:221], v[174:177], v[44:47]
	v_mfma_f32_16x16x32_bf16 v[36:39], v[210:213], v[182:185], v[36:39]
	v_mfma_f32_16x16x32_bf16 v[28:31], v[218:221], v[182:185], v[28:31]
	v_mfma_f32_16x16x32_bf16 v[20:23], v[210:213], v[190:193], v[20:23]
	v_mfma_f32_16x16x32_bf16 v[12:15], v[218:221], v[190:193], v[12:15]
	v_mfma_f32_16x16x32_bf16 v[4:7], v[210:213], v[202:205], v[4:7]
	v_mfma_f32_16x16x32_bf16 v[0:3], v[218:221], v[202:205], v[0:3]
	s_setprio 0
	s_barrier
	ds_read_b128 v[146:149], v141
	ds_read_b128 v[150:153], v141 offset:1024
	ds_read_b128 v[160:163], v141 offset:2048
	ds_read_b128 v[166:169], v141 offset:3072
	s_add_u32 s28, s40, 0x200000
	s_addc_u32 s29, s41, 0
	s_mov_b32 m0, s54
	ds_read_b128 v[170:173], v139 offset:32768
	ds_read_b128 v[174:177], v139 offset:33792
	ds_read_b128 v[178:181], v139 offset:34816
	ds_read_b128 v[182:185], v139 offset:35840
	ds_read_b128 v[186:189], v139 offset:36864
	ds_read_b128 v[190:193], v139 offset:37888
	ds_read_b128 v[194:197], v139 offset:38912
	ds_read_b128 v[202:205], v139 offset:39936
	global_load_lds_dwordx4 v128, s[28:29]
	s_mov_b32 m0, s55
	s_nop 0
	global_load_lds_dwordx4 v130, s[28:29]
	s_waitcnt lgkmcnt(8)
	s_setprio 1
	s_barrier
	s_waitcnt lgkmcnt(0)
	v_mfma_f32_16x16x32_bf16 v[124:127], v[146:149], v[170:173], v[124:127]
	v_mfma_f32_16x16x32_bf16 v[120:123], v[160:163], v[170:173], v[120:123]
	v_mfma_f32_16x16x32_bf16 v[112:115], v[146:149], v[178:181], v[112:115]
	v_mfma_f32_16x16x32_bf16 v[104:107], v[160:163], v[178:181], v[104:107]
	v_mfma_f32_16x16x32_bf16 v[96:99], v[146:149], v[186:189], v[96:99]
	v_mfma_f32_16x16x32_bf16 v[88:91], v[160:163], v[186:189], v[88:91]
	v_mfma_f32_16x16x32_bf16 v[80:83], v[146:149], v[194:197], v[80:83]
	v_mfma_f32_16x16x32_bf16 v[72:75], v[160:163], v[194:197], v[72:75]
	v_mfma_f32_16x16x32_bf16 v[124:127], v[150:153], v[174:177], v[124:127]
	v_mfma_f32_16x16x32_bf16 v[120:123], v[166:169], v[174:177], v[120:123]
	v_mfma_f32_16x16x32_bf16 v[112:115], v[150:153], v[182:185], v[112:115]
	v_mfma_f32_16x16x32_bf16 v[104:107], v[166:169], v[182:185], v[104:107]
	v_mfma_f32_16x16x32_bf16 v[96:99], v[150:153], v[190:193], v[96:99]
	v_mfma_f32_16x16x32_bf16 v[88:91], v[166:169], v[190:193], v[88:91]
	v_mfma_f32_16x16x32_bf16 v[80:83], v[150:153], v[202:205], v[80:83]
	v_mfma_f32_16x16x32_bf16 v[72:75], v[166:169], v[202:205], v[72:75]
	s_setprio 0
	s_barrier
	s_mov_b32 m0, s65
	ds_read_b128 v[206:209], v142
	ds_read_b128 v[210:213], v142 offset:1024
	ds_read_b128 v[214:217], v142 offset:2048
	ds_read_b128 v[218:221], v142 offset:3072
	global_load_lds_dwordx4 v144, s[98:99]
	s_mov_b32 m0, s66
	s_nop 0
	global_load_lds_dwordx4 v132, s[98:99]
	s_setprio 1
	s_barrier
; #define PG8_STAGE(bufoff, gbase, voff) do { _Pragma("unroll") for (int _i = 0; _i < 2; ++_i) \
;         __builtin_amdgcn_global_load_lds((const unsigned*)((const char*)(gbase) + (voff)[_i]), (LAS unsigned*)(lds + (bufoff) + ldsw + _i * 8192), 16, 0, 0); } while (0)
; #define PG8_LDA(dst, b, h) do { _Pragma("unroll") for (int m = 0; m < 4; ++m) _Pragma("unroll") for (int k = 0; k < 2; ++k) dst[m][k] = *(const LAS bf16x8*)(lds + PG8_SA(b, h) + aoff + m * 2048 + k * 1024); } while (0)
; #define PG8_WAIT_V(n) asm volatile("s_waitcnt vmcnt(" #n ")" ::: "memory")
; #define PG8_WAIT_L(n) asm volatile("s_waitcnt lgkmcnt(" #n ")" ::: "memory")
; #define PG8_BAR __builtin_amdgcn_s_barrier()
; #define PG8_SCHED __builtin_amdgcn_sched_barrier(0)
; template <class Epi>
; __device__ __forceinline__ void gemm_phase(LAS unsigned char* lds, const bf16_t* A, int lda, const bf16_t* Bt, int ldb, int M, int N, int K, int asel, const Epi& E, const int fixed_round = -1) {
;     ...
;             PG8_BAR; PG8_WAIT_L(0); PG8_MMA(0, 1, At, B1); PG8_BAR;
;             PG8_LDA(At, 1, 1); PG8_STAGE(PG8_SA(1, 0), a3, voffA);
;             PG8_BAR; PG8_WAIT_L(0); PG8_MMA(1, 0, At, B0); PG8_BAR; PG8_SCHED;
;             PG8_STAGE(PG8_SB(1, 1), b3 + hstepB, voffB);
;             PG8_WAIT_V(6); PG8_BAR; PG8_MMA(1, 1, At, B1); PG8_BAR;
;     ...
;     PG8_WAIT_V(0);
;     if (wr == 0) PG8_BAR;
;     PG8_BAR;
	s_waitcnt lgkmcnt(0)
	v_mfma_f32_16x16x32_bf16 v[116:119], v[206:209], v[170:173], v[116:119]
	v_mfma_f32_16x16x32_bf16 v[108:111], v[214:217], v[170:173], v[108:111]
	v_mfma_f32_16x16x32_bf16 v[100:103], v[206:209], v[178:181], v[100:103]
	v_mfma_f32_16x16x32_bf16 v[92:95], v[214:217], v[178:181], v[92:95]
	v_mfma_f32_16x16x32_bf16 v[84:87], v[206:209], v[186:189], v[84:87]
	v_mfma_f32_16x16x32_bf16 v[76:79], v[214:217], v[186:189], v[76:79]
	v_mfma_f32_16x16x32_bf16 v[68:71], v[206:209], v[194:197], v[68:71]
	v_mfma_f32_16x16x32_bf16 v[64:67], v[214:217], v[194:197], v[64:67]
	v_mfma_f32_16x16x32_bf16 v[116:119], v[210:213], v[174:177], v[116:119]
	v_mfma_f32_16x16x32_bf16 v[108:111], v[218:221], v[174:177], v[108:111]
	v_mfma_f32_16x16x32_bf16 v[100:103], v[210:213], v[182:185], v[100:103]
	v_mfma_f32_16x16x32_bf16 v[92:95], v[218:221], v[182:185], v[92:95]
	v_mfma_f32_16x16x32_bf16 v[84:87], v[210:213], v[190:193], v[84:87]
	v_mfma_f32_16x16x32_bf16 v[76:79], v[218:221], v[190:193], v[76:79]
	v_mfma_f32_16x16x32_bf16 v[68:71], v[210:213], v[202:205], v[68:71]
	v_mfma_f32_16x16x32_bf16 v[64:67], v[218:221], v[202:205], v[64:67]
	s_setprio 0
	s_mov_b32 m0, s56
	s_barrier
	ds_read_b128 v[170:173], v139 offset:49152
	ds_read_b128 v[174:177], v139 offset:50176
	ds_read_b128 v[178:181], v139 offset:51200
	ds_read_b128 v[182:185], v139 offset:52224
	ds_read_b128 v[186:189], v139 offset:53248
	ds_read_b128 v[190:193], v139 offset:54272
	ds_read_b128 v[194:197], v139 offset:55296
	ds_read_b128 v[202:205], v139 offset:56320
	global_load_lds_dwordx4 v128, s[100:101]
	s_mov_b32 m0, s57
	s_nop 0
	global_load_lds_dwordx4 v130, s[100:101]
	s_setprio 1
	s_barrier
	s_waitcnt lgkmcnt(0)
	v_mfma_f32_16x16x32_bf16 v[60:63], v[146:149], v[170:173], v[60:63]
	v_mfma_f32_16x16x32_bf16 v[56:59], v[160:163], v[170:173], v[56:59]
	v_mfma_f32_16x16x32_bf16 v[48:51], v[146:149], v[178:181], v[48:51]
	v_mfma_f32_16x16x32_bf16 v[40:43], v[160:163], v[178:181], v[40:43]
	v_mfma_f32_16x16x32_bf16 v[32:35], v[146:149], v[186:189], v[32:35]
	v_mfma_f32_16x16x32_bf16 v[24:27], v[160:163], v[186:189], v[24:27]
	v_mfma_f32_16x16x32_bf16 v[16:19], v[146:149], v[194:197], v[16:19]
	v_mfma_f32_16x16x32_bf16 v[8:11], v[160:163], v[194:197], v[8:11]
	v_mfma_f32_16x16x32_bf16 v[60:63], v[150:153], v[174:177], v[60:63]
	v_mfma_f32_16x16x32_bf16 v[56:59], v[166:169], v[174:177], v[56:59]
	v_mfma_f32_16x16x32_bf16 v[48:51], v[150:153], v[182:185], v[48:51]
	v_mfma_f32_16x16x32_bf16 v[40:43], v[166:169], v[182:185], v[40:43]
	v_mfma_f32_16x16x32_bf16 v[32:35], v[150:153], v[190:193], v[32:35]
	v_mfma_f32_16x16x32_bf16 v[24:27], v[166:169], v[190:193], v[24:27]
	v_mfma_f32_16x16x32_bf16 v[16:19], v[150:153], v[202:205], v[16:19]
	v_mfma_f32_16x16x32_bf16 v[8:11], v[166:169], v[202:205], v[8:11]
	s_setprio 0
	s_barrier
	s_add_u32 s6, s6, 0x200080
	s_addc_u32 s7, s7, 0
	s_mov_b32 m0, s67
	s_nop 0
	global_load_lds_dwordx4 v144, s[6:7]
	s_mov_b32 m0, s68
	s_nop 0
	global_load_lds_dwordx4 v132, s[6:7]
	s_waitcnt vmcnt(6)
	s_setprio 1
	s_barrier
	v_mfma_f32_16x16x32_bf16 v[52:55], v[206:209], v[170:173], v[52:55]
	v_mfma_f32_16x16x32_bf16 v[44:47], v[214:217], v[170:173], v[44:47]
	v_mfma_f32_16x16x32_bf16 v[36:39], v[206:209], v[178:181], v[36:39]
	v_mfma_f32_16x16x32_bf16 v[28:31], v[214:217], v[178:181], v[28:31]
	v_mfma_f32_16x16x32_bf16 v[20:23], v[206:209], v[186:189], v[20:23]
	v_mfma_f32_16x16x32_bf16 v[12:15], v[214:217], v[186:189], v[12:15]
	v_mfma_f32_16x16x32_bf16 v[4:7], v[206:209], v[194:197], v[4:7]
	v_mfma_f32_16x16x32_bf16 v[0:3], v[214:217], v[194:197], v[0:3]
	v_mfma_f32_16x16x32_bf16 v[52:55], v[210:213], v[174:177], v[52:55]
	v_mfma_f32_16x16x32_bf16 v[44:47], v[218:221], v[174:177], v[44:47]
	v_mfma_f32_16x16x32_bf16 v[36:39], v[210:213], v[182:185], v[36:39]
	v_mfma_f32_16x16x32_bf16 v[28:31], v[218:221], v[182:185], v[28:31]
	v_mfma_f32_16x16x32_bf16 v[20:23], v[210:213], v[190:193], v[20:23]
	v_mfma_f32_16x16x32_bf16 v[12:15], v[218:221], v[190:193], v[12:15]
	v_mfma_f32_16x16x32_bf16 v[4:7], v[210:213], v[202:205], v[4:7]
	v_mfma_f32_16x16x32_bf16 v[0:3], v[218:221], v[202:205], v[0:3]
	s_setprio 0
	s_add_i32 s58, s58, 2
	s_add_u32 s4, s4, 0x100
	s_addc_u32 s5, s5, 0
	s_cmpk_lt_u32 s58, 0x7e
	s_cbranch_scc1 .Lrot_6
	s_barrier
	s_waitcnt vmcnt(0)
	s_cmpk_gt_u32 s51, 0xff
	s_cbranch_scc1 .LBB0_693
	s_barrier

; #define PG8_STAGE(bufoff, gbase, voff) do { _Pragma("unroll") for (int _i = 0; _i < 2; ++_i) \
;         __builtin_amdgcn_global_load_lds((const unsigned*)((const char*)(gbase) + (voff)[_i]), (LAS unsigned*)(lds + (bufoff) + ldsw + _i * 8192), 16, 0, 0); } while (0)
; #define PG8_LDA(dst, b, h) do { _Pragma("unroll") for (int m = 0; m < 4; ++m) _Pragma("unroll") for (int k = 0; k < 2; ++k) dst[m][k] = *(const LAS bf16x8*)(lds + PG8_SA(b, h) + aoff + m * 2048 + k * 1024); } while (0)
; #define PG8_LDB(dst, b, h) do { _Pragma("unroll") for (int n = 0; n < 2; ++n) _Pragma("unroll") for (int k = 0; k < 2; ++k) dst[n][k] = *(const LAS bf16x8*)(lds + PG8_SB(b, h) + boff + n * 2048 + k * 1024); } while (0)
; #define PG8_WAIT_V(n) asm volatile("s_waitcnt vmcnt(" #n ")" ::: "memory")
; #define PG8_WAIT_L(n) asm volatile("s_waitcnt lgkmcnt(" #n ")" ::: "memory")
; #define PG8_BAR __builtin_amdgcn_s_barrier()
; #define PG8_SCHED __builtin_amdgcn_sched_barrier(0)
; template <class Epi>
; __device__ __forceinline__ void gemm_phase(LAS unsigned char* lds, const bf16_t* A, int lda, const bf16_t* Bt, int ldb, int M, int N, int K, int asel, const Epi& E, const int fixed_round = -1) {
;     ...
;         const bool has_next = (fixed_round < 0) && S.next(ui + 1, nxt);
;         const char* nA = has_next ? PG8_ABASE(nxt) : cA; const char* nB = has_next ? (const char*)Bt + (size_t)nxt.pn * tstepB : cB;
;         for (int t = 0; t < nt; t += 2) {
;             const bool last = (t == nt - 2);
;             const char* a1 = cA + (size_t)(t + 1) * kstep;
;             const char* a2 = last ? nA : cA + (size_t)(t + 2) * kstep; const char* b2 = last ? nB : cB + (size_t)(t + 2) * kstep;
;             const char* a3 = a2 + kstep; const char* b3 = b2 + kstep;
;             PG8_LDB(B0, 0, 0); PG8_SCHED; PG8_LDA(At, 0, 0); PG8_STAGE(PG8_SA(1, 1), a1 + hstepA, voffA);
;             PG8_WAIT_L(8); PG8_BAR; PG8_WAIT_L(0); PG8_MMA(0, 0, At, B0); PG8_BAR; PG8_SCHED;
;             PG8_LDB(B1, 0, 1); PG8_STAGE(PG8_SB(0, 0), b2, voffB);
;             PG8_BAR; PG8_WAIT_L(0); PG8_MMA(0, 1, At, B1); PG8_BAR;
;             PG8_LDA(At, 0, 1); PG8_STAGE(PG8_SA(0, 0), a2, voffA);
;             PG8_BAR; PG8_WAIT_L(0); PG8_MMA(1, 0, At, B0); PG8_BAR; PG8_SCHED;
;             PG8_STAGE(PG8_SB(0, 1), b2 + hstepB, voffB);
;             PG8_WAIT_V(6); PG8_BAR; PG8_MMA(1, 1, At, B1); PG8_BAR;
.LBB0_799:
	ds_read_b128 v[146:149], v155
	ds_read_b128 v[158:161], v155 offset:1024
	ds_read_b128 v[162:165], v155 offset:2048
	ds_read_b128 v[166:169], v155 offset:3072
	s_add_i32 m0, s49, 0xc000
	ds_read_b128 v[170:173], v156
	ds_read_b128 v[174:177], v156 offset:1024
	ds_read_b128 v[178:181], v156 offset:2048
	ds_read_b128 v[182:185], v156 offset:3072
	ds_read_b128 v[186:189], v156 offset:4096
	ds_read_b128 v[190:193], v156 offset:5120
	ds_read_b128 v[194:197], v156 offset:6144
	ds_read_b128 v[202:205], v156 offset:7168
	global_load_lds_dwordx4 v138, s[50:51]
	s_add_i32 m0, s49, 0xe000
	s_nop 0
	global_load_lds_dwordx4 v140, s[50:51]
	s_waitcnt lgkmcnt(8)
	s_setprio 1
	s_barrier
	s_waitcnt lgkmcnt(0)
	v_mfma_f32_16x16x32_bf16 v[124:127], v[146:149], v[170:173], v[124:127]
	v_mfma_f32_16x16x32_bf16 v[120:123], v[162:165], v[170:173], v[120:123]
	v_mfma_f32_16x16x32_bf16 v[108:111], v[146:149], v[178:181], v[108:111]
	v_mfma_f32_16x16x32_bf16 v[104:107], v[162:165], v[178:181], v[104:107]
	v_mfma_f32_16x16x32_bf16 v[92:95], v[146:149], v[186:189], v[92:95]
	v_mfma_f32_16x16x32_bf16 v[88:91], v[162:165], v[186:189], v[88:91]
	v_mfma_f32_16x16x32_bf16 v[76:79], v[146:149], v[194:197], v[76:79]
	v_mfma_f32_16x16x32_bf16 v[72:75], v[162:165], v[194:197], v[72:75]
	v_mfma_f32_16x16x32_bf16 v[124:127], v[158:161], v[174:177], v[124:127]
	v_mfma_f32_16x16x32_bf16 v[120:123], v[166:169], v[174:177], v[120:123]
	v_mfma_f32_16x16x32_bf16 v[108:111], v[158:161], v[182:185], v[108:111]
	v_mfma_f32_16x16x32_bf16 v[104:107], v[166:169], v[182:185], v[104:107]
	v_mfma_f32_16x16x32_bf16 v[92:95], v[158:161], v[190:193], v[92:95]
	v_mfma_f32_16x16x32_bf16 v[88:91], v[166:169], v[190:193], v[88:91]
	v_mfma_f32_16x16x32_bf16 v[76:79], v[158:161], v[202:205], v[76:79]
	v_mfma_f32_16x16x32_bf16 v[72:75], v[166:169], v[202:205], v[72:75]
	s_setprio 0
	s_barrier
	s_add_u32 s28, s50, 0xfff80080
	s_addc_u32 s29, s51, -1
	s_cmp_eq_u32 s68, 28
	s_cselect_b32 s55, s5, s29
	s_cselect_b32 s54, s41, s28
	s_cselect_b32 s53, s7, s67
	s_cselect_b32 s52, s65, s66
	s_add_i32 s28, s81, s58
	s_add_u32 s98, s52, s2
	s_addc_u32 s99, s53, s3
	s_mov_b32 m0, s28
	ds_read_b128 v[206:209], v157
	ds_read_b128 v[210:213], v157 offset:1024
	ds_read_b128 v[214:217], v157 offset:2048
	ds_read_b128 v[218:221], v157 offset:3072
	global_load_lds_dwordx4 v130, s[52:53]
	s_add_i32 m0, s28, 0x2000
	s_nop 0
	global_load_lds_dwordx4 v134, s[52:53]
	s_setprio 1
	s_barrier
	s_waitcnt lgkmcnt(0)
	v_mfma_f32_16x16x32_bf16 v[116:119], v[206:209], v[170:173], v[116:119]
	v_mfma_f32_16x16x32_bf16 v[112:115], v[214:217], v[170:173], v[112:115]
	v_mfma_f32_16x16x32_bf16 v[100:103], v[206:209], v[178:181], v[100:103]
	v_mfma_f32_16x16x32_bf16 v[96:99], v[214:217], v[178:181], v[96:99]
	v_mfma_f32_16x16x32_bf16 v[84:87], v[206:209], v[186:189], v[84:87]
	v_mfma_f32_16x16x32_bf16 v[80:83], v[214:217], v[186:189], v[80:83]
	v_mfma_f32_16x16x32_bf16 v[68:71], v[206:209], v[194:197], v[68:71]
	v_mfma_f32_16x16x32_bf16 v[64:67], v[214:217], v[194:197], v[64:67]
	v_mfma_f32_16x16x32_bf16 v[116:119], v[210:213], v[174:177], v[116:119]
	v_mfma_f32_16x16x32_bf16 v[112:115], v[218:221], v[174:177], v[112:115]
	v_mfma_f32_16x16x32_bf16 v[100:103], v[210:213], v[182:185], v[100:103]
	v_mfma_f32_16x16x32_bf16 v[96:99], v[218:221], v[182:185], v[96:99]
	v_mfma_f32_16x16x32_bf16 v[84:87], v[210:213], v[190:193], v[84:87]
	v_mfma_f32_16x16x32_bf16 v[80:83], v[218:221], v[190:193], v[80:83]
	v_mfma_f32_16x16x32_bf16 v[68:71], v[210:213], v[202:205], v[68:71]
	v_mfma_f32_16x16x32_bf16 v[64:67], v[218:221], v[202:205], v[64:67]
	s_setprio 0
	s_mov_b32 m0, s49
	s_add_u32 s100, s54, s2
	s_addc_u32 s101, s55, s3
	s_barrier
	ds_read_b128 v[170:173], v156 offset:16384
	ds_read_b128 v[174:177], v156 offset:17408
	ds_read_b128 v[178:181], v156 offset:18432
	ds_read_b128 v[182:185], v156 offset:19456
	ds_read_b128 v[186:189], v156 offset:20480
	ds_read_b128 v[190:193], v156 offset:21504
	ds_read_b128 v[194:197], v156 offset:22528
	ds_read_b128 v[202:205], v156 offset:23552
	global_load_lds_dwordx4 v128, s[54:55]
	s_mov_b32 m0, s59
	s_nop 0
	global_load_lds_dwordx4 v132, s[54:55]
	s_setprio 1
	s_barrier
	s_waitcnt lgkmcnt(0)
	v_mfma_f32_16x16x32_bf16 v[60:63], v[146:149], v[170:173], v[60:63]
	v_mfma_f32_16x16x32_bf16 v[56:59], v[162:165], v[170:173], v[56:59]
	v_mfma_f32_16x16x32_bf16 v[44:47], v[146:149], v[178:181], v[44:47]
	v_mfma_f32_16x16x32_bf16 v[40:43], v[162:165], v[178:181], v[40:43]
	v_mfma_f32_16x16x32_bf16 v[28:31], v[146:149], v[186:189], v[28:31]
	v_mfma_f32_16x16x32_bf16 v[24:27], v[162:165], v[186:189], v[24:27]
	v_mfma_f32_16x16x32_bf16 v[12:15], v[146:149], v[194:197], v[12:15]
	v_mfma_f32_16x16x32_bf16 v[8:11], v[162:165], v[194:197], v[8:11]
	v_mfma_f32_16x16x32_bf16 v[60:63], v[158:161], v[174:177], v[60:63]
	v_mfma_f32_16x16x32_bf16 v[56:59], v[166:169], v[174:177], v[56:59]
	v_mfma_f32_16x16x32_bf16 v[44:47], v[158:161], v[182:185], v[44:47]
	v_mfma_f32_16x16x32_bf16 v[40:43], v[166:169], v[182:185], v[40:43]
	v_mfma_f32_16x16x32_bf16 v[28:31], v[158:161], v[190:193], v[28:31]
	v_mfma_f32_16x16x32_bf16 v[24:27], v[166:169], v[190:193], v[24:27]
	v_mfma_f32_16x16x32_bf16 v[12:15], v[158:161], v[202:205], v[12:15]
	v_mfma_f32_16x16x32_bf16 v[8:11], v[166:169], v[202:205], v[8:11]
	s_setprio 0
	s_barrier
	s_add_u32 s28, s52, 0x80000
	s_addc_u32 s29, s53, 0
	s_add_i32 s69, s82, s58
	s_mov_b32 m0, s69
	s_nop 0
	global_load_lds_dwordx4 v130, s[28:29]
	s_add_i32 m0, s69, 0x2000
	s_nop 0
	global_load_lds_dwordx4 v134, s[28:29]
	s_waitcnt vmcnt(6)
	s_setprio 1
	s_barrier
; #define PG8_STAGE(bufoff, gbase, voff) do { _Pragma("unroll") for (int _i = 0; _i < 2; ++_i) \
;         __builtin_amdgcn_global_load_lds((const unsigned*)((const char*)(gbase) + (voff)[_i]), (LAS unsigned*)(lds + (bufoff) + ldsw + _i * 8192), 16, 0, 0); } while (0)
; #define PG8_LDA(dst, b, h) do { _Pragma("unroll") for (int m = 0; m < 4; ++m) _Pragma("unroll") for (int k = 0; k < 2; ++k) dst[m][k] = *(const LAS bf16x8*)(lds + PG8_SA(b, h) + aoff + m * 2048 + k * 1024); } while (0)
; #define PG8_LDB(dst, b, h) do { _Pragma("unroll") for (int n = 0; n < 2; ++n) _Pragma("unroll") for (int k = 0; k < 2; ++k) dst[n][k] = *(const LAS bf16x8*)(lds + PG8_SB(b, h) + boff + n * 2048 + k * 1024); } while (0)
; #define PG8_WAIT_V(n) asm volatile("s_waitcnt vmcnt(" #n ")" ::: "memory")
; #define PG8_WAIT_L(n) asm volatile("s_waitcnt lgkmcnt(" #n ")" ::: "memory")
; #define PG8_BAR __builtin_amdgcn_s_barrier()
; #define PG8_SCHED __builtin_amdgcn_sched_barrier(0)
; template <class Epi>
; __device__ __forceinline__ void gemm_phase(LAS unsigned char* lds, const bf16_t* A, int lda, const bf16_t* Bt, int ldb, int M, int N, int K, int asel, const Epi& E, const int fixed_round = -1) {
;     ...
;             PG8_WAIT_V(6); PG8_BAR; PG8_MMA(1, 1, At, B1); PG8_BAR;
;             PG8_LDB(B0, 1, 0); PG8_SCHED; PG8_LDA(At, 1, 0); PG8_STAGE(PG8_SA(0, 1), a2 + hstepA, voffA);
;             PG8_WAIT_L(8); PG8_BAR; PG8_WAIT_L(0); PG8_MMA(0, 0, At, B0); PG8_BAR; PG8_SCHED;
;             PG8_LDB(B1, 1, 1); PG8_STAGE(PG8_SB(1, 0), b3, voffB);
;             PG8_BAR; PG8_WAIT_L(0); PG8_MMA(0, 1, At, B1); PG8_BAR;
;             PG8_LDA(At, 1, 1); PG8_STAGE(PG8_SA(1, 0), a3, voffA);
;             PG8_BAR; PG8_WAIT_L(0); PG8_MMA(1, 0, At, B0); PG8_BAR; PG8_SCHED;
	v_mfma_f32_16x16x32_bf16 v[52:55], v[206:209], v[170:173], v[52:55]
	v_mfma_f32_16x16x32_bf16 v[48:51], v[214:217], v[170:173], v[48:51]
	v_mfma_f32_16x16x32_bf16 v[36:39], v[206:209], v[178:181], v[36:39]
	v_mfma_f32_16x16x32_bf16 v[32:35], v[214:217], v[178:181], v[32:35]
	v_mfma_f32_16x16x32_bf16 v[20:23], v[206:209], v[186:189], v[20:23]
	v_mfma_f32_16x16x32_bf16 v[16:19], v[214:217], v[186:189], v[16:19]
	v_mfma_f32_16x16x32_bf16 v[4:7], v[206:209], v[194:197], v[4:7]
	v_mfma_f32_16x16x32_bf16 v[0:3], v[214:217], v[194:197], v[0:3]
	v_mfma_f32_16x16x32_bf16 v[52:55], v[210:213], v[174:177], v[52:55]
	v_mfma_f32_16x16x32_bf16 v[48:51], v[218:221], v[174:177], v[48:51]
	v_mfma_f32_16x16x32_bf16 v[36:39], v[210:213], v[182:185], v[36:39]
	v_mfma_f32_16x16x32_bf16 v[32:35], v[218:221], v[182:185], v[32:35]
	v_mfma_f32_16x16x32_bf16 v[20:23], v[210:213], v[190:193], v[20:23]
	v_mfma_f32_16x16x32_bf16 v[16:19], v[218:221], v[190:193], v[16:19]
	v_mfma_f32_16x16x32_bf16 v[4:7], v[210:213], v[202:205], v[4:7]
	v_mfma_f32_16x16x32_bf16 v[0:3], v[218:221], v[202:205], v[0:3]
	s_setprio 0
	v_add_u32_e32 v136, s83, v153
	s_barrier
	ds_read_b128 v[146:149], v136
	ds_read_b128 v[158:161], v136 offset:1024
	ds_read_b128 v[162:165], v136 offset:2048
	ds_read_b128 v[166:169], v136 offset:3072
	s_add_u32 s28, s54, 0x80000
	s_addc_u32 s29, s55, 0
	s_mov_b32 m0, s60
	ds_read_b128 v[170:173], v156 offset:32768
	ds_read_b128 v[174:177], v156 offset:33792
	ds_read_b128 v[178:181], v156 offset:34816
	ds_read_b128 v[182:185], v156 offset:35840
	ds_read_b128 v[186:189], v156 offset:36864
	ds_read_b128 v[190:193], v156 offset:37888
	ds_read_b128 v[194:197], v156 offset:38912
	ds_read_b128 v[202:205], v156 offset:39936
	global_load_lds_dwordx4 v128, s[28:29]
	s_mov_b32 m0, s61
	s_nop 0
	global_load_lds_dwordx4 v132, s[28:29]
	s_waitcnt lgkmcnt(8)
	s_setprio 1
	s_barrier
	s_waitcnt lgkmcnt(0)
	v_mfma_f32_16x16x32_bf16 v[124:127], v[146:149], v[170:173], v[124:127]
	v_mfma_f32_16x16x32_bf16 v[120:123], v[162:165], v[170:173], v[120:123]
	v_mfma_f32_16x16x32_bf16 v[108:111], v[146:149], v[178:181], v[108:111]
	v_mfma_f32_16x16x32_bf16 v[104:107], v[162:165], v[178:181], v[104:107]
	v_mfma_f32_16x16x32_bf16 v[92:95], v[146:149], v[186:189], v[92:95]
	v_mfma_f32_16x16x32_bf16 v[88:91], v[162:165], v[186:189], v[88:91]
	v_mfma_f32_16x16x32_bf16 v[76:79], v[146:149], v[194:197], v[76:79]
	v_mfma_f32_16x16x32_bf16 v[72:75], v[162:165], v[194:197], v[72:75]
	v_mfma_f32_16x16x32_bf16 v[124:127], v[158:161], v[174:177], v[124:127]
	v_mfma_f32_16x16x32_bf16 v[120:123], v[166:169], v[174:177], v[120:123]
	v_mfma_f32_16x16x32_bf16 v[108:111], v[158:161], v[182:185], v[108:111]
	v_mfma_f32_16x16x32_bf16 v[104:107], v[166:169], v[182:185], v[104:107]
	v_mfma_f32_16x16x32_bf16 v[92:95], v[158:161], v[190:193], v[92:95]
	v_mfma_f32_16x16x32_bf16 v[88:91], v[166:169], v[190:193], v[88:91]
	v_mfma_f32_16x16x32_bf16 v[76:79], v[158:161], v[202:205], v[76:79]
	v_mfma_f32_16x16x32_bf16 v[72:75], v[166:169], v[202:205], v[72:75]
	s_setprio 0
	s_barrier
	s_add_i32 s28, s83, s58
	v_add_u32_e32 v136, s84, v153
	s_mov_b32 m0, s28
	ds_read_b128 v[206:209], v136
	ds_read_b128 v[210:213], v136 offset:1024
	ds_read_b128 v[214:217], v136 offset:2048
	ds_read_b128 v[218:221], v136 offset:3072
	global_load_lds_dwordx4 v130, s[98:99]
	s_add_i32 m0, s28, 0x2000
	s_nop 0
	global_load_lds_dwordx4 v134, s[98:99]
	s_setprio 1
	s_barrier
	s_waitcnt lgkmcnt(0)
	v_mfma_f32_16x16x32_bf16 v[116:119], v[206:209], v[170:173], v[116:119]
	v_mfma_f32_16x16x32_bf16 v[112:115], v[214:217], v[170:173], v[112:115]
	v_mfma_f32_16x16x32_bf16 v[100:103], v[206:209], v[178:181], v[100:103]
	v_mfma_f32_16x16x32_bf16 v[96:99], v[214:217], v[178:181], v[96:99]
	v_mfma_f32_16x16x32_bf16 v[84:87], v[206:209], v[186:189], v[84:87]
	v_mfma_f32_16x16x32_bf16 v[80:83], v[214:217], v[186:189], v[80:83]
	v_mfma_f32_16x16x32_bf16 v[68:71], v[206:209], v[194:197], v[68:71]
	v_mfma_f32_16x16x32_bf16 v[64:67], v[214:217], v[194:197], v[64:67]
	v_mfma_f32_16x16x32_bf16 v[116:119], v[210:213], v[174:177], v[116:119]
	v_mfma_f32_16x16x32_bf16 v[112:115], v[218:221], v[174:177], v[112:115]
	v_mfma_f32_16x16x32_bf16 v[100:103], v[210:213], v[182:185], v[100:103]
	v_mfma_f32_16x16x32_bf16 v[96:99], v[218:221], v[182:185], v[96:99]
	v_mfma_f32_16x16x32_bf16 v[84:87], v[210:213], v[190:193], v[84:87]
	v_mfma_f32_16x16x32_bf16 v[80:83], v[218:221], v[190:193], v[80:83]
	v_mfma_f32_16x16x32_bf16 v[68:71], v[210:213], v[202:205], v[68:71]
	v_mfma_f32_16x16x32_bf16 v[64:67], v[218:221], v[202:205], v[64:67]
	s_setprio 0
	s_mov_b32 m0, s63
	s_barrier
	ds_read_b128 v[170:173], v156 offset:49152
	ds_read_b128 v[174:177], v156 offset:50176
	ds_read_b128 v[178:181], v156 offset:51200
	ds_read_b128 v[182:185], v156 offset:52224
	ds_read_b128 v[186:189], v156 offset:53248
	ds_read_b128 v[190:193], v156 offset:54272
	ds_read_b128 v[194:197], v156 offset:55296
	ds_read_b128 v[202:205], v156 offset:56320
	global_load_lds_dwordx4 v128, s[100:101]
	s_mov_b32 m0, s64
	s_nop 0
	global_load_lds_dwordx4 v132, s[100:101]
	s_setprio 1
	s_barrier
; #define PG8_STAGE(bufoff, gbase, voff) do { _Pragma("unroll") for (int _i = 0; _i < 2; ++_i) \
;         __builtin_amdgcn_global_load_lds((const unsigned*)((const char*)(gbase) + (voff)[_i]), (LAS unsigned*)(lds + (bufoff) + ldsw + _i * 8192), 16, 0, 0); } while (0)
; #define PG8_WAIT_V(n) asm volatile("s_waitcnt vmcnt(" #n ")" ::: "memory")
; #define PG8_WAIT_L(n) asm volatile("s_waitcnt lgkmcnt(" #n ")" ::: "memory")
; #define PG8_BAR __builtin_amdgcn_s_barrier()
; #define PG8_SCHED __builtin_amdgcn_sched_barrier(0)
; template <class Epi>
; __device__ __forceinline__ void gemm_phase(LAS unsigned char* lds, const bf16_t* A, int lda, const bf16_t* Bt, int ldb, int M, int N, int K, int asel, const Epi& E, const int fixed_round = -1) {
;     ...
;             PG8_BAR; PG8_WAIT_L(0); PG8_MMA(1, 0, At, B0); PG8_BAR; PG8_SCHED;
;             PG8_STAGE(PG8_SB(1, 1), b3 + hstepB, voffB);
;             PG8_WAIT_V(6); PG8_BAR; PG8_MMA(1, 1, At, B1); PG8_BAR;
;     __device__ __forceinline__ void operator()(const AccT& acc, const Unit& u, int wr, int wc, int fr, int fq) const {
;         const int row0 = u.pm * BM + wr * 64 + fr; const bool isg = u.pn >= 8;
;         bf16_t* base = isg ? GB : XB; const int col0 = (u.pn & 7) * BM + wc * 32 + 8 * fq;
; #pragma unroll
;         for (int ai = 0; ai < 2; ++ai)
; #pragma unroll
;             for (int m = 0; m < 4; ++m) { bf16_t* rowp = base + (size_t)(row0 + ai * HALF + m * 16) * DM + col0;
; #pragma unroll
;                 for (int bj = 0; bj < 2; ++bj) { f32x4 v0 = acc[ai][bj][m][0], v1 = acc[ai][bj][m][1];
;                     if (isg) {
; #pragma unroll
;                         for (int j = 0; j < 4; ++j) { float a = v0[j], b = v1[j];
;                             const float ta = 1.5957691216057308f * (a + 0.044715f * a * a * a), tb = 1.5957691216057308f * (b + 0.044715f * b * b * b);
;                             v0[j] = a * __builtin_amdgcn_rcpf(1.0f + __expf(-ta)); v1[j] = b * __builtin_amdgcn_rcpf(1.0f + __expf(-tb)); } }
	s_waitcnt lgkmcnt(0)
	v_mfma_f32_16x16x32_bf16 v[60:63], v[146:149], v[170:173], v[60:63]
	v_mfma_f32_16x16x32_bf16 v[56:59], v[162:165], v[170:173], v[56:59]
	v_mfma_f32_16x16x32_bf16 v[44:47], v[146:149], v[178:181], v[44:47]
	v_mfma_f32_16x16x32_bf16 v[40:43], v[162:165], v[178:181], v[40:43]
	v_mfma_f32_16x16x32_bf16 v[28:31], v[146:149], v[186:189], v[28:31]
	v_mfma_f32_16x16x32_bf16 v[24:27], v[162:165], v[186:189], v[24:27]
	v_mfma_f32_16x16x32_bf16 v[12:15], v[146:149], v[194:197], v[12:15]
	v_mfma_f32_16x16x32_bf16 v[8:11], v[162:165], v[194:197], v[8:11]
	v_mfma_f32_16x16x32_bf16 v[60:63], v[158:161], v[174:177], v[60:63]
	v_mfma_f32_16x16x32_bf16 v[56:59], v[166:169], v[174:177], v[56:59]
	v_mfma_f32_16x16x32_bf16 v[44:47], v[158:161], v[182:185], v[44:47]
	v_mfma_f32_16x16x32_bf16 v[40:43], v[166:169], v[182:185], v[40:43]
	v_mfma_f32_16x16x32_bf16 v[28:31], v[158:161], v[190:193], v[28:31]
	v_mfma_f32_16x16x32_bf16 v[24:27], v[166:169], v[190:193], v[24:27]
	v_mfma_f32_16x16x32_bf16 v[12:15], v[158:161], v[202:205], v[12:15]
	v_mfma_f32_16x16x32_bf16 v[8:11], v[166:169], v[202:205], v[8:11]
	s_setprio 0
	s_barrier
	s_add_u32 s28, s52, 0x80080
	s_addc_u32 s29, s53, 0
	s_add_i32 s52, s84, s58
	s_mov_b32 m0, s52
	s_nop 0
	global_load_lds_dwordx4 v130, s[28:29]
	s_add_i32 m0, s52, 0x2000
	s_nop 0
	global_load_lds_dwordx4 v134, s[28:29]
	s_waitcnt vmcnt(6)
	s_setprio 1
	s_barrier
	v_mfma_f32_16x16x32_bf16 v[52:55], v[206:209], v[170:173], v[52:55]
	v_mfma_f32_16x16x32_bf16 v[48:51], v[214:217], v[170:173], v[48:51]
	v_mfma_f32_16x16x32_bf16 v[36:39], v[206:209], v[178:181], v[36:39]
	v_mfma_f32_16x16x32_bf16 v[32:35], v[214:217], v[178:181], v[32:35]
	v_mfma_f32_16x16x32_bf16 v[20:23], v[206:209], v[186:189], v[20:23]
	v_mfma_f32_16x16x32_bf16 v[16:19], v[214:217], v[186:189], v[16:19]
	v_mfma_f32_16x16x32_bf16 v[4:7], v[206:209], v[194:197], v[4:7]
	v_mfma_f32_16x16x32_bf16 v[0:3], v[214:217], v[194:197], v[0:3]
	v_mfma_f32_16x16x32_bf16 v[52:55], v[210:213], v[174:177], v[52:55]
	v_mfma_f32_16x16x32_bf16 v[48:51], v[218:221], v[174:177], v[48:51]
	v_mfma_f32_16x16x32_bf16 v[36:39], v[210:213], v[182:185], v[36:39]
	v_mfma_f32_16x16x32_bf16 v[32:35], v[218:221], v[182:185], v[32:35]
	v_mfma_f32_16x16x32_bf16 v[20:23], v[210:213], v[190:193], v[20:23]
	v_mfma_f32_16x16x32_bf16 v[16:19], v[218:221], v[190:193], v[16:19]
	v_mfma_f32_16x16x32_bf16 v[4:7], v[210:213], v[202:205], v[4:7]
	v_mfma_f32_16x16x32_bf16 v[0:3], v[218:221], v[202:205], v[0:3]
	s_setprio 0
	s_add_i32 s68, s68, 2
	s_add_u32 s50, s50, 0x100
	s_addc_u32 s51, s51, 0
	s_add_u32 s66, s66, 0x100
	s_addc_u32 s67, s67, 0
	s_cmp_gt_u32 s68, 29
	s_cbranch_scc0 .Lrot_7
	s_barrier
	s_cmp_gt_i32 s4, 7
	s_cselect_b64 s[50:51], -1, 0
	s_cmp_lt_i32 s4, 8
	s_cbranch_scc1 .LBB0_802
	v_mul_f32_e32 v136, 0x3d372713, v124
	v_mul_f32_e32 v136, v124, v136
	v_mul_f32_e32 v146, 0x3d372713, v120
	v_fma_f32 v136, v124, v136, v124
	v_mul_f32_e32 v146, v120, v146
	v_fma_f32 v146, v120, v146, v120
	v_mul_f32_e32 v136, 0xbfcc422a, v136
	v_mul_f32_e32 v136, 0x3fb8aa3b, v136
	v_mul_f32_e32 v146, 0xbfcc422a, v146
	v_exp_f32_e32 v136, v136
	v_mul_f32_e32 v146, 0x3fb8aa3b, v146
	v_exp_f32_e32 v147, v146
	v_mul_f32_e32 v150, 0x3d372713, v122
	v_add_f32_e32 v136, 1.0, v136
	v_rcp_f32_e32 v146, v136
	v_add_f32_e32 v136, 1.0, v147
	v_rcp_f32_e32 v148, v136
	v_mul_f32_e32 v136, 0x3d372713, v125
	v_mul_f32_e32 v136, v125, v136
	v_fma_f32 v136, v125, v136, v125
	v_mul_f32_e32 v136, 0xbfcc422a, v136
	v_mul_f32_e32 v136, 0x3fb8aa3b, v136
	v_exp_f32_e32 v136, v136
	v_mul_f32_e32 v147, 0x3d372713, v121
	v_mul_f32_e32 v147, v121, v147
	v_fma_f32 v149, v121, v147, v121
	v_add_f32_e32 v136, 1.0, v136
	v_rcp_f32_e32 v147, v136
	v_mul_f32_e32 v136, 0xbfcc422a, v149
	v_mul_f32_e32 v149, 0x3d372713, v126
	v_mul_f32_e32 v149, v126, v149
	v_fma_f32 v149, v126, v149, v126
	v_mul_f32_e32 v150, v122, v150
	v_fma_f32 v150, v122, v150, v122
	v_mul_f32_e32 v149, 0xbfcc422a, v149
	v_mul_f32_e32 v149, 0x3fb8aa3b, v149
	v_mul_f32_e32 v150, 0xbfcc422a, v150
	v_exp_f32_e32 v149, v149
	v_mul_f32_e32 v150, 0x3fb8aa3b, v150
	v_exp_f32_e32 v151, v150
	v_mul_f32_e32 v158, 0x3d372713, v123
	v_add_f32_e32 v149, 1.0, v149
	v_rcp_f32_e32 v150, v149
	v_add_f32_e32 v149, 1.0, v151
	v_mul_f32_e32 v151, 0x3d372713, v127
	v_mul_f32_e32 v151, v127, v151
	v_fma_f32 v151, v127, v151, v127
	v_mul_f32_e32 v158, v123, v158
	v_fma_f32 v158, v123, v158, v123
	v_mul_f32_e32 v151, 0xbfcc422a, v151
	v_mul_f32_e32 v151, 0x3fb8aa3b, v151
	v_mul_f32_e32 v158, 0xbfcc422a, v158
	v_mul_f32_e32 v136, 0x3fb8aa3b, v136
	v_exp_f32_e32 v151, v151
	v_mul_f32_e32 v158, 0x3fb8aa3b, v158
	v_exp_f32_e32 v136, v136
	v_exp_f32_e32 v159, v158
	v_rcp_f32_e32 v158, v149
	v_add_f32_e32 v149, 1.0, v151
	v_add_f32_e32 v136, 1.0, v136
	v_rcp_f32_e32 v151, v149
	v_add_f32_e32 v149, 1.0, v159
	v_rcp_f32_e32 v159, v149
	v_rcp_f32_e32 v149, v136
	v_pk_mul_f32 v[126:127], v[126:127], v[150:151]
	v_pk_mul_f32 v[124:125], v[124:125], v[146:147]
	v_pk_mul_f32 v[122:123], v[122:123], v[158:159]
	v_pk_mul_f32 v[120:121], v[120:121], v[148:149]

; #define PG8_STAGE(bufoff, gbase, voff) do { _Pragma("unroll") for (int _i = 0; _i < 2; ++_i) \
;         __builtin_amdgcn_global_load_lds((const unsigned*)((const char*)(gbase) + (voff)[_i]), (LAS unsigned*)(lds + (bufoff) + ldsw + _i * 8192), 16, 0, 0); } while (0)
; #define PG8_LDA(dst, b, h) do { _Pragma("unroll") for (int m = 0; m < 4; ++m) _Pragma("unroll") for (int k = 0; k < 2; ++k) dst[m][k] = *(const LAS bf16x8*)(lds + PG8_SA(b, h) + aoff + m * 2048 + k * 1024); } while (0)
; #define PG8_LDB(dst, b, h) do { _Pragma("unroll") for (int n = 0; n < 2; ++n) _Pragma("unroll") for (int k = 0; k < 2; ++k) dst[n][k] = *(const LAS bf16x8*)(lds + PG8_SB(b, h) + boff + n * 2048 + k * 1024); } while (0)
; #define PG8_WAIT_V(n) asm volatile("s_waitcnt vmcnt(" #n ")" ::: "memory")
; #define PG8_WAIT_L(n) asm volatile("s_waitcnt lgkmcnt(" #n ")" ::: "memory")
; #define PG8_BAR __builtin_amdgcn_s_barrier()
; #define PG8_SCHED __builtin_amdgcn_sched_barrier(0)
; template <class Epi>
; __device__ __forceinline__ void gemm_phase(LAS unsigned char* lds, const bf16_t* A, int lda, const bf16_t* Bt, int ldb, int M, int N, int K, int asel, const Epi& E, const int fixed_round = -1) {
;     ...
;         const bool has_next = (fixed_round < 0) && S.next(ui + 1, nxt);
;         const char* nA = has_next ? PG8_ABASE(nxt) : cA; const char* nB = has_next ? (const char*)Bt + (size_t)nxt.pn * tstepB : cB;
;         for (int t = 0; t < nt; t += 2) {
;             const bool last = (t == nt - 2);
;             const char* a1 = cA + (size_t)(t + 1) * kstep;
;             const char* a2 = last ? nA : cA + (size_t)(t + 2) * kstep; const char* b2 = last ? nB : cB + (size_t)(t + 2) * kstep;
;             const char* a3 = a2 + kstep; const char* b3 = b2 + kstep;
;             PG8_LDB(B0, 0, 0); PG8_SCHED; PG8_LDA(At, 0, 0); PG8_STAGE(PG8_SA(1, 1), a1 + hstepA, voffA);
;             PG8_WAIT_L(8); PG8_BAR; PG8_WAIT_L(0); PG8_MMA(0, 0, At, B0); PG8_BAR; PG8_SCHED;
;             PG8_LDB(B1, 0, 1); PG8_STAGE(PG8_SB(0, 0), b2, voffB);
;             PG8_BAR; PG8_WAIT_L(0); PG8_MMA(0, 1, At, B1); PG8_BAR;
;             PG8_LDA(At, 0, 1); PG8_STAGE(PG8_SA(0, 0), a2, voffA);
;             PG8_BAR; PG8_WAIT_L(0); PG8_MMA(1, 0, At, B0); PG8_BAR; PG8_SCHED;
;             PG8_STAGE(PG8_SB(0, 1), b2 + hstepB, voffB);
;             PG8_WAIT_V(6); PG8_BAR; PG8_MMA(1, 1, At, B1); PG8_BAR;
.LBB0_1081:
	ds_read_b128 v[146:149], v140
	ds_read_b128 v[150:153], v140 offset:1024
	ds_read_b128 v[160:163], v140 offset:2048
	ds_read_b128 v[166:169], v140 offset:3072
	s_mov_b32 m0, s57
	v_lshl_add_u64 v[156:157], v[136:137], 0, s[22:23]
	ds_read_b128 v[170:173], v141
	ds_read_b128 v[174:177], v141 offset:1024
	ds_read_b128 v[178:181], v141 offset:2048
	ds_read_b128 v[182:185], v141 offset:3072
	ds_read_b128 v[186:189], v141 offset:4096
	ds_read_b128 v[190:193], v141 offset:5120
	ds_read_b128 v[194:197], v141 offset:6144
	ds_read_b128 v[202:205], v141 offset:7168
	global_load_lds_dwordx4 v[156:157], off
	v_lshl_add_u64 v[156:157], v[138:139], 0, s[22:23]
	s_mov_b32 m0, s58
	s_nop 0
	global_load_lds_dwordx4 v[156:157], off
	s_waitcnt lgkmcnt(8)
	s_setprio 1
	s_barrier
	s_waitcnt lgkmcnt(0)
	v_mfma_f32_16x16x32_bf16 v[124:127], v[146:149], v[170:173], v[124:127]
	v_mfma_f32_16x16x32_bf16 v[120:123], v[160:163], v[170:173], v[120:123]
	v_mfma_f32_16x16x32_bf16 v[112:115], v[146:149], v[178:181], v[112:115]
	v_mfma_f32_16x16x32_bf16 v[104:107], v[160:163], v[178:181], v[104:107]
	v_mfma_f32_16x16x32_bf16 v[96:99], v[146:149], v[186:189], v[96:99]
	v_mfma_f32_16x16x32_bf16 v[88:91], v[160:163], v[186:189], v[88:91]
	v_mfma_f32_16x16x32_bf16 v[80:83], v[146:149], v[194:197], v[80:83]
	v_mfma_f32_16x16x32_bf16 v[72:75], v[160:163], v[194:197], v[72:75]
	v_mfma_f32_16x16x32_bf16 v[124:127], v[150:153], v[174:177], v[124:127]
	v_mfma_f32_16x16x32_bf16 v[120:123], v[166:169], v[174:177], v[120:123]
	v_mfma_f32_16x16x32_bf16 v[112:115], v[150:153], v[182:185], v[112:115]
	v_mfma_f32_16x16x32_bf16 v[104:107], v[166:169], v[182:185], v[104:107]
	v_mfma_f32_16x16x32_bf16 v[96:99], v[150:153], v[190:193], v[96:99]
	v_mfma_f32_16x16x32_bf16 v[88:91], v[166:169], v[190:193], v[88:91]
	v_mfma_f32_16x16x32_bf16 v[80:83], v[150:153], v[202:205], v[80:83]
	v_mfma_f32_16x16x32_bf16 v[72:75], v[166:169], v[202:205], v[72:75]
	s_setprio 0
	s_barrier
	s_add_u32 s28, s22, 0xdfa80080
	s_addc_u32 s29, s23, -1
	s_cmp_lg_u32 s56, 28
	s_cselect_b32 s28, s28, 0
	s_cselect_b32 s29, s29, 0
	s_add_u32 s46, s0, s28
	s_addc_u32 s47, s1, s29
	s_add_u32 s44, s2, s28
	s_addc_u32 s45, s3, s29
	s_mov_b32 m0, s59
	s_add_u32 s98, s44, s42
	s_addc_u32 s99, s45, s43
	ds_read_b128 v[206:209], v142
	ds_read_b128 v[210:213], v142 offset:1024
	ds_read_b128 v[214:217], v142 offset:2048
	ds_read_b128 v[218:221], v142 offset:3072
	global_load_lds_dwordx4 v130, s[44:45]
	s_mov_b32 m0, s60
	s_nop 0
	global_load_lds_dwordx4 v134, s[44:45]
	s_setprio 1
	s_barrier
	s_waitcnt lgkmcnt(0)
	v_mfma_f32_16x16x32_bf16 v[116:119], v[206:209], v[170:173], v[116:119]
	v_mfma_f32_16x16x32_bf16 v[108:111], v[214:217], v[170:173], v[108:111]
	v_mfma_f32_16x16x32_bf16 v[100:103], v[206:209], v[178:181], v[100:103]
	v_mfma_f32_16x16x32_bf16 v[92:95], v[214:217], v[178:181], v[92:95]
	v_mfma_f32_16x16x32_bf16 v[84:87], v[206:209], v[186:189], v[84:87]
	v_mfma_f32_16x16x32_bf16 v[76:79], v[214:217], v[186:189], v[76:79]
	v_mfma_f32_16x16x32_bf16 v[68:71], v[206:209], v[194:197], v[68:71]
	v_mfma_f32_16x16x32_bf16 v[64:67], v[214:217], v[194:197], v[64:67]
	v_mfma_f32_16x16x32_bf16 v[116:119], v[210:213], v[174:177], v[116:119]
	v_mfma_f32_16x16x32_bf16 v[108:111], v[218:221], v[174:177], v[108:111]
	v_mfma_f32_16x16x32_bf16 v[100:103], v[210:213], v[182:185], v[100:103]
	v_mfma_f32_16x16x32_bf16 v[92:95], v[218:221], v[182:185], v[92:95]
	v_mfma_f32_16x16x32_bf16 v[84:87], v[210:213], v[190:193], v[84:87]
	v_mfma_f32_16x16x32_bf16 v[76:79], v[218:221], v[190:193], v[76:79]
	v_mfma_f32_16x16x32_bf16 v[68:71], v[210:213], v[202:205], v[68:71]
	v_mfma_f32_16x16x32_bf16 v[64:67], v[218:221], v[202:205], v[64:67]
	s_setprio 0
	s_mov_b32 m0, s49
	s_add_u32 s100, s46, s42
	s_addc_u32 s101, s47, s43
	s_barrier
	ds_read_b128 v[170:173], v141 offset:16384
	ds_read_b128 v[174:177], v141 offset:17408
	ds_read_b128 v[178:181], v141 offset:18432
	ds_read_b128 v[182:185], v141 offset:19456
	ds_read_b128 v[186:189], v141 offset:20480
	ds_read_b128 v[190:193], v141 offset:21504
	ds_read_b128 v[194:197], v141 offset:22528
	ds_read_b128 v[202:205], v141 offset:23552
	global_load_lds_dwordx4 v128, s[46:47]
	s_mov_b32 m0, s50
	s_nop 0
	global_load_lds_dwordx4 v132, s[46:47]
	s_setprio 1
	s_barrier
	s_waitcnt lgkmcnt(0)
	v_mfma_f32_16x16x32_bf16 v[60:63], v[146:149], v[170:173], v[60:63]
	v_mfma_f32_16x16x32_bf16 v[56:59], v[160:163], v[170:173], v[56:59]
	v_mfma_f32_16x16x32_bf16 v[48:51], v[146:149], v[178:181], v[48:51]
	v_mfma_f32_16x16x32_bf16 v[40:43], v[160:163], v[178:181], v[40:43]
	v_mfma_f32_16x16x32_bf16 v[32:35], v[146:149], v[186:189], v[32:35]
	v_mfma_f32_16x16x32_bf16 v[24:27], v[160:163], v[186:189], v[24:27]
	v_mfma_f32_16x16x32_bf16 v[16:19], v[146:149], v[194:197], v[16:19]
	v_mfma_f32_16x16x32_bf16 v[8:11], v[160:163], v[194:197], v[8:11]
	v_mfma_f32_16x16x32_bf16 v[60:63], v[150:153], v[174:177], v[60:63]
	v_mfma_f32_16x16x32_bf16 v[56:59], v[166:169], v[174:177], v[56:59]
	v_mfma_f32_16x16x32_bf16 v[48:51], v[150:153], v[182:185], v[48:51]
	v_mfma_f32_16x16x32_bf16 v[40:43], v[166:169], v[182:185], v[40:43]
	v_mfma_f32_16x16x32_bf16 v[32:35], v[150:153], v[190:193], v[32:35]
	v_mfma_f32_16x16x32_bf16 v[24:27], v[166:169], v[190:193], v[24:27]
	v_mfma_f32_16x16x32_bf16 v[16:19], v[150:153], v[202:205], v[16:19]
	v_mfma_f32_16x16x32_bf16 v[8:11], v[166:169], v[202:205], v[8:11]
	s_setprio 0
	s_barrier
	s_add_u32 s28, s44, 0x80000
	s_addc_u32 s29, s45, 0
	s_mov_b32 m0, s61
	s_nop 0
	global_load_lds_dwordx4 v130, s[28:29]
	s_mov_b32 m0, s62
	s_nop 0
	global_load_lds_dwordx4 v134, s[28:29]
	s_waitcnt vmcnt(6)
	s_setprio 1
	s_barrier
; #define PG8_STAGE(bufoff, gbase, voff) do { _Pragma("unroll") for (int _i = 0; _i < 2; ++_i) \
;         __builtin_amdgcn_global_load_lds((const unsigned*)((const char*)(gbase) + (voff)[_i]), (LAS unsigned*)(lds + (bufoff) + ldsw + _i * 8192), 16, 0, 0); } while (0)
; #define PG8_LDA(dst, b, h) do { _Pragma("unroll") for (int m = 0; m < 4; ++m) _Pragma("unroll") for (int k = 0; k < 2; ++k) dst[m][k] = *(const LAS bf16x8*)(lds + PG8_SA(b, h) + aoff + m * 2048 + k * 1024); } while (0)
; #define PG8_LDB(dst, b, h) do { _Pragma("unroll") for (int n = 0; n < 2; ++n) _Pragma("unroll") for (int k = 0; k < 2; ++k) dst[n][k] = *(const LAS bf16x8*)(lds + PG8_SB(b, h) + boff + n * 2048 + k * 1024); } while (0)
; #define PG8_WAIT_V(n) asm volatile("s_waitcnt vmcnt(" #n ")" ::: "memory")
; #define PG8_WAIT_L(n) asm volatile("s_waitcnt lgkmcnt(" #n ")" ::: "memory")
; #define PG8_BAR __builtin_amdgcn_s_barrier()
; #define PG8_SCHED __builtin_amdgcn_sched_barrier(0)
; template <class Epi>
; __device__ __forceinline__ void gemm_phase(LAS unsigned char* lds, const bf16_t* A, int lda, const bf16_t* Bt, int ldb, int M, int N, int K, int asel, const Epi& E, const int fixed_round = -1) {
;     ...
;             PG8_WAIT_V(6); PG8_BAR; PG8_MMA(1, 1, At, B1); PG8_BAR;
;             PG8_LDB(B0, 1, 0); PG8_SCHED; PG8_LDA(At, 1, 0); PG8_STAGE(PG8_SA(0, 1), a2 + hstepA, voffA);
;             PG8_WAIT_L(8); PG8_BAR; PG8_WAIT_L(0); PG8_MMA(0, 0, At, B0); PG8_BAR; PG8_SCHED;
;             PG8_LDB(B1, 1, 1); PG8_STAGE(PG8_SB(1, 0), b3, voffB);
;             PG8_BAR; PG8_WAIT_L(0); PG8_MMA(0, 1, At, B1); PG8_BAR;
;             PG8_LDA(At, 1, 1); PG8_STAGE(PG8_SA(1, 0), a3, voffA);
;             PG8_BAR; PG8_WAIT_L(0); PG8_MMA(1, 0, At, B0); PG8_BAR; PG8_SCHED;
	v_mfma_f32_16x16x32_bf16 v[52:55], v[206:209], v[170:173], v[52:55]
	v_mfma_f32_16x16x32_bf16 v[44:47], v[214:217], v[170:173], v[44:47]
	v_mfma_f32_16x16x32_bf16 v[36:39], v[206:209], v[178:181], v[36:39]
	v_mfma_f32_16x16x32_bf16 v[28:31], v[214:217], v[178:181], v[28:31]
	v_mfma_f32_16x16x32_bf16 v[20:23], v[206:209], v[186:189], v[20:23]
	v_mfma_f32_16x16x32_bf16 v[12:15], v[214:217], v[186:189], v[12:15]
	v_mfma_f32_16x16x32_bf16 v[4:7], v[206:209], v[194:197], v[4:7]
	v_mfma_f32_16x16x32_bf16 v[0:3], v[214:217], v[194:197], v[0:3]
	v_mfma_f32_16x16x32_bf16 v[52:55], v[210:213], v[174:177], v[52:55]
	v_mfma_f32_16x16x32_bf16 v[44:47], v[218:221], v[174:177], v[44:47]
	v_mfma_f32_16x16x32_bf16 v[36:39], v[210:213], v[182:185], v[36:39]
	v_mfma_f32_16x16x32_bf16 v[28:31], v[218:221], v[182:185], v[28:31]
	v_mfma_f32_16x16x32_bf16 v[20:23], v[210:213], v[190:193], v[20:23]
	v_mfma_f32_16x16x32_bf16 v[12:15], v[218:221], v[190:193], v[12:15]
	v_mfma_f32_16x16x32_bf16 v[4:7], v[210:213], v[202:205], v[4:7]
	v_mfma_f32_16x16x32_bf16 v[0:3], v[218:221], v[202:205], v[0:3]
	s_setprio 0
	s_barrier
	ds_read_b128 v[146:149], v143
	ds_read_b128 v[150:153], v143 offset:1024
	ds_read_b128 v[160:163], v143 offset:2048
	ds_read_b128 v[166:169], v143 offset:3072
	s_add_u32 s28, s46, 0x80000
	s_addc_u32 s29, s47, 0
	s_mov_b32 m0, s52
	ds_read_b128 v[170:173], v141 offset:32768
	ds_read_b128 v[174:177], v141 offset:33792
	ds_read_b128 v[178:181], v141 offset:34816
	ds_read_b128 v[182:185], v141 offset:35840
	ds_read_b128 v[186:189], v141 offset:36864
	ds_read_b128 v[190:193], v141 offset:37888
	ds_read_b128 v[194:197], v141 offset:38912
	ds_read_b128 v[202:205], v141 offset:39936
	global_load_lds_dwordx4 v128, s[28:29]
	s_mov_b32 m0, s53
	s_nop 0
	global_load_lds_dwordx4 v132, s[28:29]
	s_waitcnt lgkmcnt(8)
	s_setprio 1
	s_barrier
	s_waitcnt lgkmcnt(0)
	v_mfma_f32_16x16x32_bf16 v[124:127], v[146:149], v[170:173], v[124:127]
	v_mfma_f32_16x16x32_bf16 v[120:123], v[160:163], v[170:173], v[120:123]
	v_mfma_f32_16x16x32_bf16 v[112:115], v[146:149], v[178:181], v[112:115]
	v_mfma_f32_16x16x32_bf16 v[104:107], v[160:163], v[178:181], v[104:107]
	v_mfma_f32_16x16x32_bf16 v[96:99], v[146:149], v[186:189], v[96:99]
	v_mfma_f32_16x16x32_bf16 v[88:91], v[160:163], v[186:189], v[88:91]
	v_mfma_f32_16x16x32_bf16 v[80:83], v[146:149], v[194:197], v[80:83]
	v_mfma_f32_16x16x32_bf16 v[72:75], v[160:163], v[194:197], v[72:75]
	v_mfma_f32_16x16x32_bf16 v[124:127], v[150:153], v[174:177], v[124:127]
	v_mfma_f32_16x16x32_bf16 v[120:123], v[166:169], v[174:177], v[120:123]
	v_mfma_f32_16x16x32_bf16 v[112:115], v[150:153], v[182:185], v[112:115]
	v_mfma_f32_16x16x32_bf16 v[104:107], v[166:169], v[182:185], v[104:107]
	v_mfma_f32_16x16x32_bf16 v[96:99], v[150:153], v[190:193], v[96:99]
	v_mfma_f32_16x16x32_bf16 v[88:91], v[166:169], v[190:193], v[88:91]
	v_mfma_f32_16x16x32_bf16 v[80:83], v[150:153], v[202:205], v[80:83]
	v_mfma_f32_16x16x32_bf16 v[72:75], v[166:169], v[202:205], v[72:75]
	s_setprio 0
	s_barrier
	s_mov_b32 m0, s63
	ds_read_b128 v[206:209], v144
	ds_read_b128 v[210:213], v144 offset:1024
	ds_read_b128 v[214:217], v144 offset:2048
	ds_read_b128 v[218:221], v144 offset:3072
	global_load_lds_dwordx4 v130, s[98:99]
	s_mov_b32 m0, s64
	s_nop 0
	global_load_lds_dwordx4 v134, s[98:99]
	s_setprio 1
	s_barrier
; #define PG8_STAGE(bufoff, gbase, voff) do { _Pragma("unroll") for (int _i = 0; _i < 2; ++_i) \
;         __builtin_amdgcn_global_load_lds((const unsigned*)((const char*)(gbase) + (voff)[_i]), (LAS unsigned*)(lds + (bufoff) + ldsw + _i * 8192), 16, 0, 0); } while (0)
; #define PG8_LDA(dst, b, h) do { _Pragma("unroll") for (int m = 0; m < 4; ++m) _Pragma("unroll") for (int k = 0; k < 2; ++k) dst[m][k] = *(const LAS bf16x8*)(lds + PG8_SA(b, h) + aoff + m * 2048 + k * 1024); } while (0)
; #define PG8_WAIT_V(n) asm volatile("s_waitcnt vmcnt(" #n ")" ::: "memory")
; #define PG8_WAIT_L(n) asm volatile("s_waitcnt lgkmcnt(" #n ")" ::: "memory")
; #define PG8_BAR __builtin_amdgcn_s_barrier()
; #define PG8_SCHED __builtin_amdgcn_sched_barrier(0)
; template <class Epi>
; __device__ __forceinline__ void gemm_phase(LAS unsigned char* lds, const bf16_t* A, int lda, const bf16_t* Bt, int ldb, int M, int N, int K, int asel, const Epi& E, const int fixed_round = -1) {
;     ...
;             PG8_BAR; PG8_WAIT_L(0); PG8_MMA(0, 1, At, B1); PG8_BAR;
;             PG8_LDA(At, 1, 1); PG8_STAGE(PG8_SA(1, 0), a3, voffA);
;             PG8_BAR; PG8_WAIT_L(0); PG8_MMA(1, 0, At, B0); PG8_BAR; PG8_SCHED;
;             PG8_STAGE(PG8_SB(1, 1), b3 + hstepB, voffB);
;             PG8_WAIT_V(6); PG8_BAR; PG8_MMA(1, 1, At, B1); PG8_BAR;
;     ...
;     PG8_WAIT_V(0);
;     if (wr == 0) PG8_BAR;
;     PG8_BAR;
	s_waitcnt lgkmcnt(0)
	v_mfma_f32_16x16x32_bf16 v[116:119], v[206:209], v[170:173], v[116:119]
	v_mfma_f32_16x16x32_bf16 v[108:111], v[214:217], v[170:173], v[108:111]
	v_mfma_f32_16x16x32_bf16 v[100:103], v[206:209], v[178:181], v[100:103]
	v_mfma_f32_16x16x32_bf16 v[92:95], v[214:217], v[178:181], v[92:95]
	v_mfma_f32_16x16x32_bf16 v[84:87], v[206:209], v[186:189], v[84:87]
	v_mfma_f32_16x16x32_bf16 v[76:79], v[214:217], v[186:189], v[76:79]
	v_mfma_f32_16x16x32_bf16 v[68:71], v[206:209], v[194:197], v[68:71]
	v_mfma_f32_16x16x32_bf16 v[64:67], v[214:217], v[194:197], v[64:67]
	v_mfma_f32_16x16x32_bf16 v[116:119], v[210:213], v[174:177], v[116:119]
	v_mfma_f32_16x16x32_bf16 v[108:111], v[218:221], v[174:177], v[108:111]
	v_mfma_f32_16x16x32_bf16 v[100:103], v[210:213], v[182:185], v[100:103]
	v_mfma_f32_16x16x32_bf16 v[92:95], v[218:221], v[182:185], v[92:95]
	v_mfma_f32_16x16x32_bf16 v[84:87], v[210:213], v[190:193], v[84:87]
	v_mfma_f32_16x16x32_bf16 v[76:79], v[218:221], v[190:193], v[76:79]
	v_mfma_f32_16x16x32_bf16 v[68:71], v[210:213], v[202:205], v[68:71]
	v_mfma_f32_16x16x32_bf16 v[64:67], v[218:221], v[202:205], v[64:67]
	s_setprio 0
	s_mov_b32 m0, s54
	s_barrier
	ds_read_b128 v[170:173], v141 offset:49152
	ds_read_b128 v[174:177], v141 offset:50176
	ds_read_b128 v[178:181], v141 offset:51200
	ds_read_b128 v[182:185], v141 offset:52224
	ds_read_b128 v[186:189], v141 offset:53248
	ds_read_b128 v[190:193], v141 offset:54272
	ds_read_b128 v[194:197], v141 offset:55296
	ds_read_b128 v[202:205], v141 offset:56320
	global_load_lds_dwordx4 v128, s[100:101]
	s_mov_b32 m0, s55
	s_nop 0
	global_load_lds_dwordx4 v132, s[100:101]
	s_setprio 1
	s_barrier
	s_waitcnt lgkmcnt(0)
	v_mfma_f32_16x16x32_bf16 v[60:63], v[146:149], v[170:173], v[60:63]
	v_mfma_f32_16x16x32_bf16 v[56:59], v[160:163], v[170:173], v[56:59]
	v_mfma_f32_16x16x32_bf16 v[48:51], v[146:149], v[178:181], v[48:51]
	v_mfma_f32_16x16x32_bf16 v[40:43], v[160:163], v[178:181], v[40:43]
	v_mfma_f32_16x16x32_bf16 v[32:35], v[146:149], v[186:189], v[32:35]
	v_mfma_f32_16x16x32_bf16 v[24:27], v[160:163], v[186:189], v[24:27]
	v_mfma_f32_16x16x32_bf16 v[16:19], v[146:149], v[194:197], v[16:19]
	v_mfma_f32_16x16x32_bf16 v[8:11], v[160:163], v[194:197], v[8:11]
	v_mfma_f32_16x16x32_bf16 v[60:63], v[150:153], v[174:177], v[60:63]
	v_mfma_f32_16x16x32_bf16 v[56:59], v[166:169], v[174:177], v[56:59]
	v_mfma_f32_16x16x32_bf16 v[48:51], v[150:153], v[182:185], v[48:51]
	v_mfma_f32_16x16x32_bf16 v[40:43], v[166:169], v[182:185], v[40:43]
	v_mfma_f32_16x16x32_bf16 v[32:35], v[150:153], v[190:193], v[32:35]
	v_mfma_f32_16x16x32_bf16 v[24:27], v[166:169], v[190:193], v[24:27]
	v_mfma_f32_16x16x32_bf16 v[16:19], v[150:153], v[202:205], v[16:19]
	v_mfma_f32_16x16x32_bf16 v[8:11], v[166:169], v[202:205], v[8:11]
	s_setprio 0
	s_barrier
	s_add_u32 s28, s44, 0x80080
	s_addc_u32 s29, s45, 0
	s_mov_b32 m0, s65
	s_nop 0
	global_load_lds_dwordx4 v130, s[28:29]
	s_mov_b32 m0, s66
	s_nop 0
	global_load_lds_dwordx4 v134, s[28:29]
	s_waitcnt vmcnt(6)
	s_setprio 1
	s_barrier
	v_mfma_f32_16x16x32_bf16 v[52:55], v[206:209], v[170:173], v[52:55]
	v_mfma_f32_16x16x32_bf16 v[44:47], v[214:217], v[170:173], v[44:47]
	v_mfma_f32_16x16x32_bf16 v[36:39], v[206:209], v[178:181], v[36:39]
	v_mfma_f32_16x16x32_bf16 v[28:31], v[214:217], v[178:181], v[28:31]
	v_mfma_f32_16x16x32_bf16 v[20:23], v[206:209], v[186:189], v[20:23]
	v_mfma_f32_16x16x32_bf16 v[12:15], v[214:217], v[186:189], v[12:15]
	v_mfma_f32_16x16x32_bf16 v[4:7], v[206:209], v[194:197], v[4:7]
	v_mfma_f32_16x16x32_bf16 v[0:3], v[214:217], v[194:197], v[0:3]
	v_mfma_f32_16x16x32_bf16 v[52:55], v[210:213], v[174:177], v[52:55]
	v_mfma_f32_16x16x32_bf16 v[44:47], v[218:221], v[174:177], v[44:47]
	v_mfma_f32_16x16x32_bf16 v[36:39], v[210:213], v[182:185], v[36:39]
	v_mfma_f32_16x16x32_bf16 v[28:31], v[218:221], v[182:185], v[28:31]
	v_mfma_f32_16x16x32_bf16 v[20:23], v[210:213], v[190:193], v[20:23]
	v_mfma_f32_16x16x32_bf16 v[12:15], v[218:221], v[190:193], v[12:15]
	v_mfma_f32_16x16x32_bf16 v[4:7], v[210:213], v[202:205], v[4:7]
	v_mfma_f32_16x16x32_bf16 v[0:3], v[218:221], v[202:205], v[0:3]
	s_setprio 0
	s_add_i32 s56, s56, 2
	s_add_u32 s22, s22, 0x100
	s_addc_u32 s23, s23, 0
	s_cmp_lt_u32 s56, 30
	s_cbranch_scc1 .Lrot_8
	s_barrier
	s_waitcnt vmcnt(0)
	s_cmpk_gt_u32 s48, 0xff
	s_cbranch_scc1 .LBB0_1084
	s_barrier

; #define PG8_STAGE(bufoff, gbase, voff) do { _Pragma("unroll") for (int _i = 0; _i < 2; ++_i) \
;         __builtin_amdgcn_global_load_lds((const unsigned*)((const char*)(gbase) + (voff)[_i]), (LAS unsigned*)(lds + (bufoff) + ldsw + _i * 8192), 16, 0, 0); } while (0)
; #define PG8_LDA(dst, b, h) do { _Pragma("unroll") for (int m = 0; m < 4; ++m) _Pragma("unroll") for (int k = 0; k < 2; ++k) dst[m][k] = *(const LAS bf16x8*)(lds + PG8_SA(b, h) + aoff + m * 2048 + k * 1024); } while (0)
; #define PG8_LDB(dst, b, h) do { _Pragma("unroll") for (int n = 0; n < 2; ++n) _Pragma("unroll") for (int k = 0; k < 2; ++k) dst[n][k] = *(const LAS bf16x8*)(lds + PG8_SB(b, h) + boff + n * 2048 + k * 1024); } while (0)
; #define PG8_WAIT_V(n) asm volatile("s_waitcnt vmcnt(" #n ")" ::: "memory")
; #define PG8_WAIT_L(n) asm volatile("s_waitcnt lgkmcnt(" #n ")" ::: "memory")
; #define PG8_BAR __builtin_amdgcn_s_barrier()
; #define PG8_SCHED __builtin_amdgcn_sched_barrier(0)
; template <class Epi>
; __device__ __forceinline__ void gemm_phase(LAS unsigned char* lds, const bf16_t* A, int lda, const bf16_t* Bt, int ldb, int M, int N, int K, int asel, const Epi& E, const int fixed_round = -1) {
;     ...
;         const bool has_next = (fixed_round < 0) && S.next(ui + 1, nxt);
;         const char* nA = has_next ? PG8_ABASE(nxt) : cA; const char* nB = has_next ? (const char*)Bt + (size_t)nxt.pn * tstepB : cB;
;         for (int t = 0; t < nt; t += 2) {
;             const bool last = (t == nt - 2);
;             const char* a1 = cA + (size_t)(t + 1) * kstep;
;             const char* a2 = last ? nA : cA + (size_t)(t + 2) * kstep; const char* b2 = last ? nB : cB + (size_t)(t + 2) * kstep;
;             const char* a3 = a2 + kstep; const char* b3 = b2 + kstep;
;             PG8_LDB(B0, 0, 0); PG8_SCHED; PG8_LDA(At, 0, 0); PG8_STAGE(PG8_SA(1, 1), a1 + hstepA, voffA);
;             PG8_WAIT_L(8); PG8_BAR; PG8_WAIT_L(0); PG8_MMA(0, 0, At, B0); PG8_BAR; PG8_SCHED;
;             PG8_LDB(B1, 0, 1); PG8_STAGE(PG8_SB(0, 0), b2, voffB);
;             PG8_BAR; PG8_WAIT_L(0); PG8_MMA(0, 1, At, B1); PG8_BAR;
;             PG8_LDA(At, 0, 1); PG8_STAGE(PG8_SA(0, 0), a2, voffA);
;             PG8_BAR; PG8_WAIT_L(0); PG8_MMA(1, 0, At, B0); PG8_BAR; PG8_SCHED;
;             PG8_STAGE(PG8_SB(0, 1), b2 + hstepB, voffB);
;             PG8_WAIT_V(6); PG8_BAR; PG8_MMA(1, 1, At, B1); PG8_BAR;
.LBB0_1120:
	ds_read_b128 v[146:149], v138
	ds_read_b128 v[150:153], v138 offset:1024
	ds_read_b128 v[160:163], v138 offset:2048
	ds_read_b128 v[166:169], v138 offset:3072
	s_mov_b32 m0, s41
	v_lshl_add_u64 v[156:157], v[134:135], 0, s[6:7]
	ds_read_b128 v[170:173], v139
	ds_read_b128 v[174:177], v139 offset:1024
	ds_read_b128 v[178:181], v139 offset:2048
	ds_read_b128 v[182:185], v139 offset:3072
	ds_read_b128 v[186:189], v139 offset:4096
	ds_read_b128 v[190:193], v139 offset:5120
	ds_read_b128 v[194:197], v139 offset:6144
	ds_read_b128 v[202:205], v139 offset:7168
	global_load_lds_dwordx4 v[156:157], off
	v_lshl_add_u64 v[156:157], v[136:137], 0, s[6:7]
	s_mov_b32 m0, s58
	s_nop 0
	global_load_lds_dwordx4 v[156:157], off
	s_waitcnt lgkmcnt(8)
	s_setprio 1
	s_barrier
	s_waitcnt lgkmcnt(0)
	v_mfma_f32_16x16x32_bf16 v[124:127], v[146:149], v[170:173], v[124:127]
	v_mfma_f32_16x16x32_bf16 v[120:123], v[160:163], v[170:173], v[120:123]
	v_mfma_f32_16x16x32_bf16 v[112:115], v[146:149], v[178:181], v[112:115]
	v_mfma_f32_16x16x32_bf16 v[104:107], v[160:163], v[178:181], v[104:107]
	v_mfma_f32_16x16x32_bf16 v[96:99], v[146:149], v[186:189], v[96:99]
	v_mfma_f32_16x16x32_bf16 v[88:91], v[160:163], v[186:189], v[88:91]
	v_mfma_f32_16x16x32_bf16 v[80:83], v[146:149], v[194:197], v[80:83]
	v_mfma_f32_16x16x32_bf16 v[72:75], v[160:163], v[194:197], v[72:75]
	v_mfma_f32_16x16x32_bf16 v[124:127], v[150:153], v[174:177], v[124:127]
	v_mfma_f32_16x16x32_bf16 v[120:123], v[166:169], v[174:177], v[120:123]
	v_mfma_f32_16x16x32_bf16 v[112:115], v[150:153], v[182:185], v[112:115]
	v_mfma_f32_16x16x32_bf16 v[104:107], v[166:169], v[182:185], v[104:107]
	v_mfma_f32_16x16x32_bf16 v[96:99], v[150:153], v[190:193], v[96:99]
	v_mfma_f32_16x16x32_bf16 v[88:91], v[166:169], v[190:193], v[88:91]
	v_mfma_f32_16x16x32_bf16 v[80:83], v[150:153], v[202:205], v[80:83]
	v_mfma_f32_16x16x32_bf16 v[72:75], v[166:169], v[202:205], v[72:75]
	s_setprio 0
	s_barrier
	s_add_u32 s22, s6, 0xdfa80080
	s_addc_u32 s23, s7, -1
	s_cmp_lg_u32 s40, 28
	s_cselect_b32 s22, s22, 0
	s_cselect_b32 s23, s23, 0
	s_add_u32 s24, s0, s22
	s_addc_u32 s25, s1, s23
	s_add_u32 s22, s2, s22
	s_addc_u32 s23, s3, s23
	s_mov_b32 m0, s59
	s_add_u32 s98, s22, s4
	s_addc_u32 s99, s23, s5
	ds_read_b128 v[206:209], v140
	ds_read_b128 v[210:213], v140 offset:1024
	ds_read_b128 v[214:217], v140 offset:2048
	ds_read_b128 v[218:221], v140 offset:3072
	global_load_lds_dwordx4 v144, s[22:23]
	s_mov_b32 m0, s60
	s_nop 0
	global_load_lds_dwordx4 v132, s[22:23]
	s_setprio 1
	s_barrier
	s_waitcnt lgkmcnt(0)
	v_mfma_f32_16x16x32_bf16 v[116:119], v[206:209], v[170:173], v[116:119]
	v_mfma_f32_16x16x32_bf16 v[108:111], v[214:217], v[170:173], v[108:111]
	v_mfma_f32_16x16x32_bf16 v[100:103], v[206:209], v[178:181], v[100:103]
	v_mfma_f32_16x16x32_bf16 v[92:95], v[214:217], v[178:181], v[92:95]
	v_mfma_f32_16x16x32_bf16 v[84:87], v[206:209], v[186:189], v[84:87]
	v_mfma_f32_16x16x32_bf16 v[76:79], v[214:217], v[186:189], v[76:79]
	v_mfma_f32_16x16x32_bf16 v[68:71], v[206:209], v[194:197], v[68:71]
	v_mfma_f32_16x16x32_bf16 v[64:67], v[214:217], v[194:197], v[64:67]
	v_mfma_f32_16x16x32_bf16 v[116:119], v[210:213], v[174:177], v[116:119]
	v_mfma_f32_16x16x32_bf16 v[108:111], v[218:221], v[174:177], v[108:111]
	v_mfma_f32_16x16x32_bf16 v[100:103], v[210:213], v[182:185], v[100:103]
	v_mfma_f32_16x16x32_bf16 v[92:95], v[218:221], v[182:185], v[92:95]
	v_mfma_f32_16x16x32_bf16 v[84:87], v[210:213], v[190:193], v[84:87]
	v_mfma_f32_16x16x32_bf16 v[76:79], v[218:221], v[190:193], v[76:79]
	v_mfma_f32_16x16x32_bf16 v[68:71], v[210:213], v[202:205], v[68:71]
	v_mfma_f32_16x16x32_bf16 v[64:67], v[218:221], v[202:205], v[64:67]
	s_setprio 0
	s_mov_b32 m0, s52
	s_add_u32 s100, s24, s4
	s_addc_u32 s101, s25, s5
	s_barrier
	ds_read_b128 v[170:173], v139 offset:16384
	ds_read_b128 v[174:177], v139 offset:17408
	ds_read_b128 v[178:181], v139 offset:18432
	ds_read_b128 v[182:185], v139 offset:19456
	ds_read_b128 v[186:189], v139 offset:20480
	ds_read_b128 v[190:193], v139 offset:21504
	ds_read_b128 v[194:197], v139 offset:22528
	ds_read_b128 v[202:205], v139 offset:23552
	global_load_lds_dwordx4 v128, s[24:25]
	s_mov_b32 m0, s53
	s_nop 0
	global_load_lds_dwordx4 v130, s[24:25]
	s_setprio 1
	s_barrier
	s_waitcnt lgkmcnt(0)
	v_mfma_f32_16x16x32_bf16 v[60:63], v[146:149], v[170:173], v[60:63]
	v_mfma_f32_16x16x32_bf16 v[56:59], v[160:163], v[170:173], v[56:59]
	v_mfma_f32_16x16x32_bf16 v[48:51], v[146:149], v[178:181], v[48:51]
	v_mfma_f32_16x16x32_bf16 v[40:43], v[160:163], v[178:181], v[40:43]
	v_mfma_f32_16x16x32_bf16 v[32:35], v[146:149], v[186:189], v[32:35]
	v_mfma_f32_16x16x32_bf16 v[24:27], v[160:163], v[186:189], v[24:27]
	v_mfma_f32_16x16x32_bf16 v[16:19], v[146:149], v[194:197], v[16:19]
	v_mfma_f32_16x16x32_bf16 v[8:11], v[160:163], v[194:197], v[8:11]
	v_mfma_f32_16x16x32_bf16 v[60:63], v[150:153], v[174:177], v[60:63]
	v_mfma_f32_16x16x32_bf16 v[56:59], v[166:169], v[174:177], v[56:59]
	v_mfma_f32_16x16x32_bf16 v[48:51], v[150:153], v[182:185], v[48:51]
	v_mfma_f32_16x16x32_bf16 v[40:43], v[166:169], v[182:185], v[40:43]
	v_mfma_f32_16x16x32_bf16 v[32:35], v[150:153], v[190:193], v[32:35]
	v_mfma_f32_16x16x32_bf16 v[24:27], v[166:169], v[190:193], v[24:27]
	v_mfma_f32_16x16x32_bf16 v[16:19], v[150:153], v[202:205], v[16:19]
	v_mfma_f32_16x16x32_bf16 v[8:11], v[166:169], v[202:205], v[8:11]
	s_setprio 0
	s_barrier
	s_add_u32 s28, s22, 0x80000
	s_addc_u32 s29, s23, 0
	s_mov_b32 m0, s61
	s_nop 0
	global_load_lds_dwordx4 v144, s[28:29]
	s_mov_b32 m0, s62
	s_nop 0
	global_load_lds_dwordx4 v132, s[28:29]
	s_waitcnt vmcnt(6)
	s_setprio 1
	s_barrier
; #define PG8_STAGE(bufoff, gbase, voff) do { _Pragma("unroll") for (int _i = 0; _i < 2; ++_i) \
;         __builtin_amdgcn_global_load_lds((const unsigned*)((const char*)(gbase) + (voff)[_i]), (LAS unsigned*)(lds + (bufoff) + ldsw + _i * 8192), 16, 0, 0); } while (0)
; #define PG8_LDA(dst, b, h) do { _Pragma("unroll") for (int m = 0; m < 4; ++m) _Pragma("unroll") for (int k = 0; k < 2; ++k) dst[m][k] = *(const LAS bf16x8*)(lds + PG8_SA(b, h) + aoff + m * 2048 + k * 1024); } while (0)
; #define PG8_LDB(dst, b, h) do { _Pragma("unroll") for (int n = 0; n < 2; ++n) _Pragma("unroll") for (int k = 0; k < 2; ++k) dst[n][k] = *(const LAS bf16x8*)(lds + PG8_SB(b, h) + boff + n * 2048 + k * 1024); } while (0)
; #define PG8_WAIT_V(n) asm volatile("s_waitcnt vmcnt(" #n ")" ::: "memory")
; #define PG8_WAIT_L(n) asm volatile("s_waitcnt lgkmcnt(" #n ")" ::: "memory")
; #define PG8_BAR __builtin_amdgcn_s_barrier()
; #define PG8_SCHED __builtin_amdgcn_sched_barrier(0)
; template <class Epi>
; __device__ __forceinline__ void gemm_phase(LAS unsigned char* lds, const bf16_t* A, int lda, const bf16_t* Bt, int ldb, int M, int N, int K, int asel, const Epi& E, const int fixed_round = -1) {
;     ...
;             PG8_WAIT_V(6); PG8_BAR; PG8_MMA(1, 1, At, B1); PG8_BAR;
;             PG8_LDB(B0, 1, 0); PG8_SCHED; PG8_LDA(At, 1, 0); PG8_STAGE(PG8_SA(0, 1), a2 + hstepA, voffA);
;             PG8_WAIT_L(8); PG8_BAR; PG8_WAIT_L(0); PG8_MMA(0, 0, At, B0); PG8_BAR; PG8_SCHED;
;             PG8_LDB(B1, 1, 1); PG8_STAGE(PG8_SB(1, 0), b3, voffB);
;             PG8_BAR; PG8_WAIT_L(0); PG8_MMA(0, 1, At, B1); PG8_BAR;
;             PG8_LDA(At, 1, 1); PG8_STAGE(PG8_SA(1, 0), a3, voffA);
;             PG8_BAR; PG8_WAIT_L(0); PG8_MMA(1, 0, At, B0); PG8_BAR; PG8_SCHED;
	v_mfma_f32_16x16x32_bf16 v[52:55], v[206:209], v[170:173], v[52:55]
	v_mfma_f32_16x16x32_bf16 v[44:47], v[214:217], v[170:173], v[44:47]
	v_mfma_f32_16x16x32_bf16 v[36:39], v[206:209], v[178:181], v[36:39]
	v_mfma_f32_16x16x32_bf16 v[28:31], v[214:217], v[178:181], v[28:31]
	v_mfma_f32_16x16x32_bf16 v[20:23], v[206:209], v[186:189], v[20:23]
	v_mfma_f32_16x16x32_bf16 v[12:15], v[214:217], v[186:189], v[12:15]
	v_mfma_f32_16x16x32_bf16 v[4:7], v[206:209], v[194:197], v[4:7]
	v_mfma_f32_16x16x32_bf16 v[0:3], v[214:217], v[194:197], v[0:3]
	v_mfma_f32_16x16x32_bf16 v[52:55], v[210:213], v[174:177], v[52:55]
	v_mfma_f32_16x16x32_bf16 v[44:47], v[218:221], v[174:177], v[44:47]
	v_mfma_f32_16x16x32_bf16 v[36:39], v[210:213], v[182:185], v[36:39]
	v_mfma_f32_16x16x32_bf16 v[28:31], v[218:221], v[182:185], v[28:31]
	v_mfma_f32_16x16x32_bf16 v[20:23], v[210:213], v[190:193], v[20:23]
	v_mfma_f32_16x16x32_bf16 v[12:15], v[218:221], v[190:193], v[12:15]
	v_mfma_f32_16x16x32_bf16 v[4:7], v[210:213], v[202:205], v[4:7]
	v_mfma_f32_16x16x32_bf16 v[0:3], v[218:221], v[202:205], v[0:3]
	s_setprio 0
	s_barrier
	ds_read_b128 v[146:149], v141
	ds_read_b128 v[150:153], v141 offset:1024
	ds_read_b128 v[160:163], v141 offset:2048
	ds_read_b128 v[166:169], v141 offset:3072
	s_add_u32 s24, s24, 0x80000
	s_addc_u32 s25, s25, 0
	s_mov_b32 m0, s54
	ds_read_b128 v[170:173], v139 offset:32768
	ds_read_b128 v[174:177], v139 offset:33792
	ds_read_b128 v[178:181], v139 offset:34816
	ds_read_b128 v[182:185], v139 offset:35840
	ds_read_b128 v[186:189], v139 offset:36864
	ds_read_b128 v[190:193], v139 offset:37888
	ds_read_b128 v[194:197], v139 offset:38912
	ds_read_b128 v[202:205], v139 offset:39936
	global_load_lds_dwordx4 v128, s[24:25]
	s_mov_b32 m0, s55
	s_nop 0
	global_load_lds_dwordx4 v130, s[24:25]
	s_waitcnt lgkmcnt(8)
	s_setprio 1
	s_barrier
	s_waitcnt lgkmcnt(0)
	v_mfma_f32_16x16x32_bf16 v[124:127], v[146:149], v[170:173], v[124:127]
	v_mfma_f32_16x16x32_bf16 v[120:123], v[160:163], v[170:173], v[120:123]
	v_mfma_f32_16x16x32_bf16 v[112:115], v[146:149], v[178:181], v[112:115]
	v_mfma_f32_16x16x32_bf16 v[104:107], v[160:163], v[178:181], v[104:107]
	v_mfma_f32_16x16x32_bf16 v[96:99], v[146:149], v[186:189], v[96:99]
	v_mfma_f32_16x16x32_bf16 v[88:91], v[160:163], v[186:189], v[88:91]
	v_mfma_f32_16x16x32_bf16 v[80:83], v[146:149], v[194:197], v[80:83]
	v_mfma_f32_16x16x32_bf16 v[72:75], v[160:163], v[194:197], v[72:75]
	v_mfma_f32_16x16x32_bf16 v[124:127], v[150:153], v[174:177], v[124:127]
	v_mfma_f32_16x16x32_bf16 v[120:123], v[166:169], v[174:177], v[120:123]
	v_mfma_f32_16x16x32_bf16 v[112:115], v[150:153], v[182:185], v[112:115]
	v_mfma_f32_16x16x32_bf16 v[104:107], v[166:169], v[182:185], v[104:107]
	v_mfma_f32_16x16x32_bf16 v[96:99], v[150:153], v[190:193], v[96:99]
	v_mfma_f32_16x16x32_bf16 v[88:91], v[166:169], v[190:193], v[88:91]
	v_mfma_f32_16x16x32_bf16 v[80:83], v[150:153], v[202:205], v[80:83]
	v_mfma_f32_16x16x32_bf16 v[72:75], v[166:169], v[202:205], v[72:75]
	s_setprio 0
	s_barrier
	s_mov_b32 m0, s63
	ds_read_b128 v[206:209], v142
	ds_read_b128 v[210:213], v142 offset:1024
	ds_read_b128 v[214:217], v142 offset:2048
	ds_read_b128 v[218:221], v142 offset:3072
	global_load_lds_dwordx4 v144, s[98:99]
	s_mov_b32 m0, s64
	s_nop 0
	global_load_lds_dwordx4 v132, s[98:99]
	s_setprio 1
	s_barrier
; #define PG8_STAGE(bufoff, gbase, voff) do { _Pragma("unroll") for (int _i = 0; _i < 2; ++_i) \
;         __builtin_amdgcn_global_load_lds((const unsigned*)((const char*)(gbase) + (voff)[_i]), (LAS unsigned*)(lds + (bufoff) + ldsw + _i * 8192), 16, 0, 0); } while (0)
; #define PG8_LDA(dst, b, h) do { _Pragma("unroll") for (int m = 0; m < 4; ++m) _Pragma("unroll") for (int k = 0; k < 2; ++k) dst[m][k] = *(const LAS bf16x8*)(lds + PG8_SA(b, h) + aoff + m * 2048 + k * 1024); } while (0)
; #define PG8_WAIT_V(n) asm volatile("s_waitcnt vmcnt(" #n ")" ::: "memory")
; #define PG8_WAIT_L(n) asm volatile("s_waitcnt lgkmcnt(" #n ")" ::: "memory")
; #define PG8_BAR __builtin_amdgcn_s_barrier()
; #define PG8_SCHED __builtin_amdgcn_sched_barrier(0)
; template <class Epi>
; __device__ __forceinline__ void gemm_phase(LAS unsigned char* lds, const bf16_t* A, int lda, const bf16_t* Bt, int ldb, int M, int N, int K, int asel, const Epi& E, const int fixed_round = -1) {
;     ...
;             PG8_BAR; PG8_WAIT_L(0); PG8_MMA(0, 1, At, B1); PG8_BAR;
;             PG8_LDA(At, 1, 1); PG8_STAGE(PG8_SA(1, 0), a3, voffA);
;             PG8_BAR; PG8_WAIT_L(0); PG8_MMA(1, 0, At, B0); PG8_BAR; PG8_SCHED;
;             PG8_STAGE(PG8_SB(1, 1), b3 + hstepB, voffB);
;             PG8_WAIT_V(6); PG8_BAR; PG8_MMA(1, 1, At, B1); PG8_BAR;
;     ...
;     PG8_WAIT_V(0);
;     if (wr == 0) PG8_BAR;
;     PG8_BAR;
	s_waitcnt lgkmcnt(0)
	v_mfma_f32_16x16x32_bf16 v[116:119], v[206:209], v[170:173], v[116:119]
	v_mfma_f32_16x16x32_bf16 v[108:111], v[214:217], v[170:173], v[108:111]
	v_mfma_f32_16x16x32_bf16 v[100:103], v[206:209], v[178:181], v[100:103]
	v_mfma_f32_16x16x32_bf16 v[92:95], v[214:217], v[178:181], v[92:95]
	v_mfma_f32_16x16x32_bf16 v[84:87], v[206:209], v[186:189], v[84:87]
	v_mfma_f32_16x16x32_bf16 v[76:79], v[214:217], v[186:189], v[76:79]
	v_mfma_f32_16x16x32_bf16 v[68:71], v[206:209], v[194:197], v[68:71]
	v_mfma_f32_16x16x32_bf16 v[64:67], v[214:217], v[194:197], v[64:67]
	v_mfma_f32_16x16x32_bf16 v[116:119], v[210:213], v[174:177], v[116:119]
	v_mfma_f32_16x16x32_bf16 v[108:111], v[218:221], v[174:177], v[108:111]
	v_mfma_f32_16x16x32_bf16 v[100:103], v[210:213], v[182:185], v[100:103]
	v_mfma_f32_16x16x32_bf16 v[92:95], v[218:221], v[182:185], v[92:95]
	v_mfma_f32_16x16x32_bf16 v[84:87], v[210:213], v[190:193], v[84:87]
	v_mfma_f32_16x16x32_bf16 v[76:79], v[218:221], v[190:193], v[76:79]
	v_mfma_f32_16x16x32_bf16 v[68:71], v[210:213], v[202:205], v[68:71]
	v_mfma_f32_16x16x32_bf16 v[64:67], v[218:221], v[202:205], v[64:67]
	s_setprio 0
	s_mov_b32 m0, s56
	s_barrier
	ds_read_b128 v[170:173], v139 offset:49152
	ds_read_b128 v[174:177], v139 offset:50176
	ds_read_b128 v[178:181], v139 offset:51200
	ds_read_b128 v[182:185], v139 offset:52224
	ds_read_b128 v[186:189], v139 offset:53248
	ds_read_b128 v[190:193], v139 offset:54272
	ds_read_b128 v[194:197], v139 offset:55296
	ds_read_b128 v[202:205], v139 offset:56320
	global_load_lds_dwordx4 v128, s[100:101]
	s_mov_b32 m0, s57
	s_nop 0
	global_load_lds_dwordx4 v130, s[100:101]
	s_setprio 1
	s_barrier
	s_waitcnt lgkmcnt(0)
	v_mfma_f32_16x16x32_bf16 v[60:63], v[146:149], v[170:173], v[60:63]
	v_mfma_f32_16x16x32_bf16 v[56:59], v[160:163], v[170:173], v[56:59]
	v_mfma_f32_16x16x32_bf16 v[48:51], v[146:149], v[178:181], v[48:51]
	v_mfma_f32_16x16x32_bf16 v[40:43], v[160:163], v[178:181], v[40:43]
	v_mfma_f32_16x16x32_bf16 v[32:35], v[146:149], v[186:189], v[32:35]
	v_mfma_f32_16x16x32_bf16 v[24:27], v[160:163], v[186:189], v[24:27]
	v_mfma_f32_16x16x32_bf16 v[16:19], v[146:149], v[194:197], v[16:19]
	v_mfma_f32_16x16x32_bf16 v[8:11], v[160:163], v[194:197], v[8:11]
	v_mfma_f32_16x16x32_bf16 v[60:63], v[150:153], v[174:177], v[60:63]
	v_mfma_f32_16x16x32_bf16 v[56:59], v[166:169], v[174:177], v[56:59]
	v_mfma_f32_16x16x32_bf16 v[48:51], v[150:153], v[182:185], v[48:51]
	v_mfma_f32_16x16x32_bf16 v[40:43], v[166:169], v[182:185], v[40:43]
	v_mfma_f32_16x16x32_bf16 v[32:35], v[150:153], v[190:193], v[32:35]
	v_mfma_f32_16x16x32_bf16 v[24:27], v[166:169], v[190:193], v[24:27]
	v_mfma_f32_16x16x32_bf16 v[16:19], v[150:153], v[202:205], v[16:19]
	v_mfma_f32_16x16x32_bf16 v[8:11], v[166:169], v[202:205], v[8:11]
	s_setprio 0
	s_barrier
	s_add_u32 s22, s22, 0x80080
	s_addc_u32 s23, s23, 0
	s_mov_b32 m0, s65
	s_nop 0
	global_load_lds_dwordx4 v144, s[22:23]
	s_mov_b32 m0, s66
	s_nop 0
	global_load_lds_dwordx4 v132, s[22:23]
	s_waitcnt vmcnt(6)
	s_setprio 1
	s_barrier
	v_mfma_f32_16x16x32_bf16 v[52:55], v[206:209], v[170:173], v[52:55]
	v_mfma_f32_16x16x32_bf16 v[44:47], v[214:217], v[170:173], v[44:47]
	v_mfma_f32_16x16x32_bf16 v[36:39], v[206:209], v[178:181], v[36:39]
	v_mfma_f32_16x16x32_bf16 v[28:31], v[214:217], v[178:181], v[28:31]
	v_mfma_f32_16x16x32_bf16 v[20:23], v[206:209], v[186:189], v[20:23]
	v_mfma_f32_16x16x32_bf16 v[12:15], v[214:217], v[186:189], v[12:15]
	v_mfma_f32_16x16x32_bf16 v[4:7], v[206:209], v[194:197], v[4:7]
	v_mfma_f32_16x16x32_bf16 v[0:3], v[214:217], v[194:197], v[0:3]
	v_mfma_f32_16x16x32_bf16 v[52:55], v[210:213], v[174:177], v[52:55]
	v_mfma_f32_16x16x32_bf16 v[44:47], v[218:221], v[174:177], v[44:47]
	v_mfma_f32_16x16x32_bf16 v[36:39], v[210:213], v[182:185], v[36:39]
	v_mfma_f32_16x16x32_bf16 v[28:31], v[218:221], v[182:185], v[28:31]
	v_mfma_f32_16x16x32_bf16 v[20:23], v[210:213], v[190:193], v[20:23]
	v_mfma_f32_16x16x32_bf16 v[12:15], v[218:221], v[190:193], v[12:15]
	v_mfma_f32_16x16x32_bf16 v[4:7], v[210:213], v[202:205], v[4:7]
	v_mfma_f32_16x16x32_bf16 v[0:3], v[218:221], v[202:205], v[0:3]
	s_setprio 0
	s_add_i32 s40, s40, 2
	s_add_u32 s6, s6, 0x100
	s_addc_u32 s7, s7, 0
	s_cmp_lt_u32 s40, 30
	s_cbranch_scc1 .Lrot_9
	s_barrier
	s_waitcnt vmcnt(0)
	s_cmpk_gt_u32 s51, 0xff
	s_cbranch_scc1 .LBB0_1123
	s_barrier

; #define PG8_STAGE(bufoff, gbase, voff) do { _Pragma("unroll") for (int _i = 0; _i < 2; ++_i) \
;         __builtin_amdgcn_global_load_lds((const unsigned*)((const char*)(gbase) + (voff)[_i]), (LAS unsigned*)(lds + (bufoff) + ldsw + _i * 8192), 16, 0, 0); } while (0)
; #define PG8_LDA(dst, b, h) do { _Pragma("unroll") for (int m = 0; m < 4; ++m) _Pragma("unroll") for (int k = 0; k < 2; ++k) dst[m][k] = *(const LAS bf16x8*)(lds + PG8_SA(b, h) + aoff + m * 2048 + k * 1024); } while (0)
; #define PG8_LDB(dst, b, h) do { _Pragma("unroll") for (int n = 0; n < 2; ++n) _Pragma("unroll") for (int k = 0; k < 2; ++k) dst[n][k] = *(const LAS bf16x8*)(lds + PG8_SB(b, h) + boff + n * 2048 + k * 1024); } while (0)
; #define PG8_WAIT_V(n) asm volatile("s_waitcnt vmcnt(" #n ")" ::: "memory")
; #define PG8_WAIT_L(n) asm volatile("s_waitcnt lgkmcnt(" #n ")" ::: "memory")
; #define PG8_BAR __builtin_amdgcn_s_barrier()
; #define PG8_SCHED __builtin_amdgcn_sched_barrier(0)
; template <class Epi>
; __device__ __forceinline__ void gemm_phase(LAS unsigned char* lds, const bf16_t* A, int lda, const bf16_t* Bt, int ldb, int M, int N, int K, int asel, const Epi& E, const int fixed_round = -1) {
;     ...
;         const bool has_next = (fixed_round < 0) && S.next(ui + 1, nxt);
;         const char* nA = has_next ? PG8_ABASE(nxt) : cA; const char* nB = has_next ? (const char*)Bt + (size_t)nxt.pn * tstepB : cB;
;         for (int t = 0; t < nt; t += 2) {
;             const bool last = (t == nt - 2);
;             const char* a1 = cA + (size_t)(t + 1) * kstep;
;             const char* a2 = last ? nA : cA + (size_t)(t + 2) * kstep; const char* b2 = last ? nB : cB + (size_t)(t + 2) * kstep;
;             const char* a3 = a2 + kstep; const char* b3 = b2 + kstep;
;             PG8_LDB(B0, 0, 0); PG8_SCHED; PG8_LDA(At, 0, 0); PG8_STAGE(PG8_SA(1, 1), a1 + hstepA, voffA);
;             PG8_WAIT_L(8); PG8_BAR; PG8_WAIT_L(0); PG8_MMA(0, 0, At, B0); PG8_BAR; PG8_SCHED;
;             PG8_LDB(B1, 0, 1); PG8_STAGE(PG8_SB(0, 0), b2, voffB);
;             PG8_BAR; PG8_WAIT_L(0); PG8_MMA(0, 1, At, B1); PG8_BAR;
;             PG8_LDA(At, 0, 1); PG8_STAGE(PG8_SA(0, 0), a2, voffA);
;             PG8_BAR; PG8_WAIT_L(0); PG8_MMA(1, 0, At, B0); PG8_BAR; PG8_SCHED;
;             PG8_STAGE(PG8_SB(0, 1), b2 + hstepB, voffB);
;             PG8_WAIT_V(6); PG8_BAR; PG8_MMA(1, 1, At, B1); PG8_BAR;
.LBB0_1223:
	ds_read_b128 v[152:155], v149
	ds_read_b128 v[156:159], v149 offset:1024
	ds_read_b128 v[160:163], v149 offset:2048
	ds_read_b128 v[164:167], v149 offset:3072
	s_add_i32 m0, s45, 0xc000
	ds_read_b128 v[168:171], v150
	ds_read_b128 v[172:175], v150 offset:1024
	ds_read_b128 v[176:179], v150 offset:2048
	ds_read_b128 v[180:183], v150 offset:3072
	ds_read_b128 v[184:187], v150 offset:4096
	ds_read_b128 v[188:191], v150 offset:5120
	ds_read_b128 v[192:195], v150 offset:6144
	ds_read_b128 v[196:199], v150 offset:7168
	global_load_lds_dwordx4 v136, s[46:47]
	s_add_i32 m0, s45, 0xe000
	s_nop 0
	global_load_lds_dwordx4 v138, s[46:47]
	s_waitcnt lgkmcnt(8)
	s_setprio 1
	s_barrier
	s_waitcnt lgkmcnt(0)
	v_mfma_f32_16x16x32_bf16 v[124:127], v[152:155], v[168:171], v[124:127]
	v_mfma_f32_16x16x32_bf16 v[120:123], v[160:163], v[168:171], v[120:123]
	v_mfma_f32_16x16x32_bf16 v[108:111], v[152:155], v[176:179], v[108:111]
	v_mfma_f32_16x16x32_bf16 v[104:107], v[160:163], v[176:179], v[104:107]
	v_mfma_f32_16x16x32_bf16 v[92:95], v[152:155], v[184:187], v[92:95]
	v_mfma_f32_16x16x32_bf16 v[88:91], v[160:163], v[184:187], v[88:91]
	v_mfma_f32_16x16x32_bf16 v[76:79], v[152:155], v[192:195], v[76:79]
	v_mfma_f32_16x16x32_bf16 v[72:75], v[160:163], v[192:195], v[72:75]
	v_mfma_f32_16x16x32_bf16 v[124:127], v[156:159], v[172:175], v[124:127]
	v_mfma_f32_16x16x32_bf16 v[120:123], v[164:167], v[172:175], v[120:123]
	v_mfma_f32_16x16x32_bf16 v[108:111], v[156:159], v[180:183], v[108:111]
	v_mfma_f32_16x16x32_bf16 v[104:107], v[164:167], v[180:183], v[104:107]
	v_mfma_f32_16x16x32_bf16 v[92:95], v[156:159], v[188:191], v[92:95]
	v_mfma_f32_16x16x32_bf16 v[88:91], v[164:167], v[188:191], v[88:91]
	v_mfma_f32_16x16x32_bf16 v[76:79], v[156:159], v[196:199], v[76:79]
	v_mfma_f32_16x16x32_bf16 v[72:75], v[164:167], v[196:199], v[72:75]
	s_setprio 0
	s_barrier
	s_add_u32 s48, s46, 0xfff80080
	s_addc_u32 s49, s47, -1
	s_cmp_eq_u32 s70, 28
	s_cselect_b32 s51, s29, s49
	s_cselect_b32 s50, s66, s48
	s_cselect_b32 s49, s25, s69
	s_cselect_b32 s48, s67, s68
	s_add_i32 s71, s81, s54
	s_add_u32 s98, s48, s2
	s_addc_u32 s99, s49, s3
	s_mov_b32 m0, s71
	ds_read_b128 v[202:205], v151
	ds_read_b128 v[206:209], v151 offset:1024
	ds_read_b128 v[210:213], v151 offset:2048
	ds_read_b128 v[214:217], v151 offset:3072
	global_load_lds_dwordx4 v130, s[48:49]
	s_add_i32 m0, s71, 0x2000
	s_nop 0
	global_load_lds_dwordx4 v134, s[48:49]
	s_setprio 1
	s_barrier
	s_waitcnt lgkmcnt(0)
	v_mfma_f32_16x16x32_bf16 v[116:119], v[202:205], v[168:171], v[116:119]
	v_mfma_f32_16x16x32_bf16 v[112:115], v[210:213], v[168:171], v[112:115]
	v_mfma_f32_16x16x32_bf16 v[100:103], v[202:205], v[176:179], v[100:103]
	v_mfma_f32_16x16x32_bf16 v[96:99], v[210:213], v[176:179], v[96:99]
	v_mfma_f32_16x16x32_bf16 v[84:87], v[202:205], v[184:187], v[84:87]
	v_mfma_f32_16x16x32_bf16 v[80:83], v[210:213], v[184:187], v[80:83]
	v_mfma_f32_16x16x32_bf16 v[68:71], v[202:205], v[192:195], v[68:71]
	v_mfma_f32_16x16x32_bf16 v[64:67], v[210:213], v[192:195], v[64:67]
	v_mfma_f32_16x16x32_bf16 v[116:119], v[206:209], v[172:175], v[116:119]
	v_mfma_f32_16x16x32_bf16 v[112:115], v[214:217], v[172:175], v[112:115]
	v_mfma_f32_16x16x32_bf16 v[100:103], v[206:209], v[180:183], v[100:103]
	v_mfma_f32_16x16x32_bf16 v[96:99], v[214:217], v[180:183], v[96:99]
	v_mfma_f32_16x16x32_bf16 v[84:87], v[206:209], v[188:191], v[84:87]
	v_mfma_f32_16x16x32_bf16 v[80:83], v[214:217], v[188:191], v[80:83]
	v_mfma_f32_16x16x32_bf16 v[68:71], v[206:209], v[196:199], v[68:71]
	v_mfma_f32_16x16x32_bf16 v[64:67], v[214:217], v[196:199], v[64:67]
	s_setprio 0
	s_mov_b32 m0, s45
	s_add_u32 s100, s50, s2
	s_addc_u32 s101, s51, s3
	s_barrier
	ds_read_b128 v[168:171], v150 offset:16384
	ds_read_b128 v[172:175], v150 offset:17408
	ds_read_b128 v[176:179], v150 offset:18432
	ds_read_b128 v[180:183], v150 offset:19456
	ds_read_b128 v[184:187], v150 offset:20480
	ds_read_b128 v[188:191], v150 offset:21504
	ds_read_b128 v[192:195], v150 offset:22528
	ds_read_b128 v[196:199], v150 offset:23552
	global_load_lds_dwordx4 v128, s[50:51]
	s_mov_b32 m0, s55
	s_nop 0
	global_load_lds_dwordx4 v132, s[50:51]
	s_setprio 1
	s_barrier
	s_waitcnt lgkmcnt(0)
	v_mfma_f32_16x16x32_bf16 v[60:63], v[152:155], v[168:171], v[60:63]
	v_mfma_f32_16x16x32_bf16 v[56:59], v[160:163], v[168:171], v[56:59]
	v_mfma_f32_16x16x32_bf16 v[44:47], v[152:155], v[176:179], v[44:47]
	v_mfma_f32_16x16x32_bf16 v[40:43], v[160:163], v[176:179], v[40:43]
	v_mfma_f32_16x16x32_bf16 v[28:31], v[152:155], v[184:187], v[28:31]
	v_mfma_f32_16x16x32_bf16 v[24:27], v[160:163], v[184:187], v[24:27]
	v_mfma_f32_16x16x32_bf16 v[12:15], v[152:155], v[192:195], v[12:15]
	v_mfma_f32_16x16x32_bf16 v[8:11], v[160:163], v[192:195], v[8:11]
	v_mfma_f32_16x16x32_bf16 v[60:63], v[156:159], v[172:175], v[60:63]
	v_mfma_f32_16x16x32_bf16 v[56:59], v[164:167], v[172:175], v[56:59]
	v_mfma_f32_16x16x32_bf16 v[44:47], v[156:159], v[180:183], v[44:47]
	v_mfma_f32_16x16x32_bf16 v[40:43], v[164:167], v[180:183], v[40:43]
	v_mfma_f32_16x16x32_bf16 v[28:31], v[156:159], v[188:191], v[28:31]
	v_mfma_f32_16x16x32_bf16 v[24:27], v[164:167], v[188:191], v[24:27]
	v_mfma_f32_16x16x32_bf16 v[12:15], v[156:159], v[196:199], v[12:15]
	v_mfma_f32_16x16x32_bf16 v[8:11], v[164:167], v[196:199], v[8:11]
	s_setprio 0
	s_barrier
	s_add_u32 s72, s48, 0x80000
	s_addc_u32 s73, s49, 0
	s_add_i32 s71, s82, s54
	s_mov_b32 m0, s71
	s_nop 0
	global_load_lds_dwordx4 v130, s[72:73]
	s_add_i32 m0, s71, 0x2000
	s_nop 0
	global_load_lds_dwordx4 v134, s[72:73]
	s_waitcnt vmcnt(6)
	s_setprio 1
	s_barrier
; #define PG8_STAGE(bufoff, gbase, voff) do { _Pragma("unroll") for (int _i = 0; _i < 2; ++_i) \
;         __builtin_amdgcn_global_load_lds((const unsigned*)((const char*)(gbase) + (voff)[_i]), (LAS unsigned*)(lds + (bufoff) + ldsw + _i * 8192), 16, 0, 0); } while (0)
; #define PG8_LDA(dst, b, h) do { _Pragma("unroll") for (int m = 0; m < 4; ++m) _Pragma("unroll") for (int k = 0; k < 2; ++k) dst[m][k] = *(const LAS bf16x8*)(lds + PG8_SA(b, h) + aoff + m * 2048 + k * 1024); } while (0)
; #define PG8_LDB(dst, b, h) do { _Pragma("unroll") for (int n = 0; n < 2; ++n) _Pragma("unroll") for (int k = 0; k < 2; ++k) dst[n][k] = *(const LAS bf16x8*)(lds + PG8_SB(b, h) + boff + n * 2048 + k * 1024); } while (0)
; #define PG8_WAIT_V(n) asm volatile("s_waitcnt vmcnt(" #n ")" ::: "memory")
; #define PG8_WAIT_L(n) asm volatile("s_waitcnt lgkmcnt(" #n ")" ::: "memory")
; #define PG8_BAR __builtin_amdgcn_s_barrier()
; #define PG8_SCHED __builtin_amdgcn_sched_barrier(0)
; template <class Epi>
; __device__ __forceinline__ void gemm_phase(LAS unsigned char* lds, const bf16_t* A, int lda, const bf16_t* Bt, int ldb, int M, int N, int K, int asel, const Epi& E, const int fixed_round = -1) {
;     ...
;             PG8_WAIT_V(6); PG8_BAR; PG8_MMA(1, 1, At, B1); PG8_BAR;
;             PG8_LDB(B0, 1, 0); PG8_SCHED; PG8_LDA(At, 1, 0); PG8_STAGE(PG8_SA(0, 1), a2 + hstepA, voffA);
;             PG8_WAIT_L(8); PG8_BAR; PG8_WAIT_L(0); PG8_MMA(0, 0, At, B0); PG8_BAR; PG8_SCHED;
;             PG8_LDB(B1, 1, 1); PG8_STAGE(PG8_SB(1, 0), b3, voffB);
;             PG8_BAR; PG8_WAIT_L(0); PG8_MMA(0, 1, At, B1); PG8_BAR;
;             PG8_LDA(At, 1, 1); PG8_STAGE(PG8_SA(1, 0), a3, voffA);
;             PG8_BAR; PG8_WAIT_L(0); PG8_MMA(1, 0, At, B0); PG8_BAR; PG8_SCHED;
	v_mfma_f32_16x16x32_bf16 v[52:55], v[202:205], v[168:171], v[52:55]
	v_mfma_f32_16x16x32_bf16 v[48:51], v[210:213], v[168:171], v[48:51]
	v_mfma_f32_16x16x32_bf16 v[36:39], v[202:205], v[176:179], v[36:39]
	v_mfma_f32_16x16x32_bf16 v[32:35], v[210:213], v[176:179], v[32:35]
	v_mfma_f32_16x16x32_bf16 v[20:23], v[202:205], v[184:187], v[20:23]
	v_mfma_f32_16x16x32_bf16 v[16:19], v[210:213], v[184:187], v[16:19]
	v_mfma_f32_16x16x32_bf16 v[4:7], v[202:205], v[192:195], v[4:7]
	v_mfma_f32_16x16x32_bf16 v[0:3], v[210:213], v[192:195], v[0:3]
	v_mfma_f32_16x16x32_bf16 v[52:55], v[206:209], v[172:175], v[52:55]
	v_mfma_f32_16x16x32_bf16 v[48:51], v[214:217], v[172:175], v[48:51]
	v_mfma_f32_16x16x32_bf16 v[36:39], v[206:209], v[180:183], v[36:39]
	v_mfma_f32_16x16x32_bf16 v[32:35], v[214:217], v[180:183], v[32:35]
	v_mfma_f32_16x16x32_bf16 v[20:23], v[206:209], v[188:191], v[20:23]
	v_mfma_f32_16x16x32_bf16 v[16:19], v[214:217], v[188:191], v[16:19]
	v_mfma_f32_16x16x32_bf16 v[4:7], v[206:209], v[196:199], v[4:7]
	v_mfma_f32_16x16x32_bf16 v[0:3], v[214:217], v[196:199], v[0:3]
	s_setprio 0
	v_add_u32_e32 v164, s83, v147
	s_barrier
	ds_read_b128 v[152:155], v164
	ds_read_b128 v[156:159], v164 offset:1024
	ds_read_b128 v[160:163], v164 offset:2048
	ds_read_b128 v[164:167], v164 offset:3072
	s_add_u32 s50, s50, 0x80000
	s_addc_u32 s51, s51, 0
	s_mov_b32 m0, s56
	ds_read_b128 v[168:171], v150 offset:32768
	ds_read_b128 v[172:175], v150 offset:33792
	ds_read_b128 v[176:179], v150 offset:34816
	ds_read_b128 v[180:183], v150 offset:35840
	ds_read_b128 v[184:187], v150 offset:36864
	ds_read_b128 v[188:191], v150 offset:37888
	ds_read_b128 v[192:195], v150 offset:38912
	ds_read_b128 v[196:199], v150 offset:39936
	global_load_lds_dwordx4 v128, s[50:51]
	s_mov_b32 m0, s57
	s_nop 0
	global_load_lds_dwordx4 v132, s[50:51]
	s_waitcnt lgkmcnt(8)
	s_setprio 1
	s_barrier
	s_waitcnt lgkmcnt(0)
	v_mfma_f32_16x16x32_bf16 v[124:127], v[152:155], v[168:171], v[124:127]
	v_mfma_f32_16x16x32_bf16 v[120:123], v[160:163], v[168:171], v[120:123]
	v_mfma_f32_16x16x32_bf16 v[108:111], v[152:155], v[176:179], v[108:111]
	v_mfma_f32_16x16x32_bf16 v[104:107], v[160:163], v[176:179], v[104:107]
	v_mfma_f32_16x16x32_bf16 v[92:95], v[152:155], v[184:187], v[92:95]
	v_mfma_f32_16x16x32_bf16 v[88:91], v[160:163], v[184:187], v[88:91]
	v_mfma_f32_16x16x32_bf16 v[76:79], v[152:155], v[192:195], v[76:79]
	v_mfma_f32_16x16x32_bf16 v[72:75], v[160:163], v[192:195], v[72:75]
	v_mfma_f32_16x16x32_bf16 v[124:127], v[156:159], v[172:175], v[124:127]
	v_mfma_f32_16x16x32_bf16 v[120:123], v[164:167], v[172:175], v[120:123]
	v_mfma_f32_16x16x32_bf16 v[108:111], v[156:159], v[180:183], v[108:111]
	v_mfma_f32_16x16x32_bf16 v[104:107], v[164:167], v[180:183], v[104:107]
	v_mfma_f32_16x16x32_bf16 v[92:95], v[156:159], v[188:191], v[92:95]
	v_mfma_f32_16x16x32_bf16 v[88:91], v[164:167], v[188:191], v[88:91]
	v_mfma_f32_16x16x32_bf16 v[76:79], v[156:159], v[196:199], v[76:79]
	v_mfma_f32_16x16x32_bf16 v[72:75], v[164:167], v[196:199], v[72:75]
	s_setprio 0
	s_barrier
	s_add_i32 s50, s83, s54
	v_add_u32_e32 v214, s84, v147
	s_mov_b32 m0, s50
	ds_read_b128 v[202:205], v214
	ds_read_b128 v[206:209], v214 offset:1024
	ds_read_b128 v[210:213], v214 offset:2048
	ds_read_b128 v[214:217], v214 offset:3072
	global_load_lds_dwordx4 v130, s[98:99]
	s_add_i32 m0, s50, 0x2000
	s_nop 0
	global_load_lds_dwordx4 v134, s[98:99]
	s_setprio 1
	s_barrier
	s_waitcnt lgkmcnt(0)
	v_mfma_f32_16x16x32_bf16 v[116:119], v[202:205], v[168:171], v[116:119]
	v_mfma_f32_16x16x32_bf16 v[112:115], v[210:213], v[168:171], v[112:115]
	v_mfma_f32_16x16x32_bf16 v[100:103], v[202:205], v[176:179], v[100:103]
	v_mfma_f32_16x16x32_bf16 v[96:99], v[210:213], v[176:179], v[96:99]
	v_mfma_f32_16x16x32_bf16 v[84:87], v[202:205], v[184:187], v[84:87]
	v_mfma_f32_16x16x32_bf16 v[80:83], v[210:213], v[184:187], v[80:83]
	v_mfma_f32_16x16x32_bf16 v[68:71], v[202:205], v[192:195], v[68:71]
	v_mfma_f32_16x16x32_bf16 v[64:67], v[210:213], v[192:195], v[64:67]
	v_mfma_f32_16x16x32_bf16 v[116:119], v[206:209], v[172:175], v[116:119]
	v_mfma_f32_16x16x32_bf16 v[112:115], v[214:217], v[172:175], v[112:115]
	v_mfma_f32_16x16x32_bf16 v[100:103], v[206:209], v[180:183], v[100:103]
	v_mfma_f32_16x16x32_bf16 v[96:99], v[214:217], v[180:183], v[96:99]
	v_mfma_f32_16x16x32_bf16 v[84:87], v[206:209], v[188:191], v[84:87]
	v_mfma_f32_16x16x32_bf16 v[80:83], v[214:217], v[188:191], v[80:83]
	v_mfma_f32_16x16x32_bf16 v[68:71], v[206:209], v[196:199], v[68:71]
	v_mfma_f32_16x16x32_bf16 v[64:67], v[214:217], v[196:199], v[64:67]
	s_setprio 0
	s_mov_b32 m0, s59
	s_barrier
	ds_read_b128 v[168:171], v150 offset:49152
	ds_read_b128 v[172:175], v150 offset:50176
	ds_read_b128 v[176:179], v150 offset:51200
	ds_read_b128 v[180:183], v150 offset:52224
	ds_read_b128 v[184:187], v150 offset:53248
	ds_read_b128 v[188:191], v150 offset:54272
	ds_read_b128 v[192:195], v150 offset:55296
	ds_read_b128 v[196:199], v150 offset:56320
	global_load_lds_dwordx4 v128, s[100:101]
	s_mov_b32 m0, s60
	s_nop 0
	global_load_lds_dwordx4 v132, s[100:101]
	s_setprio 1
	s_barrier
; #define PG8_WAIT_V(n) asm volatile("s_waitcnt vmcnt(" #n ")" ::: "memory")
; #define PG8_BAR __builtin_amdgcn_s_barrier()
; template <class Epi>
; __device__ __forceinline__ void gemm_phase(LAS unsigned char* lds, const bf16_t* A, int lda, const bf16_t* Bt, int ldb, int M, int N, int K, int asel, const Epi& E, const int fixed_round = -1) {
;     ...
;             PG8_WAIT_L(8); PG8_BAR; PG8_WAIT_L(0); PG8_MMA(0, 0, At, B0); PG8_BAR; PG8_SCHED;
;             PG8_LDB(B1, 0, 1); PG8_STAGE(PG8_SB(0, 0), b2, voffB);
;             PG8_BAR; PG8_WAIT_L(0); PG8_MMA(0, 1, At, B1); PG8_BAR;
;             PG8_LDA(At, 0, 1); PG8_STAGE(PG8_SA(0, 0), a2, voffA);
;             PG8_BAR; PG8_WAIT_L(0); PG8_MMA(1, 0, At, B0); PG8_BAR; PG8_SCHED;
;             PG8_STAGE(PG8_SB(0, 1), b2 + hstepB, voffB);
;             PG8_WAIT_V(6); PG8_BAR; PG8_MMA(1, 1, At, B1); PG8_BAR;
;             PG8_LDB(B0, 1, 0); PG8_SCHED; PG8_LDA(At, 1, 0); PG8_STAGE(PG8_SA(0, 1), a2 + hstepA, voffA);
;             PG8_WAIT_L(8); PG8_BAR; PG8_WAIT_L(0); PG8_MMA(0, 0, At, B0); PG8_BAR; PG8_SCHED;
;             PG8_LDB(B1, 1, 1); PG8_STAGE(PG8_SB(1, 0), b3, voffB);
;             PG8_BAR; PG8_WAIT_L(0); PG8_MMA(0, 1, At, B1); PG8_BAR;
;             PG8_LDA(At, 1, 1); PG8_STAGE(PG8_SA(1, 0), a3, voffA);
;             PG8_BAR; PG8_WAIT_L(0); PG8_MMA(1, 0, At, B0); PG8_BAR; PG8_SCHED;
;             PG8_STAGE(PG8_SB(1, 1), b3 + hstepB, voffB);
;             PG8_WAIT_V(6); PG8_BAR; PG8_MMA(1, 1, At, B1); PG8_BAR;
;     __device__ __forceinline__ void operator()(const AccT& acc, const Unit& u, int wr, int wc, int fr, int fq) const {
;         const int row0 = u.pm * BM + wr * 64 + fr, col0 = u.pn * BM + wc * 32 + 8 * fq;
; #pragma unroll
;         for (int ai = 0; ai < 2; ++ai)
; #pragma unroll
;             for (int m = 0; m < 4; ++m) { bf16_t* rowp = O + (size_t)(row0 + ai * HALF + m * 16) * DFF + col0;
; #pragma unroll
;                 for (int bj = 0; bj < 2; ++bj) { f32x4 v0 = acc[ai][bj][m][0], v1 = acc[ai][bj][m][1];
; #pragma unroll
;                     for (int j = 0; j < 4; ++j) { float a = fmaxf(v0[j], 0.f), b = fmaxf(v1[j], 0.f); v0[j] = a * a; v1[j] = b * b; }
;                     u32x4 w; w.x = cvt_pk_bf16(v0[0], v0[1]); w.y = cvt_pk_bf16(v0[2], v0[3]); w.z = cvt_pk_bf16(v1[0], v1[1]); w.w = cvt_pk_bf16(v1[2], v1[3]);
;                     *(u32x4*)(rowp + bj * HALF) = w; } }
	s_waitcnt lgkmcnt(0)
	v_mfma_f32_16x16x32_bf16 v[60:63], v[152:155], v[168:171], v[60:63]
	v_mfma_f32_16x16x32_bf16 v[56:59], v[160:163], v[168:171], v[56:59]
	v_mfma_f32_16x16x32_bf16 v[44:47], v[152:155], v[176:179], v[44:47]
	v_mfma_f32_16x16x32_bf16 v[40:43], v[160:163], v[176:179], v[40:43]
	v_mfma_f32_16x16x32_bf16 v[28:31], v[152:155], v[184:187], v[28:31]
	v_mfma_f32_16x16x32_bf16 v[24:27], v[160:163], v[184:187], v[24:27]
	v_mfma_f32_16x16x32_bf16 v[12:15], v[152:155], v[192:195], v[12:15]
	v_mfma_f32_16x16x32_bf16 v[8:11], v[160:163], v[192:195], v[8:11]
	v_mfma_f32_16x16x32_bf16 v[60:63], v[156:159], v[172:175], v[60:63]
	v_mfma_f32_16x16x32_bf16 v[56:59], v[164:167], v[172:175], v[56:59]
	v_mfma_f32_16x16x32_bf16 v[44:47], v[156:159], v[180:183], v[44:47]
	v_mfma_f32_16x16x32_bf16 v[40:43], v[164:167], v[180:183], v[40:43]
	v_mfma_f32_16x16x32_bf16 v[28:31], v[156:159], v[188:191], v[28:31]
	v_mfma_f32_16x16x32_bf16 v[24:27], v[164:167], v[188:191], v[24:27]
	v_mfma_f32_16x16x32_bf16 v[12:15], v[156:159], v[196:199], v[12:15]
	v_mfma_f32_16x16x32_bf16 v[8:11], v[164:167], v[196:199], v[8:11]
	s_setprio 0
	s_barrier
	s_add_u32 s48, s48, 0x80080
	s_addc_u32 s49, s49, 0
	s_add_i32 s50, s84, s54
	s_mov_b32 m0, s50
	s_nop 0
	global_load_lds_dwordx4 v130, s[48:49]
	s_add_i32 m0, s50, 0x2000
	s_nop 0
	global_load_lds_dwordx4 v134, s[48:49]
	s_waitcnt vmcnt(6)
	s_setprio 1
	s_barrier
	v_mfma_f32_16x16x32_bf16 v[52:55], v[202:205], v[168:171], v[52:55]
	v_mfma_f32_16x16x32_bf16 v[48:51], v[210:213], v[168:171], v[48:51]
	v_mfma_f32_16x16x32_bf16 v[36:39], v[202:205], v[176:179], v[36:39]
	v_mfma_f32_16x16x32_bf16 v[32:35], v[210:213], v[176:179], v[32:35]
	v_mfma_f32_16x16x32_bf16 v[20:23], v[202:205], v[184:187], v[20:23]
	v_mfma_f32_16x16x32_bf16 v[16:19], v[210:213], v[184:187], v[16:19]
	v_mfma_f32_16x16x32_bf16 v[4:7], v[202:205], v[192:195], v[4:7]
	v_mfma_f32_16x16x32_bf16 v[0:3], v[210:213], v[192:195], v[0:3]
	v_mfma_f32_16x16x32_bf16 v[52:55], v[206:209], v[172:175], v[52:55]
	v_mfma_f32_16x16x32_bf16 v[48:51], v[214:217], v[172:175], v[48:51]
	v_mfma_f32_16x16x32_bf16 v[36:39], v[206:209], v[180:183], v[36:39]
	v_mfma_f32_16x16x32_bf16 v[32:35], v[214:217], v[180:183], v[32:35]
	v_mfma_f32_16x16x32_bf16 v[20:23], v[206:209], v[188:191], v[20:23]
	v_mfma_f32_16x16x32_bf16 v[16:19], v[214:217], v[188:191], v[16:19]
	v_mfma_f32_16x16x32_bf16 v[4:7], v[206:209], v[196:199], v[4:7]
	v_mfma_f32_16x16x32_bf16 v[0:3], v[214:217], v[196:199], v[0:3]
	s_setprio 0
	s_add_i32 s70, s70, 2
	s_add_u32 s46, s46, 0x100
	s_addc_u32 s47, s47, 0
	s_add_u32 s68, s68, 0x100
	s_addc_u32 s69, s69, 0
	s_cmp_gt_u32 s70, 29
	s_cbranch_scc0 .Lrot_10
	s_barrier
	v_lshl_add_u32 v152, s44, 8, v146
	v_lshl_or_b32 v144, s65, 8, v148
	v_ashrrev_i32_e32 v153, 31, v152
	v_readlane_b32 s46, v254, 60
	v_ashrrev_i32_e32 v145, 31, v144
	v_lshlrev_b64 v[154:155], 14, v[152:153]
	v_readlane_b32 s47, v254, 61
	v_lshl_add_u64 v[154:155], s[46:47], 0, v[154:155]
	v_lshlrev_b64 v[156:157], 1, v[144:145]
	v_max_f32_e32 v120, 0, v120
	v_max_f32_e32 v121, 0, v121
	v_lshl_add_u64 v[144:145], v[154:155], 0, v[156:157]
	v_pk_mul_f32 v[154:155], v[120:121], v[120:121]
	v_max_f32_e32 v121, v122, v122
	v_max_f32_e32 v120, v126, v126
	v_max_f32_e32 v122, 0, v121
	v_max_f32_e32 v121, v127, v127
	v_max_f32_e32 v124, 0, v124
	v_max_f32_e32 v125, 0, v125
	v_max_f32_e32 v120, 0, v120
	v_max_f32_e32 v121, 0, v121
	v_max_f32_e32 v123, 0, v123
	v_pk_mul_f32 v[124:125], v[124:125], v[124:125]
	v_pk_mul_f32 v[126:127], v[120:121], v[120:121]
	v_pk_mul_f32 v[158:159], v[122:123], v[122:123]
	v_cvt_pk_bf16_f32 v120, v124, v125
	v_cvt_pk_bf16_f32 v121, v126, v127
	v_cvt_pk_bf16_f32 v122, v154, v155
	v_cvt_pk_bf16_f32 v123, v158, v159
	v_max_f32_e32 v112, 0, v112
	v_max_f32_e32 v113, 0, v113
	global_store_dwordx4 v[144:145], v[120:123], off
	s_nop 1
	v_pk_mul_f32 v[120:121], v[112:113], v[112:113]
	v_max_f32_e32 v113, v114, v114
	v_max_f32_e32 v112, v118, v118
	v_max_f32_e32 v114, 0, v113
	v_max_f32_e32 v113, v119, v119
	v_max_f32_e32 v116, 0, v116
	v_max_f32_e32 v117, 0, v117
	v_max_f32_e32 v112, 0, v112
	v_max_f32_e32 v113, 0, v113
	v_max_f32_e32 v115, 0, v115
	v_pk_mul_f32 v[116:117], v[116:117], v[116:117]
	v_pk_mul_f32 v[118:119], v[112:113], v[112:113]
	v_pk_mul_f32 v[122:123], v[114:115], v[114:115]
	v_cvt_pk_bf16_f32 v112, v116, v117
	v_cvt_pk_bf16_f32 v113, v118, v119
	v_cvt_pk_bf16_f32 v114, v120, v121
	v_cvt_pk_bf16_f32 v115, v122, v123
	v_max_f32_e32 v104, 0, v104
	v_max_f32_e32 v105, 0, v105
	global_store_dwordx4 v[144:145], v[112:115], off offset:256
	s_nop 1
	v_or_b32_e32 v112, 16, v152
	v_pk_mul_f32 v[114:115], v[104:105], v[104:105]
	v_max_f32_e32 v105, v106, v106
	v_ashrrev_i32_e32 v113, 31, v112
	v_max_f32_e32 v104, v110, v110
	v_max_f32_e32 v106, 0, v105
	v_max_f32_e32 v105, v111, v111
	v_lshlrev_b64 v[112:113], 14, v[112:113]
	v_max_f32_e32 v108, 0, v108
	v_max_f32_e32 v109, 0, v109
	v_max_f32_e32 v104, 0, v104
	v_max_f32_e32 v105, 0, v105
	v_max_f32_e32 v107, 0, v107
	v_lshl_add_u64 v[112:113], s[46:47], 0, v[112:113]
	v_pk_mul_f32 v[108:109], v[108:109], v[108:109]
	v_pk_mul_f32 v[110:111], v[104:105], v[104:105]
	v_pk_mul_f32 v[116:117], v[106:107], v[106:107]
	v_lshl_add_u64 v[112:113], v[112:113], 0, v[156:157]
	v_cvt_pk_bf16_f32 v104, v108, v109
	v_cvt_pk_bf16_f32 v105, v110, v111
	v_cvt_pk_bf16_f32 v106, v114, v115
	v_cvt_pk_bf16_f32 v107, v116, v117
	v_max_f32_e32 v96, 0, v96
	v_max_f32_e32 v97, 0, v97
	global_store_dwordx4 v[112:113], v[104:107], off
	s_nop 1
	v_pk_mul_f32 v[104:105], v[96:97], v[96:97]
	v_max_f32_e32 v97, v98, v98
	v_max_f32_e32 v96, v102, v102
; __device__ __forceinline__ unsigned cvt_pk_bf16(float lo, float hi) { const bf16x2_t r = __builtin_convertvector((f32x2){lo, hi}, bf16x2_t); return __builtin_bit_cast(unsigned, r); }
;     __device__ __forceinline__ void operator()(const AccT& acc, const Unit& u, int wr, int wc, int fr, int fq) const {
;         const int row0 = u.pm * BM + wr * 64 + fr, col0 = u.pn * BM + wc * 32 + 8 * fq;
; #pragma unroll
;         for (int ai = 0; ai < 2; ++ai)
; #pragma unroll
;             for (int m = 0; m < 4; ++m) { bf16_t* rowp = O + (size_t)(row0 + ai * HALF + m * 16) * DFF + col0;
; #pragma unroll
;                 for (int bj = 0; bj < 2; ++bj) { f32x4 v0 = acc[ai][bj][m][0], v1 = acc[ai][bj][m][1];
; #pragma unroll
;                     for (int j = 0; j < 4; ++j) { float a = fmaxf(v0[j], 0.f), b = fmaxf(v1[j], 0.f); v0[j] = a * a; v1[j] = b * b; }
;                     u32x4 w; w.x = cvt_pk_bf16(v0[0], v0[1]); w.y = cvt_pk_bf16(v0[2], v0[3]); w.z = cvt_pk_bf16(v1[0], v1[1]); w.w = cvt_pk_bf16(v1[2], v1[3]);
;                     *(u32x4*)(rowp + bj * HALF) = w; } }
	v_max_f32_e32 v98, 0, v97
	v_max_f32_e32 v97, v103, v103
	v_max_f32_e32 v100, 0, v100
	v_max_f32_e32 v101, 0, v101
	v_max_f32_e32 v96, 0, v96
	v_max_f32_e32 v97, 0, v97
	v_max_f32_e32 v99, 0, v99
	v_pk_mul_f32 v[100:101], v[100:101], v[100:101]
	v_pk_mul_f32 v[102:103], v[96:97], v[96:97]
	v_pk_mul_f32 v[106:107], v[98:99], v[98:99]
	v_cvt_pk_bf16_f32 v96, v100, v101
	v_cvt_pk_bf16_f32 v97, v102, v103
	v_cvt_pk_bf16_f32 v98, v104, v105
	v_cvt_pk_bf16_f32 v99, v106, v107
	v_max_f32_e32 v88, 0, v88
	v_max_f32_e32 v89, 0, v89
	global_store_dwordx4 v[112:113], v[96:99], off offset:256
	s_nop 1
	v_or_b32_e32 v96, 32, v152
	v_pk_mul_f32 v[98:99], v[88:89], v[88:89]
	v_max_f32_e32 v89, v90, v90
	v_ashrrev_i32_e32 v97, 31, v96
	v_max_f32_e32 v88, v94, v94
	v_max_f32_e32 v90, 0, v89
	v_max_f32_e32 v89, v95, v95
	v_lshlrev_b64 v[96:97], 14, v[96:97]
	v_max_f32_e32 v92, 0, v92
	v_max_f32_e32 v93, 0, v93
	v_max_f32_e32 v88, 0, v88
	v_max_f32_e32 v89, 0, v89
	v_max_f32_e32 v91, 0, v91
	v_lshl_add_u64 v[96:97], s[46:47], 0, v[96:97]
	v_pk_mul_f32 v[92:93], v[92:93], v[92:93]
	v_pk_mul_f32 v[94:95], v[88:89], v[88:89]
	v_pk_mul_f32 v[100:101], v[90:91], v[90:91]
	v_lshl_add_u64 v[96:97], v[96:97], 0, v[156:157]
	v_cvt_pk_bf16_f32 v88, v92, v93
	v_cvt_pk_bf16_f32 v89, v94, v95
	v_cvt_pk_bf16_f32 v90, v98, v99
	v_cvt_pk_bf16_f32 v91, v100, v101
	v_max_f32_e32 v80, 0, v80
	v_max_f32_e32 v81, 0, v81
	global_store_dwordx4 v[96:97], v[88:91], off
	s_nop 1
	v_pk_mul_f32 v[88:89], v[80:81], v[80:81]
	v_max_f32_e32 v81, v82, v82
	v_max_f32_e32 v80, v86, v86
	v_max_f32_e32 v82, 0, v81
	v_max_f32_e32 v81, v87, v87
	v_max_f32_e32 v84, 0, v84
	v_max_f32_e32 v85, 0, v85
	v_max_f32_e32 v80, 0, v80
	v_max_f32_e32 v81, 0, v81
	v_max_f32_e32 v83, 0, v83
	v_pk_mul_f32 v[84:85], v[84:85], v[84:85]
	v_pk_mul_f32 v[86:87], v[80:81], v[80:81]
	v_pk_mul_f32 v[90:91], v[82:83], v[82:83]
	v_cvt_pk_bf16_f32 v80, v84, v85
	v_cvt_pk_bf16_f32 v81, v86, v87
	v_cvt_pk_bf16_f32 v82, v88, v89
	v_cvt_pk_bf16_f32 v83, v90, v91
	v_max_f32_e32 v72, 0, v72
	v_max_f32_e32 v73, 0, v73
	global_store_dwordx4 v[96:97], v[80:83], off offset:256
	s_nop 1
	v_or_b32_e32 v80, 48, v152
	v_pk_mul_f32 v[82:83], v[72:73], v[72:73]
	v_max_f32_e32 v73, v74, v74
	v_ashrrev_i32_e32 v81, 31, v80
	v_max_f32_e32 v72, v78, v78
	v_max_f32_e32 v74, 0, v73
	v_max_f32_e32 v73, v79, v79
	v_lshlrev_b64 v[80:81], 14, v[80:81]
	v_max_f32_e32 v76, 0, v76
	v_max_f32_e32 v77, 0, v77
	v_max_f32_e32 v72, 0, v72
	v_max_f32_e32 v73, 0, v73
	v_max_f32_e32 v75, 0, v75
	v_lshl_add_u64 v[80:81], s[46:47], 0, v[80:81]
	v_pk_mul_f32 v[76:77], v[76:77], v[76:77]
	v_pk_mul_f32 v[78:79], v[72:73], v[72:73]
	v_pk_mul_f32 v[84:85], v[74:75], v[74:75]
	v_lshl_add_u64 v[80:81], v[80:81], 0, v[156:157]
	v_cvt_pk_bf16_f32 v72, v76, v77
	v_cvt_pk_bf16_f32 v73, v78, v79
	v_cvt_pk_bf16_f32 v74, v82, v83
	v_cvt_pk_bf16_f32 v75, v84, v85
	v_max_f32_e32 v64, 0, v64
	v_max_f32_e32 v65, 0, v65
	global_store_dwordx4 v[80:81], v[72:75], off
	s_nop 1
	v_pk_mul_f32 v[72:73], v[64:65], v[64:65]
	v_max_f32_e32 v65, v66, v66
	v_max_f32_e32 v64, v70, v70
	v_max_f32_e32 v66, 0, v65
	v_max_f32_e32 v65, v71, v71
	v_max_f32_e32 v68, 0, v68
	v_max_f32_e32 v69, 0, v69
	v_max_f32_e32 v64, 0, v64
	v_max_f32_e32 v65, 0, v65
	v_max_f32_e32 v67, 0, v67
	v_pk_mul_f32 v[68:69], v[68:69], v[68:69]
	v_pk_mul_f32 v[70:71], v[64:65], v[64:65]
	v_pk_mul_f32 v[74:75], v[66:67], v[66:67]
	v_cvt_pk_bf16_f32 v64, v68, v69
	v_cvt_pk_bf16_f32 v65, v70, v71
	v_cvt_pk_bf16_f32 v66, v72, v73
	v_cvt_pk_bf16_f32 v67, v74, v75
	v_max_f32_e32 v56, 0, v56
	v_max_f32_e32 v57, 0, v57
	global_store_dwordx4 v[80:81], v[64:67], off offset:256
	s_nop 1
	v_pk_mul_f32 v[66:67], v[56:57], v[56:57]
	v_max_f32_e32 v57, v58, v58
	v_max_f32_e32 v60, 0, v60
	v_max_f32_e32 v61, 0, v61
	v_max_f32_e32 v56, v62, v62
	v_max_f32_e32 v58, 0, v57
	v_max_f32_e32 v57, v63, v63
	v_pk_mul_f32 v[60:61], v[60:61], v[60:61]
	v_max_f32_e32 v56, 0, v56
	v_max_f32_e32 v57, 0, v57
	v_max_f32_e32 v59, 0, v59
	v_pk_mul_f32 v[62:63], v[56:57], v[56:57]
	v_pk_mul_f32 v[68:69], v[58:59], v[58:59]
	v_cvt_pk_bf16_f32 v56, v60, v61
	v_add_co_u32_e32 v60, vcc, s61, v144
	v_cvt_pk_bf16_f32 v57, v62, v63
	v_cvt_pk_bf16_f32 v58, v66, v67
	v_cvt_pk_bf16_f32 v59, v68, v69
	v_addc_co_u32_e32 v61, vcc, 0, v145, vcc
	v_max_f32_e32 v48, 0, v48
	v_max_f32_e32 v49, 0, v49
	global_store_dwordx4 v[60:61], v[56:59], off
	s_nop 1
	v_pk_mul_f32 v[56:57], v[48:49], v[48:49]
	v_max_f32_e32 v49, v50, v50
	v_max_f32_e32 v48, v54, v54
	v_max_f32_e32 v50, 0, v49
	v_max_f32_e32 v49, v55, v55
	v_max_f32_e32 v52, 0, v52
	v_max_f32_e32 v53, 0, v53
	v_max_f32_e32 v48, 0, v48
	v_max_f32_e32 v49, 0, v49
	v_max_f32_e32 v51, 0, v51
	s_mov_b64 s[46:47], 0x200000
	v_pk_mul_f32 v[52:53], v[52:53], v[52:53]
	v_pk_mul_f32 v[54:55], v[48:49], v[48:49]
	v_pk_mul_f32 v[58:59], v[50:51], v[50:51]
; __device__ __forceinline__ unsigned cvt_pk_bf16(float lo, float hi) { const bf16x2_t r = __builtin_convertvector((f32x2){lo, hi}, bf16x2_t); return __builtin_bit_cast(unsigned, r); }
; #define PG8_WAIT_V(n) asm volatile("s_waitcnt vmcnt(" #n ")" ::: "memory")
; #define PG8_BAR __builtin_amdgcn_s_barrier()
; template <class Epi>
; __device__ __forceinline__ void gemm_phase(LAS unsigned char* lds, const bf16_t* A, int lda, const bf16_t* Bt, int ldb, int M, int N, int K, int asel, const Epi& E, const int fixed_round = -1) {
;     ...
;         if (!has_next) break;
; #pragma unroll
;         for (int a = 0; a < 2; ++a)
; #pragma unroll
;             for (int b = 0; b < 2; ++b)
; #pragma unroll
;                 for (int m = 0; m < 4; ++m)
; #pragma unroll
;                     for (int n = 0; n < 2; ++n) acc[a][b][m][n] = (f32x4){0.f, 0.f, 0.f, 0.f};
;         cur = nxt; cA = nA; cB = nB; ++ui;
;     }
;     PG8_WAIT_V(0);
;     if (wr == 0) PG8_BAR;
;     PG8_BAR;
;     __device__ __forceinline__ void operator()(const AccT& acc, const Unit& u, int wr, int wc, int fr, int fq) const {
;         const int row0 = u.pm * BM + wr * 64 + fr, col0 = u.pn * BM + wc * 32 + 8 * fq;
; #pragma unroll
;         for (int ai = 0; ai < 2; ++ai)
; #pragma unroll
;             for (int m = 0; m < 4; ++m) { bf16_t* rowp = O + (size_t)(row0 + ai * HALF + m * 16) * DFF + col0;
; #pragma unroll
;                 for (int bj = 0; bj < 2; ++bj) { f32x4 v0 = acc[ai][bj][m][0], v1 = acc[ai][bj][m][1];
; #pragma unroll
;                     for (int j = 0; j < 4; ++j) { float a = fmaxf(v0[j], 0.f), b = fmaxf(v1[j], 0.f); v0[j] = a * a; v1[j] = b * b; }
;                     u32x4 w; w.x = cvt_pk_bf16(v0[0], v0[1]); w.y = cvt_pk_bf16(v0[2], v0[3]); w.z = cvt_pk_bf16(v1[0], v1[1]); w.w = cvt_pk_bf16(v1[2], v1[3]);
;                     *(u32x4*)(rowp + bj * HALF) = w; } }
	v_lshl_add_u64 v[64:65], v[144:145], 0, s[46:47]
	v_cvt_pk_bf16_f32 v48, v52, v53
	v_cvt_pk_bf16_f32 v49, v54, v55
	v_cvt_pk_bf16_f32 v50, v56, v57
	v_cvt_pk_bf16_f32 v51, v58, v59
	v_max_f32_e32 v40, 0, v40
	v_max_f32_e32 v41, 0, v41
	global_store_dwordx4 v[64:65], v[48:51], off offset:256
	s_nop 1
	v_pk_mul_f32 v[50:51], v[40:41], v[40:41]
	v_max_f32_e32 v41, v42, v42
	v_max_f32_e32 v44, 0, v44
	v_max_f32_e32 v45, 0, v45
	v_max_f32_e32 v40, v46, v46
	v_max_f32_e32 v42, 0, v41
	v_max_f32_e32 v41, v47, v47
	v_pk_mul_f32 v[44:45], v[44:45], v[44:45]
	v_max_f32_e32 v40, 0, v40
	v_max_f32_e32 v41, 0, v41
	v_max_f32_e32 v43, 0, v43
	v_pk_mul_f32 v[46:47], v[40:41], v[40:41]
	v_pk_mul_f32 v[52:53], v[42:43], v[42:43]
	v_cvt_pk_bf16_f32 v40, v44, v45
	v_add_co_u32_e32 v44, vcc, s62, v144
	v_cvt_pk_bf16_f32 v41, v46, v47
	v_cvt_pk_bf16_f32 v42, v50, v51
	v_cvt_pk_bf16_f32 v43, v52, v53
	v_addc_co_u32_e32 v45, vcc, 0, v145, vcc
	v_max_f32_e32 v32, 0, v32
	v_max_f32_e32 v33, 0, v33
	global_store_dwordx4 v[44:45], v[40:43], off
	s_nop 1
	v_pk_mul_f32 v[40:41], v[32:33], v[32:33]
	v_max_f32_e32 v33, v34, v34
	v_max_f32_e32 v32, v38, v38
	v_max_f32_e32 v34, 0, v33
	v_max_f32_e32 v33, v39, v39
	v_max_f32_e32 v36, 0, v36
	v_max_f32_e32 v37, 0, v37
	v_max_f32_e32 v32, 0, v32
	v_max_f32_e32 v33, 0, v33
	v_max_f32_e32 v35, 0, v35
	v_pk_mul_f32 v[36:37], v[36:37], v[36:37]
	v_pk_mul_f32 v[38:39], v[32:33], v[32:33]
	v_pk_mul_f32 v[42:43], v[34:35], v[34:35]
	v_lshl_add_u64 v[48:49], v[144:145], 0, s[4:5]
	v_cvt_pk_bf16_f32 v32, v36, v37
	v_cvt_pk_bf16_f32 v33, v38, v39
	v_cvt_pk_bf16_f32 v34, v40, v41
	v_cvt_pk_bf16_f32 v35, v42, v43
	v_max_f32_e32 v24, 0, v24
	v_max_f32_e32 v25, 0, v25
	global_store_dwordx4 v[48:49], v[32:35], off offset:256
	s_nop 1
	v_pk_mul_f32 v[34:35], v[24:25], v[24:25]
	v_max_f32_e32 v25, v26, v26
	v_max_f32_e32 v28, 0, v28
	v_max_f32_e32 v29, 0, v29
	v_max_f32_e32 v24, v30, v30
	v_max_f32_e32 v26, 0, v25
	v_max_f32_e32 v25, v31, v31
	v_pk_mul_f32 v[28:29], v[28:29], v[28:29]
	v_max_f32_e32 v24, 0, v24
	v_max_f32_e32 v25, 0, v25
	v_max_f32_e32 v27, 0, v27
	v_pk_mul_f32 v[30:31], v[24:25], v[24:25]
	v_pk_mul_f32 v[36:37], v[26:27], v[26:27]
	v_cvt_pk_bf16_f32 v24, v28, v29
	v_add_co_u32_e32 v28, vcc, s63, v144
	v_cvt_pk_bf16_f32 v25, v30, v31
	v_cvt_pk_bf16_f32 v26, v34, v35
	v_cvt_pk_bf16_f32 v27, v36, v37
	v_addc_co_u32_e32 v29, vcc, 0, v145, vcc
	v_max_f32_e32 v16, 0, v16
	v_max_f32_e32 v17, 0, v17
	global_store_dwordx4 v[28:29], v[24:27], off
	s_nop 1
	v_pk_mul_f32 v[24:25], v[16:17], v[16:17]
	v_max_f32_e32 v17, v18, v18
	v_max_f32_e32 v16, v22, v22
	v_max_f32_e32 v18, 0, v17
	v_max_f32_e32 v17, v23, v23
	v_max_f32_e32 v20, 0, v20
	v_max_f32_e32 v21, 0, v21
	v_max_f32_e32 v16, 0, v16
	v_max_f32_e32 v17, 0, v17
	v_max_f32_e32 v19, 0, v19
	v_pk_mul_f32 v[20:21], v[20:21], v[20:21]
	v_pk_mul_f32 v[22:23], v[16:17], v[16:17]
	v_pk_mul_f32 v[26:27], v[18:19], v[18:19]
	v_lshl_add_u64 v[32:33], v[144:145], 0, s[6:7]
	v_cvt_pk_bf16_f32 v16, v20, v21
	v_cvt_pk_bf16_f32 v17, v22, v23
	v_cvt_pk_bf16_f32 v18, v24, v25
	v_cvt_pk_bf16_f32 v19, v26, v27
	v_max_f32_e32 v8, 0, v8
	v_max_f32_e32 v9, 0, v9
	global_store_dwordx4 v[32:33], v[16:19], off offset:256
	s_nop 1
	v_pk_mul_f32 v[18:19], v[8:9], v[8:9]
	v_max_f32_e32 v9, v10, v10
	v_max_f32_e32 v12, 0, v12
	v_max_f32_e32 v13, 0, v13
	v_max_f32_e32 v8, v14, v14
	v_max_f32_e32 v10, 0, v9
	v_max_f32_e32 v9, v15, v15
	v_pk_mul_f32 v[12:13], v[12:13], v[12:13]
	v_max_f32_e32 v8, 0, v8
	v_max_f32_e32 v9, 0, v9
	v_max_f32_e32 v11, 0, v11
	v_pk_mul_f32 v[14:15], v[8:9], v[8:9]
	v_pk_mul_f32 v[20:21], v[10:11], v[10:11]
	v_cvt_pk_bf16_f32 v8, v12, v13
	v_add_co_u32_e32 v12, vcc, s64, v144
	v_cvt_pk_bf16_f32 v9, v14, v15
	v_cvt_pk_bf16_f32 v10, v18, v19
	v_cvt_pk_bf16_f32 v11, v20, v21
	v_addc_co_u32_e32 v13, vcc, 0, v145, vcc
	v_max_f32_e32 v0, 0, v0
	v_max_f32_e32 v1, 0, v1
	global_store_dwordx4 v[12:13], v[8:11], off
	s_nop 1
	v_pk_mul_f32 v[8:9], v[0:1], v[0:1]
	v_max_f32_e32 v1, v2, v2
	v_max_f32_e32 v0, v6, v6
	v_max_f32_e32 v2, 0, v1
	v_max_f32_e32 v1, v7, v7
	v_max_f32_e32 v4, 0, v4
	v_max_f32_e32 v5, 0, v5
	v_max_f32_e32 v0, 0, v0
	v_max_f32_e32 v1, 0, v1
	v_max_f32_e32 v3, 0, v3
	v_pk_mul_f32 v[4:5], v[4:5], v[4:5]
	v_pk_mul_f32 v[6:7], v[0:1], v[0:1]
	v_pk_mul_f32 v[10:11], v[2:3], v[2:3]
	v_lshl_add_u64 v[16:17], v[144:145], 0, s[22:23]
	v_cvt_pk_bf16_f32 v0, v4, v5
	v_cvt_pk_bf16_f32 v1, v6, v7
	v_cvt_pk_bf16_f32 v2, v8, v9
	v_cvt_pk_bf16_f32 v3, v10, v11
	s_and_b64 vcc, exec, s[0:1]
	s_mov_b32 s65, s24
	s_mov_b32 s44, s28
	s_mov_b64 s[48:49], s[42:43]
	s_mov_b64 s[46:47], s[40:41]
	s_mov_b64 s[70:71], s[26:27]
	global_store_dwordx4 v[16:17], v[0:3], off offset:256
	s_cbranch_vccz .LBB0_1216
	s_waitcnt vmcnt(0)
	s_cmpk_gt_u32 s33, 0xff
	s_cbranch_scc1 .LBB0_1227
	s_barrier

; #define PG8_STAGE(bufoff, gbase, voff) do { _Pragma("unroll") for (int _i = 0; _i < 2; ++_i) \
;         __builtin_amdgcn_global_load_lds((const unsigned*)((const char*)(gbase) + (voff)[_i]), (LAS unsigned*)(lds + (bufoff) + ldsw + _i * 8192), 16, 0, 0); } while (0)
; #define PG8_LDA(dst, b, h) do { _Pragma("unroll") for (int m = 0; m < 4; ++m) _Pragma("unroll") for (int k = 0; k < 2; ++k) dst[m][k] = *(const LAS bf16x8*)(lds + PG8_SA(b, h) + aoff + m * 2048 + k * 1024); } while (0)
; #define PG8_LDB(dst, b, h) do { _Pragma("unroll") for (int n = 0; n < 2; ++n) _Pragma("unroll") for (int k = 0; k < 2; ++k) dst[n][k] = *(const LAS bf16x8*)(lds + PG8_SB(b, h) + boff + n * 2048 + k * 1024); } while (0)
; #define PG8_WAIT_V(n) asm volatile("s_waitcnt vmcnt(" #n ")" ::: "memory")
; #define PG8_WAIT_L(n) asm volatile("s_waitcnt lgkmcnt(" #n ")" ::: "memory")
; #define PG8_BAR __builtin_amdgcn_s_barrier()
; #define PG8_SCHED __builtin_amdgcn_sched_barrier(0)
; template <class Epi>
; __device__ __forceinline__ void gemm_phase(LAS unsigned char* lds, const bf16_t* A, int lda, const bf16_t* Bt, int ldb, int M, int N, int K, int asel, const Epi& E, const int fixed_round = -1) {
;     ...
;             PG8_LDB(B0, 0, 0); PG8_SCHED; PG8_LDA(At, 0, 0); PG8_STAGE(PG8_SA(1, 1), a1 + hstepA, voffA);
;             PG8_WAIT_L(8); PG8_BAR; PG8_WAIT_L(0); PG8_MMA(0, 0, At, B0); PG8_BAR; PG8_SCHED;
;             PG8_LDB(B1, 0, 1); PG8_STAGE(PG8_SB(0, 0), b2, voffB);
;             PG8_BAR; PG8_WAIT_L(0); PG8_MMA(0, 1, At, B1); PG8_BAR;
;             PG8_LDA(At, 0, 1); PG8_STAGE(PG8_SA(0, 0), a2, voffA);
;             PG8_BAR; PG8_WAIT_L(0); PG8_MMA(1, 0, At, B0); PG8_BAR; PG8_SCHED;
;             PG8_STAGE(PG8_SB(0, 1), b2 + hstepB, voffB);
;             PG8_WAIT_V(6); PG8_BAR; PG8_MMA(1, 1, At, B1); PG8_BAR;
.LBB0_1283:
	ds_read_b128 v[146:149], v124
	ds_read_b128 v[150:153], v124 offset:1024
	ds_read_b128 v[154:157], v124 offset:2048
	ds_read_b128 v[158:161], v124 offset:3072
	s_mov_b32 m0, s47
	v_lshl_add_u64 v[194:195], v[120:121], 0, s[22:23]
	ds_read_b128 v[162:165], v125
	ds_read_b128 v[166:169], v125 offset:1024
	ds_read_b128 v[170:173], v125 offset:2048
	ds_read_b128 v[174:177], v125 offset:3072
	ds_read_b128 v[178:181], v125 offset:4096
	ds_read_b128 v[182:185], v125 offset:5120
	ds_read_b128 v[186:189], v125 offset:6144
	ds_read_b128 v[190:193], v125 offset:7168
	global_load_lds_dwordx4 v[194:195], off
	v_lshl_add_u64 v[194:195], v[122:123], 0, s[22:23]
	s_mov_b32 m0, s48
	s_nop 0
	global_load_lds_dwordx4 v[194:195], off
	s_waitcnt lgkmcnt(8)
	s_setprio 1
	s_barrier
	s_waitcnt lgkmcnt(0)
	v_mfma_f32_16x16x32_bf16 v[140:143], v[146:149], v[162:165], v[140:143]
	v_mfma_f32_16x16x32_bf16 v[136:139], v[154:157], v[162:165], v[136:139]
	v_mfma_f32_16x16x32_bf16 v[108:111], v[146:149], v[170:173], v[108:111]
	v_mfma_f32_16x16x32_bf16 v[104:107], v[154:157], v[170:173], v[104:107]
	v_mfma_f32_16x16x32_bf16 v[92:95], v[146:149], v[178:181], v[92:95]
	v_mfma_f32_16x16x32_bf16 v[88:91], v[154:157], v[178:181], v[88:91]
	v_mfma_f32_16x16x32_bf16 v[76:79], v[146:149], v[186:189], v[76:79]
	v_mfma_f32_16x16x32_bf16 v[72:75], v[154:157], v[186:189], v[72:75]
	v_mfma_f32_16x16x32_bf16 v[140:143], v[150:153], v[166:169], v[140:143]
	v_mfma_f32_16x16x32_bf16 v[136:139], v[158:161], v[166:169], v[136:139]
	v_mfma_f32_16x16x32_bf16 v[108:111], v[150:153], v[174:177], v[108:111]
	v_mfma_f32_16x16x32_bf16 v[104:107], v[158:161], v[174:177], v[104:107]
	v_mfma_f32_16x16x32_bf16 v[92:95], v[150:153], v[182:185], v[92:95]
	v_mfma_f32_16x16x32_bf16 v[88:91], v[158:161], v[182:185], v[88:91]
	v_mfma_f32_16x16x32_bf16 v[76:79], v[150:153], v[190:193], v[76:79]
	v_mfma_f32_16x16x32_bf16 v[72:75], v[158:161], v[190:193], v[72:75]
	s_setprio 0
	s_barrier
	s_add_u32 s24, s16, s22
	s_addc_u32 s25, s17, s23
	s_add_u32 s24, s24, 0x18500100
	s_addc_u32 s25, s25, 0
	s_add_u32 s57, s28, s22
	s_addc_u32 s58, s29, s23
	s_cmpk_eq_i32 s22, 0x3f00
	s_cselect_b32 s27, s87, s25
	s_cselect_b32 s26, s86, s24
	s_cselect_b32 s25, s3, s58
	s_cselect_b32 s24, s2, s57
	s_mov_b32 m0, s49
	s_add_u32 s98, s24, s0
	s_addc_u32 s99, s25, s1
	ds_read_b128 v[194:197], v126
	ds_read_b128 v[204:207], v126 offset:1024
	ds_read_b128 v[208:211], v126 offset:2048
	ds_read_b128 v[212:215], v126 offset:3072
	global_load_lds_dwordx4 v114, s[24:25]
	s_mov_b32 m0, s50
	s_nop 0
	global_load_lds_dwordx4 v118, s[24:25]
	s_setprio 1
	s_barrier
	s_waitcnt lgkmcnt(0)
	v_mfma_f32_16x16x32_bf16 v[132:135], v[194:197], v[162:165], v[132:135]
	v_mfma_f32_16x16x32_bf16 v[128:131], v[208:211], v[162:165], v[128:131]
	v_mfma_f32_16x16x32_bf16 v[100:103], v[194:197], v[170:173], v[100:103]
	v_mfma_f32_16x16x32_bf16 v[96:99], v[208:211], v[170:173], v[96:99]
	v_mfma_f32_16x16x32_bf16 v[84:87], v[194:197], v[178:181], v[84:87]
	v_mfma_f32_16x16x32_bf16 v[80:83], v[208:211], v[178:181], v[80:83]
	v_mfma_f32_16x16x32_bf16 v[68:71], v[194:197], v[186:189], v[68:71]
	v_mfma_f32_16x16x32_bf16 v[64:67], v[208:211], v[186:189], v[64:67]
	v_mfma_f32_16x16x32_bf16 v[132:135], v[204:207], v[166:169], v[132:135]
	v_mfma_f32_16x16x32_bf16 v[128:131], v[212:215], v[166:169], v[128:131]
	v_mfma_f32_16x16x32_bf16 v[100:103], v[204:207], v[174:177], v[100:103]
	v_mfma_f32_16x16x32_bf16 v[96:99], v[212:215], v[174:177], v[96:99]
	v_mfma_f32_16x16x32_bf16 v[84:87], v[204:207], v[182:185], v[84:87]
	v_mfma_f32_16x16x32_bf16 v[80:83], v[212:215], v[182:185], v[80:83]
	v_mfma_f32_16x16x32_bf16 v[68:71], v[204:207], v[190:193], v[68:71]
	v_mfma_f32_16x16x32_bf16 v[64:67], v[212:215], v[190:193], v[64:67]
	s_setprio 0
	s_mov_b32 m0, s40
	s_add_u32 s100, s26, s0
	s_addc_u32 s101, s27, s1
	s_barrier
	ds_read_b128 v[162:165], v125 offset:16384
	ds_read_b128 v[166:169], v125 offset:17408
	ds_read_b128 v[170:173], v125 offset:18432
	ds_read_b128 v[174:177], v125 offset:19456
	ds_read_b128 v[178:181], v125 offset:20480
	ds_read_b128 v[182:185], v125 offset:21504
	ds_read_b128 v[186:189], v125 offset:22528
	ds_read_b128 v[190:193], v125 offset:23552
	global_load_lds_dwordx4 v112, s[26:27]
	s_mov_b32 m0, s41
	s_nop 0
	global_load_lds_dwordx4 v116, s[26:27]
	s_setprio 1
	s_barrier
	s_waitcnt lgkmcnt(0)
	v_mfma_f32_16x16x32_bf16 v[60:63], v[146:149], v[162:165], v[60:63]
	v_mfma_f32_16x16x32_bf16 v[56:59], v[154:157], v[162:165], v[56:59]
	v_mfma_f32_16x16x32_bf16 v[44:47], v[146:149], v[170:173], v[44:47]
	v_mfma_f32_16x16x32_bf16 v[40:43], v[154:157], v[170:173], v[40:43]
	v_mfma_f32_16x16x32_bf16 v[28:31], v[146:149], v[178:181], v[28:31]
	v_mfma_f32_16x16x32_bf16 v[24:27], v[154:157], v[178:181], v[24:27]
	v_mfma_f32_16x16x32_bf16 v[12:15], v[146:149], v[186:189], v[12:15]
	v_mfma_f32_16x16x32_bf16 v[8:11], v[154:157], v[186:189], v[8:11]
	v_mfma_f32_16x16x32_bf16 v[60:63], v[150:153], v[166:169], v[60:63]
	v_mfma_f32_16x16x32_bf16 v[56:59], v[158:161], v[166:169], v[56:59]
	v_mfma_f32_16x16x32_bf16 v[44:47], v[150:153], v[174:177], v[44:47]
	v_mfma_f32_16x16x32_bf16 v[40:43], v[158:161], v[174:177], v[40:43]
	v_mfma_f32_16x16x32_bf16 v[28:31], v[150:153], v[182:185], v[28:31]
	v_mfma_f32_16x16x32_bf16 v[24:27], v[158:161], v[182:185], v[24:27]
	v_mfma_f32_16x16x32_bf16 v[12:15], v[150:153], v[190:193], v[12:15]
	v_mfma_f32_16x16x32_bf16 v[8:11], v[158:161], v[190:193], v[8:11]
	s_setprio 0
	s_barrier
	s_add_u32 s58, s24, 0x200000
	s_addc_u32 s59, s25, 0
	s_mov_b32 m0, s51
	s_nop 0
	global_load_lds_dwordx4 v114, s[58:59]
	s_mov_b32 m0, s52
	s_nop 0
	global_load_lds_dwordx4 v118, s[58:59]
	s_waitcnt vmcnt(6)
	s_setprio 1
	s_barrier
; #define PG8_STAGE(bufoff, gbase, voff) do { _Pragma("unroll") for (int _i = 0; _i < 2; ++_i) \
;         __builtin_amdgcn_global_load_lds((const unsigned*)((const char*)(gbase) + (voff)[_i]), (LAS unsigned*)(lds + (bufoff) + ldsw + _i * 8192), 16, 0, 0); } while (0)
; #define PG8_LDA(dst, b, h) do { _Pragma("unroll") for (int m = 0; m < 4; ++m) _Pragma("unroll") for (int k = 0; k < 2; ++k) dst[m][k] = *(const LAS bf16x8*)(lds + PG8_SA(b, h) + aoff + m * 2048 + k * 1024); } while (0)
; #define PG8_LDB(dst, b, h) do { _Pragma("unroll") for (int n = 0; n < 2; ++n) _Pragma("unroll") for (int k = 0; k < 2; ++k) dst[n][k] = *(const LAS bf16x8*)(lds + PG8_SB(b, h) + boff + n * 2048 + k * 1024); } while (0)
; #define PG8_WAIT_V(n) asm volatile("s_waitcnt vmcnt(" #n ")" ::: "memory")
; #define PG8_WAIT_L(n) asm volatile("s_waitcnt lgkmcnt(" #n ")" ::: "memory")
; #define PG8_BAR __builtin_amdgcn_s_barrier()
; #define PG8_SCHED __builtin_amdgcn_sched_barrier(0)
; template <class Epi>
; __device__ __forceinline__ void gemm_phase(LAS unsigned char* lds, const bf16_t* A, int lda, const bf16_t* Bt, int ldb, int M, int N, int K, int asel, const Epi& E, const int fixed_round = -1) {
;     ...
;             PG8_WAIT_V(6); PG8_BAR; PG8_MMA(1, 1, At, B1); PG8_BAR;
;             PG8_LDB(B0, 1, 0); PG8_SCHED; PG8_LDA(At, 1, 0); PG8_STAGE(PG8_SA(0, 1), a2 + hstepA, voffA);
;             PG8_WAIT_L(8); PG8_BAR; PG8_WAIT_L(0); PG8_MMA(0, 0, At, B0); PG8_BAR; PG8_SCHED;
;             PG8_LDB(B1, 1, 1); PG8_STAGE(PG8_SB(1, 0), b3, voffB);
;             PG8_BAR; PG8_WAIT_L(0); PG8_MMA(0, 1, At, B1); PG8_BAR;
;             PG8_LDA(At, 1, 1); PG8_STAGE(PG8_SA(1, 0), a3, voffA);
;             PG8_BAR; PG8_WAIT_L(0); PG8_MMA(1, 0, At, B0); PG8_BAR; PG8_SCHED;
	v_mfma_f32_16x16x32_bf16 v[52:55], v[194:197], v[162:165], v[52:55]
	v_mfma_f32_16x16x32_bf16 v[48:51], v[208:211], v[162:165], v[48:51]
	v_mfma_f32_16x16x32_bf16 v[36:39], v[194:197], v[170:173], v[36:39]
	v_mfma_f32_16x16x32_bf16 v[32:35], v[208:211], v[170:173], v[32:35]
	v_mfma_f32_16x16x32_bf16 v[20:23], v[194:197], v[178:181], v[20:23]
	v_mfma_f32_16x16x32_bf16 v[16:19], v[208:211], v[178:181], v[16:19]
	v_mfma_f32_16x16x32_bf16 v[4:7], v[194:197], v[186:189], v[4:7]
	v_mfma_f32_16x16x32_bf16 v[0:3], v[208:211], v[186:189], v[0:3]
	v_mfma_f32_16x16x32_bf16 v[52:55], v[204:207], v[166:169], v[52:55]
	v_mfma_f32_16x16x32_bf16 v[48:51], v[212:215], v[166:169], v[48:51]
	v_mfma_f32_16x16x32_bf16 v[36:39], v[204:207], v[174:177], v[36:39]
	v_mfma_f32_16x16x32_bf16 v[32:35], v[212:215], v[174:177], v[32:35]
	v_mfma_f32_16x16x32_bf16 v[20:23], v[204:207], v[182:185], v[20:23]
	v_mfma_f32_16x16x32_bf16 v[16:19], v[212:215], v[182:185], v[16:19]
	v_mfma_f32_16x16x32_bf16 v[4:7], v[204:207], v[190:193], v[4:7]
	v_mfma_f32_16x16x32_bf16 v[0:3], v[212:215], v[190:193], v[0:3]
	s_setprio 0
	s_barrier
	ds_read_b128 v[146:149], v127
	ds_read_b128 v[150:153], v127 offset:1024
	ds_read_b128 v[154:157], v127 offset:2048
	ds_read_b128 v[158:161], v127 offset:3072
	s_add_u32 s26, s26, 0x200000
	s_addc_u32 s27, s27, 0
	s_mov_b32 m0, s42
	ds_read_b128 v[162:165], v125 offset:32768
	ds_read_b128 v[166:169], v125 offset:33792
	ds_read_b128 v[170:173], v125 offset:34816
	ds_read_b128 v[174:177], v125 offset:35840
	ds_read_b128 v[178:181], v125 offset:36864
	ds_read_b128 v[182:185], v125 offset:37888
	ds_read_b128 v[186:189], v125 offset:38912
	ds_read_b128 v[190:193], v125 offset:39936
	global_load_lds_dwordx4 v112, s[26:27]
	s_mov_b32 m0, s43
	s_nop 0
	global_load_lds_dwordx4 v116, s[26:27]
	s_waitcnt lgkmcnt(8)
	s_setprio 1
	s_barrier
	s_waitcnt lgkmcnt(0)
	v_mfma_f32_16x16x32_bf16 v[140:143], v[146:149], v[162:165], v[140:143]
	v_mfma_f32_16x16x32_bf16 v[136:139], v[154:157], v[162:165], v[136:139]
	v_mfma_f32_16x16x32_bf16 v[108:111], v[146:149], v[170:173], v[108:111]
	v_mfma_f32_16x16x32_bf16 v[104:107], v[154:157], v[170:173], v[104:107]
	v_mfma_f32_16x16x32_bf16 v[92:95], v[146:149], v[178:181], v[92:95]
	v_mfma_f32_16x16x32_bf16 v[88:91], v[154:157], v[178:181], v[88:91]
	v_mfma_f32_16x16x32_bf16 v[76:79], v[146:149], v[186:189], v[76:79]
	v_mfma_f32_16x16x32_bf16 v[72:75], v[154:157], v[186:189], v[72:75]
	v_mfma_f32_16x16x32_bf16 v[140:143], v[150:153], v[166:169], v[140:143]
	v_mfma_f32_16x16x32_bf16 v[136:139], v[158:161], v[166:169], v[136:139]
	v_mfma_f32_16x16x32_bf16 v[108:111], v[150:153], v[174:177], v[108:111]
	v_mfma_f32_16x16x32_bf16 v[104:107], v[158:161], v[174:177], v[104:107]
	v_mfma_f32_16x16x32_bf16 v[92:95], v[150:153], v[182:185], v[92:95]
	v_mfma_f32_16x16x32_bf16 v[88:91], v[158:161], v[182:185], v[88:91]
	v_mfma_f32_16x16x32_bf16 v[76:79], v[150:153], v[190:193], v[76:79]
	v_mfma_f32_16x16x32_bf16 v[72:75], v[158:161], v[190:193], v[72:75]
	s_setprio 0
	s_barrier
	s_mov_b32 m0, s53
	ds_read_b128 v[194:197], v144
	ds_read_b128 v[204:207], v144 offset:1024
	ds_read_b128 v[208:211], v144 offset:2048
	ds_read_b128 v[212:215], v144 offset:3072
	global_load_lds_dwordx4 v114, s[98:99]
	s_mov_b32 m0, s54
	s_nop 0
	global_load_lds_dwordx4 v118, s[98:99]
	s_setprio 1
	s_barrier
	s_waitcnt lgkmcnt(0)
	v_mfma_f32_16x16x32_bf16 v[132:135], v[194:197], v[162:165], v[132:135]
	v_mfma_f32_16x16x32_bf16 v[128:131], v[208:211], v[162:165], v[128:131]
	v_mfma_f32_16x16x32_bf16 v[100:103], v[194:197], v[170:173], v[100:103]
	v_mfma_f32_16x16x32_bf16 v[96:99], v[208:211], v[170:173], v[96:99]
	v_mfma_f32_16x16x32_bf16 v[84:87], v[194:197], v[178:181], v[84:87]
	v_mfma_f32_16x16x32_bf16 v[80:83], v[208:211], v[178:181], v[80:83]
	v_mfma_f32_16x16x32_bf16 v[68:71], v[194:197], v[186:189], v[68:71]
	v_mfma_f32_16x16x32_bf16 v[64:67], v[208:211], v[186:189], v[64:67]
	v_mfma_f32_16x16x32_bf16 v[132:135], v[204:207], v[166:169], v[132:135]
	v_mfma_f32_16x16x32_bf16 v[128:131], v[212:215], v[166:169], v[128:131]
	v_mfma_f32_16x16x32_bf16 v[100:103], v[204:207], v[174:177], v[100:103]
	v_mfma_f32_16x16x32_bf16 v[96:99], v[212:215], v[174:177], v[96:99]
	v_mfma_f32_16x16x32_bf16 v[84:87], v[204:207], v[182:185], v[84:87]
	v_mfma_f32_16x16x32_bf16 v[80:83], v[212:215], v[182:185], v[80:83]
	v_mfma_f32_16x16x32_bf16 v[68:71], v[204:207], v[190:193], v[68:71]
	v_mfma_f32_16x16x32_bf16 v[64:67], v[212:215], v[190:193], v[64:67]
	s_setprio 0
	s_mov_b32 m0, s44
	s_barrier
; #define PG8_STAGE(bufoff, gbase, voff) do { _Pragma("unroll") for (int _i = 0; _i < 2; ++_i) \
;         __builtin_amdgcn_global_load_lds((const unsigned*)((const char*)(gbase) + (voff)[_i]), (LAS unsigned*)(lds + (bufoff) + ldsw + _i * 8192), 16, 0, 0); } while (0)
; #define PG8_LDA(dst, b, h) do { _Pragma("unroll") for (int m = 0; m < 4; ++m) _Pragma("unroll") for (int k = 0; k < 2; ++k) dst[m][k] = *(const LAS bf16x8*)(lds + PG8_SA(b, h) + aoff + m * 2048 + k * 1024); } while (0)
; #define PG8_WAIT_V(n) asm volatile("s_waitcnt vmcnt(" #n ")" ::: "memory")
; #define PG8_WAIT_L(n) asm volatile("s_waitcnt lgkmcnt(" #n ")" ::: "memory")
; #define PG8_BAR __builtin_amdgcn_s_barrier()
; #define PG8_SCHED __builtin_amdgcn_sched_barrier(0)
; template <class Epi>
; __device__ __forceinline__ void gemm_phase(LAS unsigned char* lds, const bf16_t* A, int lda, const bf16_t* Bt, int ldb, int M, int N, int K, int asel, const Epi& E, const int fixed_round = -1) {
;     ...
;             PG8_LDA(At, 1, 1); PG8_STAGE(PG8_SA(1, 0), a3, voffA);
;             PG8_BAR; PG8_WAIT_L(0); PG8_MMA(1, 0, At, B0); PG8_BAR; PG8_SCHED;
;             PG8_STAGE(PG8_SB(1, 1), b3 + hstepB, voffB);
;             PG8_WAIT_V(6); PG8_BAR; PG8_MMA(1, 1, At, B1); PG8_BAR;
;     ...
;     PG8_WAIT_V(0);
;     if (wr == 0) PG8_BAR;
;     PG8_BAR;
	ds_read_b128 v[162:165], v125 offset:49152
	ds_read_b128 v[166:169], v125 offset:50176
	ds_read_b128 v[170:173], v125 offset:51200
	ds_read_b128 v[174:177], v125 offset:52224
	ds_read_b128 v[178:181], v125 offset:53248
	ds_read_b128 v[182:185], v125 offset:54272
	ds_read_b128 v[186:189], v125 offset:55296
	ds_read_b128 v[190:193], v125 offset:56320
	global_load_lds_dwordx4 v112, s[100:101]
	s_mov_b32 m0, s45
	s_nop 0
	global_load_lds_dwordx4 v116, s[100:101]
	s_setprio 1
	s_barrier
	s_waitcnt lgkmcnt(0)
	v_mfma_f32_16x16x32_bf16 v[60:63], v[146:149], v[162:165], v[60:63]
	v_mfma_f32_16x16x32_bf16 v[56:59], v[154:157], v[162:165], v[56:59]
	v_mfma_f32_16x16x32_bf16 v[44:47], v[146:149], v[170:173], v[44:47]
	v_mfma_f32_16x16x32_bf16 v[40:43], v[154:157], v[170:173], v[40:43]
	v_mfma_f32_16x16x32_bf16 v[28:31], v[146:149], v[178:181], v[28:31]
	v_mfma_f32_16x16x32_bf16 v[24:27], v[154:157], v[178:181], v[24:27]
	v_mfma_f32_16x16x32_bf16 v[12:15], v[146:149], v[186:189], v[12:15]
	v_mfma_f32_16x16x32_bf16 v[8:11], v[154:157], v[186:189], v[8:11]
	v_mfma_f32_16x16x32_bf16 v[60:63], v[150:153], v[166:169], v[60:63]
	v_mfma_f32_16x16x32_bf16 v[56:59], v[158:161], v[166:169], v[56:59]
	v_mfma_f32_16x16x32_bf16 v[44:47], v[150:153], v[174:177], v[44:47]
	v_mfma_f32_16x16x32_bf16 v[40:43], v[158:161], v[174:177], v[40:43]
	v_mfma_f32_16x16x32_bf16 v[28:31], v[150:153], v[182:185], v[28:31]
	v_mfma_f32_16x16x32_bf16 v[24:27], v[158:161], v[182:185], v[24:27]
	v_mfma_f32_16x16x32_bf16 v[12:15], v[150:153], v[190:193], v[12:15]
	v_mfma_f32_16x16x32_bf16 v[8:11], v[158:161], v[190:193], v[8:11]
	s_setprio 0
	s_barrier
	s_add_u32 s24, s24, 0x200080
	s_addc_u32 s25, s25, 0
	s_mov_b32 m0, s55
	s_nop 0
	global_load_lds_dwordx4 v114, s[24:25]
	s_mov_b32 m0, s56
	s_nop 0
	global_load_lds_dwordx4 v118, s[24:25]
	s_waitcnt vmcnt(6)
	s_setprio 1
	s_barrier
	v_mfma_f32_16x16x32_bf16 v[52:55], v[194:197], v[162:165], v[52:55]
	v_mfma_f32_16x16x32_bf16 v[48:51], v[208:211], v[162:165], v[48:51]
	v_mfma_f32_16x16x32_bf16 v[36:39], v[194:197], v[170:173], v[36:39]
	v_mfma_f32_16x16x32_bf16 v[32:35], v[208:211], v[170:173], v[32:35]
	v_mfma_f32_16x16x32_bf16 v[20:23], v[194:197], v[178:181], v[20:23]
	v_mfma_f32_16x16x32_bf16 v[16:19], v[208:211], v[178:181], v[16:19]
	v_mfma_f32_16x16x32_bf16 v[4:7], v[194:197], v[186:189], v[4:7]
	v_mfma_f32_16x16x32_bf16 v[0:3], v[208:211], v[186:189], v[0:3]
	v_mfma_f32_16x16x32_bf16 v[52:55], v[204:207], v[166:169], v[52:55]
	v_mfma_f32_16x16x32_bf16 v[48:51], v[212:215], v[166:169], v[48:51]
	v_mfma_f32_16x16x32_bf16 v[36:39], v[204:207], v[174:177], v[36:39]
	v_mfma_f32_16x16x32_bf16 v[32:35], v[212:215], v[174:177], v[32:35]
	v_mfma_f32_16x16x32_bf16 v[20:23], v[204:207], v[182:185], v[20:23]
	v_mfma_f32_16x16x32_bf16 v[16:19], v[212:215], v[182:185], v[16:19]
	v_mfma_f32_16x16x32_bf16 v[4:7], v[204:207], v[190:193], v[4:7]
	v_mfma_f32_16x16x32_bf16 v[0:3], v[212:215], v[190:193], v[0:3]
	s_setprio 0
	s_add_i32 s46, s46, 2
	s_add_u32 s22, s22, 0x100
	s_addc_u32 s23, s23, 0
	s_cmpk_lt_u32 s46, 0x7e
	s_cbranch_scc1 .Lrot_11
	s_barrier
	s_waitcnt vmcnt(0)
	v_readlane_b32 s48, v254, 0
	s_cmpk_gt_u32 s33, 0xff
	v_readlane_b32 s54, v254, 6
	v_readlane_b32 s55, v254, 7
	v_readlane_b32 s49, v254, 1
	v_readlane_b32 s50, v254, 2
	v_readlane_b32 s51, v254, 3
	v_readlane_b32 s52, v254, 4
	v_readlane_b32 s53, v254, 5
	s_cbranch_scc1 .LBB0_1286
	s_barrier

; #define PG8_STAGE(bufoff, gbase, voff) do { _Pragma("unroll") for (int _i = 0; _i < 2; ++_i) \
;         __builtin_amdgcn_global_load_lds((const unsigned*)((const char*)(gbase) + (voff)[_i]), (LAS unsigned*)(lds + (bufoff) + ldsw + _i * 8192), 16, 0, 0); } while (0)
; #define PG8_LDA(dst, b, h) do { _Pragma("unroll") for (int m = 0; m < 4; ++m) _Pragma("unroll") for (int k = 0; k < 2; ++k) dst[m][k] = *(const LAS bf16x8*)(lds + PG8_SA(b, h) + aoff + m * 2048 + k * 1024); } while (0)
; #define PG8_LDB(dst, b, h) do { _Pragma("unroll") for (int n = 0; n < 2; ++n) _Pragma("unroll") for (int k = 0; k < 2; ++k) dst[n][k] = *(const LAS bf16x8*)(lds + PG8_SB(b, h) + boff + n * 2048 + k * 1024); } while (0)
; #define PG8_WAIT_V(n) asm volatile("s_waitcnt vmcnt(" #n ")" ::: "memory")
; #define PG8_WAIT_L(n) asm volatile("s_waitcnt lgkmcnt(" #n ")" ::: "memory")
; #define PG8_BAR __builtin_amdgcn_s_barrier()
; #define PG8_SCHED __builtin_amdgcn_sched_barrier(0)
; template <class Epi>
; __device__ __forceinline__ void gemm_phase(LAS unsigned char* lds, const bf16_t* A, int lda, const bf16_t* Bt, int ldb, int M, int N, int K, int asel, const Epi& E, const int fixed_round = -1) {
;     ...
;             PG8_LDB(B0, 0, 0); PG8_SCHED; PG8_LDA(At, 0, 0); PG8_STAGE(PG8_SA(1, 1), a1 + hstepA, voffA);
;             PG8_WAIT_L(8); PG8_BAR; PG8_WAIT_L(0); PG8_MMA(0, 0, At, B0); PG8_BAR; PG8_SCHED;
;             PG8_LDB(B1, 0, 1); PG8_STAGE(PG8_SB(0, 0), b2, voffB);
;             PG8_BAR; PG8_WAIT_L(0); PG8_MMA(0, 1, At, B1); PG8_BAR;
;             PG8_LDA(At, 0, 1); PG8_STAGE(PG8_SA(0, 0), a2, voffA);
;             PG8_BAR; PG8_WAIT_L(0); PG8_MMA(1, 0, At, B0); PG8_BAR; PG8_SCHED;
;             PG8_STAGE(PG8_SB(0, 1), b2 + hstepB, voffB);
;             PG8_WAIT_V(6); PG8_BAR; PG8_MMA(1, 1, At, B1); PG8_BAR;
.LBB0_1322:
	ds_read_b128 v[144:147], v122
	ds_read_b128 v[148:151], v122 offset:1024
	ds_read_b128 v[152:155], v122 offset:2048
	ds_read_b128 v[156:159], v122 offset:3072
	s_mov_b32 m0, s35
	v_lshl_add_u64 v[192:193], v[118:119], 0, s[6:7]
	ds_read_b128 v[160:163], v123
	ds_read_b128 v[164:167], v123 offset:1024
	ds_read_b128 v[168:171], v123 offset:2048
	ds_read_b128 v[172:175], v123 offset:3072
	ds_read_b128 v[176:179], v123 offset:4096
	ds_read_b128 v[180:183], v123 offset:5120
	ds_read_b128 v[184:187], v123 offset:6144
	ds_read_b128 v[188:191], v123 offset:7168
	global_load_lds_dwordx4 v[192:193], off
	v_lshl_add_u64 v[192:193], v[120:121], 0, s[6:7]
	s_mov_b32 m0, s40
	s_nop 0
	global_load_lds_dwordx4 v[192:193], off
	s_waitcnt lgkmcnt(8)
	s_setprio 1
	s_barrier
	s_waitcnt lgkmcnt(0)
	v_mfma_f32_16x16x32_bf16 v[140:143], v[144:147], v[160:163], v[140:143]
	v_mfma_f32_16x16x32_bf16 v[136:139], v[152:155], v[160:163], v[136:139]
	v_mfma_f32_16x16x32_bf16 v[108:111], v[144:147], v[168:171], v[108:111]
	v_mfma_f32_16x16x32_bf16 v[104:107], v[152:155], v[168:171], v[104:107]
	v_mfma_f32_16x16x32_bf16 v[92:95], v[144:147], v[176:179], v[92:95]
	v_mfma_f32_16x16x32_bf16 v[88:91], v[152:155], v[176:179], v[88:91]
	v_mfma_f32_16x16x32_bf16 v[76:79], v[144:147], v[184:187], v[76:79]
	v_mfma_f32_16x16x32_bf16 v[72:75], v[152:155], v[184:187], v[72:75]
	v_mfma_f32_16x16x32_bf16 v[140:143], v[148:151], v[164:167], v[140:143]
	v_mfma_f32_16x16x32_bf16 v[136:139], v[156:159], v[164:167], v[136:139]
	v_mfma_f32_16x16x32_bf16 v[108:111], v[148:151], v[172:175], v[108:111]
	v_mfma_f32_16x16x32_bf16 v[104:107], v[156:159], v[172:175], v[104:107]
	v_mfma_f32_16x16x32_bf16 v[92:95], v[148:151], v[180:183], v[92:95]
	v_mfma_f32_16x16x32_bf16 v[88:91], v[156:159], v[180:183], v[88:91]
	v_mfma_f32_16x16x32_bf16 v[76:79], v[148:151], v[188:191], v[76:79]
	v_mfma_f32_16x16x32_bf16 v[72:75], v[156:159], v[188:191], v[72:75]
	s_setprio 0
	s_barrier
	s_add_u32 s8, s4, s6
	s_addc_u32 s9, s5, s7
	s_add_u32 s8, s8, 0x18500100
	s_addc_u32 s9, s9, 0
	s_add_u32 s49, s28, s6
	s_addc_u32 s50, s29, s7
	s_cmpk_eq_i32 s6, 0x3f00
	s_cselect_b32 s13, s11, s9
	s_cselect_b32 s12, s10, s8
	s_cselect_b32 s9, s3, s50
	s_cselect_b32 s8, s2, s49
	s_mov_b32 m0, s41
	s_add_u32 s98, s8, s0
	s_addc_u32 s99, s9, s1
	ds_read_b128 v[192:195], v124
	ds_read_b128 v[196:199], v124 offset:1024
	ds_read_b128 v[204:207], v124 offset:2048
	ds_read_b128 v[208:211], v124 offset:3072
	global_load_lds_dwordx4 v202, s[8:9]
	s_mov_b32 m0, s42
	s_nop 0
	global_load_lds_dwordx4 v116, s[8:9]
	s_setprio 1
	s_barrier
	s_waitcnt lgkmcnt(0)
	v_mfma_f32_16x16x32_bf16 v[132:135], v[192:195], v[160:163], v[132:135]
	v_mfma_f32_16x16x32_bf16 v[128:131], v[204:207], v[160:163], v[128:131]
	v_mfma_f32_16x16x32_bf16 v[100:103], v[192:195], v[168:171], v[100:103]
	v_mfma_f32_16x16x32_bf16 v[96:99], v[204:207], v[168:171], v[96:99]
	v_mfma_f32_16x16x32_bf16 v[84:87], v[192:195], v[176:179], v[84:87]
	v_mfma_f32_16x16x32_bf16 v[80:83], v[204:207], v[176:179], v[80:83]
	v_mfma_f32_16x16x32_bf16 v[68:71], v[192:195], v[184:187], v[68:71]
	v_mfma_f32_16x16x32_bf16 v[64:67], v[204:207], v[184:187], v[64:67]
	v_mfma_f32_16x16x32_bf16 v[132:135], v[196:199], v[164:167], v[132:135]
	v_mfma_f32_16x16x32_bf16 v[128:131], v[208:211], v[164:167], v[128:131]
	v_mfma_f32_16x16x32_bf16 v[100:103], v[196:199], v[172:175], v[100:103]
	v_mfma_f32_16x16x32_bf16 v[96:99], v[208:211], v[172:175], v[96:99]
	v_mfma_f32_16x16x32_bf16 v[84:87], v[196:199], v[180:183], v[84:87]
	v_mfma_f32_16x16x32_bf16 v[80:83], v[208:211], v[180:183], v[80:83]
	v_mfma_f32_16x16x32_bf16 v[68:71], v[196:199], v[188:191], v[68:71]
	v_mfma_f32_16x16x32_bf16 v[64:67], v[208:211], v[188:191], v[64:67]
	s_setprio 0
	s_mov_b32 m0, s19
	s_add_u32 s100, s12, s0
	s_addc_u32 s101, s13, s1
	s_barrier
	ds_read_b128 v[160:163], v123 offset:16384
	ds_read_b128 v[164:167], v123 offset:17408
	ds_read_b128 v[168:171], v123 offset:18432
	ds_read_b128 v[172:175], v123 offset:19456
	ds_read_b128 v[176:179], v123 offset:20480
	ds_read_b128 v[180:183], v123 offset:21504
	ds_read_b128 v[184:187], v123 offset:22528
	ds_read_b128 v[188:191], v123 offset:23552
	global_load_lds_dwordx4 v112, s[12:13]
	s_mov_b32 m0, s30
	s_nop 0
	global_load_lds_dwordx4 v114, s[12:13]
	s_setprio 1
	s_barrier
	s_waitcnt lgkmcnt(0)
	v_mfma_f32_16x16x32_bf16 v[60:63], v[144:147], v[160:163], v[60:63]
	v_mfma_f32_16x16x32_bf16 v[56:59], v[152:155], v[160:163], v[56:59]
	v_mfma_f32_16x16x32_bf16 v[44:47], v[144:147], v[168:171], v[44:47]
	v_mfma_f32_16x16x32_bf16 v[40:43], v[152:155], v[168:171], v[40:43]
	v_mfma_f32_16x16x32_bf16 v[28:31], v[144:147], v[176:179], v[28:31]
	v_mfma_f32_16x16x32_bf16 v[24:27], v[152:155], v[176:179], v[24:27]
	v_mfma_f32_16x16x32_bf16 v[12:15], v[144:147], v[184:187], v[12:15]
	v_mfma_f32_16x16x32_bf16 v[8:11], v[152:155], v[184:187], v[8:11]
	v_mfma_f32_16x16x32_bf16 v[60:63], v[148:151], v[164:167], v[60:63]
	v_mfma_f32_16x16x32_bf16 v[56:59], v[156:159], v[164:167], v[56:59]
	v_mfma_f32_16x16x32_bf16 v[44:47], v[148:151], v[172:175], v[44:47]
	v_mfma_f32_16x16x32_bf16 v[40:43], v[156:159], v[172:175], v[40:43]
	v_mfma_f32_16x16x32_bf16 v[28:31], v[148:151], v[180:183], v[28:31]
	v_mfma_f32_16x16x32_bf16 v[24:27], v[156:159], v[180:183], v[24:27]
	v_mfma_f32_16x16x32_bf16 v[12:15], v[148:151], v[188:191], v[12:15]
	v_mfma_f32_16x16x32_bf16 v[8:11], v[156:159], v[188:191], v[8:11]
	s_setprio 0
	s_barrier
	s_add_u32 s50, s8, 0x200000
	s_addc_u32 s51, s9, 0
	s_mov_b32 m0, s43
	s_nop 0
	global_load_lds_dwordx4 v202, s[50:51]
	s_mov_b32 m0, s44
	s_nop 0
	global_load_lds_dwordx4 v116, s[50:51]
	s_waitcnt vmcnt(6)
	s_setprio 1
	s_barrier
; #define PG8_STAGE(bufoff, gbase, voff) do { _Pragma("unroll") for (int _i = 0; _i < 2; ++_i) \
;         __builtin_amdgcn_global_load_lds((const unsigned*)((const char*)(gbase) + (voff)[_i]), (LAS unsigned*)(lds + (bufoff) + ldsw + _i * 8192), 16, 0, 0); } while (0)
; #define PG8_LDA(dst, b, h) do { _Pragma("unroll") for (int m = 0; m < 4; ++m) _Pragma("unroll") for (int k = 0; k < 2; ++k) dst[m][k] = *(const LAS bf16x8*)(lds + PG8_SA(b, h) + aoff + m * 2048 + k * 1024); } while (0)
; #define PG8_LDB(dst, b, h) do { _Pragma("unroll") for (int n = 0; n < 2; ++n) _Pragma("unroll") for (int k = 0; k < 2; ++k) dst[n][k] = *(const LAS bf16x8*)(lds + PG8_SB(b, h) + boff + n * 2048 + k * 1024); } while (0)
; #define PG8_WAIT_V(n) asm volatile("s_waitcnt vmcnt(" #n ")" ::: "memory")
; #define PG8_WAIT_L(n) asm volatile("s_waitcnt lgkmcnt(" #n ")" ::: "memory")
; #define PG8_BAR __builtin_amdgcn_s_barrier()
; #define PG8_SCHED __builtin_amdgcn_sched_barrier(0)
; template <class Epi>
; __device__ __forceinline__ void gemm_phase(LAS unsigned char* lds, const bf16_t* A, int lda, const bf16_t* Bt, int ldb, int M, int N, int K, int asel, const Epi& E, const int fixed_round = -1) {
;     ...
;             PG8_WAIT_V(6); PG8_BAR; PG8_MMA(1, 1, At, B1); PG8_BAR;
;             PG8_LDB(B0, 1, 0); PG8_SCHED; PG8_LDA(At, 1, 0); PG8_STAGE(PG8_SA(0, 1), a2 + hstepA, voffA);
;             PG8_WAIT_L(8); PG8_BAR; PG8_WAIT_L(0); PG8_MMA(0, 0, At, B0); PG8_BAR; PG8_SCHED;
;             PG8_LDB(B1, 1, 1); PG8_STAGE(PG8_SB(1, 0), b3, voffB);
;             PG8_BAR; PG8_WAIT_L(0); PG8_MMA(0, 1, At, B1); PG8_BAR;
	v_mfma_f32_16x16x32_bf16 v[52:55], v[192:195], v[160:163], v[52:55]
	v_mfma_f32_16x16x32_bf16 v[48:51], v[204:207], v[160:163], v[48:51]
	v_mfma_f32_16x16x32_bf16 v[36:39], v[192:195], v[168:171], v[36:39]
	v_mfma_f32_16x16x32_bf16 v[32:35], v[204:207], v[168:171], v[32:35]
	v_mfma_f32_16x16x32_bf16 v[20:23], v[192:195], v[176:179], v[20:23]
	v_mfma_f32_16x16x32_bf16 v[16:19], v[204:207], v[176:179], v[16:19]
	v_mfma_f32_16x16x32_bf16 v[4:7], v[192:195], v[184:187], v[4:7]
	v_mfma_f32_16x16x32_bf16 v[0:3], v[204:207], v[184:187], v[0:3]
	v_mfma_f32_16x16x32_bf16 v[52:55], v[196:199], v[164:167], v[52:55]
	v_mfma_f32_16x16x32_bf16 v[48:51], v[208:211], v[164:167], v[48:51]
	v_mfma_f32_16x16x32_bf16 v[36:39], v[196:199], v[172:175], v[36:39]
	v_mfma_f32_16x16x32_bf16 v[32:35], v[208:211], v[172:175], v[32:35]
	v_mfma_f32_16x16x32_bf16 v[20:23], v[196:199], v[180:183], v[20:23]
	v_mfma_f32_16x16x32_bf16 v[16:19], v[208:211], v[180:183], v[16:19]
	v_mfma_f32_16x16x32_bf16 v[4:7], v[196:199], v[188:191], v[4:7]
	v_mfma_f32_16x16x32_bf16 v[0:3], v[208:211], v[188:191], v[0:3]
	s_setprio 0
	s_barrier
	ds_read_b128 v[144:147], v125
	ds_read_b128 v[148:151], v125 offset:1024
	ds_read_b128 v[152:155], v125 offset:2048
	ds_read_b128 v[156:159], v125 offset:3072
	s_add_u32 s12, s12, 0x200000
	s_addc_u32 s13, s13, 0
	s_mov_b32 m0, s31
	ds_read_b128 v[160:163], v123 offset:32768
	ds_read_b128 v[164:167], v123 offset:33792
	ds_read_b128 v[168:171], v123 offset:34816
	ds_read_b128 v[172:175], v123 offset:35840
	ds_read_b128 v[176:179], v123 offset:36864
	ds_read_b128 v[180:183], v123 offset:37888
	ds_read_b128 v[184:187], v123 offset:38912
	ds_read_b128 v[188:191], v123 offset:39936
	global_load_lds_dwordx4 v112, s[12:13]
	s_mov_b32 m0, s33
	s_nop 0
	global_load_lds_dwordx4 v114, s[12:13]
	s_waitcnt lgkmcnt(8)
	s_setprio 1
	s_barrier
	s_waitcnt lgkmcnt(0)
	v_mfma_f32_16x16x32_bf16 v[140:143], v[144:147], v[160:163], v[140:143]
	v_mfma_f32_16x16x32_bf16 v[136:139], v[152:155], v[160:163], v[136:139]
	v_mfma_f32_16x16x32_bf16 v[108:111], v[144:147], v[168:171], v[108:111]
	v_mfma_f32_16x16x32_bf16 v[104:107], v[152:155], v[168:171], v[104:107]
	v_mfma_f32_16x16x32_bf16 v[92:95], v[144:147], v[176:179], v[92:95]
	v_mfma_f32_16x16x32_bf16 v[88:91], v[152:155], v[176:179], v[88:91]
	v_mfma_f32_16x16x32_bf16 v[76:79], v[144:147], v[184:187], v[76:79]
	v_mfma_f32_16x16x32_bf16 v[72:75], v[152:155], v[184:187], v[72:75]
	v_mfma_f32_16x16x32_bf16 v[140:143], v[148:151], v[164:167], v[140:143]
	v_mfma_f32_16x16x32_bf16 v[136:139], v[156:159], v[164:167], v[136:139]
	v_mfma_f32_16x16x32_bf16 v[108:111], v[148:151], v[172:175], v[108:111]
	v_mfma_f32_16x16x32_bf16 v[104:107], v[156:159], v[172:175], v[104:107]
	v_mfma_f32_16x16x32_bf16 v[92:95], v[148:151], v[180:183], v[92:95]
	v_mfma_f32_16x16x32_bf16 v[88:91], v[156:159], v[180:183], v[88:91]
	v_mfma_f32_16x16x32_bf16 v[76:79], v[148:151], v[188:191], v[76:79]
	v_mfma_f32_16x16x32_bf16 v[72:75], v[156:159], v[188:191], v[72:75]
	s_setprio 0
	s_barrier
	s_mov_b32 m0, s45
	ds_read_b128 v[192:195], v126
	ds_read_b128 v[196:199], v126 offset:1024
	ds_read_b128 v[204:207], v126 offset:2048
	ds_read_b128 v[208:211], v126 offset:3072
	global_load_lds_dwordx4 v202, s[98:99]
	s_mov_b32 m0, s46
	s_nop 0
	global_load_lds_dwordx4 v116, s[98:99]
	s_setprio 1
	s_barrier
; #define PG8_STAGE(bufoff, gbase, voff) do { _Pragma("unroll") for (int _i = 0; _i < 2; ++_i) \
;         __builtin_amdgcn_global_load_lds((const unsigned*)((const char*)(gbase) + (voff)[_i]), (LAS unsigned*)(lds + (bufoff) + ldsw + _i * 8192), 16, 0, 0); } while (0)
; #define PG8_LDA(dst, b, h) do { _Pragma("unroll") for (int m = 0; m < 4; ++m) _Pragma("unroll") for (int k = 0; k < 2; ++k) dst[m][k] = *(const LAS bf16x8*)(lds + PG8_SA(b, h) + aoff + m * 2048 + k * 1024); } while (0)
; #define PG8_WAIT_V(n) asm volatile("s_waitcnt vmcnt(" #n ")" ::: "memory")
; #define PG8_WAIT_L(n) asm volatile("s_waitcnt lgkmcnt(" #n ")" ::: "memory")
; #define PG8_BAR __builtin_amdgcn_s_barrier()
; #define PG8_SCHED __builtin_amdgcn_sched_barrier(0)
; template <class Epi>
; __device__ __forceinline__ void gemm_phase(LAS unsigned char* lds, const bf16_t* A, int lda, const bf16_t* Bt, int ldb, int M, int N, int K, int asel, const Epi& E, const int fixed_round = -1) {
;     ...
;             PG8_BAR; PG8_WAIT_L(0); PG8_MMA(0, 1, At, B1); PG8_BAR;
;             PG8_LDA(At, 1, 1); PG8_STAGE(PG8_SA(1, 0), a3, voffA);
;             PG8_BAR; PG8_WAIT_L(0); PG8_MMA(1, 0, At, B0); PG8_BAR; PG8_SCHED;
;             PG8_STAGE(PG8_SB(1, 1), b3 + hstepB, voffB);
;             PG8_WAIT_V(6); PG8_BAR; PG8_MMA(1, 1, At, B1); PG8_BAR;
;     ...
;     PG8_WAIT_V(0);
;     if (wr == 0) PG8_BAR;
;     PG8_BAR;
	s_waitcnt lgkmcnt(0)
	v_mfma_f32_16x16x32_bf16 v[132:135], v[192:195], v[160:163], v[132:135]
	v_mfma_f32_16x16x32_bf16 v[128:131], v[204:207], v[160:163], v[128:131]
	v_mfma_f32_16x16x32_bf16 v[100:103], v[192:195], v[168:171], v[100:103]
	v_mfma_f32_16x16x32_bf16 v[96:99], v[204:207], v[168:171], v[96:99]
	v_mfma_f32_16x16x32_bf16 v[84:87], v[192:195], v[176:179], v[84:87]
	v_mfma_f32_16x16x32_bf16 v[80:83], v[204:207], v[176:179], v[80:83]
	v_mfma_f32_16x16x32_bf16 v[68:71], v[192:195], v[184:187], v[68:71]
	v_mfma_f32_16x16x32_bf16 v[64:67], v[204:207], v[184:187], v[64:67]
	v_mfma_f32_16x16x32_bf16 v[132:135], v[196:199], v[164:167], v[132:135]
	v_mfma_f32_16x16x32_bf16 v[128:131], v[208:211], v[164:167], v[128:131]
	v_mfma_f32_16x16x32_bf16 v[100:103], v[196:199], v[172:175], v[100:103]
	v_mfma_f32_16x16x32_bf16 v[96:99], v[208:211], v[172:175], v[96:99]
	v_mfma_f32_16x16x32_bf16 v[84:87], v[196:199], v[180:183], v[84:87]
	v_mfma_f32_16x16x32_bf16 v[80:83], v[208:211], v[180:183], v[80:83]
	v_mfma_f32_16x16x32_bf16 v[68:71], v[196:199], v[188:191], v[68:71]
	v_mfma_f32_16x16x32_bf16 v[64:67], v[208:211], v[188:191], v[64:67]
	s_setprio 0
	s_mov_b32 m0, s36
	s_barrier
	ds_read_b128 v[160:163], v123 offset:49152
	ds_read_b128 v[164:167], v123 offset:50176
	ds_read_b128 v[168:171], v123 offset:51200
	ds_read_b128 v[172:175], v123 offset:52224
	ds_read_b128 v[176:179], v123 offset:53248
	ds_read_b128 v[180:183], v123 offset:54272
	ds_read_b128 v[184:187], v123 offset:55296
	ds_read_b128 v[188:191], v123 offset:56320
	global_load_lds_dwordx4 v112, s[100:101]
	s_mov_b32 m0, s37
	s_nop 0
	global_load_lds_dwordx4 v114, s[100:101]
	s_setprio 1
	s_barrier
	s_waitcnt lgkmcnt(0)
	v_mfma_f32_16x16x32_bf16 v[60:63], v[144:147], v[160:163], v[60:63]
	v_mfma_f32_16x16x32_bf16 v[56:59], v[152:155], v[160:163], v[56:59]
	v_mfma_f32_16x16x32_bf16 v[44:47], v[144:147], v[168:171], v[44:47]
	v_mfma_f32_16x16x32_bf16 v[40:43], v[152:155], v[168:171], v[40:43]
	v_mfma_f32_16x16x32_bf16 v[28:31], v[144:147], v[176:179], v[28:31]
	v_mfma_f32_16x16x32_bf16 v[24:27], v[152:155], v[176:179], v[24:27]
	v_mfma_f32_16x16x32_bf16 v[12:15], v[144:147], v[184:187], v[12:15]
	v_mfma_f32_16x16x32_bf16 v[8:11], v[152:155], v[184:187], v[8:11]
	v_mfma_f32_16x16x32_bf16 v[60:63], v[148:151], v[164:167], v[60:63]
	v_mfma_f32_16x16x32_bf16 v[56:59], v[156:159], v[164:167], v[56:59]
	v_mfma_f32_16x16x32_bf16 v[44:47], v[148:151], v[172:175], v[44:47]
	v_mfma_f32_16x16x32_bf16 v[40:43], v[156:159], v[172:175], v[40:43]
	v_mfma_f32_16x16x32_bf16 v[28:31], v[148:151], v[180:183], v[28:31]
	v_mfma_f32_16x16x32_bf16 v[24:27], v[156:159], v[180:183], v[24:27]
	v_mfma_f32_16x16x32_bf16 v[12:15], v[148:151], v[188:191], v[12:15]
	v_mfma_f32_16x16x32_bf16 v[8:11], v[156:159], v[188:191], v[8:11]
	s_setprio 0
	s_barrier
	s_add_u32 s8, s8, 0x200080
	s_addc_u32 s9, s9, 0
	s_mov_b32 m0, s47
	s_nop 0
	global_load_lds_dwordx4 v202, s[8:9]
	s_mov_b32 m0, s48
	s_nop 0
	global_load_lds_dwordx4 v116, s[8:9]
	s_waitcnt vmcnt(6)
	s_setprio 1
	s_barrier
	v_mfma_f32_16x16x32_bf16 v[52:55], v[192:195], v[160:163], v[52:55]
	v_mfma_f32_16x16x32_bf16 v[48:51], v[204:207], v[160:163], v[48:51]
	v_mfma_f32_16x16x32_bf16 v[36:39], v[192:195], v[168:171], v[36:39]
	v_mfma_f32_16x16x32_bf16 v[32:35], v[204:207], v[168:171], v[32:35]
	v_mfma_f32_16x16x32_bf16 v[20:23], v[192:195], v[176:179], v[20:23]
	v_mfma_f32_16x16x32_bf16 v[16:19], v[204:207], v[176:179], v[16:19]
	v_mfma_f32_16x16x32_bf16 v[4:7], v[192:195], v[184:187], v[4:7]
	v_mfma_f32_16x16x32_bf16 v[0:3], v[204:207], v[184:187], v[0:3]
	v_mfma_f32_16x16x32_bf16 v[52:55], v[196:199], v[164:167], v[52:55]
	v_mfma_f32_16x16x32_bf16 v[48:51], v[208:211], v[164:167], v[48:51]
	v_mfma_f32_16x16x32_bf16 v[36:39], v[196:199], v[172:175], v[36:39]
	v_mfma_f32_16x16x32_bf16 v[32:35], v[208:211], v[172:175], v[32:35]
	v_mfma_f32_16x16x32_bf16 v[20:23], v[196:199], v[180:183], v[20:23]
	v_mfma_f32_16x16x32_bf16 v[16:19], v[208:211], v[180:183], v[16:19]
	v_mfma_f32_16x16x32_bf16 v[4:7], v[196:199], v[188:191], v[4:7]
	v_mfma_f32_16x16x32_bf16 v[0:3], v[208:211], v[188:191], v[0:3]
	s_setprio 0
	s_add_i32 s34, s34, 2
	s_add_u32 s6, s6, 0x100
	s_addc_u32 s7, s7, 0
	s_cmpk_lt_u32 s34, 0x7e
	s_cbranch_scc1 .Lrot_12
	s_barrier
	s_waitcnt vmcnt(0)
	s_cmpk_gt_u32 s18, 0xff
	s_cbranch_scc1 .LBB0_1325
	s_barrier
